# v007 + GEMM tiles: accumulator zero-init removed, first K-iteration peeled with SrcC=0
# speedup vs baseline: 1.0008x; 1.0008x over previous
; #define LAS __attribute__((address_space(3)))
; __device__ __forceinline__ unsigned cvtpk(float lo, float hi) { f32x2_t v = {lo, hi}; bf16x2_t b = __builtin_convertvector(v, bf16x2_t); return __builtin_bit_cast(unsigned, b); }
; #define NTL(p) __builtin_nontemporal_load(&(p))
; __device__ __forceinline__ void tr_item(const float* W, int N, int K, int k0, int n0, bf16_t* dst, LAS float* scr, int lane) {
; #pragma unroll 8
;     for (int i = 0; i < 32; ++i) { const int kk = 2 * i + (lane >> 5); scr[kk * 33 + (lane & 31)] = NTL(W[(size_t)(k0 + kk) * N + n0 + (lane & 31)]); }
;     asm volatile("s_waitcnt lgkmcnt(0)" ::: "memory");
;     const int c = lane & 7;
; #pragma unroll
;     for (int j = 0; j < 4; ++j) { const int n = (lane >> 3) + 8 * j; const LAS float* s = scr + (8 * c) * 33 + n;
;         u32x4 o; o.x = cvtpk(s[0 * 33], s[1 * 33]); o.y = cvtpk(s[2 * 33], s[3 * 33]); o.z = cvtpk(s[4 * 33], s[5 * 33]); o.w = cvtpk(s[6 * 33], s[7 * 33]);
;         *(u32x4*)(dst + (size_t)n * K + k0 + 8 * c) = o; }
;     asm volatile("s_waitcnt lgkmcnt(0)" ::: "memory");
.LBB0_17:
	v_lshl_add_u64 v[58:59], v[36:37], 0, s[12:13]
	v_lshl_add_u64 v[60:61], v[34:35], 0, s[12:13]
	v_lshl_add_u64 v[62:63], v[32:33], 0, s[12:13]
	v_lshl_add_u64 v[64:65], v[30:31], 0, s[12:13]
	v_lshl_add_u64 v[66:67], v[28:29], 0, s[12:13]
	v_lshl_add_u64 v[68:69], v[26:27], 0, s[12:13]
	v_lshl_add_u64 v[70:71], v[24:25], 0, s[12:13]
	v_lshl_add_u64 v[72:73], v[22:23], 0, s[12:13]
	global_load_dword v112, v[58:59], off nt
	global_load_dword v113, v[60:61], off nt
	global_load_dword v114, v[62:63], off nt
	global_load_dword v115, v[64:65], off nt
	global_load_dword v116, v[66:67], off nt
	global_load_dword v117, v[68:69], off nt
	global_load_dword v118, v[70:71], off nt
	global_load_dword v119, v[72:73], off nt
	s_add_u32 s12, s12, 0x20000
	s_addc_u32 s13, s13, 0
	v_lshl_add_u64 v[58:59], v[36:37], 0, s[12:13]
	v_lshl_add_u64 v[60:61], v[34:35], 0, s[12:13]
	v_lshl_add_u64 v[62:63], v[32:33], 0, s[12:13]
	v_lshl_add_u64 v[64:65], v[30:31], 0, s[12:13]
	v_lshl_add_u64 v[66:67], v[28:29], 0, s[12:13]
	v_lshl_add_u64 v[68:69], v[26:27], 0, s[12:13]
	v_lshl_add_u64 v[70:71], v[24:25], 0, s[12:13]
	v_lshl_add_u64 v[72:73], v[22:23], 0, s[12:13]
	global_load_dword v120, v[58:59], off nt
	global_load_dword v121, v[60:61], off nt
	global_load_dword v122, v[62:63], off nt
	global_load_dword v123, v[64:65], off nt
	global_load_dword v124, v[66:67], off nt
	global_load_dword v125, v[68:69], off nt
	global_load_dword v126, v[70:71], off nt
	global_load_dword v127, v[72:73], off nt
	s_add_u32 s12, s12, 0x20000
	s_addc_u32 s13, s13, 0
	v_lshl_add_u64 v[58:59], v[36:37], 0, s[12:13]
	v_lshl_add_u64 v[60:61], v[34:35], 0, s[12:13]
	v_lshl_add_u64 v[62:63], v[32:33], 0, s[12:13]
	v_lshl_add_u64 v[64:65], v[30:31], 0, s[12:13]
	v_lshl_add_u64 v[66:67], v[28:29], 0, s[12:13]
	v_lshl_add_u64 v[68:69], v[26:27], 0, s[12:13]
	v_lshl_add_u64 v[70:71], v[24:25], 0, s[12:13]
	v_lshl_add_u64 v[72:73], v[22:23], 0, s[12:13]
	global_load_dword v128, v[58:59], off nt
	global_load_dword v129, v[60:61], off nt
	global_load_dword v130, v[62:63], off nt
	global_load_dword v131, v[64:65], off nt
	global_load_dword v132, v[66:67], off nt
	global_load_dword v133, v[68:69], off nt
	global_load_dword v134, v[70:71], off nt
	global_load_dword v135, v[72:73], off nt
	s_add_u32 s12, s12, 0x20000
	s_addc_u32 s13, s13, 0
	v_lshl_add_u64 v[58:59], v[36:37], 0, s[12:13]
	v_lshl_add_u64 v[60:61], v[34:35], 0, s[12:13]
	v_lshl_add_u64 v[62:63], v[32:33], 0, s[12:13]
	v_lshl_add_u64 v[64:65], v[30:31], 0, s[12:13]
	v_lshl_add_u64 v[66:67], v[28:29], 0, s[12:13]
	v_lshl_add_u64 v[68:69], v[26:27], 0, s[12:13]
	v_lshl_add_u64 v[70:71], v[24:25], 0, s[12:13]
	v_lshl_add_u64 v[72:73], v[22:23], 0, s[12:13]
	global_load_dword v136, v[58:59], off nt
	global_load_dword v137, v[60:61], off nt
	global_load_dword v138, v[62:63], off nt
	global_load_dword v139, v[64:65], off nt
	global_load_dword v140, v[66:67], off nt
	global_load_dword v141, v[68:69], off nt
	global_load_dword v142, v[70:71], off nt
	global_load_dword v143, v[72:73], off nt
	s_add_u32 s12, s12, 0x20000
	s_addc_u32 s13, s13, 0
	v_add_u32_e32 v66, 0x400, v4
	s_waitcnt vmcnt(30)
	ds_write2_b32 v4, v112, v113 offset1:66
	s_waitcnt vmcnt(28)
	ds_write2_b32 v4, v114, v115 offset0:132 offset1:198
	s_waitcnt vmcnt(26)
	ds_write2_b32 v66, v116, v117 offset0:8 offset1:74
	s_waitcnt vmcnt(24)
	ds_write2_b32 v66, v118, v119 offset0:140 offset1:206
	v_add_u32_e32 v4, 0x840, v4
	v_add_u32_e32 v66, 0x400, v4
	s_waitcnt vmcnt(22)
	ds_write2_b32 v4, v120, v121 offset1:66
	s_waitcnt vmcnt(20)
	ds_write2_b32 v4, v122, v123 offset0:132 offset1:198
	s_waitcnt vmcnt(18)
	ds_write2_b32 v66, v124, v125 offset0:8 offset1:74
	s_waitcnt vmcnt(16)
	ds_write2_b32 v66, v126, v127 offset0:140 offset1:206
	v_add_u32_e32 v4, 0x840, v4
	v_add_u32_e32 v66, 0x400, v4
	s_waitcnt vmcnt(14)
	ds_write2_b32 v4, v128, v129 offset1:66
	s_waitcnt vmcnt(12)
	ds_write2_b32 v4, v130, v131 offset0:132 offset1:198
	s_waitcnt vmcnt(10)
	ds_write2_b32 v66, v132, v133 offset0:8 offset1:74
	s_waitcnt vmcnt(8)
	ds_write2_b32 v66, v134, v135 offset0:140 offset1:206
	v_add_u32_e32 v4, 0x840, v4
	v_add_u32_e32 v66, 0x400, v4
	s_waitcnt vmcnt(6)
	ds_write2_b32 v4, v136, v137 offset1:66
	s_waitcnt vmcnt(4)
	ds_write2_b32 v4, v138, v139 offset0:132 offset1:198
	s_waitcnt vmcnt(2)
	ds_write2_b32 v66, v140, v141 offset0:8 offset1:74
	s_waitcnt vmcnt(0)
	ds_write2_b32 v66, v142, v143 offset0:140 offset1:206
	v_add_u32_e32 v4, 0x840, v4
	s_and_b32 s4, s25, 0x7fffffc0
	s_lshl_b32 s12, s25, 17
	s_addk_i32 s4, 0xd000
	s_and_b32 s12, s12, 0x7e0000
	v_readlane_b32 s13, v245, 6
	s_waitcnt lgkmcnt(0)
	s_add_u32 s16, s13, s12
	v_readlane_b32 s12, v245, 7
	ds_read2_b32 v[26:27], v3 offset0:33 offset1:41
	ds_read2_b32 v[28:29], v3 offset1:8
	ds_read2_b32 v[30:31], v3 offset0:66 offset1:74
	ds_read2_b32 v[32:33], v3 offset0:99 offset1:107
	ds_read2_b32 v[34:35], v3 offset0:132 offset1:140
	ds_read2_b32 v[36:37], v3 offset0:165 offset1:173
	ds_read2_b32 v[58:59], v3 offset0:198 offset1:206
	ds_read2_b32 v[60:61], v3 offset0:231 offset1:239
	s_addc_u32 s17, s12, 0
	s_lshl_b64 s[12:13], s[4:5], 1
	s_add_u32 s12, s16, s12
	s_addc_u32 s13, s17, s13
	v_lshlrev_b32_e32 v4, 1, v2
	v_lshl_add_u64 v[62:63], s[12:13], 0, v[4:5]
	v_lshlrev_b32_e32 v4, 1, v6
	s_waitcnt lgkmcnt(6)
	v_cvt_pk_bf16_f32 v22, v28, v26
	s_waitcnt lgkmcnt(4)
	v_cvt_pk_bf16_f32 v23, v30, v32
	s_waitcnt lgkmcnt(2)
	v_cvt_pk_bf16_f32 v24, v34, v36
	s_waitcnt lgkmcnt(0)
	v_cvt_pk_bf16_f32 v25, v58, v60
	v_lshl_add_u64 v[64:65], v[62:63], 0, v[4:5]
	global_store_dwordx4 v[64:65], v[22:25], off
	v_lshlrev_b32_e32 v4, 1, v8
	s_mov_b64 s[12:13], 0
	v_cvt_pk_bf16_f32 v22, v29, v27
	v_cvt_pk_bf16_f32 v23, v31, v33
	v_cvt_pk_bf16_f32 v24, v35, v37
	v_cvt_pk_bf16_f32 v25, v59, v61
	ds_read2_b32 v[28:29], v3 offset0:49 offset1:57
	ds_read2_b32 v[30:31], v3 offset0:16 offset1:24
	ds_read2_b32 v[32:33], v3 offset0:82 offset1:90
	ds_read2_b32 v[34:35], v3 offset0:115 offset1:123
	ds_read2_b32 v[36:37], v3 offset0:148 offset1:156
	ds_read2_b32 v[58:59], v3 offset0:181 offset1:189
	ds_read2_b32 v[60:61], v3 offset0:214 offset1:222
	ds_read2_b32 v[64:65], v3 offset0:247 offset1:255
	v_lshl_add_u64 v[26:27], v[62:63], 0, v[4:5]
	v_lshlrev_b32_e32 v4, 1, v10
	global_store_dwordx4 v[26:27], v[22:25], off
	v_lshl_add_u64 v[26:27], v[62:63], 0, v[4:5]
	v_lshlrev_b32_e32 v4, 1, v12
	s_waitcnt lgkmcnt(6)
	v_cvt_pk_bf16_f32 v22, v30, v28
	s_waitcnt lgkmcnt(4)
	v_cvt_pk_bf16_f32 v23, v32, v34
	s_waitcnt lgkmcnt(2)
	v_cvt_pk_bf16_f32 v24, v36, v58
	s_waitcnt lgkmcnt(0)
	v_cvt_pk_bf16_f32 v25, v60, v64
	global_store_dwordx4 v[26:27], v[22:25], off
	v_lshl_add_u64 v[26:27], v[62:63], 0, v[4:5]
	s_nop 0
	v_cvt_pk_bf16_f32 v22, v31, v29
	v_cvt_pk_bf16_f32 v23, v33, v35
	v_cvt_pk_bf16_f32 v24, v37, v59
	v_cvt_pk_bf16_f32 v25, v61, v65
	global_store_dwordx4 v[26:27], v[22:25], off
	s_waitcnt lgkmcnt(0)

; #define LAS __attribute__((address_space(3)))
; __device__ __forceinline__ unsigned cvtpk(float lo, float hi) { f32x2_t v = {lo, hi}; bf16x2_t b = __builtin_convertvector(v, bf16x2_t); return __builtin_bit_cast(unsigned, b); }
; #define NTL(p) __builtin_nontemporal_load(&(p))
; __device__ __forceinline__ void tr_item(const float* W, int N, int K, int k0, int n0, bf16_t* dst, LAS float* scr, int lane) {
; #pragma unroll 8
;     for (int i = 0; i < 32; ++i) { const int kk = 2 * i + (lane >> 5); scr[kk * 33 + (lane & 31)] = NTL(W[(size_t)(k0 + kk) * N + n0 + (lane & 31)]); }
;     asm volatile("s_waitcnt lgkmcnt(0)" ::: "memory");
;     const int c = lane & 7;
; #pragma unroll
;     for (int j = 0; j < 4; ++j) { const int n = (lane >> 3) + 8 * j; const LAS float* s = scr + (8 * c) * 33 + n;
;         u32x4 o; o.x = cvtpk(s[0 * 33], s[1 * 33]); o.y = cvtpk(s[2 * 33], s[3 * 33]); o.z = cvtpk(s[4 * 33], s[5 * 33]); o.w = cvtpk(s[6 * 33], s[7 * 33]);
;         *(u32x4*)(dst + (size_t)n * K + k0 + 8 * c) = o; }
;     asm volatile("s_waitcnt lgkmcnt(0)" ::: "memory");
.LBB0_21:
	v_lshl_add_u64 v[58:59], v[36:37], 0, s[12:13]
	v_lshl_add_u64 v[60:61], v[34:35], 0, s[12:13]
	v_lshl_add_u64 v[62:63], v[32:33], 0, s[12:13]
	v_lshl_add_u64 v[64:65], v[30:31], 0, s[12:13]
	v_lshl_add_u64 v[66:67], v[28:29], 0, s[12:13]
	v_lshl_add_u64 v[68:69], v[26:27], 0, s[12:13]
	v_lshl_add_u64 v[70:71], v[24:25], 0, s[12:13]
	v_lshl_add_u64 v[72:73], v[22:23], 0, s[12:13]
	global_load_dword v112, v[58:59], off nt
	global_load_dword v113, v[60:61], off nt
	global_load_dword v114, v[62:63], off nt
	global_load_dword v115, v[64:65], off nt
	global_load_dword v116, v[66:67], off nt
	global_load_dword v117, v[68:69], off nt
	global_load_dword v118, v[70:71], off nt
	global_load_dword v119, v[72:73], off nt
	s_add_u32 s12, s12, 0x40000
	s_addc_u32 s13, s13, 0
	v_lshl_add_u64 v[58:59], v[36:37], 0, s[12:13]
	v_lshl_add_u64 v[60:61], v[34:35], 0, s[12:13]
	v_lshl_add_u64 v[62:63], v[32:33], 0, s[12:13]
	v_lshl_add_u64 v[64:65], v[30:31], 0, s[12:13]
	v_lshl_add_u64 v[66:67], v[28:29], 0, s[12:13]
	v_lshl_add_u64 v[68:69], v[26:27], 0, s[12:13]
	v_lshl_add_u64 v[70:71], v[24:25], 0, s[12:13]
	v_lshl_add_u64 v[72:73], v[22:23], 0, s[12:13]
	global_load_dword v120, v[58:59], off nt
	global_load_dword v121, v[60:61], off nt
	global_load_dword v122, v[62:63], off nt
	global_load_dword v123, v[64:65], off nt
	global_load_dword v124, v[66:67], off nt
	global_load_dword v125, v[68:69], off nt
	global_load_dword v126, v[70:71], off nt
	global_load_dword v127, v[72:73], off nt
	s_add_u32 s12, s12, 0x40000
	s_addc_u32 s13, s13, 0
	v_lshl_add_u64 v[58:59], v[36:37], 0, s[12:13]
	v_lshl_add_u64 v[60:61], v[34:35], 0, s[12:13]
	v_lshl_add_u64 v[62:63], v[32:33], 0, s[12:13]
	v_lshl_add_u64 v[64:65], v[30:31], 0, s[12:13]
	v_lshl_add_u64 v[66:67], v[28:29], 0, s[12:13]
	v_lshl_add_u64 v[68:69], v[26:27], 0, s[12:13]
	v_lshl_add_u64 v[70:71], v[24:25], 0, s[12:13]
	v_lshl_add_u64 v[72:73], v[22:23], 0, s[12:13]
	global_load_dword v128, v[58:59], off nt
	global_load_dword v129, v[60:61], off nt
	global_load_dword v130, v[62:63], off nt
	global_load_dword v131, v[64:65], off nt
	global_load_dword v132, v[66:67], off nt
	global_load_dword v133, v[68:69], off nt
	global_load_dword v134, v[70:71], off nt
	global_load_dword v135, v[72:73], off nt
	s_add_u32 s12, s12, 0x40000
	s_addc_u32 s13, s13, 0
	v_lshl_add_u64 v[58:59], v[36:37], 0, s[12:13]
	v_lshl_add_u64 v[60:61], v[34:35], 0, s[12:13]
	v_lshl_add_u64 v[62:63], v[32:33], 0, s[12:13]
	v_lshl_add_u64 v[64:65], v[30:31], 0, s[12:13]
	v_lshl_add_u64 v[66:67], v[28:29], 0, s[12:13]
	v_lshl_add_u64 v[68:69], v[26:27], 0, s[12:13]
	v_lshl_add_u64 v[70:71], v[24:25], 0, s[12:13]
	v_lshl_add_u64 v[72:73], v[22:23], 0, s[12:13]
	global_load_dword v136, v[58:59], off nt
	global_load_dword v137, v[60:61], off nt
	global_load_dword v138, v[62:63], off nt
	global_load_dword v139, v[64:65], off nt
	global_load_dword v140, v[66:67], off nt
	global_load_dword v141, v[68:69], off nt
	global_load_dword v142, v[70:71], off nt
	global_load_dword v143, v[72:73], off nt
	s_add_u32 s12, s12, 0x40000
	s_addc_u32 s13, s13, 0
	v_add_u32_e32 v66, 0x400, v4
	s_waitcnt vmcnt(30)
	ds_write2_b32 v4, v112, v113 offset1:66
	s_waitcnt vmcnt(28)
	ds_write2_b32 v4, v114, v115 offset0:132 offset1:198
	s_waitcnt vmcnt(26)
	ds_write2_b32 v66, v116, v117 offset0:8 offset1:74
	s_waitcnt vmcnt(24)
	ds_write2_b32 v66, v118, v119 offset0:140 offset1:206
	v_add_u32_e32 v4, 0x840, v4
	v_add_u32_e32 v66, 0x400, v4
	s_waitcnt vmcnt(22)
	ds_write2_b32 v4, v120, v121 offset1:66
	s_waitcnt vmcnt(20)
	ds_write2_b32 v4, v122, v123 offset0:132 offset1:198
	s_waitcnt vmcnt(18)
	ds_write2_b32 v66, v124, v125 offset0:8 offset1:74
	s_waitcnt vmcnt(16)
	ds_write2_b32 v66, v126, v127 offset0:140 offset1:206
	v_add_u32_e32 v4, 0x840, v4
	v_add_u32_e32 v66, 0x400, v4
	s_waitcnt vmcnt(14)
	ds_write2_b32 v4, v128, v129 offset1:66
	s_waitcnt vmcnt(12)
	ds_write2_b32 v4, v130, v131 offset0:132 offset1:198
	s_waitcnt vmcnt(10)
	ds_write2_b32 v66, v132, v133 offset0:8 offset1:74
	s_waitcnt vmcnt(8)
	ds_write2_b32 v66, v134, v135 offset0:140 offset1:206
	v_add_u32_e32 v4, 0x840, v4
	v_add_u32_e32 v66, 0x400, v4
	s_waitcnt vmcnt(6)
	ds_write2_b32 v4, v136, v137 offset1:66
	s_waitcnt vmcnt(4)
	ds_write2_b32 v4, v138, v139 offset0:132 offset1:198
	s_waitcnt vmcnt(2)
	ds_write2_b32 v66, v140, v141 offset0:8 offset1:74
	s_waitcnt vmcnt(0)
	ds_write2_b32 v66, v142, v143 offset0:140 offset1:206
	v_add_u32_e32 v4, 0x840, v4
	s_lshl_b32 s12, s25, 17
	s_add_i32 s4, s25, 0xffffe000
	s_and_b32 s12, s12, 0xfe0000
	v_readlane_b32 s13, v245, 4
	s_waitcnt lgkmcnt(0)
	s_add_u32 s12, s13, s12
	v_readlane_b32 s13, v245, 5
	ds_read2_b32 v[26:27], v3 offset0:33 offset1:41
	ds_read2_b32 v[28:29], v3 offset1:8
	ds_read2_b32 v[30:31], v3 offset0:66 offset1:74
	ds_read2_b32 v[32:33], v3 offset0:99 offset1:107
	ds_read2_b32 v[34:35], v3 offset0:132 offset1:140
	ds_read2_b32 v[36:37], v3 offset0:165 offset1:173
	ds_read2_b32 v[58:59], v3 offset0:198 offset1:206
	ds_read2_b32 v[60:61], v3 offset0:231 offset1:239
	s_addc_u32 s13, s13, 0
	s_and_b32 s4, s4, 0xffffff80
	s_add_u32 s12, s12, s4
	s_addc_u32 s13, s13, 0
	v_lshlrev_b32_e32 v4, 1, v2
	v_lshl_add_u64 v[62:63], s[12:13], 0, v[4:5]
	v_lshlrev_b32_e32 v4, 1, v6
	s_waitcnt lgkmcnt(6)
	v_cvt_pk_bf16_f32 v22, v28, v26
	s_waitcnt lgkmcnt(4)
	v_cvt_pk_bf16_f32 v23, v30, v32
	s_waitcnt lgkmcnt(2)
	v_cvt_pk_bf16_f32 v24, v34, v36
	s_waitcnt lgkmcnt(0)
	v_cvt_pk_bf16_f32 v25, v58, v60
	v_lshl_add_u64 v[64:65], v[62:63], 0, v[4:5]
	global_store_dwordx4 v[64:65], v[22:25], off
	v_lshlrev_b32_e32 v4, 1, v8
	s_nop 0
	v_cvt_pk_bf16_f32 v22, v29, v27
	v_cvt_pk_bf16_f32 v23, v31, v33
	v_cvt_pk_bf16_f32 v24, v35, v37
	v_cvt_pk_bf16_f32 v25, v59, v61
	ds_read2_b32 v[28:29], v3 offset0:49 offset1:57
	ds_read2_b32 v[30:31], v3 offset0:16 offset1:24
	ds_read2_b32 v[32:33], v3 offset0:82 offset1:90
	ds_read2_b32 v[34:35], v3 offset0:115 offset1:123
	ds_read2_b32 v[36:37], v3 offset0:148 offset1:156
	ds_read2_b32 v[58:59], v3 offset0:181 offset1:189
	ds_read2_b32 v[60:61], v3 offset0:214 offset1:222
	ds_read2_b32 v[64:65], v3 offset0:247 offset1:255
	v_lshl_add_u64 v[26:27], v[62:63], 0, v[4:5]
	v_lshlrev_b32_e32 v4, 1, v10
	global_store_dwordx4 v[26:27], v[22:25], off
	v_lshl_add_u64 v[26:27], v[62:63], 0, v[4:5]
	v_lshlrev_b32_e32 v4, 1, v12
	s_waitcnt lgkmcnt(6)
	v_cvt_pk_bf16_f32 v22, v30, v28
	s_waitcnt lgkmcnt(4)
	v_cvt_pk_bf16_f32 v23, v32, v34
	s_waitcnt lgkmcnt(2)
	v_cvt_pk_bf16_f32 v24, v36, v58
	s_waitcnt lgkmcnt(0)
	v_cvt_pk_bf16_f32 v25, v60, v64
	global_store_dwordx4 v[26:27], v[22:25], off
	v_lshl_add_u64 v[26:27], v[62:63], 0, v[4:5]
	s_nop 0
	v_cvt_pk_bf16_f32 v22, v31, v29
	v_cvt_pk_bf16_f32 v23, v33, v35
	v_cvt_pk_bf16_f32 v24, v37, v59
	v_cvt_pk_bf16_f32 v25, v61, v65
	global_store_dwordx4 v[26:27], v[22:25], off
	s_waitcnt lgkmcnt(0)

; #define LAS __attribute__((address_space(3)))
; __device__ __forceinline__ unsigned cvtpk(float lo, float hi) { f32x2_t v = {lo, hi}; bf16x2_t b = __builtin_convertvector(v, bf16x2_t); return __builtin_bit_cast(unsigned, b); }
; #define NTL(p) __builtin_nontemporal_load(&(p))
; __device__ __forceinline__ void tr_item(const float* W, int N, int K, int k0, int n0, bf16_t* dst, LAS float* scr, int lane) {
; #pragma unroll 8
;     for (int i = 0; i < 32; ++i) { const int kk = 2 * i + (lane >> 5); scr[kk * 33 + (lane & 31)] = NTL(W[(size_t)(k0 + kk) * N + n0 + (lane & 31)]); }
;     asm volatile("s_waitcnt lgkmcnt(0)" ::: "memory");
;     const int c = lane & 7;
; #pragma unroll
;     for (int j = 0; j < 4; ++j) { const int n = (lane >> 3) + 8 * j; const LAS float* s = scr + (8 * c) * 33 + n;
;         u32x4 o; o.x = cvtpk(s[0 * 33], s[1 * 33]); o.y = cvtpk(s[2 * 33], s[3 * 33]); o.z = cvtpk(s[4 * 33], s[5 * 33]); o.w = cvtpk(s[6 * 33], s[7 * 33]);
;         *(u32x4*)(dst + (size_t)n * K + k0 + 8 * c) = o; }
;     asm volatile("s_waitcnt lgkmcnt(0)" ::: "memory");
.LBB0_26:
	v_lshl_add_u64 v[58:59], v[36:37], 0, s[12:13]
	v_lshl_add_u64 v[60:61], v[34:35], 0, s[12:13]
	v_lshl_add_u64 v[62:63], v[32:33], 0, s[12:13]
	v_lshl_add_u64 v[64:65], v[30:31], 0, s[12:13]
	v_lshl_add_u64 v[66:67], v[28:29], 0, s[12:13]
	v_lshl_add_u64 v[68:69], v[26:27], 0, s[12:13]
	v_lshl_add_u64 v[70:71], v[24:25], 0, s[12:13]
	v_lshl_add_u64 v[72:73], v[22:23], 0, s[12:13]
	global_load_dword v112, v[58:59], off nt
	global_load_dword v113, v[60:61], off nt
	global_load_dword v114, v[62:63], off nt
	global_load_dword v115, v[64:65], off nt
	global_load_dword v116, v[66:67], off nt
	global_load_dword v117, v[68:69], off nt
	global_load_dword v118, v[70:71], off nt
	global_load_dword v119, v[72:73], off nt
	s_add_u32 s12, s12, 0x20000
	s_addc_u32 s13, s13, 0
	v_lshl_add_u64 v[58:59], v[36:37], 0, s[12:13]
	v_lshl_add_u64 v[60:61], v[34:35], 0, s[12:13]
	v_lshl_add_u64 v[62:63], v[32:33], 0, s[12:13]
	v_lshl_add_u64 v[64:65], v[30:31], 0, s[12:13]
	v_lshl_add_u64 v[66:67], v[28:29], 0, s[12:13]
	v_lshl_add_u64 v[68:69], v[26:27], 0, s[12:13]
	v_lshl_add_u64 v[70:71], v[24:25], 0, s[12:13]
	v_lshl_add_u64 v[72:73], v[22:23], 0, s[12:13]
	global_load_dword v120, v[58:59], off nt
	global_load_dword v121, v[60:61], off nt
	global_load_dword v122, v[62:63], off nt
	global_load_dword v123, v[64:65], off nt
	global_load_dword v124, v[66:67], off nt
	global_load_dword v125, v[68:69], off nt
	global_load_dword v126, v[70:71], off nt
	global_load_dword v127, v[72:73], off nt
	s_add_u32 s12, s12, 0x20000
	s_addc_u32 s13, s13, 0
	v_lshl_add_u64 v[58:59], v[36:37], 0, s[12:13]
	v_lshl_add_u64 v[60:61], v[34:35], 0, s[12:13]
	v_lshl_add_u64 v[62:63], v[32:33], 0, s[12:13]
	v_lshl_add_u64 v[64:65], v[30:31], 0, s[12:13]
	v_lshl_add_u64 v[66:67], v[28:29], 0, s[12:13]
	v_lshl_add_u64 v[68:69], v[26:27], 0, s[12:13]
	v_lshl_add_u64 v[70:71], v[24:25], 0, s[12:13]
	v_lshl_add_u64 v[72:73], v[22:23], 0, s[12:13]
	global_load_dword v128, v[58:59], off nt
	global_load_dword v129, v[60:61], off nt
	global_load_dword v130, v[62:63], off nt
	global_load_dword v131, v[64:65], off nt
	global_load_dword v132, v[66:67], off nt
	global_load_dword v133, v[68:69], off nt
	global_load_dword v134, v[70:71], off nt
	global_load_dword v135, v[72:73], off nt
	s_add_u32 s12, s12, 0x20000
	s_addc_u32 s13, s13, 0
	v_lshl_add_u64 v[58:59], v[36:37], 0, s[12:13]
	v_lshl_add_u64 v[60:61], v[34:35], 0, s[12:13]
	v_lshl_add_u64 v[62:63], v[32:33], 0, s[12:13]
	v_lshl_add_u64 v[64:65], v[30:31], 0, s[12:13]
	v_lshl_add_u64 v[66:67], v[28:29], 0, s[12:13]
	v_lshl_add_u64 v[68:69], v[26:27], 0, s[12:13]
	v_lshl_add_u64 v[70:71], v[24:25], 0, s[12:13]
	v_lshl_add_u64 v[72:73], v[22:23], 0, s[12:13]
	global_load_dword v136, v[58:59], off nt
	global_load_dword v137, v[60:61], off nt
	global_load_dword v138, v[62:63], off nt
	global_load_dword v139, v[64:65], off nt
	global_load_dword v140, v[66:67], off nt
	global_load_dword v141, v[68:69], off nt
	global_load_dword v142, v[70:71], off nt
	global_load_dword v143, v[72:73], off nt
	s_add_u32 s12, s12, 0x20000
	s_addc_u32 s13, s13, 0
	v_add_u32_e32 v66, 0x400, v4
	s_waitcnt vmcnt(30)
	ds_write2_b32 v4, v112, v113 offset1:66
	s_waitcnt vmcnt(28)
	ds_write2_b32 v4, v114, v115 offset0:132 offset1:198
	s_waitcnt vmcnt(26)
	ds_write2_b32 v66, v116, v117 offset0:8 offset1:74
	s_waitcnt vmcnt(24)
	ds_write2_b32 v66, v118, v119 offset0:140 offset1:206
	v_add_u32_e32 v4, 0x840, v4
	v_add_u32_e32 v66, 0x400, v4
	s_waitcnt vmcnt(22)
	ds_write2_b32 v4, v120, v121 offset1:66
	s_waitcnt vmcnt(20)
	ds_write2_b32 v4, v122, v123 offset0:132 offset1:198
	s_waitcnt vmcnt(18)
	ds_write2_b32 v66, v124, v125 offset0:8 offset1:74
	s_waitcnt vmcnt(16)
	ds_write2_b32 v66, v126, v127 offset0:140 offset1:206
	v_add_u32_e32 v4, 0x840, v4
	v_add_u32_e32 v66, 0x400, v4
	s_waitcnt vmcnt(14)
	ds_write2_b32 v4, v128, v129 offset1:66
	s_waitcnt vmcnt(12)
	ds_write2_b32 v4, v130, v131 offset0:132 offset1:198
	s_waitcnt vmcnt(10)
	ds_write2_b32 v66, v132, v133 offset0:8 offset1:74
	s_waitcnt vmcnt(8)
	ds_write2_b32 v66, v134, v135 offset0:140 offset1:206
	v_add_u32_e32 v4, 0x840, v4
	v_add_u32_e32 v66, 0x400, v4
	s_waitcnt vmcnt(6)
	ds_write2_b32 v4, v136, v137 offset1:66
	s_waitcnt vmcnt(4)
	ds_write2_b32 v4, v138, v139 offset0:132 offset1:198
	s_waitcnt vmcnt(2)
	ds_write2_b32 v66, v140, v141 offset0:8 offset1:74
	s_waitcnt vmcnt(0)
	ds_write2_b32 v66, v142, v143 offset0:140 offset1:206
	v_add_u32_e32 v4, 0x840, v4
	s_and_b32 s4, s25, 0x1fc0
	s_lshl_b32 s12, s25, 17
	s_addk_i32 s4, 0xe800
	s_and_b32 s12, s12, 0x7e0000
	v_readlane_b32 s13, v245, 2
	s_waitcnt lgkmcnt(0)
	s_add_u32 s14, s13, s12
	v_readlane_b32 s12, v245, 3
	ds_read2_b32 v[26:27], v3 offset0:33 offset1:41
	ds_read2_b32 v[28:29], v3 offset1:8
	ds_read2_b32 v[30:31], v3 offset0:66 offset1:74
	ds_read2_b32 v[32:33], v3 offset0:99 offset1:107
	ds_read2_b32 v[34:35], v3 offset0:132 offset1:140
	ds_read2_b32 v[36:37], v3 offset0:165 offset1:173
	ds_read2_b32 v[58:59], v3 offset0:198 offset1:206
	ds_read2_b32 v[60:61], v3 offset0:231 offset1:239
	s_addc_u32 s15, s12, 0
	s_lshl_b64 s[12:13], s[4:5], 1
	s_add_u32 s12, s14, s12
	s_addc_u32 s13, s15, s13
	v_lshlrev_b32_e32 v4, 1, v2
	v_lshl_add_u64 v[62:63], s[12:13], 0, v[4:5]
	v_lshlrev_b32_e32 v4, 1, v6
	s_waitcnt lgkmcnt(6)
	v_cvt_pk_bf16_f32 v22, v28, v26
	s_waitcnt lgkmcnt(4)
	v_cvt_pk_bf16_f32 v23, v30, v32
	s_waitcnt lgkmcnt(2)
	v_cvt_pk_bf16_f32 v24, v34, v36
	s_waitcnt lgkmcnt(0)
	v_cvt_pk_bf16_f32 v25, v58, v60
	v_lshl_add_u64 v[64:65], v[62:63], 0, v[4:5]
	global_store_dwordx4 v[64:65], v[22:25], off
	v_lshlrev_b32_e32 v4, 1, v8
	s_nop 0
	v_cvt_pk_bf16_f32 v22, v29, v27
	v_cvt_pk_bf16_f32 v23, v31, v33
	v_cvt_pk_bf16_f32 v24, v35, v37
	v_cvt_pk_bf16_f32 v25, v59, v61
	ds_read2_b32 v[28:29], v3 offset0:49 offset1:57
	ds_read2_b32 v[30:31], v3 offset0:16 offset1:24
	ds_read2_b32 v[32:33], v3 offset0:82 offset1:90
	ds_read2_b32 v[34:35], v3 offset0:115 offset1:123
	ds_read2_b32 v[36:37], v3 offset0:148 offset1:156
	ds_read2_b32 v[58:59], v3 offset0:181 offset1:189
	ds_read2_b32 v[60:61], v3 offset0:214 offset1:222
	ds_read2_b32 v[64:65], v3 offset0:247 offset1:255
	v_lshl_add_u64 v[26:27], v[62:63], 0, v[4:5]
	v_lshlrev_b32_e32 v4, 1, v10
	global_store_dwordx4 v[26:27], v[22:25], off
	v_lshl_add_u64 v[26:27], v[62:63], 0, v[4:5]
	v_lshlrev_b32_e32 v4, 1, v12
	s_waitcnt lgkmcnt(6)
	v_cvt_pk_bf16_f32 v22, v30, v28
	s_waitcnt lgkmcnt(4)
	v_cvt_pk_bf16_f32 v23, v32, v34
	s_waitcnt lgkmcnt(2)
	v_cvt_pk_bf16_f32 v24, v36, v58
	s_waitcnt lgkmcnt(0)
	v_cvt_pk_bf16_f32 v25, v60, v64
	global_store_dwordx4 v[26:27], v[22:25], off
	v_lshl_add_u64 v[26:27], v[62:63], 0, v[4:5]
	s_nop 0
	v_cvt_pk_bf16_f32 v22, v31, v29
	v_cvt_pk_bf16_f32 v23, v33, v35
	v_cvt_pk_bf16_f32 v24, v37, v59
	v_cvt_pk_bf16_f32 v25, v61, v65
	global_store_dwordx4 v[26:27], v[22:25], off
	s_waitcnt lgkmcnt(0)

; #define LAS __attribute__((address_space(3)))
; __device__ __forceinline__ unsigned cvtpk(float lo, float hi) { f32x2_t v = {lo, hi}; bf16x2_t b = __builtin_convertvector(v, bf16x2_t); return __builtin_bit_cast(unsigned, b); }
; #define NTL(p) __builtin_nontemporal_load(&(p))
; __device__ __forceinline__ void tr_item(const float* W, int N, int K, int k0, int n0, bf16_t* dst, LAS float* scr, int lane) {
; #pragma unroll 8
;     for (int i = 0; i < 32; ++i) { const int kk = 2 * i + (lane >> 5); scr[kk * 33 + (lane & 31)] = NTL(W[(size_t)(k0 + kk) * N + n0 + (lane & 31)]); }
;     asm volatile("s_waitcnt lgkmcnt(0)" ::: "memory");
;     const int c = lane & 7;
; #pragma unroll
;     for (int j = 0; j < 4; ++j) { const int n = (lane >> 3) + 8 * j; const LAS float* s = scr + (8 * c) * 33 + n;
;         u32x4 o; o.x = cvtpk(s[0 * 33], s[1 * 33]); o.y = cvtpk(s[2 * 33], s[3 * 33]); o.z = cvtpk(s[4 * 33], s[5 * 33]); o.w = cvtpk(s[6 * 33], s[7 * 33]);
;         *(u32x4*)(dst + (size_t)n * K + k0 + 8 * c) = o; }
;     asm volatile("s_waitcnt lgkmcnt(0)" ::: "memory");
.LBB0_43:
	v_lshl_add_u64 v[58:59], v[36:37], 0, s[16:17]
	v_lshl_add_u64 v[60:61], v[34:35], 0, s[16:17]
	v_lshl_add_u64 v[62:63], v[32:33], 0, s[16:17]
	v_lshl_add_u64 v[64:65], v[30:31], 0, s[16:17]
	v_lshl_add_u64 v[66:67], v[28:29], 0, s[16:17]
	v_lshl_add_u64 v[68:69], v[26:27], 0, s[16:17]
	v_lshl_add_u64 v[70:71], v[24:25], 0, s[16:17]
	v_lshl_add_u64 v[72:73], v[22:23], 0, s[16:17]
	global_load_dword v112, v[58:59], off nt
	global_load_dword v113, v[60:61], off nt
	global_load_dword v114, v[62:63], off nt
	global_load_dword v115, v[64:65], off nt
	global_load_dword v116, v[66:67], off nt
	global_load_dword v117, v[68:69], off nt
	global_load_dword v118, v[70:71], off nt
	global_load_dword v119, v[72:73], off nt
	s_add_u32 s16, s16, 0x60000
	s_addc_u32 s17, s17, 0
	v_lshl_add_u64 v[58:59], v[36:37], 0, s[16:17]
	v_lshl_add_u64 v[60:61], v[34:35], 0, s[16:17]
	v_lshl_add_u64 v[62:63], v[32:33], 0, s[16:17]
	v_lshl_add_u64 v[64:65], v[30:31], 0, s[16:17]
	v_lshl_add_u64 v[66:67], v[28:29], 0, s[16:17]
	v_lshl_add_u64 v[68:69], v[26:27], 0, s[16:17]
	v_lshl_add_u64 v[70:71], v[24:25], 0, s[16:17]
	v_lshl_add_u64 v[72:73], v[22:23], 0, s[16:17]
	global_load_dword v120, v[58:59], off nt
	global_load_dword v121, v[60:61], off nt
	global_load_dword v122, v[62:63], off nt
	global_load_dword v123, v[64:65], off nt
	global_load_dword v124, v[66:67], off nt
	global_load_dword v125, v[68:69], off nt
	global_load_dword v126, v[70:71], off nt
	global_load_dword v127, v[72:73], off nt
	s_add_u32 s16, s16, 0x60000
	s_addc_u32 s17, s17, 0
	v_lshl_add_u64 v[58:59], v[36:37], 0, s[16:17]
	v_lshl_add_u64 v[60:61], v[34:35], 0, s[16:17]
	v_lshl_add_u64 v[62:63], v[32:33], 0, s[16:17]
	v_lshl_add_u64 v[64:65], v[30:31], 0, s[16:17]
	v_lshl_add_u64 v[66:67], v[28:29], 0, s[16:17]
	v_lshl_add_u64 v[68:69], v[26:27], 0, s[16:17]
	v_lshl_add_u64 v[70:71], v[24:25], 0, s[16:17]
	v_lshl_add_u64 v[72:73], v[22:23], 0, s[16:17]
	global_load_dword v128, v[58:59], off nt
	global_load_dword v129, v[60:61], off nt
	global_load_dword v130, v[62:63], off nt
	global_load_dword v131, v[64:65], off nt
	global_load_dword v132, v[66:67], off nt
	global_load_dword v133, v[68:69], off nt
	global_load_dword v134, v[70:71], off nt
	global_load_dword v135, v[72:73], off nt
	s_add_u32 s16, s16, 0x60000
	s_addc_u32 s17, s17, 0
	v_lshl_add_u64 v[58:59], v[36:37], 0, s[16:17]
	v_lshl_add_u64 v[60:61], v[34:35], 0, s[16:17]
	v_lshl_add_u64 v[62:63], v[32:33], 0, s[16:17]
	v_lshl_add_u64 v[64:65], v[30:31], 0, s[16:17]
	v_lshl_add_u64 v[66:67], v[28:29], 0, s[16:17]
	v_lshl_add_u64 v[68:69], v[26:27], 0, s[16:17]
	v_lshl_add_u64 v[70:71], v[24:25], 0, s[16:17]
	v_lshl_add_u64 v[72:73], v[22:23], 0, s[16:17]
	global_load_dword v136, v[58:59], off nt
	global_load_dword v137, v[60:61], off nt
	global_load_dword v138, v[62:63], off nt
	global_load_dword v139, v[64:65], off nt
	global_load_dword v140, v[66:67], off nt
	global_load_dword v141, v[68:69], off nt
	global_load_dword v142, v[70:71], off nt
	global_load_dword v143, v[72:73], off nt
	s_add_u32 s16, s16, 0x60000
	s_addc_u32 s17, s17, 0
	v_add_u32_e32 v66, 0x400, v4
	s_waitcnt vmcnt(30)
	ds_write2_b32 v4, v112, v113 offset1:66
	s_waitcnt vmcnt(28)
	ds_write2_b32 v4, v114, v115 offset0:132 offset1:198
	s_waitcnt vmcnt(26)
	ds_write2_b32 v66, v116, v117 offset0:8 offset1:74
	s_waitcnt vmcnt(24)
	ds_write2_b32 v66, v118, v119 offset0:140 offset1:206
	v_add_u32_e32 v4, 0x840, v4
	v_add_u32_e32 v66, 0x400, v4
	s_waitcnt vmcnt(22)
	ds_write2_b32 v4, v120, v121 offset1:66
	s_waitcnt vmcnt(20)
	ds_write2_b32 v4, v122, v123 offset0:132 offset1:198
	s_waitcnt vmcnt(18)
	ds_write2_b32 v66, v124, v125 offset0:8 offset1:74
	s_waitcnt vmcnt(16)
	ds_write2_b32 v66, v126, v127 offset0:140 offset1:206
	v_add_u32_e32 v4, 0x840, v4
	v_add_u32_e32 v66, 0x400, v4
	s_waitcnt vmcnt(14)
	ds_write2_b32 v4, v128, v129 offset1:66
	s_waitcnt vmcnt(12)
	ds_write2_b32 v4, v130, v131 offset0:132 offset1:198
	s_waitcnt vmcnt(10)
	ds_write2_b32 v66, v132, v133 offset0:8 offset1:74
	s_waitcnt vmcnt(8)
	ds_write2_b32 v66, v134, v135 offset0:140 offset1:206
	v_add_u32_e32 v4, 0x840, v4
	v_add_u32_e32 v66, 0x400, v4
	s_waitcnt vmcnt(6)
	ds_write2_b32 v4, v136, v137 offset1:66
	s_waitcnt vmcnt(4)
	ds_write2_b32 v4, v138, v139 offset0:132 offset1:198
	s_waitcnt vmcnt(2)
	ds_write2_b32 v66, v140, v141 offset0:8 offset1:74
	s_waitcnt vmcnt(0)
	ds_write2_b32 v66, v142, v143 offset0:140 offset1:206
	v_add_u32_e32 v4, 0x840, v4
	s_lshl_b64 s[12:13], s[12:13], 12
	s_add_u32 s4, s14, s12
	s_waitcnt lgkmcnt(0)
	s_addc_u32 s14, s15, s13
	s_ashr_i32 s19, s18, 31
	ds_read2_b32 v[26:27], v3 offset0:33 offset1:41
	ds_read2_b32 v[28:29], v3 offset1:8
	ds_read2_b32 v[30:31], v3 offset0:66 offset1:74
	ds_read2_b32 v[32:33], v3 offset0:99 offset1:107
	ds_read2_b32 v[34:35], v3 offset0:132 offset1:140
	ds_read2_b32 v[36:37], v3 offset0:165 offset1:173
	ds_read2_b32 v[58:59], v3 offset0:198 offset1:206
	ds_read2_b32 v[60:61], v3 offset0:231 offset1:239
	s_lshl_b64 s[12:13], s[18:19], 1
	s_add_u32 s12, s4, s12
	s_addc_u32 s13, s14, s13
	v_lshlrev_b32_e32 v4, 1, v2
	v_lshl_add_u64 v[62:63], s[12:13], 0, v[4:5]
	v_lshlrev_b32_e32 v4, 1, v6
	s_waitcnt lgkmcnt(6)
	v_cvt_pk_bf16_f32 v22, v28, v26
	s_waitcnt lgkmcnt(4)
	v_cvt_pk_bf16_f32 v23, v30, v32
	s_waitcnt lgkmcnt(2)
	v_cvt_pk_bf16_f32 v24, v34, v36
	s_waitcnt lgkmcnt(0)
	v_cvt_pk_bf16_f32 v25, v58, v60
	v_lshl_add_u64 v[64:65], v[62:63], 0, v[4:5]
	global_store_dwordx4 v[64:65], v[22:25], off
	v_lshlrev_b32_e32 v4, 1, v8
	s_nop 0
	v_cvt_pk_bf16_f32 v22, v29, v27
	v_cvt_pk_bf16_f32 v23, v31, v33
	v_cvt_pk_bf16_f32 v24, v35, v37
	v_cvt_pk_bf16_f32 v25, v59, v61
	ds_read2_b32 v[28:29], v3 offset0:49 offset1:57
	ds_read2_b32 v[30:31], v3 offset0:16 offset1:24
	ds_read2_b32 v[32:33], v3 offset0:82 offset1:90
	ds_read2_b32 v[34:35], v3 offset0:115 offset1:123
	ds_read2_b32 v[36:37], v3 offset0:148 offset1:156
	ds_read2_b32 v[58:59], v3 offset0:181 offset1:189
	ds_read2_b32 v[60:61], v3 offset0:214 offset1:222
	ds_read2_b32 v[64:65], v3 offset0:247 offset1:255
	v_lshl_add_u64 v[26:27], v[62:63], 0, v[4:5]
	v_lshlrev_b32_e32 v4, 1, v10
	global_store_dwordx4 v[26:27], v[22:25], off
	v_lshl_add_u64 v[26:27], v[62:63], 0, v[4:5]
	v_lshlrev_b32_e32 v4, 1, v12
	s_waitcnt lgkmcnt(6)
	v_cvt_pk_bf16_f32 v22, v30, v28
	s_waitcnt lgkmcnt(4)
	v_cvt_pk_bf16_f32 v23, v32, v34
	s_waitcnt lgkmcnt(2)
	v_cvt_pk_bf16_f32 v24, v36, v58
	s_waitcnt lgkmcnt(0)
	v_cvt_pk_bf16_f32 v25, v60, v64
	global_store_dwordx4 v[26:27], v[22:25], off
	v_lshl_add_u64 v[26:27], v[62:63], 0, v[4:5]
	s_nop 0
	v_cvt_pk_bf16_f32 v22, v31, v29
	v_cvt_pk_bf16_f32 v23, v33, v35
	v_cvt_pk_bf16_f32 v24, v37, v59
	v_cvt_pk_bf16_f32 v25, v61, v65
	global_store_dwordx4 v[26:27], v[22:25], off
	s_waitcnt lgkmcnt(0)
	s_branch .LBB0_12
; __device__ __forceinline__ unsigned cvtpk(float lo, float hi) { f32x2_t v = {lo, hi}; bf16x2_t b = __builtin_convertvector(v, bf16x2_t); return __builtin_bit_cast(unsigned, b); }
; #define NTL(p) __builtin_nontemporal_load(&(p))
; template <int PART>
; __device__ __forceinline__ void prologue(const Params& p, LAS unsigned char* lds, int G, int blk) {
;     ...
;     { bf16_t* Wmq = (bf16_t*)(ws + WS_WMQ); const int gt = blk * 512 + tid, NGT = G * 512;
;       for (int i = gt; i < 2048 * 2048 / 4; i += NGT) { const f32x4 v = NTL(((const f32x4*)p.w_mq)[i]); u32x2 w; w.x = cvtpk(v.x, v.y); w.y = cvtpk(v.z, v.w); ((u32x2*)Wmq)[i] = w; } }
.LBB0_45:
	v_lshl_add_u32 v2, s2, 9, v162
	s_mov_b32 s3, 0x100000
	v_cmp_gt_i32_e32 vcc, s3, v2
	s_and_saveexec_b64 s[4:5], vcc
	s_cbranch_execz .LBB0_48
	s_lshl_b32 s12, s30, 9
	v_ashrrev_i32_e32 v3, 31, v2
	s_waitcnt lgkmcnt(0)
	v_mov_b32_e32 v4, s62
	v_mov_b32_e32 v5, s63
	s_ashr_i32 s13, s12, 31
	v_lshl_add_u64 v[6:7], v[2:3], 3, s[28:29]
	s_mov_b64 s[16:17], 0x2200000
	v_lshl_add_u64 v[4:5], v[2:3], 4, v[4:5]
	s_lshl_b64 s[14:15], s[12:13], 4
	v_lshl_add_u64 v[6:7], v[6:7], 0, s[16:17]
	s_lshl_b64 s[16:17], s[12:13], 3
	s_mov_b64 s[18:19], 0
	s_mov_b32 s3, 0xfffff
	s_cmp_eq_u32 s30, 0x100
	s_cbranch_scc0 .LBB0_47
	global_load_dwordx4 v[112:115], v[4:5], off nt
	v_lshl_add_u64 v[4:5], v[4:5], 0, s[14:15]
	global_load_dwordx4 v[116:119], v[4:5], off nt
	v_lshl_add_u64 v[4:5], v[4:5], 0, s[14:15]
	global_load_dwordx4 v[120:123], v[4:5], off nt
	v_lshl_add_u64 v[4:5], v[4:5], 0, s[14:15]
	global_load_dwordx4 v[124:127], v[4:5], off nt
	v_lshl_add_u64 v[4:5], v[4:5], 0, s[14:15]
	global_load_dwordx4 v[128:131], v[4:5], off nt
	v_lshl_add_u64 v[4:5], v[4:5], 0, s[14:15]
	global_load_dwordx4 v[132:135], v[4:5], off nt
	v_lshl_add_u64 v[4:5], v[4:5], 0, s[14:15]
	global_load_dwordx4 v[136:139], v[4:5], off nt
	v_lshl_add_u64 v[4:5], v[4:5], 0, s[14:15]
	global_load_dwordx4 v[140:143], v[4:5], off nt
	s_waitcnt vmcnt(7)
	v_cvt_pk_bf16_f32 v144, v112, v113
	v_cvt_pk_bf16_f32 v145, v114, v115
	global_store_dwordx2 v[6:7], v[144:145], off
	v_lshl_add_u64 v[6:7], v[6:7], 0, s[16:17]
	s_waitcnt vmcnt(6)
	v_cvt_pk_bf16_f32 v146, v116, v117
	v_cvt_pk_bf16_f32 v147, v118, v119
	global_store_dwordx2 v[6:7], v[146:147], off
	v_lshl_add_u64 v[6:7], v[6:7], 0, s[16:17]
	s_waitcnt vmcnt(5)
	v_cvt_pk_bf16_f32 v148, v120, v121
	v_cvt_pk_bf16_f32 v149, v122, v123
	global_store_dwordx2 v[6:7], v[148:149], off
	v_lshl_add_u64 v[6:7], v[6:7], 0, s[16:17]
	s_waitcnt vmcnt(4)
	v_cvt_pk_bf16_f32 v150, v124, v125
	v_cvt_pk_bf16_f32 v151, v126, v127
	global_store_dwordx2 v[6:7], v[150:151], off
	v_lshl_add_u64 v[6:7], v[6:7], 0, s[16:17]
	s_waitcnt vmcnt(3)
	v_cvt_pk_bf16_f32 v152, v128, v129
	v_cvt_pk_bf16_f32 v153, v130, v131
	global_store_dwordx2 v[6:7], v[152:153], off
	v_lshl_add_u64 v[6:7], v[6:7], 0, s[16:17]
	s_waitcnt vmcnt(2)
	v_cvt_pk_bf16_f32 v154, v132, v133
	v_cvt_pk_bf16_f32 v155, v134, v135
	global_store_dwordx2 v[6:7], v[154:155], off
	v_lshl_add_u64 v[6:7], v[6:7], 0, s[16:17]
	s_waitcnt vmcnt(1)
	v_cvt_pk_bf16_f32 v156, v136, v137
	v_cvt_pk_bf16_f32 v157, v138, v139
	global_store_dwordx2 v[6:7], v[156:157], off
	v_lshl_add_u64 v[6:7], v[6:7], 0, s[16:17]
	s_waitcnt vmcnt(0)
	v_cvt_pk_bf16_f32 v158, v140, v141
	v_cvt_pk_bf16_f32 v159, v142, v143
	global_store_dwordx2 v[6:7], v[158:159], off
	s_mov_b64 s[18:19], -1
	s_branch .LBB0_48

; #define PG8_STAGE(bufoff, gbase, voff) do { _Pragma("unroll") for (int _i = 0; _i < 2; ++_i) \
;         __builtin_amdgcn_global_load_lds((const unsigned*)((const char*)(gbase) + (voff)[_i]), (LAS unsigned*)(lds + (bufoff) + ldsw + _i * 8192), 16, 0, 0); } while (0)
; #define PG8_LDA(dst, b, h) do { _Pragma("unroll") for (int m = 0; m < 4; ++m) _Pragma("unroll") for (int k = 0; k < 2; ++k) dst[m][k] = *(const LAS bf16x8*)(lds + PG8_SA(b, h) + aoff + m * 2048 + k * 1024); } while (0)
; #define PG8_LDB(dst, b, h) do { _Pragma("unroll") for (int n = 0; n < 2; ++n) _Pragma("unroll") for (int k = 0; k < 2; ++k) dst[n][k] = *(const LAS bf16x8*)(lds + PG8_SB(b, h) + boff + n * 2048 + k * 1024); } while (0)
; #define PG8_MMA(ai, bj, At, Bt) do { __builtin_amdgcn_s_setprio(1); _Pragma("unroll") for (int m = 0; m < 4; ++m) _Pragma("unroll") for (int n = 0; n < 2; ++n) _Pragma("unroll") for (int k = 0; k < 2; ++k) \
;         acc[ai][bj][m][n] = __builtin_amdgcn_mfma_f32_16x16x32_bf16(Bt[n][k], At[m][k], acc[ai][bj][m][n], 0, 0, 0); __builtin_amdgcn_s_setprio(0); } while (0)
; #define PG8_WAIT_V(n) asm volatile("s_waitcnt vmcnt(" #n ")" ::: "memory")
; #define PG8_WAIT_L(n) asm volatile("s_waitcnt lgkmcnt(" #n ")" ::: "memory")
; #define PG8_BAR __builtin_amdgcn_s_barrier()
; #define PG8_SCHED __builtin_amdgcn_sched_barrier(0)
; template <int GI>
; __device__ __forceinline__ void gemm_phase(LAS unsigned char* lds, unsigned char* ws, int G, int cblk) {
;     ...
;         for (int t = 0; t < nt; t += 2) {
;             const bool last = (t == nt - 2);
;             const char* a1 = cA + (size_t)(t + 1) * kstep;
;             const char* a2 = last ? nA : cA + (size_t)(t + 2) * kstep; const char* b2 = last ? nB : cB + (size_t)(t + 2) * kstep;
;             const char* a3 = a2 + kstep; const char* b3 = b2 + kstep;
;             PG8_LDB(B0, 0, 0); PG8_LDB(B1, 0, 1); PG8_SCHED; PG8_LDA(At, 0, 0); PG8_STAGE(PG8_SA(1, 1), a1 + hstepA, voffA);
;             PG8_WAIT_V(8); PG8_WAIT_L(0); PG8_BAR; PG8_MMA(0, 0, At, B0); PG8_MMA(0, 1, At, B1); PG8_BAR; PG8_SCHED;
;             PG8_LDA(At, 0, 1); PG8_STAGE(PG8_SB(0, 0), b2, voffB); PG8_STAGE(PG8_SB(0, 1), b2 + hstepB, voffB); PG8_STAGE(PG8_SA(0, 0), a2, voffA);
;             PG8_WAIT_V(8); PG8_WAIT_L(0); PG8_BAR; PG8_MMA(1, 0, At, B0); PG8_MMA(1, 1, At, B1); PG8_BAR; PG8_SCHED;
.LBB0_97:
	s_add_u32 s4, s94, 0x80080
	s_addc_u32 s5, s95, 0
	s_add_u32 s15, s92, 0x100
	s_addc_u32 s58, s93, 0
	s_mov_b32 s94, -2
	ds_read_b128 v[164:167], v154
	ds_read_b128 v[168:171], v154 offset:1024
	ds_read_b128 v[172:175], v154 offset:2048
	ds_read_b128 v[176:179], v154 offset:3072
	ds_read_b128 v[180:183], v155
	ds_read_b128 v[184:187], v155 offset:1024
	ds_read_b128 v[192:195], v155 offset:2048
	ds_read_b128 v[196:199], v155 offset:3072
	s_add_u32 s6, s4, 0xfff80080
	s_addc_u32 s7, s5, -1
	s_cmp_eq_u32 s94, 28
	s_cselect_b32 s93, s81, s7
	s_cselect_b32 s92, s80, s6
	s_cselect_b32 s7, s85, s58
	s_cselect_b32 s6, s84, s15
	v_lshl_add_u64 v[158:159], s[4:5], 0, v[148:149]
	s_add_i32 m0, s19, 0xc000
	ds_read_b128 v[200:203], v156
	ds_read_b128 v[204:207], v156 offset:1024
	ds_read_b128 v[208:211], v156 offset:2048
	ds_read_b128 v[212:215], v156 offset:3072
	ds_read_b128 v[216:219], v156 offset:4096
	ds_read_b128 v[220:223], v156 offset:5120
	ds_read_b128 v[224:227], v156 offset:6144
	ds_read_b128 v[228:231], v156 offset:7168
	global_load_lds_dwordx4 v[158:159], off
	v_lshl_add_u64 v[158:159], s[4:5], 0, v[150:151]
	s_add_i32 m0, s19, 0xe000
	s_nop 0
	global_load_lds_dwordx4 v[158:159], off
	s_waitcnt vmcnt(8)
	s_waitcnt lgkmcnt(0)
	s_barrier
	s_setprio 1
	s_waitcnt lgkmcnt(0)
	v_mfma_f32_16x16x32_bf16 v[124:127], v[164:167], v[200:203], 0
	v_mfma_f32_16x16x32_bf16 v[120:123], v[172:175], v[200:203], 0
	v_mfma_f32_16x16x32_bf16 v[112:115], v[164:167], v[208:211], 0
	v_mfma_f32_16x16x32_bf16 v[104:107], v[172:175], v[208:211], 0
	v_mfma_f32_16x16x32_bf16 v[96:99], v[164:167], v[216:219], 0
	v_mfma_f32_16x16x32_bf16 v[88:91], v[172:175], v[216:219], 0
	v_mfma_f32_16x16x32_bf16 v[80:83], v[164:167], v[224:227], 0
	v_mfma_f32_16x16x32_bf16 v[72:75], v[172:175], v[224:227], 0
	v_mfma_f32_16x16x32_bf16 v[124:127], v[168:171], v[204:207], v[124:127]
	v_mfma_f32_16x16x32_bf16 v[120:123], v[176:179], v[204:207], v[120:123]
	v_mfma_f32_16x16x32_bf16 v[112:115], v[168:171], v[212:215], v[112:115]
	v_mfma_f32_16x16x32_bf16 v[104:107], v[176:179], v[212:215], v[104:107]
	v_mfma_f32_16x16x32_bf16 v[96:99], v[168:171], v[220:223], v[96:99]
	v_mfma_f32_16x16x32_bf16 v[88:91], v[176:179], v[220:223], v[88:91]
	v_mfma_f32_16x16x32_bf16 v[80:83], v[168:171], v[228:231], v[80:83]
	v_mfma_f32_16x16x32_bf16 v[72:75], v[176:179], v[228:231], v[72:75]
	s_setprio 0
	s_setprio 1
	v_mfma_f32_16x16x32_bf16 v[116:119], v[180:183], v[200:203], 0
	v_mfma_f32_16x16x32_bf16 v[108:111], v[192:195], v[200:203], 0
	v_mfma_f32_16x16x32_bf16 v[100:103], v[180:183], v[208:211], 0
	v_mfma_f32_16x16x32_bf16 v[92:95], v[192:195], v[208:211], 0
	v_mfma_f32_16x16x32_bf16 v[84:87], v[180:183], v[216:219], 0
	v_mfma_f32_16x16x32_bf16 v[76:79], v[192:195], v[216:219], 0
	v_mfma_f32_16x16x32_bf16 v[68:71], v[180:183], v[224:227], 0
	v_mfma_f32_16x16x32_bf16 v[64:67], v[192:195], v[224:227], 0
	v_mfma_f32_16x16x32_bf16 v[116:119], v[184:187], v[204:207], v[116:119]
	v_mfma_f32_16x16x32_bf16 v[108:111], v[196:199], v[204:207], v[108:111]
	v_mfma_f32_16x16x32_bf16 v[100:103], v[184:187], v[212:215], v[100:103]
	v_mfma_f32_16x16x32_bf16 v[92:95], v[196:199], v[212:215], v[92:95]
	v_mfma_f32_16x16x32_bf16 v[84:87], v[184:187], v[220:223], v[84:87]
	v_mfma_f32_16x16x32_bf16 v[76:79], v[196:199], v[220:223], v[76:79]
	v_mfma_f32_16x16x32_bf16 v[68:71], v[184:187], v[228:231], v[68:71]
	v_mfma_f32_16x16x32_bf16 v[64:67], v[196:199], v[228:231], v[64:67]
	s_setprio 0
	s_barrier
	s_add_i32 s34, s27, s18
	v_lshl_add_u64 v[158:159], s[6:7], 0, v[130:131]
	s_mov_b32 m0, s34
	ds_read_b128 v[200:203], v156 offset:16384
	ds_read_b128 v[204:207], v156 offset:17408
	ds_read_b128 v[208:211], v156 offset:18432
	ds_read_b128 v[212:215], v156 offset:19456
	ds_read_b128 v[216:219], v156 offset:20480
	ds_read_b128 v[220:223], v156 offset:21504
	ds_read_b128 v[224:227], v156 offset:22528
	ds_read_b128 v[228:231], v156 offset:23552
	global_load_lds_dwordx4 v[158:159], off
	s_add_i32 m0, s34, 0x2000
	s_add_u32 s96, s6, 0x80000
	v_lshl_add_u64 v[188:189], s[6:7], 0, v[134:135]
	s_addc_u32 s97, s7, 0
	s_add_i32 s34, s24, s18
	global_load_lds_dwordx4 v[188:189], off
	v_lshl_add_u64 v[232:233], s[96:97], 0, v[130:131]
	s_mov_b32 m0, s34
	v_lshl_add_u64 v[234:235], s[92:93], 0, v[132:133]
	global_load_lds_dwordx4 v[232:233], off
	v_lshl_add_u64 v[232:233], s[96:97], 0, v[134:135]
	s_add_i32 m0, s34, 0x2000
	s_nop 0
	global_load_lds_dwordx4 v[232:233], off
	v_lshl_add_u64 v[232:233], s[92:93], 0, v[128:129]
	s_mov_b32 m0, s19
	s_nop 0
	global_load_lds_dwordx4 v[232:233], off
	s_mov_b32 m0, s20
	s_nop 0
	global_load_lds_dwordx4 v[234:235], off
	s_waitcnt vmcnt(8)
	s_waitcnt lgkmcnt(0)
	s_barrier
; #define PG8_STAGE(bufoff, gbase, voff) do { _Pragma("unroll") for (int _i = 0; _i < 2; ++_i) \
;         __builtin_amdgcn_global_load_lds((const unsigned*)((const char*)(gbase) + (voff)[_i]), (LAS unsigned*)(lds + (bufoff) + ldsw + _i * 8192), 16, 0, 0); } while (0)
; #define PG8_LDA(dst, b, h) do { _Pragma("unroll") for (int m = 0; m < 4; ++m) _Pragma("unroll") for (int k = 0; k < 2; ++k) dst[m][k] = *(const LAS bf16x8*)(lds + PG8_SA(b, h) + aoff + m * 2048 + k * 1024); } while (0)
; #define PG8_LDB(dst, b, h) do { _Pragma("unroll") for (int n = 0; n < 2; ++n) _Pragma("unroll") for (int k = 0; k < 2; ++k) dst[n][k] = *(const LAS bf16x8*)(lds + PG8_SB(b, h) + boff + n * 2048 + k * 1024); } while (0)
; #define PG8_MMA(ai, bj, At, Bt) do { __builtin_amdgcn_s_setprio(1); _Pragma("unroll") for (int m = 0; m < 4; ++m) _Pragma("unroll") for (int n = 0; n < 2; ++n) _Pragma("unroll") for (int k = 0; k < 2; ++k) \
;         acc[ai][bj][m][n] = __builtin_amdgcn_mfma_f32_16x16x32_bf16(Bt[n][k], At[m][k], acc[ai][bj][m][n], 0, 0, 0); __builtin_amdgcn_s_setprio(0); } while (0)
; #define PG8_WAIT_V(n) asm volatile("s_waitcnt vmcnt(" #n ")" ::: "memory")
; #define PG8_WAIT_L(n) asm volatile("s_waitcnt lgkmcnt(" #n ")" ::: "memory")
; #define PG8_BAR __builtin_amdgcn_s_barrier()
; #define PG8_SCHED __builtin_amdgcn_sched_barrier(0)
; template <int GI>
; __device__ __forceinline__ void gemm_phase(LAS unsigned char* lds, unsigned char* ws, int G, int cblk) {
;     ...
;             PG8_WAIT_V(8); PG8_WAIT_L(0); PG8_BAR; PG8_MMA(1, 0, At, B0); PG8_MMA(1, 1, At, B1); PG8_BAR; PG8_SCHED;
;             PG8_LDB(B0, 1, 0); PG8_LDB(B1, 1, 1); PG8_SCHED; PG8_LDA(At, 1, 0); PG8_STAGE(PG8_SA(0, 1), a2 + hstepA, voffA);
;             PG8_WAIT_V(8); PG8_WAIT_L(0); PG8_BAR; PG8_MMA(0, 0, At, B0); PG8_MMA(0, 1, At, B1); PG8_BAR; PG8_SCHED;
	s_setprio 1
	s_waitcnt lgkmcnt(0)
	v_mfma_f32_16x16x32_bf16 v[60:63], v[164:167], v[200:203], 0
	v_mfma_f32_16x16x32_bf16 v[56:59], v[172:175], v[200:203], 0
	v_mfma_f32_16x16x32_bf16 v[52:55], v[164:167], v[208:211], 0
	v_mfma_f32_16x16x32_bf16 v[44:47], v[172:175], v[208:211], 0
	v_mfma_f32_16x16x32_bf16 v[36:39], v[164:167], v[216:219], 0
	v_mfma_f32_16x16x32_bf16 v[28:31], v[172:175], v[216:219], 0
	v_mfma_f32_16x16x32_bf16 v[20:23], v[164:167], v[224:227], 0
	v_mfma_f32_16x16x32_bf16 v[12:15], v[172:175], v[224:227], 0
	v_mfma_f32_16x16x32_bf16 v[60:63], v[168:171], v[204:207], v[60:63]
	v_mfma_f32_16x16x32_bf16 v[56:59], v[176:179], v[204:207], v[56:59]
	v_mfma_f32_16x16x32_bf16 v[52:55], v[168:171], v[212:215], v[52:55]
	v_mfma_f32_16x16x32_bf16 v[44:47], v[176:179], v[212:215], v[44:47]
	v_mfma_f32_16x16x32_bf16 v[36:39], v[168:171], v[220:223], v[36:39]
	v_mfma_f32_16x16x32_bf16 v[28:31], v[176:179], v[220:223], v[28:31]
	v_mfma_f32_16x16x32_bf16 v[20:23], v[168:171], v[228:231], v[20:23]
	v_mfma_f32_16x16x32_bf16 v[12:15], v[176:179], v[228:231], v[12:15]
	s_setprio 0
	s_setprio 1
	v_mfma_f32_16x16x32_bf16 v[48:51], v[180:183], v[200:203], 0
	v_mfma_f32_16x16x32_bf16 v[40:43], v[192:195], v[200:203], 0
	v_mfma_f32_16x16x32_bf16 v[32:35], v[180:183], v[208:211], 0
	v_mfma_f32_16x16x32_bf16 v[24:27], v[192:195], v[208:211], 0
	v_mfma_f32_16x16x32_bf16 v[16:19], v[180:183], v[216:219], 0
	v_mfma_f32_16x16x32_bf16 v[8:11], v[192:195], v[216:219], 0
	v_mfma_f32_16x16x32_bf16 v[4:7], v[180:183], v[224:227], 0
	v_mfma_f32_16x16x32_bf16 v[0:3], v[192:195], v[224:227], 0
	v_mfma_f32_16x16x32_bf16 v[48:51], v[184:187], v[204:207], v[48:51]
	v_mfma_f32_16x16x32_bf16 v[40:43], v[196:199], v[204:207], v[40:43]
	v_mfma_f32_16x16x32_bf16 v[32:35], v[184:187], v[212:215], v[32:35]
	v_mfma_f32_16x16x32_bf16 v[24:27], v[196:199], v[212:215], v[24:27]
	v_mfma_f32_16x16x32_bf16 v[16:19], v[184:187], v[220:223], v[16:19]
	v_mfma_f32_16x16x32_bf16 v[8:11], v[196:199], v[220:223], v[8:11]
	v_mfma_f32_16x16x32_bf16 v[4:7], v[184:187], v[228:231], v[4:7]
	v_mfma_f32_16x16x32_bf16 v[0:3], v[196:199], v[228:231], v[0:3]
	s_setprio 0
	s_barrier
	s_add_i32 s34, 0, 0x18000
	v_add_u32_e32 v161, s34, v153
	s_add_i32 s95, 0, 0x1c000
	ds_read_b128 v[164:167], v161
	ds_read_b128 v[168:171], v161 offset:1024
	ds_read_b128 v[172:175], v161 offset:2048
	ds_read_b128 v[176:179], v161 offset:3072
	v_add_u32_e32 v161, s95, v153
	ds_read_b128 v[180:183], v161
	ds_read_b128 v[184:187], v161 offset:1024
	ds_read_b128 v[192:195], v161 offset:2048
	ds_read_b128 v[196:199], v161 offset:3072
	s_add_u32 s92, s92, 0x80000
	s_addc_u32 s93, s93, 0
	s_mov_b32 m0, s21
	v_lshl_add_u64 v[236:237], s[92:93], 0, v[128:129]
	ds_read_b128 v[200:203], v156 offset:32768
	ds_read_b128 v[204:207], v156 offset:33792
	ds_read_b128 v[208:211], v156 offset:34816
	ds_read_b128 v[212:215], v156 offset:35840
	ds_read_b128 v[216:219], v156 offset:36864
	ds_read_b128 v[220:223], v156 offset:37888
	ds_read_b128 v[224:227], v156 offset:38912
	ds_read_b128 v[228:231], v156 offset:39936
	global_load_lds_dwordx4 v[236:237], off
	v_lshl_add_u64 v[236:237], s[92:93], 0, v[132:133]
	s_mov_b32 m0, s35
	s_nop 0
	global_load_lds_dwordx4 v[236:237], off
	s_waitcnt vmcnt(8)
	s_waitcnt lgkmcnt(0)
	s_barrier
	s_setprio 1
	s_waitcnt lgkmcnt(0)
	v_mfma_f32_16x16x32_bf16 v[124:127], v[164:167], v[200:203], v[124:127]
	v_mfma_f32_16x16x32_bf16 v[120:123], v[172:175], v[200:203], v[120:123]
	v_mfma_f32_16x16x32_bf16 v[112:115], v[164:167], v[208:211], v[112:115]
	v_mfma_f32_16x16x32_bf16 v[104:107], v[172:175], v[208:211], v[104:107]
	v_mfma_f32_16x16x32_bf16 v[96:99], v[164:167], v[216:219], v[96:99]
	v_mfma_f32_16x16x32_bf16 v[88:91], v[172:175], v[216:219], v[88:91]
	v_mfma_f32_16x16x32_bf16 v[80:83], v[164:167], v[224:227], v[80:83]
	v_mfma_f32_16x16x32_bf16 v[72:75], v[172:175], v[224:227], v[72:75]
	v_mfma_f32_16x16x32_bf16 v[124:127], v[168:171], v[204:207], v[124:127]
	v_mfma_f32_16x16x32_bf16 v[120:123], v[176:179], v[204:207], v[120:123]
	v_mfma_f32_16x16x32_bf16 v[112:115], v[168:171], v[212:215], v[112:115]
	v_mfma_f32_16x16x32_bf16 v[104:107], v[176:179], v[212:215], v[104:107]
	v_mfma_f32_16x16x32_bf16 v[96:99], v[168:171], v[220:223], v[96:99]
	v_mfma_f32_16x16x32_bf16 v[88:91], v[176:179], v[220:223], v[88:91]
	v_mfma_f32_16x16x32_bf16 v[80:83], v[168:171], v[228:231], v[80:83]
	v_mfma_f32_16x16x32_bf16 v[72:75], v[176:179], v[228:231], v[72:75]
	s_setprio 0
	s_setprio 1
	v_mfma_f32_16x16x32_bf16 v[116:119], v[180:183], v[200:203], v[116:119]
	v_mfma_f32_16x16x32_bf16 v[108:111], v[192:195], v[200:203], v[108:111]
	v_mfma_f32_16x16x32_bf16 v[100:103], v[180:183], v[208:211], v[100:103]
	v_mfma_f32_16x16x32_bf16 v[92:95], v[192:195], v[208:211], v[92:95]
	v_mfma_f32_16x16x32_bf16 v[84:87], v[180:183], v[216:219], v[84:87]
	v_mfma_f32_16x16x32_bf16 v[76:79], v[192:195], v[216:219], v[76:79]
	v_mfma_f32_16x16x32_bf16 v[68:71], v[180:183], v[224:227], v[68:71]
	v_mfma_f32_16x16x32_bf16 v[64:67], v[192:195], v[224:227], v[64:67]
	v_mfma_f32_16x16x32_bf16 v[116:119], v[184:187], v[204:207], v[116:119]
	v_mfma_f32_16x16x32_bf16 v[108:111], v[196:199], v[204:207], v[108:111]
	v_mfma_f32_16x16x32_bf16 v[100:103], v[184:187], v[212:215], v[100:103]
	v_mfma_f32_16x16x32_bf16 v[92:95], v[196:199], v[212:215], v[92:95]
	v_mfma_f32_16x16x32_bf16 v[84:87], v[184:187], v[220:223], v[84:87]
	v_mfma_f32_16x16x32_bf16 v[76:79], v[196:199], v[220:223], v[76:79]
	v_mfma_f32_16x16x32_bf16 v[68:71], v[184:187], v[228:231], v[68:71]
	v_mfma_f32_16x16x32_bf16 v[64:67], v[196:199], v[228:231], v[64:67]
	s_setprio 0
	s_barrier
; #define PG8_STAGE(bufoff, gbase, voff) do { _Pragma("unroll") for (int _i = 0; _i < 2; ++_i) \
;         __builtin_amdgcn_global_load_lds((const unsigned*)((const char*)(gbase) + (voff)[_i]), (LAS unsigned*)(lds + (bufoff) + ldsw + _i * 8192), 16, 0, 0); } while (0)
; #define PG8_LDA(dst, b, h) do { _Pragma("unroll") for (int m = 0; m < 4; ++m) _Pragma("unroll") for (int k = 0; k < 2; ++k) dst[m][k] = *(const LAS bf16x8*)(lds + PG8_SA(b, h) + aoff + m * 2048 + k * 1024); } while (0)
; #define PG8_MMA(ai, bj, At, Bt) do { __builtin_amdgcn_s_setprio(1); _Pragma("unroll") for (int m = 0; m < 4; ++m) _Pragma("unroll") for (int n = 0; n < 2; ++n) _Pragma("unroll") for (int k = 0; k < 2; ++k) \
;         acc[ai][bj][m][n] = __builtin_amdgcn_mfma_f32_16x16x32_bf16(Bt[n][k], At[m][k], acc[ai][bj][m][n], 0, 0, 0); __builtin_amdgcn_s_setprio(0); } while (0)
; #define PG8_WAIT_V(n) asm volatile("s_waitcnt vmcnt(" #n ")" ::: "memory")
; #define PG8_WAIT_L(n) asm volatile("s_waitcnt lgkmcnt(" #n ")" ::: "memory")
; #define PG8_BAR __builtin_amdgcn_s_barrier()
; #define PG8_SCHED __builtin_amdgcn_sched_barrier(0)
; template <int GI>
; __device__ __forceinline__ void gemm_phase(LAS unsigned char* lds, unsigned char* ws, int G, int cblk) {
;     ...
;         for (int t = 0; t < nt; t += 2) {
;     ...
;             PG8_LDA(At, 1, 1); PG8_STAGE(PG8_SB(1, 0), b3, voffB); PG8_STAGE(PG8_SB(1, 1), b3 + hstepB, voffB); PG8_STAGE(PG8_SA(1, 0), a3, voffA);
;             PG8_WAIT_V(8); PG8_WAIT_L(0); PG8_BAR; PG8_MMA(1, 0, At, B0); PG8_MMA(1, 1, At, B1); PG8_BAR; PG8_SCHED;
	s_add_i32 s34, s34, s18
	v_lshl_add_u64 v[158:159], v[158:159], 0, s[70:71]
	s_mov_b32 m0, s34
	ds_read_b128 v[200:203], v156 offset:49152
	ds_read_b128 v[204:207], v156 offset:50176
	ds_read_b128 v[208:211], v156 offset:51200
	ds_read_b128 v[212:215], v156 offset:52224
	ds_read_b128 v[216:219], v156 offset:53248
	ds_read_b128 v[220:223], v156 offset:54272
	ds_read_b128 v[224:227], v156 offset:55296
	ds_read_b128 v[228:231], v156 offset:56320
	global_load_lds_dwordx4 v[158:159], off
	s_add_i32 m0, s34, 0x2000
	s_add_u32 s6, s6, 0x80080
	v_lshl_add_u64 v[158:159], v[188:189], 0, s[70:71]
	s_addc_u32 s7, s7, 0
	s_add_i32 s34, s95, s18
	global_load_lds_dwordx4 v[158:159], off
	v_lshl_add_u64 v[158:159], s[6:7], 0, v[130:131]
	s_mov_b32 m0, s34
	s_nop 0
	global_load_lds_dwordx4 v[158:159], off
	v_lshl_add_u64 v[158:159], s[6:7], 0, v[134:135]
	s_add_i32 m0, s34, 0x2000
	s_nop 0
	global_load_lds_dwordx4 v[158:159], off
	v_lshl_add_u64 v[158:159], v[232:233], 0, s[70:71]
	s_mov_b32 m0, s0
	s_nop 0
	global_load_lds_dwordx4 v[158:159], off
	v_lshl_add_u64 v[158:159], v[234:235], 0, s[70:71]
	s_mov_b32 m0, s1
	s_nop 0
	global_load_lds_dwordx4 v[158:159], off
	s_waitcnt vmcnt(8)
	s_waitcnt lgkmcnt(0)
	s_barrier
	s_setprio 1
	s_waitcnt lgkmcnt(0)
	v_mfma_f32_16x16x32_bf16 v[60:63], v[164:167], v[200:203], v[60:63]
	v_mfma_f32_16x16x32_bf16 v[56:59], v[172:175], v[200:203], v[56:59]
	v_mfma_f32_16x16x32_bf16 v[52:55], v[164:167], v[208:211], v[52:55]
	v_mfma_f32_16x16x32_bf16 v[44:47], v[172:175], v[208:211], v[44:47]
	v_mfma_f32_16x16x32_bf16 v[36:39], v[164:167], v[216:219], v[36:39]
	v_mfma_f32_16x16x32_bf16 v[28:31], v[172:175], v[216:219], v[28:31]
	v_mfma_f32_16x16x32_bf16 v[20:23], v[164:167], v[224:227], v[20:23]
	v_mfma_f32_16x16x32_bf16 v[12:15], v[172:175], v[224:227], v[12:15]
	v_mfma_f32_16x16x32_bf16 v[60:63], v[168:171], v[204:207], v[60:63]
	v_mfma_f32_16x16x32_bf16 v[56:59], v[176:179], v[204:207], v[56:59]
	v_mfma_f32_16x16x32_bf16 v[52:55], v[168:171], v[212:215], v[52:55]
	v_mfma_f32_16x16x32_bf16 v[44:47], v[176:179], v[212:215], v[44:47]
	v_mfma_f32_16x16x32_bf16 v[36:39], v[168:171], v[220:223], v[36:39]
	v_mfma_f32_16x16x32_bf16 v[28:31], v[176:179], v[220:223], v[28:31]
	v_mfma_f32_16x16x32_bf16 v[20:23], v[168:171], v[228:231], v[20:23]
	v_mfma_f32_16x16x32_bf16 v[12:15], v[176:179], v[228:231], v[12:15]
	s_setprio 0
	s_setprio 1
	v_mfma_f32_16x16x32_bf16 v[48:51], v[180:183], v[200:203], v[48:51]
	v_mfma_f32_16x16x32_bf16 v[40:43], v[192:195], v[200:203], v[40:43]
	v_mfma_f32_16x16x32_bf16 v[32:35], v[180:183], v[208:211], v[32:35]
	v_mfma_f32_16x16x32_bf16 v[24:27], v[192:195], v[208:211], v[24:27]
	v_mfma_f32_16x16x32_bf16 v[16:19], v[180:183], v[216:219], v[16:19]
	v_mfma_f32_16x16x32_bf16 v[8:11], v[192:195], v[216:219], v[8:11]
	v_mfma_f32_16x16x32_bf16 v[4:7], v[180:183], v[224:227], v[4:7]
	v_mfma_f32_16x16x32_bf16 v[0:3], v[192:195], v[224:227], v[0:3]
	v_mfma_f32_16x16x32_bf16 v[48:51], v[184:187], v[204:207], v[48:51]
	v_mfma_f32_16x16x32_bf16 v[40:43], v[196:199], v[204:207], v[40:43]
	v_mfma_f32_16x16x32_bf16 v[32:35], v[184:187], v[212:215], v[32:35]
	v_mfma_f32_16x16x32_bf16 v[24:27], v[196:199], v[212:215], v[24:27]
	v_mfma_f32_16x16x32_bf16 v[16:19], v[184:187], v[220:223], v[16:19]
	v_mfma_f32_16x16x32_bf16 v[8:11], v[196:199], v[220:223], v[8:11]
	v_mfma_f32_16x16x32_bf16 v[4:7], v[184:187], v[228:231], v[4:7]
	v_mfma_f32_16x16x32_bf16 v[0:3], v[196:199], v[228:231], v[0:3]
	s_setprio 0
	s_barrier
	s_add_i32 s94, s94, 2
	s_add_u32 s4, s4, 0x100
	s_addc_u32 s5, s5, 0
	s_add_u32 s15, s15, 0x100
	s_addc_u32 s58, s58, 0
	s_cmp_gt_u32 s94, 29
	s_cbranch_scc0 .LBB0_98
	s_branch .Lpeel_exit_0

; #define PG8_BAR __builtin_amdgcn_s_barrier()
; template <int GI>
; __device__ __forceinline__ void gemm_phase(LAS unsigned char* lds, unsigned char* ws, int G, int cblk) {
;     ...
;         if (wr == 0) PG8_BAR;
.Lpeel_exit_0:
	s_and_b64 vcc, exec, s[72:73]
	s_cbranch_vccz .LBB0_101
	s_barrier

; #define PG8_STAGE(bufoff, gbase, voff) do { _Pragma("unroll") for (int _i = 0; _i < 2; ++_i) \
;         __builtin_amdgcn_global_load_lds((const unsigned*)((const char*)(gbase) + (voff)[_i]), (LAS unsigned*)(lds + (bufoff) + ldsw + _i * 8192), 16, 0, 0); } while (0)
; #define PG8_LDA(dst, b, h) do { _Pragma("unroll") for (int m = 0; m < 4; ++m) _Pragma("unroll") for (int k = 0; k < 2; ++k) dst[m][k] = *(const LAS bf16x8*)(lds + PG8_SA(b, h) + aoff + m * 2048 + k * 1024); } while (0)
; #define PG8_LDB(dst, b, h) do { _Pragma("unroll") for (int n = 0; n < 2; ++n) _Pragma("unroll") for (int k = 0; k < 2; ++k) dst[n][k] = *(const LAS bf16x8*)(lds + PG8_SB(b, h) + boff + n * 2048 + k * 1024); } while (0)
; #define PG8_MMA(ai, bj, At, Bt) do { __builtin_amdgcn_s_setprio(1); _Pragma("unroll") for (int m = 0; m < 4; ++m) _Pragma("unroll") for (int n = 0; n < 2; ++n) _Pragma("unroll") for (int k = 0; k < 2; ++k) \
;         acc[ai][bj][m][n] = __builtin_amdgcn_mfma_f32_16x16x32_bf16(Bt[n][k], At[m][k], acc[ai][bj][m][n], 0, 0, 0); __builtin_amdgcn_s_setprio(0); } while (0)
; #define PG8_WAIT_V(n) asm volatile("s_waitcnt vmcnt(" #n ")" ::: "memory")
; #define PG8_WAIT_L(n) asm volatile("s_waitcnt lgkmcnt(" #n ")" ::: "memory")
; #define PG8_BAR __builtin_amdgcn_s_barrier()
; #define PG8_SCHED __builtin_amdgcn_sched_barrier(0)
; template <int GI>
; __device__ __forceinline__ void gemm_phase(LAS unsigned char* lds, unsigned char* ws, int G, int cblk) {
;     ...
;         for (int t = 0; t < nt; t += 2) {
;             const bool last = (t == nt - 2);
;             const char* a1 = cA + (size_t)(t + 1) * kstep;
;             const char* a2 = last ? nA : cA + (size_t)(t + 2) * kstep; const char* b2 = last ? nB : cB + (size_t)(t + 2) * kstep;
;             const char* a3 = a2 + kstep; const char* b3 = b2 + kstep;
;             PG8_LDB(B0, 0, 0); PG8_LDB(B1, 0, 1); PG8_SCHED; PG8_LDA(At, 0, 0); PG8_STAGE(PG8_SA(1, 1), a1 + hstepA, voffA);
;             PG8_WAIT_V(8); PG8_WAIT_L(0); PG8_BAR; PG8_MMA(0, 0, At, B0); PG8_MMA(0, 1, At, B1); PG8_BAR; PG8_SCHED;
;             PG8_LDA(At, 0, 1); PG8_STAGE(PG8_SB(0, 0), b2, voffB); PG8_STAGE(PG8_SB(0, 1), b2 + hstepB, voffB); PG8_STAGE(PG8_SA(0, 0), a2, voffA);
;             PG8_WAIT_V(8); PG8_WAIT_L(0); PG8_BAR; PG8_MMA(1, 0, At, B0); PG8_MMA(1, 1, At, B1); PG8_BAR; PG8_SCHED;
.LBB0_123:
	s_add_u32 s86, s86, 0x80080
	s_addc_u32 s87, s87, 0
	s_add_u32 s4, s88, 0x100
	s_addc_u32 s14, s89, 0
	s_mov_b32 s15, -2
	ds_read_b128 v[154:157], v151
	ds_read_b128 v[164:167], v151 offset:1024
	ds_read_b128 v[168:171], v151 offset:2048
	ds_read_b128 v[172:175], v151 offset:3072
	ds_read_b128 v[176:179], v152
	ds_read_b128 v[180:183], v152 offset:1024
	ds_read_b128 v[184:187], v152 offset:2048
	ds_read_b128 v[192:195], v152 offset:3072
	s_add_u32 s34, s86, 0xfff80080
	s_addc_u32 s63, s87, -1
	s_cmp_eq_u32 s15, 28
	s_cselect_b32 s91, s75, s63
	s_cselect_b32 s90, s74, s34
	s_cselect_b32 s89, s77, s14
	s_cselect_b32 s88, s76, s4
	v_lshl_add_u64 v[158:159], s[86:87], 0, v[146:147]
	s_add_i32 m0, s16, 0xc000
	ds_read_b128 v[196:199], v153
	ds_read_b128 v[200:203], v153 offset:1024
	ds_read_b128 v[204:207], v153 offset:2048
	ds_read_b128 v[208:211], v153 offset:3072
	ds_read_b128 v[212:215], v153 offset:4096
	ds_read_b128 v[216:219], v153 offset:5120
	ds_read_b128 v[220:223], v153 offset:6144
	ds_read_b128 v[224:227], v153 offset:7168
	global_load_lds_dwordx4 v[158:159], off
	v_lshl_add_u64 v[158:159], s[86:87], 0, v[148:149]
	s_add_i32 m0, s16, 0xe000
	s_nop 0
	global_load_lds_dwordx4 v[158:159], off
	s_waitcnt vmcnt(8)
	s_waitcnt lgkmcnt(0)
	s_barrier
	s_setprio 1
	s_waitcnt lgkmcnt(0)
	v_mfma_f32_16x16x32_bf16 v[124:127], v[154:157], v[196:199], 0
	v_mfma_f32_16x16x32_bf16 v[120:123], v[168:171], v[196:199], 0
	v_mfma_f32_16x16x32_bf16 v[116:119], v[154:157], v[204:207], 0
	v_mfma_f32_16x16x32_bf16 v[108:111], v[168:171], v[204:207], 0
	v_mfma_f32_16x16x32_bf16 v[100:103], v[154:157], v[212:215], 0
	v_mfma_f32_16x16x32_bf16 v[92:95], v[168:171], v[212:215], 0
	v_mfma_f32_16x16x32_bf16 v[84:87], v[154:157], v[220:223], 0
	v_mfma_f32_16x16x32_bf16 v[76:79], v[168:171], v[220:223], 0
	v_mfma_f32_16x16x32_bf16 v[124:127], v[164:167], v[200:203], v[124:127]
	v_mfma_f32_16x16x32_bf16 v[120:123], v[172:175], v[200:203], v[120:123]
	v_mfma_f32_16x16x32_bf16 v[116:119], v[164:167], v[208:211], v[116:119]
	v_mfma_f32_16x16x32_bf16 v[108:111], v[172:175], v[208:211], v[108:111]
	v_mfma_f32_16x16x32_bf16 v[100:103], v[164:167], v[216:219], v[100:103]
	v_mfma_f32_16x16x32_bf16 v[92:95], v[172:175], v[216:219], v[92:95]
	v_mfma_f32_16x16x32_bf16 v[84:87], v[164:167], v[224:227], v[84:87]
	v_mfma_f32_16x16x32_bf16 v[76:79], v[172:175], v[224:227], v[76:79]
	s_setprio 0
	s_setprio 1
	v_mfma_f32_16x16x32_bf16 v[112:115], v[176:179], v[196:199], 0
	v_mfma_f32_16x16x32_bf16 v[104:107], v[184:187], v[196:199], 0
	v_mfma_f32_16x16x32_bf16 v[96:99], v[176:179], v[204:207], 0
	v_mfma_f32_16x16x32_bf16 v[88:91], v[184:187], v[204:207], 0
	v_mfma_f32_16x16x32_bf16 v[80:83], v[176:179], v[212:215], 0
	v_mfma_f32_16x16x32_bf16 v[72:75], v[184:187], v[212:215], 0
	v_mfma_f32_16x16x32_bf16 v[68:71], v[176:179], v[220:223], 0
	v_mfma_f32_16x16x32_bf16 v[64:67], v[184:187], v[220:223], 0
	v_mfma_f32_16x16x32_bf16 v[112:115], v[180:183], v[200:203], v[112:115]
	v_mfma_f32_16x16x32_bf16 v[104:107], v[192:195], v[200:203], v[104:107]
	v_mfma_f32_16x16x32_bf16 v[96:99], v[180:183], v[208:211], v[96:99]
	v_mfma_f32_16x16x32_bf16 v[88:91], v[192:195], v[208:211], v[88:91]
	v_mfma_f32_16x16x32_bf16 v[80:83], v[180:183], v[216:219], v[80:83]
	v_mfma_f32_16x16x32_bf16 v[72:75], v[192:195], v[216:219], v[72:75]
	v_mfma_f32_16x16x32_bf16 v[68:71], v[180:183], v[224:227], v[68:71]
	v_mfma_f32_16x16x32_bf16 v[64:67], v[192:195], v[224:227], v[64:67]
	s_setprio 0
	s_barrier
	s_add_i32 s34, s25, s0
	v_lshl_add_u64 v[158:159], s[88:89], 0, v[130:131]
	s_mov_b32 m0, s34
	ds_read_b128 v[196:199], v153 offset:16384
	ds_read_b128 v[200:203], v153 offset:17408
	ds_read_b128 v[204:207], v153 offset:18432
	ds_read_b128 v[208:211], v153 offset:19456
	ds_read_b128 v[212:215], v153 offset:20480
	ds_read_b128 v[216:219], v153 offset:21504
	ds_read_b128 v[220:223], v153 offset:22528
	ds_read_b128 v[224:227], v153 offset:23552
	global_load_lds_dwordx4 v[158:159], off
	s_add_i32 m0, s34, 0x2000
	s_add_u32 s92, s88, 0x80000
	v_lshl_add_u64 v[188:189], s[88:89], 0, v[134:135]
	s_addc_u32 s93, s89, 0
	s_add_i32 s34, s26, s0
	global_load_lds_dwordx4 v[188:189], off
	v_lshl_add_u64 v[228:229], s[92:93], 0, v[130:131]
	s_mov_b32 m0, s34
	v_lshl_add_u64 v[230:231], s[90:91], 0, v[132:133]
	global_load_lds_dwordx4 v[228:229], off
	v_lshl_add_u64 v[228:229], s[92:93], 0, v[134:135]
	s_add_i32 m0, s34, 0x2000
	s_nop 0
	global_load_lds_dwordx4 v[228:229], off
	v_lshl_add_u64 v[228:229], s[90:91], 0, v[128:129]
	s_mov_b32 m0, s16
	s_nop 0
	global_load_lds_dwordx4 v[228:229], off
	s_mov_b32 m0, s17
	s_nop 0
	global_load_lds_dwordx4 v[230:231], off
	s_waitcnt vmcnt(8)
	s_waitcnt lgkmcnt(0)
	s_barrier
; #define PG8_STAGE(bufoff, gbase, voff) do { _Pragma("unroll") for (int _i = 0; _i < 2; ++_i) \
;         __builtin_amdgcn_global_load_lds((const unsigned*)((const char*)(gbase) + (voff)[_i]), (LAS unsigned*)(lds + (bufoff) + ldsw + _i * 8192), 16, 0, 0); } while (0)
; #define PG8_LDA(dst, b, h) do { _Pragma("unroll") for (int m = 0; m < 4; ++m) _Pragma("unroll") for (int k = 0; k < 2; ++k) dst[m][k] = *(const LAS bf16x8*)(lds + PG8_SA(b, h) + aoff + m * 2048 + k * 1024); } while (0)
; #define PG8_LDB(dst, b, h) do { _Pragma("unroll") for (int n = 0; n < 2; ++n) _Pragma("unroll") for (int k = 0; k < 2; ++k) dst[n][k] = *(const LAS bf16x8*)(lds + PG8_SB(b, h) + boff + n * 2048 + k * 1024); } while (0)
; #define PG8_MMA(ai, bj, At, Bt) do { __builtin_amdgcn_s_setprio(1); _Pragma("unroll") for (int m = 0; m < 4; ++m) _Pragma("unroll") for (int n = 0; n < 2; ++n) _Pragma("unroll") for (int k = 0; k < 2; ++k) \
;         acc[ai][bj][m][n] = __builtin_amdgcn_mfma_f32_16x16x32_bf16(Bt[n][k], At[m][k], acc[ai][bj][m][n], 0, 0, 0); __builtin_amdgcn_s_setprio(0); } while (0)
; #define PG8_WAIT_V(n) asm volatile("s_waitcnt vmcnt(" #n ")" ::: "memory")
; #define PG8_WAIT_L(n) asm volatile("s_waitcnt lgkmcnt(" #n ")" ::: "memory")
; #define PG8_BAR __builtin_amdgcn_s_barrier()
; #define PG8_SCHED __builtin_amdgcn_sched_barrier(0)
; template <int GI>
; __device__ __forceinline__ void gemm_phase(LAS unsigned char* lds, unsigned char* ws, int G, int cblk) {
;     ...
;             PG8_WAIT_V(8); PG8_WAIT_L(0); PG8_BAR; PG8_MMA(1, 0, At, B0); PG8_MMA(1, 1, At, B1); PG8_BAR; PG8_SCHED;
;             PG8_LDB(B0, 1, 0); PG8_LDB(B1, 1, 1); PG8_SCHED; PG8_LDA(At, 1, 0); PG8_STAGE(PG8_SA(0, 1), a2 + hstepA, voffA);
;             PG8_WAIT_V(8); PG8_WAIT_L(0); PG8_BAR; PG8_MMA(0, 0, At, B0); PG8_MMA(0, 1, At, B1); PG8_BAR; PG8_SCHED;
	s_setprio 1
	s_waitcnt lgkmcnt(0)
	v_mfma_f32_16x16x32_bf16 v[60:63], v[154:157], v[196:199], 0
	v_mfma_f32_16x16x32_bf16 v[56:59], v[168:171], v[196:199], 0
	v_mfma_f32_16x16x32_bf16 v[52:55], v[154:157], v[204:207], 0
	v_mfma_f32_16x16x32_bf16 v[48:51], v[168:171], v[204:207], 0
	v_mfma_f32_16x16x32_bf16 v[36:39], v[154:157], v[212:215], 0
	v_mfma_f32_16x16x32_bf16 v[32:35], v[168:171], v[212:215], 0
	v_mfma_f32_16x16x32_bf16 v[20:23], v[154:157], v[220:223], 0
	v_mfma_f32_16x16x32_bf16 v[16:19], v[168:171], v[220:223], 0
	v_mfma_f32_16x16x32_bf16 v[60:63], v[164:167], v[200:203], v[60:63]
	v_mfma_f32_16x16x32_bf16 v[56:59], v[172:175], v[200:203], v[56:59]
	v_mfma_f32_16x16x32_bf16 v[52:55], v[164:167], v[208:211], v[52:55]
	v_mfma_f32_16x16x32_bf16 v[48:51], v[172:175], v[208:211], v[48:51]
	v_mfma_f32_16x16x32_bf16 v[36:39], v[164:167], v[216:219], v[36:39]
	v_mfma_f32_16x16x32_bf16 v[32:35], v[172:175], v[216:219], v[32:35]
	v_mfma_f32_16x16x32_bf16 v[20:23], v[164:167], v[224:227], v[20:23]
	v_mfma_f32_16x16x32_bf16 v[16:19], v[172:175], v[224:227], v[16:19]
	s_setprio 0
	s_setprio 1
	v_mfma_f32_16x16x32_bf16 v[44:47], v[176:179], v[196:199], 0
	v_mfma_f32_16x16x32_bf16 v[40:43], v[184:187], v[196:199], 0
	v_mfma_f32_16x16x32_bf16 v[28:31], v[176:179], v[204:207], 0
	v_mfma_f32_16x16x32_bf16 v[24:27], v[184:187], v[204:207], 0
	v_mfma_f32_16x16x32_bf16 v[12:15], v[176:179], v[212:215], 0
	v_mfma_f32_16x16x32_bf16 v[8:11], v[184:187], v[212:215], 0
	v_mfma_f32_16x16x32_bf16 v[4:7], v[176:179], v[220:223], 0
	v_mfma_f32_16x16x32_bf16 v[0:3], v[184:187], v[220:223], 0
	v_mfma_f32_16x16x32_bf16 v[44:47], v[180:183], v[200:203], v[44:47]
	v_mfma_f32_16x16x32_bf16 v[40:43], v[192:195], v[200:203], v[40:43]
	v_mfma_f32_16x16x32_bf16 v[28:31], v[180:183], v[208:211], v[28:31]
	v_mfma_f32_16x16x32_bf16 v[24:27], v[192:195], v[208:211], v[24:27]
	v_mfma_f32_16x16x32_bf16 v[12:15], v[180:183], v[216:219], v[12:15]
	v_mfma_f32_16x16x32_bf16 v[8:11], v[192:195], v[216:219], v[8:11]
	v_mfma_f32_16x16x32_bf16 v[4:7], v[180:183], v[224:227], v[4:7]
	v_mfma_f32_16x16x32_bf16 v[0:3], v[192:195], v[224:227], v[0:3]
	s_setprio 0
	s_barrier
	s_add_i32 s34, 0, 0x18000
	v_add_u32_e32 v161, s34, v150
	s_add_i32 s63, 0, 0x1c000
	ds_read_b128 v[154:157], v161
	ds_read_b128 v[164:167], v161 offset:1024
	ds_read_b128 v[168:171], v161 offset:2048
	ds_read_b128 v[172:175], v161 offset:3072
	v_add_u32_e32 v161, s63, v150
	ds_read_b128 v[176:179], v161
	ds_read_b128 v[180:183], v161 offset:1024
	ds_read_b128 v[184:187], v161 offset:2048
	ds_read_b128 v[192:195], v161 offset:3072
	s_add_u32 s90, s90, 0x80000
	s_addc_u32 s91, s91, 0
	s_mov_b32 m0, s18
	v_lshl_add_u64 v[232:233], s[90:91], 0, v[128:129]
	ds_read_b128 v[196:199], v153 offset:32768
	ds_read_b128 v[200:203], v153 offset:33792
	ds_read_b128 v[204:207], v153 offset:34816
	ds_read_b128 v[208:211], v153 offset:35840
	ds_read_b128 v[212:215], v153 offset:36864
	ds_read_b128 v[216:219], v153 offset:37888
	ds_read_b128 v[220:223], v153 offset:38912
	ds_read_b128 v[224:227], v153 offset:39936
	global_load_lds_dwordx4 v[232:233], off
	v_lshl_add_u64 v[232:233], s[90:91], 0, v[132:133]
	s_mov_b32 m0, s19
	s_nop 0
	global_load_lds_dwordx4 v[232:233], off
	s_waitcnt vmcnt(8)
	s_waitcnt lgkmcnt(0)
	s_barrier
	s_setprio 1
	s_waitcnt lgkmcnt(0)
	v_mfma_f32_16x16x32_bf16 v[124:127], v[154:157], v[196:199], v[124:127]
	v_mfma_f32_16x16x32_bf16 v[120:123], v[168:171], v[196:199], v[120:123]
	v_mfma_f32_16x16x32_bf16 v[116:119], v[154:157], v[204:207], v[116:119]
	v_mfma_f32_16x16x32_bf16 v[108:111], v[168:171], v[204:207], v[108:111]
	v_mfma_f32_16x16x32_bf16 v[100:103], v[154:157], v[212:215], v[100:103]
	v_mfma_f32_16x16x32_bf16 v[92:95], v[168:171], v[212:215], v[92:95]
	v_mfma_f32_16x16x32_bf16 v[84:87], v[154:157], v[220:223], v[84:87]
	v_mfma_f32_16x16x32_bf16 v[76:79], v[168:171], v[220:223], v[76:79]
	v_mfma_f32_16x16x32_bf16 v[124:127], v[164:167], v[200:203], v[124:127]
	v_mfma_f32_16x16x32_bf16 v[120:123], v[172:175], v[200:203], v[120:123]
	v_mfma_f32_16x16x32_bf16 v[116:119], v[164:167], v[208:211], v[116:119]
	v_mfma_f32_16x16x32_bf16 v[108:111], v[172:175], v[208:211], v[108:111]
	v_mfma_f32_16x16x32_bf16 v[100:103], v[164:167], v[216:219], v[100:103]
	v_mfma_f32_16x16x32_bf16 v[92:95], v[172:175], v[216:219], v[92:95]
	v_mfma_f32_16x16x32_bf16 v[84:87], v[164:167], v[224:227], v[84:87]
	v_mfma_f32_16x16x32_bf16 v[76:79], v[172:175], v[224:227], v[76:79]
	s_setprio 0
	s_setprio 1
	v_mfma_f32_16x16x32_bf16 v[112:115], v[176:179], v[196:199], v[112:115]
	v_mfma_f32_16x16x32_bf16 v[104:107], v[184:187], v[196:199], v[104:107]
	v_mfma_f32_16x16x32_bf16 v[96:99], v[176:179], v[204:207], v[96:99]
	v_mfma_f32_16x16x32_bf16 v[88:91], v[184:187], v[204:207], v[88:91]
	v_mfma_f32_16x16x32_bf16 v[80:83], v[176:179], v[212:215], v[80:83]
	v_mfma_f32_16x16x32_bf16 v[72:75], v[184:187], v[212:215], v[72:75]
	v_mfma_f32_16x16x32_bf16 v[68:71], v[176:179], v[220:223], v[68:71]
	v_mfma_f32_16x16x32_bf16 v[64:67], v[184:187], v[220:223], v[64:67]
	v_mfma_f32_16x16x32_bf16 v[112:115], v[180:183], v[200:203], v[112:115]
	v_mfma_f32_16x16x32_bf16 v[104:107], v[192:195], v[200:203], v[104:107]
	v_mfma_f32_16x16x32_bf16 v[96:99], v[180:183], v[208:211], v[96:99]
	v_mfma_f32_16x16x32_bf16 v[88:91], v[192:195], v[208:211], v[88:91]
	v_mfma_f32_16x16x32_bf16 v[80:83], v[180:183], v[216:219], v[80:83]
	v_mfma_f32_16x16x32_bf16 v[72:75], v[192:195], v[216:219], v[72:75]
	v_mfma_f32_16x16x32_bf16 v[68:71], v[180:183], v[224:227], v[68:71]
	v_mfma_f32_16x16x32_bf16 v[64:67], v[192:195], v[224:227], v[64:67]
	s_setprio 0
	s_barrier
; #define PG8_STAGE(bufoff, gbase, voff) do { _Pragma("unroll") for (int _i = 0; _i < 2; ++_i) \
;         __builtin_amdgcn_global_load_lds((const unsigned*)((const char*)(gbase) + (voff)[_i]), (LAS unsigned*)(lds + (bufoff) + ldsw + _i * 8192), 16, 0, 0); } while (0)
; #define PG8_LDA(dst, b, h) do { _Pragma("unroll") for (int m = 0; m < 4; ++m) _Pragma("unroll") for (int k = 0; k < 2; ++k) dst[m][k] = *(const LAS bf16x8*)(lds + PG8_SA(b, h) + aoff + m * 2048 + k * 1024); } while (0)
; #define PG8_MMA(ai, bj, At, Bt) do { __builtin_amdgcn_s_setprio(1); _Pragma("unroll") for (int m = 0; m < 4; ++m) _Pragma("unroll") for (int n = 0; n < 2; ++n) _Pragma("unroll") for (int k = 0; k < 2; ++k) \
;         acc[ai][bj][m][n] = __builtin_amdgcn_mfma_f32_16x16x32_bf16(Bt[n][k], At[m][k], acc[ai][bj][m][n], 0, 0, 0); __builtin_amdgcn_s_setprio(0); } while (0)
; #define PG8_WAIT_V(n) asm volatile("s_waitcnt vmcnt(" #n ")" ::: "memory")
; #define PG8_WAIT_L(n) asm volatile("s_waitcnt lgkmcnt(" #n ")" ::: "memory")
; #define PG8_BAR __builtin_amdgcn_s_barrier()
; #define PG8_SCHED __builtin_amdgcn_sched_barrier(0)
; template <int GI>
; __device__ __forceinline__ void gemm_phase(LAS unsigned char* lds, unsigned char* ws, int G, int cblk) {
;     ...
;         for (int t = 0; t < nt; t += 2) {
;     ...
;             PG8_LDA(At, 1, 1); PG8_STAGE(PG8_SB(1, 0), b3, voffB); PG8_STAGE(PG8_SB(1, 1), b3 + hstepB, voffB); PG8_STAGE(PG8_SA(1, 0), a3, voffA);
;             PG8_WAIT_V(8); PG8_WAIT_L(0); PG8_BAR; PG8_MMA(1, 0, At, B0); PG8_MMA(1, 1, At, B1); PG8_BAR; PG8_SCHED;
	s_add_i32 s34, s34, s0
	v_lshl_add_u64 v[158:159], v[158:159], 0, s[38:39]
	s_mov_b32 m0, s34
	ds_read_b128 v[196:199], v153 offset:49152
	ds_read_b128 v[200:203], v153 offset:50176
	ds_read_b128 v[204:207], v153 offset:51200
	ds_read_b128 v[208:211], v153 offset:52224
	ds_read_b128 v[212:215], v153 offset:53248
	ds_read_b128 v[216:219], v153 offset:54272
	ds_read_b128 v[220:223], v153 offset:55296
	ds_read_b128 v[224:227], v153 offset:56320
	global_load_lds_dwordx4 v[158:159], off
	s_add_i32 m0, s34, 0x2000
	s_add_u32 s88, s88, 0x80080
	v_lshl_add_u64 v[158:159], v[188:189], 0, s[38:39]
	s_addc_u32 s89, s89, 0
	s_add_i32 s34, s63, s0
	global_load_lds_dwordx4 v[158:159], off
	v_lshl_add_u64 v[158:159], s[88:89], 0, v[130:131]
	s_mov_b32 m0, s34
	s_nop 0
	global_load_lds_dwordx4 v[158:159], off
	v_lshl_add_u64 v[158:159], s[88:89], 0, v[134:135]
	s_add_i32 m0, s34, 0x2000
	s_nop 0
	global_load_lds_dwordx4 v[158:159], off
	v_lshl_add_u64 v[158:159], v[228:229], 0, s[38:39]
	s_mov_b32 m0, s22
	s_nop 0
	global_load_lds_dwordx4 v[158:159], off
	v_lshl_add_u64 v[158:159], v[230:231], 0, s[38:39]
	s_mov_b32 m0, s23
	s_nop 0
	global_load_lds_dwordx4 v[158:159], off
	s_waitcnt vmcnt(8)
	s_waitcnt lgkmcnt(0)
	s_barrier
	s_setprio 1
	s_waitcnt lgkmcnt(0)
	v_mfma_f32_16x16x32_bf16 v[60:63], v[154:157], v[196:199], v[60:63]
	v_mfma_f32_16x16x32_bf16 v[56:59], v[168:171], v[196:199], v[56:59]
	v_mfma_f32_16x16x32_bf16 v[52:55], v[154:157], v[204:207], v[52:55]
	v_mfma_f32_16x16x32_bf16 v[48:51], v[168:171], v[204:207], v[48:51]
	v_mfma_f32_16x16x32_bf16 v[36:39], v[154:157], v[212:215], v[36:39]
	v_mfma_f32_16x16x32_bf16 v[32:35], v[168:171], v[212:215], v[32:35]
	v_mfma_f32_16x16x32_bf16 v[20:23], v[154:157], v[220:223], v[20:23]
	v_mfma_f32_16x16x32_bf16 v[16:19], v[168:171], v[220:223], v[16:19]
	v_mfma_f32_16x16x32_bf16 v[60:63], v[164:167], v[200:203], v[60:63]
	v_mfma_f32_16x16x32_bf16 v[56:59], v[172:175], v[200:203], v[56:59]
	v_mfma_f32_16x16x32_bf16 v[52:55], v[164:167], v[208:211], v[52:55]
	v_mfma_f32_16x16x32_bf16 v[48:51], v[172:175], v[208:211], v[48:51]
	v_mfma_f32_16x16x32_bf16 v[36:39], v[164:167], v[216:219], v[36:39]
	v_mfma_f32_16x16x32_bf16 v[32:35], v[172:175], v[216:219], v[32:35]
	v_mfma_f32_16x16x32_bf16 v[20:23], v[164:167], v[224:227], v[20:23]
	v_mfma_f32_16x16x32_bf16 v[16:19], v[172:175], v[224:227], v[16:19]
	s_setprio 0
	s_setprio 1
	v_mfma_f32_16x16x32_bf16 v[44:47], v[176:179], v[196:199], v[44:47]
	v_mfma_f32_16x16x32_bf16 v[40:43], v[184:187], v[196:199], v[40:43]
	v_mfma_f32_16x16x32_bf16 v[28:31], v[176:179], v[204:207], v[28:31]
	v_mfma_f32_16x16x32_bf16 v[24:27], v[184:187], v[204:207], v[24:27]
	v_mfma_f32_16x16x32_bf16 v[12:15], v[176:179], v[212:215], v[12:15]
	v_mfma_f32_16x16x32_bf16 v[8:11], v[184:187], v[212:215], v[8:11]
	v_mfma_f32_16x16x32_bf16 v[4:7], v[176:179], v[220:223], v[4:7]
	v_mfma_f32_16x16x32_bf16 v[0:3], v[184:187], v[220:223], v[0:3]
	v_mfma_f32_16x16x32_bf16 v[44:47], v[180:183], v[200:203], v[44:47]
	v_mfma_f32_16x16x32_bf16 v[40:43], v[192:195], v[200:203], v[40:43]
	v_mfma_f32_16x16x32_bf16 v[28:31], v[180:183], v[208:211], v[28:31]
	v_mfma_f32_16x16x32_bf16 v[24:27], v[192:195], v[208:211], v[24:27]
	v_mfma_f32_16x16x32_bf16 v[12:15], v[180:183], v[216:219], v[12:15]
	v_mfma_f32_16x16x32_bf16 v[8:11], v[192:195], v[216:219], v[8:11]
	v_mfma_f32_16x16x32_bf16 v[4:7], v[180:183], v[224:227], v[4:7]
	v_mfma_f32_16x16x32_bf16 v[0:3], v[192:195], v[224:227], v[0:3]
	s_setprio 0
	s_barrier
	s_add_i32 s15, s15, 2
	s_add_u32 s86, s86, 0x100
	s_addc_u32 s87, s87, 0
	s_add_u32 s4, s4, 0x100
	s_addc_u32 s14, s14, 0
	s_cmp_gt_u32 s15, 29
	s_cbranch_scc0 .LBB0_124
	s_branch .Lpeel_exit_1

; #define PG8_BAR __builtin_amdgcn_s_barrier()
; template <int GI>
; __device__ __forceinline__ void gemm_phase(LAS unsigned char* lds, unsigned char* ws, int G, int cblk) {
;     ...
;         if (wr == 0) PG8_BAR;
.Lpeel_exit_1:
	s_and_b64 vcc, exec, s[58:59]
	s_cbranch_vccz .LBB0_127
	s_barrier

; #define PG8_STAGE(bufoff, gbase, voff) do { _Pragma("unroll") for (int _i = 0; _i < 2; ++_i) \
;         __builtin_amdgcn_global_load_lds((const unsigned*)((const char*)(gbase) + (voff)[_i]), (LAS unsigned*)(lds + (bufoff) + ldsw + _i * 8192), 16, 0, 0); } while (0)
; #define PG8_LDA(dst, b, h) do { _Pragma("unroll") for (int m = 0; m < 4; ++m) _Pragma("unroll") for (int k = 0; k < 2; ++k) dst[m][k] = *(const LAS bf16x8*)(lds + PG8_SA(b, h) + aoff + m * 2048 + k * 1024); } while (0)
; #define PG8_LDB(dst, b, h) do { _Pragma("unroll") for (int n = 0; n < 2; ++n) _Pragma("unroll") for (int k = 0; k < 2; ++k) dst[n][k] = *(const LAS bf16x8*)(lds + PG8_SB(b, h) + boff + n * 2048 + k * 1024); } while (0)
; #define PG8_MMA(ai, bj, At, Bt) do { __builtin_amdgcn_s_setprio(1); _Pragma("unroll") for (int m = 0; m < 4; ++m) _Pragma("unroll") for (int n = 0; n < 2; ++n) _Pragma("unroll") for (int k = 0; k < 2; ++k) \
;         acc[ai][bj][m][n] = __builtin_amdgcn_mfma_f32_16x16x32_bf16(Bt[n][k], At[m][k], acc[ai][bj][m][n], 0, 0, 0); __builtin_amdgcn_s_setprio(0); } while (0)
; #define PG8_WAIT_V(n) asm volatile("s_waitcnt vmcnt(" #n ")" ::: "memory")
; #define PG8_WAIT_L(n) asm volatile("s_waitcnt lgkmcnt(" #n ")" ::: "memory")
; #define PG8_BAR __builtin_amdgcn_s_barrier()
; #define PG8_SCHED __builtin_amdgcn_sched_barrier(0)
; template <int GI>
; __device__ __forceinline__ void gemm_phase(LAS unsigned char* lds, unsigned char* ws, int G, int cblk) {
;     ...
;         for (int t = 0; t < nt; t += 2) {
;             const bool last = (t == nt - 2);
;             const char* a1 = cA + (size_t)(t + 1) * kstep;
;             const char* a2 = last ? nA : cA + (size_t)(t + 2) * kstep; const char* b2 = last ? nB : cB + (size_t)(t + 2) * kstep;
;             const char* a3 = a2 + kstep; const char* b3 = b2 + kstep;
;             PG8_LDB(B0, 0, 0); PG8_LDB(B1, 0, 1); PG8_SCHED; PG8_LDA(At, 0, 0); PG8_STAGE(PG8_SA(1, 1), a1 + hstepA, voffA);
;             PG8_WAIT_V(8); PG8_WAIT_L(0); PG8_BAR; PG8_MMA(0, 0, At, B0); PG8_MMA(0, 1, At, B1); PG8_BAR; PG8_SCHED;
;             PG8_LDA(At, 0, 1); PG8_STAGE(PG8_SB(0, 0), b2, voffB); PG8_STAGE(PG8_SB(0, 1), b2 + hstepB, voffB); PG8_STAGE(PG8_SA(0, 0), a2, voffA);
;             PG8_WAIT_V(8); PG8_WAIT_L(0); PG8_BAR; PG8_MMA(1, 0, At, B0); PG8_MMA(1, 1, At, B1); PG8_BAR; PG8_SCHED;
.LBB0_147:
	s_add_u32 s78, s78, 0x80080
	s_addc_u32 s79, s79, 0
	s_add_u32 s14, s80, 0x100
	s_addc_u32 s15, s81, 0
	s_mov_b32 s27, -2
	ds_read_b128 v[154:157], v151
	ds_read_b128 v[164:167], v151 offset:1024
	ds_read_b128 v[168:171], v151 offset:2048
	ds_read_b128 v[172:175], v151 offset:3072
	ds_read_b128 v[176:179], v152
	ds_read_b128 v[180:183], v152 offset:1024
	ds_read_b128 v[184:187], v152 offset:2048
	ds_read_b128 v[192:195], v152 offset:3072
	s_add_u32 s33, s78, 0xfff80080
	s_addc_u32 s34, s79, -1
	s_cmp_eq_u32 s27, 28
	s_cselect_b32 s83, s73, s34
	s_cselect_b32 s82, s72, s33
	s_cselect_b32 s81, s75, s15
	s_cselect_b32 s80, s74, s14
	v_lshl_add_u64 v[158:159], s[78:79], 0, v[138:139]
	s_add_i32 m0, s16, 0xc000
	ds_read_b128 v[196:199], v153
	ds_read_b128 v[200:203], v153 offset:1024
	ds_read_b128 v[204:207], v153 offset:2048
	ds_read_b128 v[208:211], v153 offset:3072
	ds_read_b128 v[212:215], v153 offset:4096
	ds_read_b128 v[216:219], v153 offset:5120
	ds_read_b128 v[220:223], v153 offset:6144
	ds_read_b128 v[224:227], v153 offset:7168
	global_load_lds_dwordx4 v[158:159], off
	v_lshl_add_u64 v[158:159], s[78:79], 0, v[140:141]
	s_add_i32 m0, s16, 0xe000
	s_nop 0
	global_load_lds_dwordx4 v[158:159], off
	s_waitcnt vmcnt(8)
	s_waitcnt lgkmcnt(0)
	s_barrier
	s_setprio 1
	s_waitcnt lgkmcnt(0)
	v_mfma_f32_16x16x32_bf16 v[124:127], v[154:157], v[196:199], 0
	v_mfma_f32_16x16x32_bf16 v[120:123], v[168:171], v[196:199], 0
	v_mfma_f32_16x16x32_bf16 v[116:119], v[154:157], v[204:207], 0
	v_mfma_f32_16x16x32_bf16 v[112:115], v[168:171], v[204:207], 0
	v_mfma_f32_16x16x32_bf16 v[100:103], v[154:157], v[212:215], 0
	v_mfma_f32_16x16x32_bf16 v[96:99], v[168:171], v[212:215], 0
	v_mfma_f32_16x16x32_bf16 v[84:87], v[154:157], v[220:223], 0
	v_mfma_f32_16x16x32_bf16 v[80:83], v[168:171], v[220:223], 0
	v_mfma_f32_16x16x32_bf16 v[124:127], v[164:167], v[200:203], v[124:127]
	v_mfma_f32_16x16x32_bf16 v[120:123], v[172:175], v[200:203], v[120:123]
	v_mfma_f32_16x16x32_bf16 v[116:119], v[164:167], v[208:211], v[116:119]
	v_mfma_f32_16x16x32_bf16 v[112:115], v[172:175], v[208:211], v[112:115]
	v_mfma_f32_16x16x32_bf16 v[100:103], v[164:167], v[216:219], v[100:103]
	v_mfma_f32_16x16x32_bf16 v[96:99], v[172:175], v[216:219], v[96:99]
	v_mfma_f32_16x16x32_bf16 v[84:87], v[164:167], v[224:227], v[84:87]
	v_mfma_f32_16x16x32_bf16 v[80:83], v[172:175], v[224:227], v[80:83]
	s_setprio 0
	s_setprio 1
	v_mfma_f32_16x16x32_bf16 v[108:111], v[176:179], v[196:199], 0
	v_mfma_f32_16x16x32_bf16 v[104:107], v[184:187], v[196:199], 0
	v_mfma_f32_16x16x32_bf16 v[92:95], v[176:179], v[204:207], 0
	v_mfma_f32_16x16x32_bf16 v[88:91], v[184:187], v[204:207], 0
	v_mfma_f32_16x16x32_bf16 v[76:79], v[176:179], v[212:215], 0
	v_mfma_f32_16x16x32_bf16 v[72:75], v[184:187], v[212:215], 0
	v_mfma_f32_16x16x32_bf16 v[68:71], v[176:179], v[220:223], 0
	v_mfma_f32_16x16x32_bf16 v[64:67], v[184:187], v[220:223], 0
	v_mfma_f32_16x16x32_bf16 v[108:111], v[180:183], v[200:203], v[108:111]
	v_mfma_f32_16x16x32_bf16 v[104:107], v[192:195], v[200:203], v[104:107]
	v_mfma_f32_16x16x32_bf16 v[92:95], v[180:183], v[208:211], v[92:95]
	v_mfma_f32_16x16x32_bf16 v[88:91], v[192:195], v[208:211], v[88:91]
	v_mfma_f32_16x16x32_bf16 v[76:79], v[180:183], v[216:219], v[76:79]
	v_mfma_f32_16x16x32_bf16 v[72:75], v[192:195], v[216:219], v[72:75]
	v_mfma_f32_16x16x32_bf16 v[68:71], v[180:183], v[224:227], v[68:71]
	v_mfma_f32_16x16x32_bf16 v[64:67], v[192:195], v[224:227], v[64:67]
	s_setprio 0
	s_barrier
	s_add_i32 s33, s24, s0
	v_lshl_add_u64 v[158:159], s[80:81], 0, v[130:131]
	s_mov_b32 m0, s33
	ds_read_b128 v[196:199], v153 offset:16384
	ds_read_b128 v[200:203], v153 offset:17408
	ds_read_b128 v[204:207], v153 offset:18432
	ds_read_b128 v[208:211], v153 offset:19456
	ds_read_b128 v[212:215], v153 offset:20480
	ds_read_b128 v[216:219], v153 offset:21504
	ds_read_b128 v[220:223], v153 offset:22528
	ds_read_b128 v[224:227], v153 offset:23552
	global_load_lds_dwordx4 v[158:159], off
	s_add_i32 m0, s33, 0x2000
	s_add_u32 s34, s80, 0x80000
	v_lshl_add_u64 v[188:189], s[80:81], 0, v[134:135]
	s_addc_u32 s35, s81, 0
	s_add_i32 s33, s25, s0
	global_load_lds_dwordx4 v[188:189], off
	v_lshl_add_u64 v[228:229], s[34:35], 0, v[130:131]
	s_mov_b32 m0, s33
	v_lshl_add_u64 v[230:231], s[82:83], 0, v[132:133]
	global_load_lds_dwordx4 v[228:229], off
	v_lshl_add_u64 v[228:229], s[34:35], 0, v[134:135]
	s_add_i32 m0, s33, 0x2000
	s_nop 0
	global_load_lds_dwordx4 v[228:229], off
	v_lshl_add_u64 v[228:229], s[82:83], 0, v[128:129]
	s_mov_b32 m0, s16
	s_nop 0
	global_load_lds_dwordx4 v[228:229], off
	s_mov_b32 m0, s17
	s_nop 0
	global_load_lds_dwordx4 v[230:231], off
	s_waitcnt vmcnt(8)
	s_waitcnt lgkmcnt(0)
	s_barrier
; #define PG8_STAGE(bufoff, gbase, voff) do { _Pragma("unroll") for (int _i = 0; _i < 2; ++_i) \
;         __builtin_amdgcn_global_load_lds((const unsigned*)((const char*)(gbase) + (voff)[_i]), (LAS unsigned*)(lds + (bufoff) + ldsw + _i * 8192), 16, 0, 0); } while (0)
; #define PG8_LDA(dst, b, h) do { _Pragma("unroll") for (int m = 0; m < 4; ++m) _Pragma("unroll") for (int k = 0; k < 2; ++k) dst[m][k] = *(const LAS bf16x8*)(lds + PG8_SA(b, h) + aoff + m * 2048 + k * 1024); } while (0)
; #define PG8_LDB(dst, b, h) do { _Pragma("unroll") for (int n = 0; n < 2; ++n) _Pragma("unroll") for (int k = 0; k < 2; ++k) dst[n][k] = *(const LAS bf16x8*)(lds + PG8_SB(b, h) + boff + n * 2048 + k * 1024); } while (0)
; #define PG8_MMA(ai, bj, At, Bt) do { __builtin_amdgcn_s_setprio(1); _Pragma("unroll") for (int m = 0; m < 4; ++m) _Pragma("unroll") for (int n = 0; n < 2; ++n) _Pragma("unroll") for (int k = 0; k < 2; ++k) \
;         acc[ai][bj][m][n] = __builtin_amdgcn_mfma_f32_16x16x32_bf16(Bt[n][k], At[m][k], acc[ai][bj][m][n], 0, 0, 0); __builtin_amdgcn_s_setprio(0); } while (0)
; #define PG8_WAIT_V(n) asm volatile("s_waitcnt vmcnt(" #n ")" ::: "memory")
; #define PG8_WAIT_L(n) asm volatile("s_waitcnt lgkmcnt(" #n ")" ::: "memory")
; #define PG8_BAR __builtin_amdgcn_s_barrier()
; #define PG8_SCHED __builtin_amdgcn_sched_barrier(0)
; template <int GI>
; __device__ __forceinline__ void gemm_phase(LAS unsigned char* lds, unsigned char* ws, int G, int cblk) {
;     ...
;             PG8_WAIT_V(8); PG8_WAIT_L(0); PG8_BAR; PG8_MMA(1, 0, At, B0); PG8_MMA(1, 1, At, B1); PG8_BAR; PG8_SCHED;
;             PG8_LDB(B0, 1, 0); PG8_LDB(B1, 1, 1); PG8_SCHED; PG8_LDA(At, 1, 0); PG8_STAGE(PG8_SA(0, 1), a2 + hstepA, voffA);
;             PG8_WAIT_V(8); PG8_WAIT_L(0); PG8_BAR; PG8_MMA(0, 0, At, B0); PG8_MMA(0, 1, At, B1); PG8_BAR; PG8_SCHED;
	s_setprio 1
	s_waitcnt lgkmcnt(0)
	v_mfma_f32_16x16x32_bf16 v[60:63], v[154:157], v[196:199], 0
	v_mfma_f32_16x16x32_bf16 v[56:59], v[168:171], v[196:199], 0
	v_mfma_f32_16x16x32_bf16 v[52:55], v[154:157], v[204:207], 0
	v_mfma_f32_16x16x32_bf16 v[48:51], v[168:171], v[204:207], 0
	v_mfma_f32_16x16x32_bf16 v[36:39], v[154:157], v[212:215], 0
	v_mfma_f32_16x16x32_bf16 v[32:35], v[168:171], v[212:215], 0
	v_mfma_f32_16x16x32_bf16 v[20:23], v[154:157], v[220:223], 0
	v_mfma_f32_16x16x32_bf16 v[16:19], v[168:171], v[220:223], 0
	v_mfma_f32_16x16x32_bf16 v[60:63], v[164:167], v[200:203], v[60:63]
	v_mfma_f32_16x16x32_bf16 v[56:59], v[172:175], v[200:203], v[56:59]
	v_mfma_f32_16x16x32_bf16 v[52:55], v[164:167], v[208:211], v[52:55]
	v_mfma_f32_16x16x32_bf16 v[48:51], v[172:175], v[208:211], v[48:51]
	v_mfma_f32_16x16x32_bf16 v[36:39], v[164:167], v[216:219], v[36:39]
	v_mfma_f32_16x16x32_bf16 v[32:35], v[172:175], v[216:219], v[32:35]
	v_mfma_f32_16x16x32_bf16 v[20:23], v[164:167], v[224:227], v[20:23]
	v_mfma_f32_16x16x32_bf16 v[16:19], v[172:175], v[224:227], v[16:19]
	s_setprio 0
	s_setprio 1
	v_mfma_f32_16x16x32_bf16 v[44:47], v[176:179], v[196:199], 0
	v_mfma_f32_16x16x32_bf16 v[40:43], v[184:187], v[196:199], 0
	v_mfma_f32_16x16x32_bf16 v[28:31], v[176:179], v[204:207], 0
	v_mfma_f32_16x16x32_bf16 v[24:27], v[184:187], v[204:207], 0
	v_mfma_f32_16x16x32_bf16 v[12:15], v[176:179], v[212:215], 0
	v_mfma_f32_16x16x32_bf16 v[8:11], v[184:187], v[212:215], 0
	v_mfma_f32_16x16x32_bf16 v[4:7], v[176:179], v[220:223], 0
	v_mfma_f32_16x16x32_bf16 v[0:3], v[184:187], v[220:223], 0
	v_mfma_f32_16x16x32_bf16 v[44:47], v[180:183], v[200:203], v[44:47]
	v_mfma_f32_16x16x32_bf16 v[40:43], v[192:195], v[200:203], v[40:43]
	v_mfma_f32_16x16x32_bf16 v[28:31], v[180:183], v[208:211], v[28:31]
	v_mfma_f32_16x16x32_bf16 v[24:27], v[192:195], v[208:211], v[24:27]
	v_mfma_f32_16x16x32_bf16 v[12:15], v[180:183], v[216:219], v[12:15]
	v_mfma_f32_16x16x32_bf16 v[8:11], v[192:195], v[216:219], v[8:11]
	v_mfma_f32_16x16x32_bf16 v[4:7], v[180:183], v[224:227], v[4:7]
	v_mfma_f32_16x16x32_bf16 v[0:3], v[192:195], v[224:227], v[0:3]
	s_setprio 0
	s_barrier
	s_add_i32 s33, 0, 0x18000
	v_add_u32_e32 v161, s33, v150
	s_add_i32 s63, 0, 0x1c000
	ds_read_b128 v[154:157], v161
	ds_read_b128 v[164:167], v161 offset:1024
	ds_read_b128 v[168:171], v161 offset:2048
	ds_read_b128 v[172:175], v161 offset:3072
	v_add_u32_e32 v161, s63, v150
	ds_read_b128 v[176:179], v161
	ds_read_b128 v[180:183], v161 offset:1024
	ds_read_b128 v[184:187], v161 offset:2048
	ds_read_b128 v[192:195], v161 offset:3072
	s_add_u32 s34, s82, 0x80000
	s_addc_u32 s35, s83, 0
	s_mov_b32 m0, s18
	v_lshl_add_u64 v[232:233], s[34:35], 0, v[128:129]
	ds_read_b128 v[196:199], v153 offset:32768
	ds_read_b128 v[200:203], v153 offset:33792
	ds_read_b128 v[204:207], v153 offset:34816
	ds_read_b128 v[208:211], v153 offset:35840
	ds_read_b128 v[212:215], v153 offset:36864
	ds_read_b128 v[216:219], v153 offset:37888
	ds_read_b128 v[220:223], v153 offset:38912
	ds_read_b128 v[224:227], v153 offset:39936
	global_load_lds_dwordx4 v[232:233], off
	v_lshl_add_u64 v[232:233], s[34:35], 0, v[132:133]
	s_mov_b32 m0, s19
	s_nop 0
	global_load_lds_dwordx4 v[232:233], off
	s_waitcnt vmcnt(8)
	s_waitcnt lgkmcnt(0)
	s_barrier
	s_setprio 1
	s_waitcnt lgkmcnt(0)
	v_mfma_f32_16x16x32_bf16 v[124:127], v[154:157], v[196:199], v[124:127]
	v_mfma_f32_16x16x32_bf16 v[120:123], v[168:171], v[196:199], v[120:123]
	v_mfma_f32_16x16x32_bf16 v[116:119], v[154:157], v[204:207], v[116:119]
	v_mfma_f32_16x16x32_bf16 v[112:115], v[168:171], v[204:207], v[112:115]
	v_mfma_f32_16x16x32_bf16 v[100:103], v[154:157], v[212:215], v[100:103]
	v_mfma_f32_16x16x32_bf16 v[96:99], v[168:171], v[212:215], v[96:99]
	v_mfma_f32_16x16x32_bf16 v[84:87], v[154:157], v[220:223], v[84:87]
	v_mfma_f32_16x16x32_bf16 v[80:83], v[168:171], v[220:223], v[80:83]
	v_mfma_f32_16x16x32_bf16 v[124:127], v[164:167], v[200:203], v[124:127]
	v_mfma_f32_16x16x32_bf16 v[120:123], v[172:175], v[200:203], v[120:123]
	v_mfma_f32_16x16x32_bf16 v[116:119], v[164:167], v[208:211], v[116:119]
	v_mfma_f32_16x16x32_bf16 v[112:115], v[172:175], v[208:211], v[112:115]
	v_mfma_f32_16x16x32_bf16 v[100:103], v[164:167], v[216:219], v[100:103]
	v_mfma_f32_16x16x32_bf16 v[96:99], v[172:175], v[216:219], v[96:99]
	v_mfma_f32_16x16x32_bf16 v[84:87], v[164:167], v[224:227], v[84:87]
	v_mfma_f32_16x16x32_bf16 v[80:83], v[172:175], v[224:227], v[80:83]
	s_setprio 0
	s_setprio 1
	v_mfma_f32_16x16x32_bf16 v[108:111], v[176:179], v[196:199], v[108:111]
	v_mfma_f32_16x16x32_bf16 v[104:107], v[184:187], v[196:199], v[104:107]
	v_mfma_f32_16x16x32_bf16 v[92:95], v[176:179], v[204:207], v[92:95]
	v_mfma_f32_16x16x32_bf16 v[88:91], v[184:187], v[204:207], v[88:91]
	v_mfma_f32_16x16x32_bf16 v[76:79], v[176:179], v[212:215], v[76:79]
	v_mfma_f32_16x16x32_bf16 v[72:75], v[184:187], v[212:215], v[72:75]
	v_mfma_f32_16x16x32_bf16 v[68:71], v[176:179], v[220:223], v[68:71]
	v_mfma_f32_16x16x32_bf16 v[64:67], v[184:187], v[220:223], v[64:67]
	v_mfma_f32_16x16x32_bf16 v[108:111], v[180:183], v[200:203], v[108:111]
	v_mfma_f32_16x16x32_bf16 v[104:107], v[192:195], v[200:203], v[104:107]
	v_mfma_f32_16x16x32_bf16 v[92:95], v[180:183], v[208:211], v[92:95]
	v_mfma_f32_16x16x32_bf16 v[88:91], v[192:195], v[208:211], v[88:91]
	v_mfma_f32_16x16x32_bf16 v[76:79], v[180:183], v[216:219], v[76:79]
	v_mfma_f32_16x16x32_bf16 v[72:75], v[192:195], v[216:219], v[72:75]
	v_mfma_f32_16x16x32_bf16 v[68:71], v[180:183], v[224:227], v[68:71]
	v_mfma_f32_16x16x32_bf16 v[64:67], v[192:195], v[224:227], v[64:67]
	s_setprio 0
	s_barrier
; #define PG8_STAGE(bufoff, gbase, voff) do { _Pragma("unroll") for (int _i = 0; _i < 2; ++_i) \
;         __builtin_amdgcn_global_load_lds((const unsigned*)((const char*)(gbase) + (voff)[_i]), (LAS unsigned*)(lds + (bufoff) + ldsw + _i * 8192), 16, 0, 0); } while (0)
; #define PG8_LDA(dst, b, h) do { _Pragma("unroll") for (int m = 0; m < 4; ++m) _Pragma("unroll") for (int k = 0; k < 2; ++k) dst[m][k] = *(const LAS bf16x8*)(lds + PG8_SA(b, h) + aoff + m * 2048 + k * 1024); } while (0)
; #define PG8_MMA(ai, bj, At, Bt) do { __builtin_amdgcn_s_setprio(1); _Pragma("unroll") for (int m = 0; m < 4; ++m) _Pragma("unroll") for (int n = 0; n < 2; ++n) _Pragma("unroll") for (int k = 0; k < 2; ++k) \
;         acc[ai][bj][m][n] = __builtin_amdgcn_mfma_f32_16x16x32_bf16(Bt[n][k], At[m][k], acc[ai][bj][m][n], 0, 0, 0); __builtin_amdgcn_s_setprio(0); } while (0)
; #define PG8_WAIT_V(n) asm volatile("s_waitcnt vmcnt(" #n ")" ::: "memory")
; #define PG8_WAIT_L(n) asm volatile("s_waitcnt lgkmcnt(" #n ")" ::: "memory")
; #define PG8_BAR __builtin_amdgcn_s_barrier()
; #define PG8_SCHED __builtin_amdgcn_sched_barrier(0)
; template <int GI>
; __device__ __forceinline__ void gemm_phase(LAS unsigned char* lds, unsigned char* ws, int G, int cblk) {
;     ...
;         for (int t = 0; t < nt; t += 2) {
;     ...
;             PG8_LDA(At, 1, 1); PG8_STAGE(PG8_SB(1, 0), b3, voffB); PG8_STAGE(PG8_SB(1, 1), b3 + hstepB, voffB); PG8_STAGE(PG8_SA(1, 0), a3, voffA);
;             PG8_WAIT_V(8); PG8_WAIT_L(0); PG8_BAR; PG8_MMA(1, 0, At, B0); PG8_MMA(1, 1, At, B1); PG8_BAR; PG8_SCHED;
	s_add_i32 s33, s33, s0
	v_lshl_add_u64 v[158:159], v[158:159], 0, s[38:39]
	s_mov_b32 m0, s33
	ds_read_b128 v[196:199], v153 offset:49152
	ds_read_b128 v[200:203], v153 offset:50176
	ds_read_b128 v[204:207], v153 offset:51200
	ds_read_b128 v[208:211], v153 offset:52224
	ds_read_b128 v[212:215], v153 offset:53248
	ds_read_b128 v[216:219], v153 offset:54272
	ds_read_b128 v[220:223], v153 offset:55296
	ds_read_b128 v[224:227], v153 offset:56320
	global_load_lds_dwordx4 v[158:159], off
	s_add_i32 m0, s33, 0x2000
	s_add_u32 s34, s80, 0x80080
	v_lshl_add_u64 v[158:159], v[188:189], 0, s[38:39]
	s_addc_u32 s35, s81, 0
	s_add_i32 s33, s63, s0
	global_load_lds_dwordx4 v[158:159], off
	v_lshl_add_u64 v[158:159], s[34:35], 0, v[130:131]
	s_mov_b32 m0, s33
	s_nop 0
	global_load_lds_dwordx4 v[158:159], off
	v_lshl_add_u64 v[158:159], s[34:35], 0, v[134:135]
	s_add_i32 m0, s33, 0x2000
	s_nop 0
	global_load_lds_dwordx4 v[158:159], off
	v_lshl_add_u64 v[158:159], v[228:229], 0, s[38:39]
	s_mov_b32 m0, s22
	s_nop 0
	global_load_lds_dwordx4 v[158:159], off
	v_lshl_add_u64 v[158:159], v[230:231], 0, s[38:39]
	s_mov_b32 m0, s23
	s_nop 0
	global_load_lds_dwordx4 v[158:159], off
	s_waitcnt vmcnt(8)
	s_waitcnt lgkmcnt(0)
	s_barrier
	s_setprio 1
	s_waitcnt lgkmcnt(0)
	v_mfma_f32_16x16x32_bf16 v[60:63], v[154:157], v[196:199], v[60:63]
	v_mfma_f32_16x16x32_bf16 v[56:59], v[168:171], v[196:199], v[56:59]
	v_mfma_f32_16x16x32_bf16 v[52:55], v[154:157], v[204:207], v[52:55]
	v_mfma_f32_16x16x32_bf16 v[48:51], v[168:171], v[204:207], v[48:51]
	v_mfma_f32_16x16x32_bf16 v[36:39], v[154:157], v[212:215], v[36:39]
	v_mfma_f32_16x16x32_bf16 v[32:35], v[168:171], v[212:215], v[32:35]
	v_mfma_f32_16x16x32_bf16 v[20:23], v[154:157], v[220:223], v[20:23]
	v_mfma_f32_16x16x32_bf16 v[16:19], v[168:171], v[220:223], v[16:19]
	v_mfma_f32_16x16x32_bf16 v[60:63], v[164:167], v[200:203], v[60:63]
	v_mfma_f32_16x16x32_bf16 v[56:59], v[172:175], v[200:203], v[56:59]
	v_mfma_f32_16x16x32_bf16 v[52:55], v[164:167], v[208:211], v[52:55]
	v_mfma_f32_16x16x32_bf16 v[48:51], v[172:175], v[208:211], v[48:51]
	v_mfma_f32_16x16x32_bf16 v[36:39], v[164:167], v[216:219], v[36:39]
	v_mfma_f32_16x16x32_bf16 v[32:35], v[172:175], v[216:219], v[32:35]
	v_mfma_f32_16x16x32_bf16 v[20:23], v[164:167], v[224:227], v[20:23]
	v_mfma_f32_16x16x32_bf16 v[16:19], v[172:175], v[224:227], v[16:19]
	s_setprio 0
	s_setprio 1
	v_mfma_f32_16x16x32_bf16 v[44:47], v[176:179], v[196:199], v[44:47]
	v_mfma_f32_16x16x32_bf16 v[40:43], v[184:187], v[196:199], v[40:43]
	v_mfma_f32_16x16x32_bf16 v[28:31], v[176:179], v[204:207], v[28:31]
	v_mfma_f32_16x16x32_bf16 v[24:27], v[184:187], v[204:207], v[24:27]
	v_mfma_f32_16x16x32_bf16 v[12:15], v[176:179], v[212:215], v[12:15]
	v_mfma_f32_16x16x32_bf16 v[8:11], v[184:187], v[212:215], v[8:11]
	v_mfma_f32_16x16x32_bf16 v[4:7], v[176:179], v[220:223], v[4:7]
	v_mfma_f32_16x16x32_bf16 v[0:3], v[184:187], v[220:223], v[0:3]
	v_mfma_f32_16x16x32_bf16 v[44:47], v[180:183], v[200:203], v[44:47]
	v_mfma_f32_16x16x32_bf16 v[40:43], v[192:195], v[200:203], v[40:43]
	v_mfma_f32_16x16x32_bf16 v[28:31], v[180:183], v[208:211], v[28:31]
	v_mfma_f32_16x16x32_bf16 v[24:27], v[192:195], v[208:211], v[24:27]
	v_mfma_f32_16x16x32_bf16 v[12:15], v[180:183], v[216:219], v[12:15]
	v_mfma_f32_16x16x32_bf16 v[8:11], v[192:195], v[216:219], v[8:11]
	v_mfma_f32_16x16x32_bf16 v[4:7], v[180:183], v[224:227], v[4:7]
	v_mfma_f32_16x16x32_bf16 v[0:3], v[192:195], v[224:227], v[0:3]
	s_setprio 0
	s_barrier
	s_add_i32 s27, s27, 2
	s_add_u32 s78, s78, 0x100
	s_addc_u32 s79, s79, 0
	s_add_u32 s14, s14, 0x100
	s_addc_u32 s15, s15, 0
	s_cmp_gt_u32 s27, 29
	s_cbranch_scc0 .LBB0_148
	s_branch .Lpeel_exit_2

; #define LAS __attribute__((address_space(3)))
; __device__ __forceinline__ unsigned cvtpk(float lo, float hi) { f32x2_t v = {lo, hi}; bf16x2_t b = __builtin_convertvector(v, bf16x2_t); return __builtin_bit_cast(unsigned, b); }
; #define NTL(p) __builtin_nontemporal_load(&(p))
; __device__ __forceinline__ void tr_item(const float* W, int N, int K, int k0, int n0, bf16_t* dst, LAS float* scr, int lane) {
; #pragma unroll 8
;     for (int i = 0; i < 32; ++i) { const int kk = 2 * i + (lane >> 5); scr[kk * 33 + (lane & 31)] = NTL(W[(size_t)(k0 + kk) * N + n0 + (lane & 31)]); }
;     asm volatile("s_waitcnt lgkmcnt(0)" ::: "memory");
;     const int c = lane & 7;
; #pragma unroll
;     for (int j = 0; j < 4; ++j) { const int n = (lane >> 3) + 8 * j; const LAS float* s = scr + (8 * c) * 33 + n;
;         u32x4 o; o.x = cvtpk(s[0 * 33], s[1 * 33]); o.y = cvtpk(s[2 * 33], s[3 * 33]); o.z = cvtpk(s[4 * 33], s[5 * 33]); o.w = cvtpk(s[6 * 33], s[7 * 33]);
;         *(u32x4*)(dst + (size_t)n * K + k0 + 8 * c) = o; }
;     asm volatile("s_waitcnt lgkmcnt(0)" ::: "memory");
.LBB0_165:
	v_lshl_add_u64 v[72:73], v[40:41], 0, s[6:7]
	v_lshl_add_u64 v[74:75], v[38:39], 0, s[6:7]
	v_lshl_add_u64 v[76:77], v[36:37], 0, s[6:7]
	v_lshl_add_u64 v[78:79], v[34:35], 0, s[6:7]
	v_lshl_add_u64 v[80:81], v[32:33], 0, s[6:7]
	v_lshl_add_u64 v[82:83], v[30:31], 0, s[6:7]
	v_lshl_add_u64 v[84:85], v[28:29], 0, s[6:7]
	v_lshl_add_u64 v[86:87], v[26:27], 0, s[6:7]
	global_load_dword v112, v[72:73], off nt
	global_load_dword v113, v[74:75], off nt
	global_load_dword v114, v[76:77], off nt
	global_load_dword v115, v[78:79], off nt
	global_load_dword v116, v[80:81], off nt
	global_load_dword v117, v[82:83], off nt
	global_load_dword v118, v[84:85], off nt
	global_load_dword v119, v[86:87], off nt
	s_add_u32 s6, s6, 0x20000
	s_addc_u32 s7, s7, 0
	v_lshl_add_u64 v[72:73], v[40:41], 0, s[6:7]
	v_lshl_add_u64 v[74:75], v[38:39], 0, s[6:7]
	v_lshl_add_u64 v[76:77], v[36:37], 0, s[6:7]
	v_lshl_add_u64 v[78:79], v[34:35], 0, s[6:7]
	v_lshl_add_u64 v[80:81], v[32:33], 0, s[6:7]
	v_lshl_add_u64 v[82:83], v[30:31], 0, s[6:7]
	v_lshl_add_u64 v[84:85], v[28:29], 0, s[6:7]
	v_lshl_add_u64 v[86:87], v[26:27], 0, s[6:7]
	global_load_dword v120, v[72:73], off nt
	global_load_dword v121, v[74:75], off nt
	global_load_dword v122, v[76:77], off nt
	global_load_dword v123, v[78:79], off nt
	global_load_dword v124, v[80:81], off nt
	global_load_dword v125, v[82:83], off nt
	global_load_dword v126, v[84:85], off nt
	global_load_dword v127, v[86:87], off nt
	s_add_u32 s6, s6, 0x20000
	s_addc_u32 s7, s7, 0
	v_lshl_add_u64 v[72:73], v[40:41], 0, s[6:7]
	v_lshl_add_u64 v[74:75], v[38:39], 0, s[6:7]
	v_lshl_add_u64 v[76:77], v[36:37], 0, s[6:7]
	v_lshl_add_u64 v[78:79], v[34:35], 0, s[6:7]
	v_lshl_add_u64 v[80:81], v[32:33], 0, s[6:7]
	v_lshl_add_u64 v[82:83], v[30:31], 0, s[6:7]
	v_lshl_add_u64 v[84:85], v[28:29], 0, s[6:7]
	v_lshl_add_u64 v[86:87], v[26:27], 0, s[6:7]
	global_load_dword v128, v[72:73], off nt
	global_load_dword v129, v[74:75], off nt
	global_load_dword v130, v[76:77], off nt
	global_load_dword v131, v[78:79], off nt
	global_load_dword v132, v[80:81], off nt
	global_load_dword v133, v[82:83], off nt
	global_load_dword v134, v[84:85], off nt
	global_load_dword v135, v[86:87], off nt
	s_add_u32 s6, s6, 0x20000
	s_addc_u32 s7, s7, 0
	v_lshl_add_u64 v[72:73], v[40:41], 0, s[6:7]
	v_lshl_add_u64 v[74:75], v[38:39], 0, s[6:7]
	v_lshl_add_u64 v[76:77], v[36:37], 0, s[6:7]
	v_lshl_add_u64 v[78:79], v[34:35], 0, s[6:7]
	v_lshl_add_u64 v[80:81], v[32:33], 0, s[6:7]
	v_lshl_add_u64 v[82:83], v[30:31], 0, s[6:7]
	v_lshl_add_u64 v[84:85], v[28:29], 0, s[6:7]
	v_lshl_add_u64 v[86:87], v[26:27], 0, s[6:7]
	global_load_dword v136, v[72:73], off nt
	global_load_dword v137, v[74:75], off nt
	global_load_dword v138, v[76:77], off nt
	global_load_dword v139, v[78:79], off nt
	global_load_dword v140, v[80:81], off nt
	global_load_dword v141, v[82:83], off nt
	global_load_dword v142, v[84:85], off nt
	global_load_dword v143, v[86:87], off nt
	s_add_u32 s6, s6, 0x20000
	s_addc_u32 s7, s7, 0
	v_add_u32_e32 v78, 0x400, v2
	s_waitcnt vmcnt(30)
	ds_write2_b32 v2, v112, v113 offset1:66
	s_waitcnt vmcnt(28)
	ds_write2_b32 v2, v114, v115 offset0:132 offset1:198
	s_waitcnt vmcnt(26)
	ds_write2_b32 v78, v116, v117 offset0:8 offset1:74
	s_waitcnt vmcnt(24)
	ds_write2_b32 v78, v118, v119 offset0:140 offset1:206
	v_add_u32_e32 v2, 0x840, v2
	v_add_u32_e32 v78, 0x400, v2
	s_waitcnt vmcnt(22)
	ds_write2_b32 v2, v120, v121 offset1:66
	s_waitcnt vmcnt(20)
	ds_write2_b32 v2, v122, v123 offset0:132 offset1:198
	s_waitcnt vmcnt(18)
	ds_write2_b32 v78, v124, v125 offset0:8 offset1:74
	s_waitcnt vmcnt(16)
	ds_write2_b32 v78, v126, v127 offset0:140 offset1:206
	v_add_u32_e32 v2, 0x840, v2
	v_add_u32_e32 v78, 0x400, v2
	s_waitcnt vmcnt(14)
	ds_write2_b32 v2, v128, v129 offset1:66
	s_waitcnt vmcnt(12)
	ds_write2_b32 v2, v130, v131 offset0:132 offset1:198
	s_waitcnt vmcnt(10)
	ds_write2_b32 v78, v132, v133 offset0:8 offset1:74
	s_waitcnt vmcnt(8)
	ds_write2_b32 v78, v134, v135 offset0:140 offset1:206
	v_add_u32_e32 v2, 0x840, v2
	v_add_u32_e32 v78, 0x400, v2
	s_waitcnt vmcnt(6)
	ds_write2_b32 v2, v136, v137 offset1:66
	s_waitcnt vmcnt(4)
	ds_write2_b32 v2, v138, v139 offset0:132 offset1:198
	s_waitcnt vmcnt(2)
	ds_write2_b32 v78, v140, v141 offset0:8 offset1:74
	s_waitcnt vmcnt(0)
	ds_write2_b32 v78, v142, v143 offset0:140 offset1:206
	v_add_u32_e32 v2, 0x840, v2
	s_lshl_b32 s6, s0, 5
	s_and_b32 s4, s0, 0x7fffffc0
	s_and_b32 s6, s6, 0x7e0
	s_addk_i32 s4, 0x9c00
	s_mulk_i32 s6, 0x2c00
	s_waitcnt lgkmcnt(0)
	s_add_u32 s14, s17, s6
	ds_read2_b32 v[30:31], v5 offset0:33 offset1:41
	ds_read2_b32 v[32:33], v5 offset1:8
	ds_read2_b32 v[34:35], v5 offset0:66 offset1:74
	ds_read2_b32 v[36:37], v5 offset0:99 offset1:107
	ds_read2_b32 v[38:39], v5 offset0:132 offset1:140
	ds_read2_b32 v[40:41], v5 offset0:165 offset1:173
	ds_read2_b32 v[72:73], v5 offset0:198 offset1:206
	ds_read2_b32 v[74:75], v5 offset0:231 offset1:239
	s_addc_u32 s15, s22, 0
	s_lshl_b64 s[6:7], s[4:5], 1
	s_add_u32 s6, s14, s6
	s_addc_u32 s7, s15, s7
	v_lshlrev_b32_e32 v2, 1, v0
	v_lshl_add_u64 v[76:77], s[6:7], 0, v[2:3]
	v_mov_b32_e32 v25, v3
	s_waitcnt lgkmcnt(6)
	v_cvt_pk_bf16_f32 v26, v32, v30
	s_waitcnt lgkmcnt(4)
	v_cvt_pk_bf16_f32 v27, v34, v36
	s_waitcnt lgkmcnt(2)
	v_cvt_pk_bf16_f32 v28, v38, v40
	s_waitcnt lgkmcnt(0)
	v_cvt_pk_bf16_f32 v29, v72, v74
	v_lshl_add_u64 v[76:77], v[76:77], 0, v[24:25]
	global_store_dwordx4 v[76:77], v[26:29], off
	v_add_co_u32_e32 v30, vcc, s26, v76
	s_nop 0
	v_cvt_pk_bf16_f32 v26, v33, v31
	v_cvt_pk_bf16_f32 v27, v35, v37
	v_cvt_pk_bf16_f32 v28, v39, v41
	v_cvt_pk_bf16_f32 v29, v73, v75
	ds_read2_b32 v[32:33], v5 offset0:49 offset1:57
	ds_read2_b32 v[34:35], v5 offset0:16 offset1:24
	ds_read2_b32 v[36:37], v5 offset0:82 offset1:90
	ds_read2_b32 v[38:39], v5 offset0:115 offset1:123
	ds_read2_b32 v[40:41], v5 offset0:148 offset1:156
	ds_read2_b32 v[72:73], v5 offset0:181 offset1:189
	ds_read2_b32 v[74:75], v5 offset0:214 offset1:222
	ds_read2_b32 v[78:79], v5 offset0:247 offset1:255
	v_addc_co_u32_e32 v31, vcc, 0, v77, vcc
	global_store_dwordx4 v[30:31], v[26:29], off
	v_add_co_u32_e32 v30, vcc, s27, v76
	s_waitcnt lgkmcnt(6)
	v_cvt_pk_bf16_f32 v26, v34, v32
	s_waitcnt lgkmcnt(4)
	v_cvt_pk_bf16_f32 v27, v36, v38
	s_waitcnt lgkmcnt(2)
	v_cvt_pk_bf16_f32 v28, v40, v72
	s_waitcnt lgkmcnt(0)
	v_cvt_pk_bf16_f32 v29, v74, v78
	v_addc_co_u32_e32 v31, vcc, 0, v77, vcc
	global_store_dwordx4 v[30:31], v[26:29], off
	v_add_co_u32_e32 v30, vcc, 0x42000, v76
	s_nop 0
	v_cvt_pk_bf16_f32 v26, v35, v33
	v_cvt_pk_bf16_f32 v27, v37, v39
	v_cvt_pk_bf16_f32 v28, v41, v73
	v_cvt_pk_bf16_f32 v29, v75, v79
	v_addc_co_u32_e32 v31, vcc, 0, v77, vcc
	global_store_dwordx4 v[30:31], v[26:29], off
	s_waitcnt lgkmcnt(0)
	s_mov_b64 s[6:7], 0

; #define LAS __attribute__((address_space(3)))
; __device__ __forceinline__ unsigned cvtpk(float lo, float hi) { f32x2_t v = {lo, hi}; bf16x2_t b = __builtin_convertvector(v, bf16x2_t); return __builtin_bit_cast(unsigned, b); }
; #define NTL(p) __builtin_nontemporal_load(&(p))
; __device__ __forceinline__ void tr_item(const float* W, int N, int K, int k0, int n0, bf16_t* dst, LAS float* scr, int lane) {
; #pragma unroll 8
;     for (int i = 0; i < 32; ++i) { const int kk = 2 * i + (lane >> 5); scr[kk * 33 + (lane & 31)] = NTL(W[(size_t)(k0 + kk) * N + n0 + (lane & 31)]); }
;     asm volatile("s_waitcnt lgkmcnt(0)" ::: "memory");
;     const int c = lane & 7;
; #pragma unroll
;     for (int j = 0; j < 4; ++j) { const int n = (lane >> 3) + 8 * j; const LAS float* s = scr + (8 * c) * 33 + n;
;         u32x4 o; o.x = cvtpk(s[0 * 33], s[1 * 33]); o.y = cvtpk(s[2 * 33], s[3 * 33]); o.z = cvtpk(s[4 * 33], s[5 * 33]); o.w = cvtpk(s[6 * 33], s[7 * 33]);
;         *(u32x4*)(dst + (size_t)n * K + k0 + 8 * c) = o; }
;     asm volatile("s_waitcnt lgkmcnt(0)" ::: "memory");
.LBB0_173:
	v_lshl_add_u64 v[72:73], v[40:41], 0, s[18:19]
	v_lshl_add_u64 v[74:75], v[38:39], 0, s[18:19]
	v_lshl_add_u64 v[76:77], v[36:37], 0, s[18:19]
	v_lshl_add_u64 v[78:79], v[34:35], 0, s[18:19]
	v_lshl_add_u64 v[80:81], v[32:33], 0, s[18:19]
	v_lshl_add_u64 v[82:83], v[30:31], 0, s[18:19]
	v_lshl_add_u64 v[84:85], v[28:29], 0, s[18:19]
	v_lshl_add_u64 v[86:87], v[26:27], 0, s[18:19]
	global_load_dword v112, v[72:73], off nt
	global_load_dword v113, v[74:75], off nt
	global_load_dword v114, v[76:77], off nt
	global_load_dword v115, v[78:79], off nt
	global_load_dword v116, v[80:81], off nt
	global_load_dword v117, v[82:83], off nt
	global_load_dword v118, v[84:85], off nt
	global_load_dword v119, v[86:87], off nt
	s_add_u32 s18, s18, 0xb0000
	s_addc_u32 s19, s19, 0
	v_lshl_add_u64 v[72:73], v[40:41], 0, s[18:19]
	v_lshl_add_u64 v[74:75], v[38:39], 0, s[18:19]
	v_lshl_add_u64 v[76:77], v[36:37], 0, s[18:19]
	v_lshl_add_u64 v[78:79], v[34:35], 0, s[18:19]
	v_lshl_add_u64 v[80:81], v[32:33], 0, s[18:19]
	v_lshl_add_u64 v[82:83], v[30:31], 0, s[18:19]
	v_lshl_add_u64 v[84:85], v[28:29], 0, s[18:19]
	v_lshl_add_u64 v[86:87], v[26:27], 0, s[18:19]
	global_load_dword v120, v[72:73], off nt
	global_load_dword v121, v[74:75], off nt
	global_load_dword v122, v[76:77], off nt
	global_load_dword v123, v[78:79], off nt
	global_load_dword v124, v[80:81], off nt
	global_load_dword v125, v[82:83], off nt
	global_load_dword v126, v[84:85], off nt
	global_load_dword v127, v[86:87], off nt
	s_add_u32 s18, s18, 0xb0000
	s_addc_u32 s19, s19, 0
	v_lshl_add_u64 v[72:73], v[40:41], 0, s[18:19]
	v_lshl_add_u64 v[74:75], v[38:39], 0, s[18:19]
	v_lshl_add_u64 v[76:77], v[36:37], 0, s[18:19]
	v_lshl_add_u64 v[78:79], v[34:35], 0, s[18:19]
	v_lshl_add_u64 v[80:81], v[32:33], 0, s[18:19]
	v_lshl_add_u64 v[82:83], v[30:31], 0, s[18:19]
	v_lshl_add_u64 v[84:85], v[28:29], 0, s[18:19]
	v_lshl_add_u64 v[86:87], v[26:27], 0, s[18:19]
	global_load_dword v128, v[72:73], off nt
	global_load_dword v129, v[74:75], off nt
	global_load_dword v130, v[76:77], off nt
	global_load_dword v131, v[78:79], off nt
	global_load_dword v132, v[80:81], off nt
	global_load_dword v133, v[82:83], off nt
	global_load_dword v134, v[84:85], off nt
	global_load_dword v135, v[86:87], off nt
	s_add_u32 s18, s18, 0xb0000
	s_addc_u32 s19, s19, 0
	v_lshl_add_u64 v[72:73], v[40:41], 0, s[18:19]
	v_lshl_add_u64 v[74:75], v[38:39], 0, s[18:19]
	v_lshl_add_u64 v[76:77], v[36:37], 0, s[18:19]
	v_lshl_add_u64 v[78:79], v[34:35], 0, s[18:19]
	v_lshl_add_u64 v[80:81], v[32:33], 0, s[18:19]
	v_lshl_add_u64 v[82:83], v[30:31], 0, s[18:19]
	v_lshl_add_u64 v[84:85], v[28:29], 0, s[18:19]
	v_lshl_add_u64 v[86:87], v[26:27], 0, s[18:19]
	global_load_dword v136, v[72:73], off nt
	global_load_dword v137, v[74:75], off nt
	global_load_dword v138, v[76:77], off nt
	global_load_dword v139, v[78:79], off nt
	global_load_dword v140, v[80:81], off nt
	global_load_dword v141, v[82:83], off nt
	global_load_dword v142, v[84:85], off nt
	global_load_dword v143, v[86:87], off nt
	s_add_u32 s18, s18, 0xb0000
	s_addc_u32 s19, s19, 0
	v_add_u32_e32 v78, 0x400, v2
	s_waitcnt vmcnt(30)
	ds_write2_b32 v2, v112, v113 offset1:66
	s_waitcnt vmcnt(28)
	ds_write2_b32 v2, v114, v115 offset0:132 offset1:198
	s_waitcnt vmcnt(26)
	ds_write2_b32 v78, v116, v117 offset0:8 offset1:74
	s_waitcnt vmcnt(24)
	ds_write2_b32 v78, v118, v119 offset0:140 offset1:206
	v_add_u32_e32 v2, 0x840, v2
	v_add_u32_e32 v78, 0x400, v2
	s_waitcnt vmcnt(22)
	ds_write2_b32 v2, v120, v121 offset1:66
	s_waitcnt vmcnt(20)
	ds_write2_b32 v2, v122, v123 offset0:132 offset1:198
	s_waitcnt vmcnt(18)
	ds_write2_b32 v78, v124, v125 offset0:8 offset1:74
	s_waitcnt vmcnt(16)
	ds_write2_b32 v78, v126, v127 offset0:140 offset1:206
	v_add_u32_e32 v2, 0x840, v2
	v_add_u32_e32 v78, 0x400, v2
	s_waitcnt vmcnt(14)
	ds_write2_b32 v2, v128, v129 offset1:66
	s_waitcnt vmcnt(12)
	ds_write2_b32 v2, v130, v131 offset0:132 offset1:198
	s_waitcnt vmcnt(10)
	ds_write2_b32 v78, v132, v133 offset0:8 offset1:74
	s_waitcnt vmcnt(8)
	ds_write2_b32 v78, v134, v135 offset0:140 offset1:206
	v_add_u32_e32 v2, 0x840, v2
	v_add_u32_e32 v78, 0x400, v2
	s_waitcnt vmcnt(6)
	ds_write2_b32 v2, v136, v137 offset1:66
	s_waitcnt vmcnt(4)
	ds_write2_b32 v2, v138, v139 offset0:132 offset1:198
	s_waitcnt vmcnt(2)
	ds_write2_b32 v78, v140, v141 offset0:8 offset1:74
	s_waitcnt vmcnt(0)
	ds_write2_b32 v78, v142, v143 offset0:140 offset1:206
	v_add_u32_e32 v2, 0x840, v2
	s_mov_b32 s7, s5
	s_lshl_b64 s[6:7], s[6:7], 12
	s_add_u32 s4, s3, s6
	s_waitcnt lgkmcnt(0)
	s_addc_u32 s7, s16, s7
	s_and_b32 s6, 0xffff, s14
	ds_read2_b32 v[30:31], v5 offset0:33 offset1:41
	ds_read2_b32 v[32:33], v5 offset1:8
	ds_read2_b32 v[34:35], v5 offset0:66 offset1:74
	ds_read2_b32 v[36:37], v5 offset0:99 offset1:107
	ds_read2_b32 v[38:39], v5 offset0:132 offset1:140
	ds_read2_b32 v[40:41], v5 offset0:165 offset1:173
	ds_read2_b32 v[72:73], v5 offset0:198 offset1:206
	ds_read2_b32 v[74:75], v5 offset0:231 offset1:239
	s_lshl_b32 s6, s6, 1
	s_add_u32 s6, s4, s6
	s_addc_u32 s7, s7, 0
	v_lshlrev_b32_e32 v2, 1, v0
	v_lshl_add_u64 v[76:77], s[6:7], 0, v[2:3]
	v_lshlrev_b32_e32 v2, 1, v4
	s_waitcnt lgkmcnt(6)
	v_cvt_pk_bf16_f32 v26, v32, v30
	s_waitcnt lgkmcnt(4)
	v_cvt_pk_bf16_f32 v27, v34, v36
	s_waitcnt lgkmcnt(2)
	v_cvt_pk_bf16_f32 v28, v38, v40
	s_waitcnt lgkmcnt(0)
	v_cvt_pk_bf16_f32 v29, v72, v74
	v_lshl_add_u64 v[78:79], v[76:77], 0, v[2:3]
	global_store_dwordx4 v[78:79], v[26:29], off
	v_lshlrev_b32_e32 v2, 1, v6
	s_mov_b64 s[6:7], 0
	v_cvt_pk_bf16_f32 v26, v33, v31
	v_cvt_pk_bf16_f32 v27, v35, v37
	v_cvt_pk_bf16_f32 v28, v39, v41
	v_cvt_pk_bf16_f32 v29, v73, v75
	ds_read2_b32 v[32:33], v5 offset0:49 offset1:57
	ds_read2_b32 v[34:35], v5 offset0:16 offset1:24
	ds_read2_b32 v[36:37], v5 offset0:82 offset1:90
	ds_read2_b32 v[38:39], v5 offset0:115 offset1:123
	ds_read2_b32 v[40:41], v5 offset0:148 offset1:156
	ds_read2_b32 v[72:73], v5 offset0:181 offset1:189
	ds_read2_b32 v[74:75], v5 offset0:214 offset1:222
	ds_read2_b32 v[78:79], v5 offset0:247 offset1:255
	v_lshl_add_u64 v[30:31], v[76:77], 0, v[2:3]
	v_lshlrev_b32_e32 v2, 1, v8
	global_store_dwordx4 v[30:31], v[26:29], off
	v_lshl_add_u64 v[30:31], v[76:77], 0, v[2:3]
	v_lshlrev_b32_e32 v2, 1, v10
	s_waitcnt lgkmcnt(6)
	v_cvt_pk_bf16_f32 v26, v34, v32
	s_waitcnt lgkmcnt(4)
	v_cvt_pk_bf16_f32 v27, v36, v38
	s_waitcnt lgkmcnt(2)
	v_cvt_pk_bf16_f32 v28, v40, v72
	s_waitcnt lgkmcnt(0)
	v_cvt_pk_bf16_f32 v29, v74, v78
	global_store_dwordx4 v[30:31], v[26:29], off
	v_lshl_add_u64 v[30:31], v[76:77], 0, v[2:3]
	s_nop 0
	v_cvt_pk_bf16_f32 v26, v35, v33
	v_cvt_pk_bf16_f32 v27, v37, v39
	v_cvt_pk_bf16_f32 v28, v41, v73
	v_cvt_pk_bf16_f32 v29, v75, v79
	global_store_dwordx4 v[30:31], v[26:29], off
	s_waitcnt lgkmcnt(0)

; #define LAS __attribute__((address_space(3)))
; __device__ __forceinline__ unsigned cvtpk(float lo, float hi) { f32x2_t v = {lo, hi}; bf16x2_t b = __builtin_convertvector(v, bf16x2_t); return __builtin_bit_cast(unsigned, b); }
; #define NTL(p) __builtin_nontemporal_load(&(p))
; __device__ __forceinline__ void tr_item(const float* W, int N, int K, int k0, int n0, bf16_t* dst, LAS float* scr, int lane) {
; #pragma unroll 8
;     for (int i = 0; i < 32; ++i) { const int kk = 2 * i + (lane >> 5); scr[kk * 33 + (lane & 31)] = NTL(W[(size_t)(k0 + kk) * N + n0 + (lane & 31)]); }
;     asm volatile("s_waitcnt lgkmcnt(0)" ::: "memory");
;     const int c = lane & 7;
; #pragma unroll
;     for (int j = 0; j < 4; ++j) { const int n = (lane >> 3) + 8 * j; const LAS float* s = scr + (8 * c) * 33 + n;
;         u32x4 o; o.x = cvtpk(s[0 * 33], s[1 * 33]); o.y = cvtpk(s[2 * 33], s[3 * 33]); o.z = cvtpk(s[4 * 33], s[5 * 33]); o.w = cvtpk(s[6 * 33], s[7 * 33]);
;         *(u32x4*)(dst + (size_t)n * K + k0 + 8 * c) = o; }
;     asm volatile("s_waitcnt lgkmcnt(0)" ::: "memory");
.LBB0_177:
	v_lshl_add_u64 v[72:73], v[40:41], 0, s[6:7]
	v_lshl_add_u64 v[74:75], v[38:39], 0, s[6:7]
	v_lshl_add_u64 v[76:77], v[36:37], 0, s[6:7]
	v_lshl_add_u64 v[78:79], v[34:35], 0, s[6:7]
	v_lshl_add_u64 v[80:81], v[32:33], 0, s[6:7]
	v_lshl_add_u64 v[82:83], v[30:31], 0, s[6:7]
	v_lshl_add_u64 v[84:85], v[28:29], 0, s[6:7]
	v_lshl_add_u64 v[86:87], v[26:27], 0, s[6:7]
	global_load_dword v112, v[72:73], off nt
	global_load_dword v113, v[74:75], off nt
	global_load_dword v114, v[76:77], off nt
	global_load_dword v115, v[78:79], off nt
	global_load_dword v116, v[80:81], off nt
	global_load_dword v117, v[82:83], off nt
	global_load_dword v118, v[84:85], off nt
	global_load_dword v119, v[86:87], off nt
	s_add_u32 s6, s6, 0x20000
	s_addc_u32 s7, s7, 0
	v_lshl_add_u64 v[72:73], v[40:41], 0, s[6:7]
	v_lshl_add_u64 v[74:75], v[38:39], 0, s[6:7]
	v_lshl_add_u64 v[76:77], v[36:37], 0, s[6:7]
	v_lshl_add_u64 v[78:79], v[34:35], 0, s[6:7]
	v_lshl_add_u64 v[80:81], v[32:33], 0, s[6:7]
	v_lshl_add_u64 v[82:83], v[30:31], 0, s[6:7]
	v_lshl_add_u64 v[84:85], v[28:29], 0, s[6:7]
	v_lshl_add_u64 v[86:87], v[26:27], 0, s[6:7]
	global_load_dword v120, v[72:73], off nt
	global_load_dword v121, v[74:75], off nt
	global_load_dword v122, v[76:77], off nt
	global_load_dword v123, v[78:79], off nt
	global_load_dword v124, v[80:81], off nt
	global_load_dword v125, v[82:83], off nt
	global_load_dword v126, v[84:85], off nt
	global_load_dword v127, v[86:87], off nt
	s_add_u32 s6, s6, 0x20000
	s_addc_u32 s7, s7, 0
	v_lshl_add_u64 v[72:73], v[40:41], 0, s[6:7]
	v_lshl_add_u64 v[74:75], v[38:39], 0, s[6:7]
	v_lshl_add_u64 v[76:77], v[36:37], 0, s[6:7]
	v_lshl_add_u64 v[78:79], v[34:35], 0, s[6:7]
	v_lshl_add_u64 v[80:81], v[32:33], 0, s[6:7]
	v_lshl_add_u64 v[82:83], v[30:31], 0, s[6:7]
	v_lshl_add_u64 v[84:85], v[28:29], 0, s[6:7]
	v_lshl_add_u64 v[86:87], v[26:27], 0, s[6:7]
	global_load_dword v128, v[72:73], off nt
	global_load_dword v129, v[74:75], off nt
	global_load_dword v130, v[76:77], off nt
	global_load_dword v131, v[78:79], off nt
	global_load_dword v132, v[80:81], off nt
	global_load_dword v133, v[82:83], off nt
	global_load_dword v134, v[84:85], off nt
	global_load_dword v135, v[86:87], off nt
	s_add_u32 s6, s6, 0x20000
	s_addc_u32 s7, s7, 0
	v_lshl_add_u64 v[72:73], v[40:41], 0, s[6:7]
	v_lshl_add_u64 v[74:75], v[38:39], 0, s[6:7]
	v_lshl_add_u64 v[76:77], v[36:37], 0, s[6:7]
	v_lshl_add_u64 v[78:79], v[34:35], 0, s[6:7]
	v_lshl_add_u64 v[80:81], v[32:33], 0, s[6:7]
	v_lshl_add_u64 v[82:83], v[30:31], 0, s[6:7]
	v_lshl_add_u64 v[84:85], v[28:29], 0, s[6:7]
	v_lshl_add_u64 v[86:87], v[26:27], 0, s[6:7]
	global_load_dword v136, v[72:73], off nt
	global_load_dword v137, v[74:75], off nt
	global_load_dword v138, v[76:77], off nt
	global_load_dword v139, v[78:79], off nt
	global_load_dword v140, v[80:81], off nt
	global_load_dword v141, v[82:83], off nt
	global_load_dword v142, v[84:85], off nt
	global_load_dword v143, v[86:87], off nt
	s_add_u32 s6, s6, 0x20000
	s_addc_u32 s7, s7, 0
	v_add_u32_e32 v78, 0x400, v2
	s_waitcnt vmcnt(30)
	ds_write2_b32 v2, v112, v113 offset1:66
	s_waitcnt vmcnt(28)
	ds_write2_b32 v2, v114, v115 offset0:132 offset1:198
	s_waitcnt vmcnt(26)
	ds_write2_b32 v78, v116, v117 offset0:8 offset1:74
	s_waitcnt vmcnt(24)
	ds_write2_b32 v78, v118, v119 offset0:140 offset1:206
	v_add_u32_e32 v2, 0x840, v2
	v_add_u32_e32 v78, 0x400, v2
	s_waitcnt vmcnt(22)
	ds_write2_b32 v2, v120, v121 offset1:66
	s_waitcnt vmcnt(20)
	ds_write2_b32 v2, v122, v123 offset0:132 offset1:198
	s_waitcnt vmcnt(18)
	ds_write2_b32 v78, v124, v125 offset0:8 offset1:74
	s_waitcnt vmcnt(16)
	ds_write2_b32 v78, v126, v127 offset0:140 offset1:206
	v_add_u32_e32 v2, 0x840, v2
	v_add_u32_e32 v78, 0x400, v2
	s_waitcnt vmcnt(14)
	ds_write2_b32 v2, v128, v129 offset1:66
	s_waitcnt vmcnt(12)
	ds_write2_b32 v2, v130, v131 offset0:132 offset1:198
	s_waitcnt vmcnt(10)
	ds_write2_b32 v78, v132, v133 offset0:8 offset1:74
	s_waitcnt vmcnt(8)
	ds_write2_b32 v78, v134, v135 offset0:140 offset1:206
	v_add_u32_e32 v2, 0x840, v2
	v_add_u32_e32 v78, 0x400, v2
	s_waitcnt vmcnt(6)
	ds_write2_b32 v2, v136, v137 offset1:66
	s_waitcnt vmcnt(4)
	ds_write2_b32 v2, v138, v139 offset0:132 offset1:198
	s_waitcnt vmcnt(2)
	ds_write2_b32 v78, v140, v141 offset0:8 offset1:74
	s_waitcnt vmcnt(0)
	ds_write2_b32 v78, v142, v143 offset0:140 offset1:206
	v_add_u32_e32 v2, 0x840, v2
	s_and_b32 s4, s0, 0x3fc0
	s_lshl_b32 s6, s0, 17
	s_addk_i32 s4, 0xd000
	s_and_b32 s6, s6, 0x7e0000
	v_readlane_b32 s7, v245, 6
	s_waitcnt lgkmcnt(0)
	s_add_u32 s14, s7, s6
	v_readlane_b32 s6, v245, 7
	ds_read2_b32 v[30:31], v5 offset0:33 offset1:41
	ds_read2_b32 v[32:33], v5 offset1:8
	ds_read2_b32 v[34:35], v5 offset0:66 offset1:74
	ds_read2_b32 v[36:37], v5 offset0:99 offset1:107
	ds_read2_b32 v[38:39], v5 offset0:132 offset1:140
	ds_read2_b32 v[40:41], v5 offset0:165 offset1:173
	ds_read2_b32 v[72:73], v5 offset0:198 offset1:206
	ds_read2_b32 v[74:75], v5 offset0:231 offset1:239
	s_addc_u32 s15, s6, 0
	s_lshl_b64 s[6:7], s[4:5], 1
	s_add_u32 s6, s14, s6
	s_addc_u32 s7, s15, s7
	v_lshlrev_b32_e32 v2, 1, v0
	v_lshl_add_u64 v[76:77], s[6:7], 0, v[2:3]
	v_lshlrev_b32_e32 v2, 1, v4
	s_waitcnt lgkmcnt(6)
	v_cvt_pk_bf16_f32 v26, v32, v30
	s_waitcnt lgkmcnt(4)
	v_cvt_pk_bf16_f32 v27, v34, v36
	s_waitcnt lgkmcnt(2)
	v_cvt_pk_bf16_f32 v28, v38, v40
	s_waitcnt lgkmcnt(0)
	v_cvt_pk_bf16_f32 v29, v72, v74
	v_lshl_add_u64 v[78:79], v[76:77], 0, v[2:3]
	global_store_dwordx4 v[78:79], v[26:29], off
	v_lshlrev_b32_e32 v2, 1, v6
	s_nop 0
	v_cvt_pk_bf16_f32 v26, v33, v31
	v_cvt_pk_bf16_f32 v27, v35, v37
	v_cvt_pk_bf16_f32 v28, v39, v41
	v_cvt_pk_bf16_f32 v29, v73, v75
	ds_read2_b32 v[32:33], v5 offset0:49 offset1:57
	ds_read2_b32 v[34:35], v5 offset0:16 offset1:24
	ds_read2_b32 v[36:37], v5 offset0:82 offset1:90
	ds_read2_b32 v[38:39], v5 offset0:115 offset1:123
	ds_read2_b32 v[40:41], v5 offset0:148 offset1:156
	ds_read2_b32 v[72:73], v5 offset0:181 offset1:189
	ds_read2_b32 v[74:75], v5 offset0:214 offset1:222
	ds_read2_b32 v[78:79], v5 offset0:247 offset1:255
	v_lshl_add_u64 v[30:31], v[76:77], 0, v[2:3]
	v_lshlrev_b32_e32 v2, 1, v8
	global_store_dwordx4 v[30:31], v[26:29], off
	v_lshl_add_u64 v[30:31], v[76:77], 0, v[2:3]
	v_lshlrev_b32_e32 v2, 1, v10
	s_waitcnt lgkmcnt(6)
	v_cvt_pk_bf16_f32 v26, v34, v32
	s_waitcnt lgkmcnt(4)
	v_cvt_pk_bf16_f32 v27, v36, v38
	s_waitcnt lgkmcnt(2)
	v_cvt_pk_bf16_f32 v28, v40, v72
	s_waitcnt lgkmcnt(0)
	v_cvt_pk_bf16_f32 v29, v74, v78
	global_store_dwordx4 v[30:31], v[26:29], off
	v_lshl_add_u64 v[30:31], v[76:77], 0, v[2:3]
	s_nop 0
	v_cvt_pk_bf16_f32 v26, v35, v33
	v_cvt_pk_bf16_f32 v27, v37, v39
	v_cvt_pk_bf16_f32 v28, v41, v73
	v_cvt_pk_bf16_f32 v29, v75, v79
	global_store_dwordx4 v[30:31], v[26:29], off
	s_waitcnt lgkmcnt(0)

; #define LAS __attribute__((address_space(3)))
; __device__ __forceinline__ unsigned cvtpk(float lo, float hi) { f32x2_t v = {lo, hi}; bf16x2_t b = __builtin_convertvector(v, bf16x2_t); return __builtin_bit_cast(unsigned, b); }
; #define NTL(p) __builtin_nontemporal_load(&(p))
; __device__ __forceinline__ void tr_item(const float* W, int N, int K, int k0, int n0, bf16_t* dst, LAS float* scr, int lane) {
; #pragma unroll 8
;     for (int i = 0; i < 32; ++i) { const int kk = 2 * i + (lane >> 5); scr[kk * 33 + (lane & 31)] = NTL(W[(size_t)(k0 + kk) * N + n0 + (lane & 31)]); }
;     asm volatile("s_waitcnt lgkmcnt(0)" ::: "memory");
;     const int c = lane & 7;
; #pragma unroll
;     for (int j = 0; j < 4; ++j) { const int n = (lane >> 3) + 8 * j; const LAS float* s = scr + (8 * c) * 33 + n;
;         u32x4 o; o.x = cvtpk(s[0 * 33], s[1 * 33]); o.y = cvtpk(s[2 * 33], s[3 * 33]); o.z = cvtpk(s[4 * 33], s[5 * 33]); o.w = cvtpk(s[6 * 33], s[7 * 33]);
;         *(u32x4*)(dst + (size_t)n * K + k0 + 8 * c) = o; }
;     asm volatile("s_waitcnt lgkmcnt(0)" ::: "memory");
.LBB0_182:
	v_lshl_add_u64 v[72:73], v[40:41], 0, s[6:7]
	v_lshl_add_u64 v[74:75], v[38:39], 0, s[6:7]
	v_lshl_add_u64 v[76:77], v[36:37], 0, s[6:7]
	v_lshl_add_u64 v[78:79], v[34:35], 0, s[6:7]
	v_lshl_add_u64 v[80:81], v[32:33], 0, s[6:7]
	v_lshl_add_u64 v[82:83], v[30:31], 0, s[6:7]
	v_lshl_add_u64 v[84:85], v[28:29], 0, s[6:7]
	v_lshl_add_u64 v[86:87], v[26:27], 0, s[6:7]
	global_load_dword v112, v[72:73], off nt
	global_load_dword v113, v[74:75], off nt
	global_load_dword v114, v[76:77], off nt
	global_load_dword v115, v[78:79], off nt
	global_load_dword v116, v[80:81], off nt
	global_load_dword v117, v[82:83], off nt
	global_load_dword v118, v[84:85], off nt
	global_load_dword v119, v[86:87], off nt
	s_add_u32 s6, s6, 0x40000
	s_addc_u32 s7, s7, 0
	v_lshl_add_u64 v[72:73], v[40:41], 0, s[6:7]
	v_lshl_add_u64 v[74:75], v[38:39], 0, s[6:7]
	v_lshl_add_u64 v[76:77], v[36:37], 0, s[6:7]
	v_lshl_add_u64 v[78:79], v[34:35], 0, s[6:7]
	v_lshl_add_u64 v[80:81], v[32:33], 0, s[6:7]
	v_lshl_add_u64 v[82:83], v[30:31], 0, s[6:7]
	v_lshl_add_u64 v[84:85], v[28:29], 0, s[6:7]
	v_lshl_add_u64 v[86:87], v[26:27], 0, s[6:7]
	global_load_dword v120, v[72:73], off nt
	global_load_dword v121, v[74:75], off nt
	global_load_dword v122, v[76:77], off nt
	global_load_dword v123, v[78:79], off nt
	global_load_dword v124, v[80:81], off nt
	global_load_dword v125, v[82:83], off nt
	global_load_dword v126, v[84:85], off nt
	global_load_dword v127, v[86:87], off nt
	s_add_u32 s6, s6, 0x40000
	s_addc_u32 s7, s7, 0
	v_lshl_add_u64 v[72:73], v[40:41], 0, s[6:7]
	v_lshl_add_u64 v[74:75], v[38:39], 0, s[6:7]
	v_lshl_add_u64 v[76:77], v[36:37], 0, s[6:7]
	v_lshl_add_u64 v[78:79], v[34:35], 0, s[6:7]
	v_lshl_add_u64 v[80:81], v[32:33], 0, s[6:7]
	v_lshl_add_u64 v[82:83], v[30:31], 0, s[6:7]
	v_lshl_add_u64 v[84:85], v[28:29], 0, s[6:7]
	v_lshl_add_u64 v[86:87], v[26:27], 0, s[6:7]
	global_load_dword v128, v[72:73], off nt
	global_load_dword v129, v[74:75], off nt
	global_load_dword v130, v[76:77], off nt
	global_load_dword v131, v[78:79], off nt
	global_load_dword v132, v[80:81], off nt
	global_load_dword v133, v[82:83], off nt
	global_load_dword v134, v[84:85], off nt
	global_load_dword v135, v[86:87], off nt
	s_add_u32 s6, s6, 0x40000
	s_addc_u32 s7, s7, 0
	v_lshl_add_u64 v[72:73], v[40:41], 0, s[6:7]
	v_lshl_add_u64 v[74:75], v[38:39], 0, s[6:7]
	v_lshl_add_u64 v[76:77], v[36:37], 0, s[6:7]
	v_lshl_add_u64 v[78:79], v[34:35], 0, s[6:7]
	v_lshl_add_u64 v[80:81], v[32:33], 0, s[6:7]
	v_lshl_add_u64 v[82:83], v[30:31], 0, s[6:7]
	v_lshl_add_u64 v[84:85], v[28:29], 0, s[6:7]
	v_lshl_add_u64 v[86:87], v[26:27], 0, s[6:7]
	global_load_dword v136, v[72:73], off nt
	global_load_dword v137, v[74:75], off nt
	global_load_dword v138, v[76:77], off nt
	global_load_dword v139, v[78:79], off nt
	global_load_dword v140, v[80:81], off nt
	global_load_dword v141, v[82:83], off nt
	global_load_dword v142, v[84:85], off nt
	global_load_dword v143, v[86:87], off nt
	s_add_u32 s6, s6, 0x40000
	s_addc_u32 s7, s7, 0
	v_add_u32_e32 v78, 0x400, v2
	s_waitcnt vmcnt(30)
	ds_write2_b32 v2, v112, v113 offset1:66
	s_waitcnt vmcnt(28)
	ds_write2_b32 v2, v114, v115 offset0:132 offset1:198
	s_waitcnt vmcnt(26)
	ds_write2_b32 v78, v116, v117 offset0:8 offset1:74
	s_waitcnt vmcnt(24)
	ds_write2_b32 v78, v118, v119 offset0:140 offset1:206
	v_add_u32_e32 v2, 0x840, v2
	v_add_u32_e32 v78, 0x400, v2
	s_waitcnt vmcnt(22)
	ds_write2_b32 v2, v120, v121 offset1:66
	s_waitcnt vmcnt(20)
	ds_write2_b32 v2, v122, v123 offset0:132 offset1:198
	s_waitcnt vmcnt(18)
	ds_write2_b32 v78, v124, v125 offset0:8 offset1:74
	s_waitcnt vmcnt(16)
	ds_write2_b32 v78, v126, v127 offset0:140 offset1:206
	v_add_u32_e32 v2, 0x840, v2
	v_add_u32_e32 v78, 0x400, v2
	s_waitcnt vmcnt(14)
	ds_write2_b32 v2, v128, v129 offset1:66
	s_waitcnt vmcnt(12)
	ds_write2_b32 v2, v130, v131 offset0:132 offset1:198
	s_waitcnt vmcnt(10)
	ds_write2_b32 v78, v132, v133 offset0:8 offset1:74
	s_waitcnt vmcnt(8)
	ds_write2_b32 v78, v134, v135 offset0:140 offset1:206
	v_add_u32_e32 v2, 0x840, v2
	v_add_u32_e32 v78, 0x400, v2
	s_waitcnt vmcnt(6)
	ds_write2_b32 v2, v136, v137 offset1:66
	s_waitcnt vmcnt(4)
	ds_write2_b32 v2, v138, v139 offset0:132 offset1:198
	s_waitcnt vmcnt(2)
	ds_write2_b32 v78, v140, v141 offset0:8 offset1:74
	s_waitcnt vmcnt(0)
	ds_write2_b32 v78, v142, v143 offset0:140 offset1:206
	v_add_u32_e32 v2, 0x840, v2
	s_lshl_b32 s6, s0, 17
	s_add_i32 s4, s0, 0xffffe000
	s_and_b32 s6, s6, 0xfe0000
	v_readlane_b32 s7, v245, 4
	s_waitcnt lgkmcnt(0)
	s_add_u32 s6, s7, s6
	v_readlane_b32 s7, v245, 5
	ds_read2_b32 v[30:31], v5 offset0:33 offset1:41
	ds_read2_b32 v[32:33], v5 offset1:8
	ds_read2_b32 v[34:35], v5 offset0:66 offset1:74
	ds_read2_b32 v[36:37], v5 offset0:99 offset1:107
	ds_read2_b32 v[38:39], v5 offset0:132 offset1:140
	ds_read2_b32 v[40:41], v5 offset0:165 offset1:173
	ds_read2_b32 v[72:73], v5 offset0:198 offset1:206
	ds_read2_b32 v[74:75], v5 offset0:231 offset1:239
	s_addc_u32 s7, s7, 0
	s_and_b32 s4, s4, 0xffffff80
	s_add_u32 s6, s6, s4
	s_addc_u32 s7, s7, 0
	v_lshlrev_b32_e32 v2, 1, v0
	v_lshl_add_u64 v[76:77], s[6:7], 0, v[2:3]
	v_lshlrev_b32_e32 v2, 1, v4
	s_waitcnt lgkmcnt(6)
	v_cvt_pk_bf16_f32 v26, v32, v30
	s_waitcnt lgkmcnt(4)
	v_cvt_pk_bf16_f32 v27, v34, v36
	s_waitcnt lgkmcnt(2)
	v_cvt_pk_bf16_f32 v28, v38, v40
	s_waitcnt lgkmcnt(0)
	v_cvt_pk_bf16_f32 v29, v72, v74
	v_lshl_add_u64 v[78:79], v[76:77], 0, v[2:3]
	global_store_dwordx4 v[78:79], v[26:29], off
	v_lshlrev_b32_e32 v2, 1, v6
	s_nop 0
	v_cvt_pk_bf16_f32 v26, v33, v31
	v_cvt_pk_bf16_f32 v27, v35, v37
	v_cvt_pk_bf16_f32 v28, v39, v41
	v_cvt_pk_bf16_f32 v29, v73, v75
	ds_read2_b32 v[32:33], v5 offset0:49 offset1:57
	ds_read2_b32 v[34:35], v5 offset0:16 offset1:24
	ds_read2_b32 v[36:37], v5 offset0:82 offset1:90
	ds_read2_b32 v[38:39], v5 offset0:115 offset1:123
	ds_read2_b32 v[40:41], v5 offset0:148 offset1:156
	ds_read2_b32 v[72:73], v5 offset0:181 offset1:189
	ds_read2_b32 v[74:75], v5 offset0:214 offset1:222
	ds_read2_b32 v[78:79], v5 offset0:247 offset1:255
	v_lshl_add_u64 v[30:31], v[76:77], 0, v[2:3]
	v_lshlrev_b32_e32 v2, 1, v8
	global_store_dwordx4 v[30:31], v[26:29], off
	v_lshl_add_u64 v[30:31], v[76:77], 0, v[2:3]
	v_lshlrev_b32_e32 v2, 1, v10
	s_waitcnt lgkmcnt(6)
	v_cvt_pk_bf16_f32 v26, v34, v32
	s_waitcnt lgkmcnt(4)
	v_cvt_pk_bf16_f32 v27, v36, v38
	s_waitcnt lgkmcnt(2)
	v_cvt_pk_bf16_f32 v28, v40, v72
	s_waitcnt lgkmcnt(0)
	v_cvt_pk_bf16_f32 v29, v74, v78
	global_store_dwordx4 v[30:31], v[26:29], off
	v_lshl_add_u64 v[30:31], v[76:77], 0, v[2:3]
	s_nop 0
	v_cvt_pk_bf16_f32 v26, v35, v33
	v_cvt_pk_bf16_f32 v27, v37, v39
	v_cvt_pk_bf16_f32 v28, v41, v73
	v_cvt_pk_bf16_f32 v29, v75, v79
	global_store_dwordx4 v[30:31], v[26:29], off
	s_waitcnt lgkmcnt(0)

; #define LAS __attribute__((address_space(3)))
; __device__ __forceinline__ unsigned cvtpk(float lo, float hi) { f32x2_t v = {lo, hi}; bf16x2_t b = __builtin_convertvector(v, bf16x2_t); return __builtin_bit_cast(unsigned, b); }
; #define NTL(p) __builtin_nontemporal_load(&(p))
; __device__ __forceinline__ void tr_item(const float* W, int N, int K, int k0, int n0, bf16_t* dst, LAS float* scr, int lane) {
; #pragma unroll 8
;     for (int i = 0; i < 32; ++i) { const int kk = 2 * i + (lane >> 5); scr[kk * 33 + (lane & 31)] = NTL(W[(size_t)(k0 + kk) * N + n0 + (lane & 31)]); }
;     asm volatile("s_waitcnt lgkmcnt(0)" ::: "memory");
;     const int c = lane & 7;
; #pragma unroll
;     for (int j = 0; j < 4; ++j) { const int n = (lane >> 3) + 8 * j; const LAS float* s = scr + (8 * c) * 33 + n;
;         u32x4 o; o.x = cvtpk(s[0 * 33], s[1 * 33]); o.y = cvtpk(s[2 * 33], s[3 * 33]); o.z = cvtpk(s[4 * 33], s[5 * 33]); o.w = cvtpk(s[6 * 33], s[7 * 33]);
;         *(u32x4*)(dst + (size_t)n * K + k0 + 8 * c) = o; }
;     asm volatile("s_waitcnt lgkmcnt(0)" ::: "memory");
.LBB0_187:
	v_lshl_add_u64 v[72:73], v[40:41], 0, s[6:7]
	v_lshl_add_u64 v[74:75], v[38:39], 0, s[6:7]
	v_lshl_add_u64 v[76:77], v[36:37], 0, s[6:7]
	v_lshl_add_u64 v[78:79], v[34:35], 0, s[6:7]
	v_lshl_add_u64 v[80:81], v[32:33], 0, s[6:7]
	v_lshl_add_u64 v[82:83], v[30:31], 0, s[6:7]
	v_lshl_add_u64 v[84:85], v[28:29], 0, s[6:7]
	v_lshl_add_u64 v[86:87], v[26:27], 0, s[6:7]
	global_load_dword v112, v[72:73], off nt
	global_load_dword v113, v[74:75], off nt
	global_load_dword v114, v[76:77], off nt
	global_load_dword v115, v[78:79], off nt
	global_load_dword v116, v[80:81], off nt
	global_load_dword v117, v[82:83], off nt
	global_load_dword v118, v[84:85], off nt
	global_load_dword v119, v[86:87], off nt
	s_add_u32 s6, s6, 0x20000
	s_addc_u32 s7, s7, 0
	v_lshl_add_u64 v[72:73], v[40:41], 0, s[6:7]
	v_lshl_add_u64 v[74:75], v[38:39], 0, s[6:7]
	v_lshl_add_u64 v[76:77], v[36:37], 0, s[6:7]
	v_lshl_add_u64 v[78:79], v[34:35], 0, s[6:7]
	v_lshl_add_u64 v[80:81], v[32:33], 0, s[6:7]
	v_lshl_add_u64 v[82:83], v[30:31], 0, s[6:7]
	v_lshl_add_u64 v[84:85], v[28:29], 0, s[6:7]
	v_lshl_add_u64 v[86:87], v[26:27], 0, s[6:7]
	global_load_dword v120, v[72:73], off nt
	global_load_dword v121, v[74:75], off nt
	global_load_dword v122, v[76:77], off nt
	global_load_dword v123, v[78:79], off nt
	global_load_dword v124, v[80:81], off nt
	global_load_dword v125, v[82:83], off nt
	global_load_dword v126, v[84:85], off nt
	global_load_dword v127, v[86:87], off nt
	s_add_u32 s6, s6, 0x20000
	s_addc_u32 s7, s7, 0
	v_lshl_add_u64 v[72:73], v[40:41], 0, s[6:7]
	v_lshl_add_u64 v[74:75], v[38:39], 0, s[6:7]
	v_lshl_add_u64 v[76:77], v[36:37], 0, s[6:7]
	v_lshl_add_u64 v[78:79], v[34:35], 0, s[6:7]
	v_lshl_add_u64 v[80:81], v[32:33], 0, s[6:7]
	v_lshl_add_u64 v[82:83], v[30:31], 0, s[6:7]
	v_lshl_add_u64 v[84:85], v[28:29], 0, s[6:7]
	v_lshl_add_u64 v[86:87], v[26:27], 0, s[6:7]
	global_load_dword v128, v[72:73], off nt
	global_load_dword v129, v[74:75], off nt
	global_load_dword v130, v[76:77], off nt
	global_load_dword v131, v[78:79], off nt
	global_load_dword v132, v[80:81], off nt
	global_load_dword v133, v[82:83], off nt
	global_load_dword v134, v[84:85], off nt
	global_load_dword v135, v[86:87], off nt
	s_add_u32 s6, s6, 0x20000
	s_addc_u32 s7, s7, 0
	v_lshl_add_u64 v[72:73], v[40:41], 0, s[6:7]
	v_lshl_add_u64 v[74:75], v[38:39], 0, s[6:7]
	v_lshl_add_u64 v[76:77], v[36:37], 0, s[6:7]
	v_lshl_add_u64 v[78:79], v[34:35], 0, s[6:7]
	v_lshl_add_u64 v[80:81], v[32:33], 0, s[6:7]
	v_lshl_add_u64 v[82:83], v[30:31], 0, s[6:7]
	v_lshl_add_u64 v[84:85], v[28:29], 0, s[6:7]
	v_lshl_add_u64 v[86:87], v[26:27], 0, s[6:7]
	global_load_dword v136, v[72:73], off nt
	global_load_dword v137, v[74:75], off nt
	global_load_dword v138, v[76:77], off nt
	global_load_dword v139, v[78:79], off nt
	global_load_dword v140, v[80:81], off nt
	global_load_dword v141, v[82:83], off nt
	global_load_dword v142, v[84:85], off nt
	global_load_dword v143, v[86:87], off nt
	s_add_u32 s6, s6, 0x20000
	s_addc_u32 s7, s7, 0
	v_add_u32_e32 v78, 0x400, v2
	s_waitcnt vmcnt(30)
	ds_write2_b32 v2, v112, v113 offset1:66
	s_waitcnt vmcnt(28)
	ds_write2_b32 v2, v114, v115 offset0:132 offset1:198
	s_waitcnt vmcnt(26)
	ds_write2_b32 v78, v116, v117 offset0:8 offset1:74
	s_waitcnt vmcnt(24)
	ds_write2_b32 v78, v118, v119 offset0:140 offset1:206
	v_add_u32_e32 v2, 0x840, v2
	v_add_u32_e32 v78, 0x400, v2
	s_waitcnt vmcnt(22)
	ds_write2_b32 v2, v120, v121 offset1:66
	s_waitcnt vmcnt(20)
	ds_write2_b32 v2, v122, v123 offset0:132 offset1:198
	s_waitcnt vmcnt(18)
	ds_write2_b32 v78, v124, v125 offset0:8 offset1:74
	s_waitcnt vmcnt(16)
	ds_write2_b32 v78, v126, v127 offset0:140 offset1:206
	v_add_u32_e32 v2, 0x840, v2
	v_add_u32_e32 v78, 0x400, v2
	s_waitcnt vmcnt(14)
	ds_write2_b32 v2, v128, v129 offset1:66
	s_waitcnt vmcnt(12)
	ds_write2_b32 v2, v130, v131 offset0:132 offset1:198
	s_waitcnt vmcnt(10)
	ds_write2_b32 v78, v132, v133 offset0:8 offset1:74
	s_waitcnt vmcnt(8)
	ds_write2_b32 v78, v134, v135 offset0:140 offset1:206
	v_add_u32_e32 v2, 0x840, v2
	v_add_u32_e32 v78, 0x400, v2
	s_waitcnt vmcnt(6)
	ds_write2_b32 v2, v136, v137 offset1:66
	s_waitcnt vmcnt(4)
	ds_write2_b32 v2, v138, v139 offset0:132 offset1:198
	s_waitcnt vmcnt(2)
	ds_write2_b32 v78, v140, v141 offset0:8 offset1:74
	s_waitcnt vmcnt(0)
	ds_write2_b32 v78, v142, v143 offset0:140 offset1:206
	v_add_u32_e32 v2, 0x840, v2
	s_and_b32 s4, s0, 0x1fc0
	s_lshl_b32 s6, s0, 17
	s_addk_i32 s4, 0xe800
	s_and_b32 s6, s6, 0x7e0000
	s_waitcnt lgkmcnt(0)
	s_add_u32 s14, s58, s6
	ds_read2_b32 v[30:31], v5 offset0:33 offset1:41
	ds_read2_b32 v[32:33], v5 offset1:8
	ds_read2_b32 v[34:35], v5 offset0:66 offset1:74
	ds_read2_b32 v[36:37], v5 offset0:99 offset1:107
	ds_read2_b32 v[38:39], v5 offset0:132 offset1:140
	ds_read2_b32 v[40:41], v5 offset0:165 offset1:173
	ds_read2_b32 v[72:73], v5 offset0:198 offset1:206
	ds_read2_b32 v[74:75], v5 offset0:231 offset1:239
	s_addc_u32 s15, s59, 0
	s_lshl_b64 s[6:7], s[4:5], 1
	s_add_u32 s6, s14, s6
	s_addc_u32 s7, s15, s7
	v_lshlrev_b32_e32 v2, 1, v0
	v_lshl_add_u64 v[76:77], s[6:7], 0, v[2:3]
	v_lshlrev_b32_e32 v2, 1, v4
	s_waitcnt lgkmcnt(6)
	v_cvt_pk_bf16_f32 v26, v32, v30
	s_waitcnt lgkmcnt(4)
	v_cvt_pk_bf16_f32 v27, v34, v36
	s_waitcnt lgkmcnt(2)
	v_cvt_pk_bf16_f32 v28, v38, v40
	s_waitcnt lgkmcnt(0)
	v_cvt_pk_bf16_f32 v29, v72, v74
	v_lshl_add_u64 v[78:79], v[76:77], 0, v[2:3]
	global_store_dwordx4 v[78:79], v[26:29], off
	v_lshlrev_b32_e32 v2, 1, v6
	s_nop 0
	v_cvt_pk_bf16_f32 v26, v33, v31
	v_cvt_pk_bf16_f32 v27, v35, v37
	v_cvt_pk_bf16_f32 v28, v39, v41
	v_cvt_pk_bf16_f32 v29, v73, v75
	ds_read2_b32 v[32:33], v5 offset0:49 offset1:57
	ds_read2_b32 v[34:35], v5 offset0:16 offset1:24
	ds_read2_b32 v[36:37], v5 offset0:82 offset1:90
	ds_read2_b32 v[38:39], v5 offset0:115 offset1:123
	ds_read2_b32 v[40:41], v5 offset0:148 offset1:156
	ds_read2_b32 v[72:73], v5 offset0:181 offset1:189
	ds_read2_b32 v[74:75], v5 offset0:214 offset1:222
	ds_read2_b32 v[78:79], v5 offset0:247 offset1:255
	v_lshl_add_u64 v[30:31], v[76:77], 0, v[2:3]
	v_lshlrev_b32_e32 v2, 1, v8
	global_store_dwordx4 v[30:31], v[26:29], off
	v_lshl_add_u64 v[30:31], v[76:77], 0, v[2:3]
	v_lshlrev_b32_e32 v2, 1, v10
	s_waitcnt lgkmcnt(6)
	v_cvt_pk_bf16_f32 v26, v34, v32
	s_waitcnt lgkmcnt(4)
	v_cvt_pk_bf16_f32 v27, v36, v38
	s_waitcnt lgkmcnt(2)
	v_cvt_pk_bf16_f32 v28, v40, v72
	s_waitcnt lgkmcnt(0)
	v_cvt_pk_bf16_f32 v29, v74, v78
	global_store_dwordx4 v[30:31], v[26:29], off
	v_lshl_add_u64 v[30:31], v[76:77], 0, v[2:3]
	s_nop 0
	v_cvt_pk_bf16_f32 v26, v35, v33
	v_cvt_pk_bf16_f32 v27, v37, v39
	v_cvt_pk_bf16_f32 v28, v41, v73
	v_cvt_pk_bf16_f32 v29, v75, v79
	global_store_dwordx4 v[30:31], v[26:29], off
	s_waitcnt lgkmcnt(0)

; #define LAS __attribute__((address_space(3)))
; __device__ __forceinline__ unsigned cvtpk(float lo, float hi) { f32x2_t v = {lo, hi}; bf16x2_t b = __builtin_convertvector(v, bf16x2_t); return __builtin_bit_cast(unsigned, b); }
; #define NTL(p) __builtin_nontemporal_load(&(p))
; __device__ __forceinline__ void tr_item(const float* W, int N, int K, int k0, int n0, bf16_t* dst, LAS float* scr, int lane) {
; #pragma unroll 8
;     for (int i = 0; i < 32; ++i) { const int kk = 2 * i + (lane >> 5); scr[kk * 33 + (lane & 31)] = NTL(W[(size_t)(k0 + kk) * N + n0 + (lane & 31)]); }
;     asm volatile("s_waitcnt lgkmcnt(0)" ::: "memory");
;     const int c = lane & 7;
; #pragma unroll
;     for (int j = 0; j < 4; ++j) { const int n = (lane >> 3) + 8 * j; const LAS float* s = scr + (8 * c) * 33 + n;
;         u32x4 o; o.x = cvtpk(s[0 * 33], s[1 * 33]); o.y = cvtpk(s[2 * 33], s[3 * 33]); o.z = cvtpk(s[4 * 33], s[5 * 33]); o.w = cvtpk(s[6 * 33], s[7 * 33]);
;         *(u32x4*)(dst + (size_t)n * K + k0 + 8 * c) = o; }
;     asm volatile("s_waitcnt lgkmcnt(0)" ::: "memory");
.LBB0_204:
	v_lshl_add_u64 v[72:73], v[40:41], 0, s[20:21]
	v_lshl_add_u64 v[74:75], v[38:39], 0, s[20:21]
	v_lshl_add_u64 v[76:77], v[36:37], 0, s[20:21]
	v_lshl_add_u64 v[78:79], v[34:35], 0, s[20:21]
	v_lshl_add_u64 v[80:81], v[32:33], 0, s[20:21]
	v_lshl_add_u64 v[82:83], v[30:31], 0, s[20:21]
	v_lshl_add_u64 v[84:85], v[28:29], 0, s[20:21]
	v_lshl_add_u64 v[86:87], v[26:27], 0, s[20:21]
	global_load_dword v112, v[72:73], off nt
	global_load_dword v113, v[74:75], off nt
	global_load_dword v114, v[76:77], off nt
	global_load_dword v115, v[78:79], off nt
	global_load_dword v116, v[80:81], off nt
	global_load_dword v117, v[82:83], off nt
	global_load_dword v118, v[84:85], off nt
	global_load_dword v119, v[86:87], off nt
	s_add_u32 s20, s20, 0x60000
	s_addc_u32 s21, s21, 0
	v_lshl_add_u64 v[72:73], v[40:41], 0, s[20:21]
	v_lshl_add_u64 v[74:75], v[38:39], 0, s[20:21]
	v_lshl_add_u64 v[76:77], v[36:37], 0, s[20:21]
	v_lshl_add_u64 v[78:79], v[34:35], 0, s[20:21]
	v_lshl_add_u64 v[80:81], v[32:33], 0, s[20:21]
	v_lshl_add_u64 v[82:83], v[30:31], 0, s[20:21]
	v_lshl_add_u64 v[84:85], v[28:29], 0, s[20:21]
	v_lshl_add_u64 v[86:87], v[26:27], 0, s[20:21]
	global_load_dword v120, v[72:73], off nt
	global_load_dword v121, v[74:75], off nt
	global_load_dword v122, v[76:77], off nt
	global_load_dword v123, v[78:79], off nt
	global_load_dword v124, v[80:81], off nt
	global_load_dword v125, v[82:83], off nt
	global_load_dword v126, v[84:85], off nt
	global_load_dword v127, v[86:87], off nt
	s_add_u32 s20, s20, 0x60000
	s_addc_u32 s21, s21, 0
	v_lshl_add_u64 v[72:73], v[40:41], 0, s[20:21]
	v_lshl_add_u64 v[74:75], v[38:39], 0, s[20:21]
	v_lshl_add_u64 v[76:77], v[36:37], 0, s[20:21]
	v_lshl_add_u64 v[78:79], v[34:35], 0, s[20:21]
	v_lshl_add_u64 v[80:81], v[32:33], 0, s[20:21]
	v_lshl_add_u64 v[82:83], v[30:31], 0, s[20:21]
	v_lshl_add_u64 v[84:85], v[28:29], 0, s[20:21]
	v_lshl_add_u64 v[86:87], v[26:27], 0, s[20:21]
	global_load_dword v128, v[72:73], off nt
	global_load_dword v129, v[74:75], off nt
	global_load_dword v130, v[76:77], off nt
	global_load_dword v131, v[78:79], off nt
	global_load_dword v132, v[80:81], off nt
	global_load_dword v133, v[82:83], off nt
	global_load_dword v134, v[84:85], off nt
	global_load_dword v135, v[86:87], off nt
	s_add_u32 s20, s20, 0x60000
	s_addc_u32 s21, s21, 0
	v_lshl_add_u64 v[72:73], v[40:41], 0, s[20:21]
	v_lshl_add_u64 v[74:75], v[38:39], 0, s[20:21]
	v_lshl_add_u64 v[76:77], v[36:37], 0, s[20:21]
	v_lshl_add_u64 v[78:79], v[34:35], 0, s[20:21]
	v_lshl_add_u64 v[80:81], v[32:33], 0, s[20:21]
	v_lshl_add_u64 v[82:83], v[30:31], 0, s[20:21]
	v_lshl_add_u64 v[84:85], v[28:29], 0, s[20:21]
	v_lshl_add_u64 v[86:87], v[26:27], 0, s[20:21]
	global_load_dword v136, v[72:73], off nt
	global_load_dword v137, v[74:75], off nt
	global_load_dword v138, v[76:77], off nt
	global_load_dword v139, v[78:79], off nt
	global_load_dword v140, v[80:81], off nt
	global_load_dword v141, v[82:83], off nt
	global_load_dword v142, v[84:85], off nt
	global_load_dword v143, v[86:87], off nt
	s_add_u32 s20, s20, 0x60000
	s_addc_u32 s21, s21, 0
	v_add_u32_e32 v78, 0x400, v2
	s_waitcnt vmcnt(30)
	ds_write2_b32 v2, v112, v113 offset1:66
	s_waitcnt vmcnt(28)
	ds_write2_b32 v2, v114, v115 offset0:132 offset1:198
	s_waitcnt vmcnt(26)
	ds_write2_b32 v78, v116, v117 offset0:8 offset1:74
	s_waitcnt vmcnt(24)
	ds_write2_b32 v78, v118, v119 offset0:140 offset1:206
	v_add_u32_e32 v2, 0x840, v2
	v_add_u32_e32 v78, 0x400, v2
	s_waitcnt vmcnt(22)
	ds_write2_b32 v2, v120, v121 offset1:66
	s_waitcnt vmcnt(20)
	ds_write2_b32 v2, v122, v123 offset0:132 offset1:198
	s_waitcnt vmcnt(18)
	ds_write2_b32 v78, v124, v125 offset0:8 offset1:74
	s_waitcnt vmcnt(16)
	ds_write2_b32 v78, v126, v127 offset0:140 offset1:206
	v_add_u32_e32 v2, 0x840, v2
	v_add_u32_e32 v78, 0x400, v2
	s_waitcnt vmcnt(14)
	ds_write2_b32 v2, v128, v129 offset1:66
	s_waitcnt vmcnt(12)
	ds_write2_b32 v2, v130, v131 offset0:132 offset1:198
	s_waitcnt vmcnt(10)
	ds_write2_b32 v78, v132, v133 offset0:8 offset1:74
	s_waitcnt vmcnt(8)
	ds_write2_b32 v78, v134, v135 offset0:140 offset1:206
	v_add_u32_e32 v2, 0x840, v2
	v_add_u32_e32 v78, 0x400, v2
	s_waitcnt vmcnt(6)
	ds_write2_b32 v2, v136, v137 offset1:66
	s_waitcnt vmcnt(4)
	ds_write2_b32 v2, v138, v139 offset0:132 offset1:198
	s_waitcnt vmcnt(2)
	ds_write2_b32 v78, v140, v141 offset0:8 offset1:74
	s_waitcnt vmcnt(0)
	ds_write2_b32 v78, v142, v143 offset0:140 offset1:206
	v_add_u32_e32 v2, 0x840, v2
	s_lshl_b64 s[6:7], s[6:7], 12
	s_add_u32 s4, s18, s6
	s_waitcnt lgkmcnt(0)
	s_addc_u32 s14, s19, s7
	s_ashr_i32 s39, s38, 31
	ds_read2_b32 v[30:31], v5 offset0:33 offset1:41
	ds_read2_b32 v[32:33], v5 offset1:8
	ds_read2_b32 v[34:35], v5 offset0:66 offset1:74
	ds_read2_b32 v[36:37], v5 offset0:99 offset1:107
	ds_read2_b32 v[38:39], v5 offset0:132 offset1:140
	ds_read2_b32 v[40:41], v5 offset0:165 offset1:173
	ds_read2_b32 v[72:73], v5 offset0:198 offset1:206
	ds_read2_b32 v[74:75], v5 offset0:231 offset1:239
	s_lshl_b64 s[6:7], s[38:39], 1
	s_add_u32 s6, s4, s6
	s_addc_u32 s7, s14, s7
	v_lshlrev_b32_e32 v2, 1, v0
	v_lshl_add_u64 v[76:77], s[6:7], 0, v[2:3]
	v_lshlrev_b32_e32 v2, 1, v4
	s_waitcnt lgkmcnt(6)
	v_cvt_pk_bf16_f32 v26, v32, v30
	s_waitcnt lgkmcnt(4)
	v_cvt_pk_bf16_f32 v27, v34, v36
	s_waitcnt lgkmcnt(2)
	v_cvt_pk_bf16_f32 v28, v38, v40
	s_waitcnt lgkmcnt(0)
	v_cvt_pk_bf16_f32 v29, v72, v74
	v_lshl_add_u64 v[78:79], v[76:77], 0, v[2:3]
	global_store_dwordx4 v[78:79], v[26:29], off
	v_lshlrev_b32_e32 v2, 1, v6
	s_nop 0
	v_cvt_pk_bf16_f32 v26, v33, v31
	v_cvt_pk_bf16_f32 v27, v35, v37
	v_cvt_pk_bf16_f32 v28, v39, v41
	v_cvt_pk_bf16_f32 v29, v73, v75
	ds_read2_b32 v[32:33], v5 offset0:49 offset1:57
	ds_read2_b32 v[34:35], v5 offset0:16 offset1:24
	ds_read2_b32 v[36:37], v5 offset0:82 offset1:90
	ds_read2_b32 v[38:39], v5 offset0:115 offset1:123
	ds_read2_b32 v[40:41], v5 offset0:148 offset1:156
	ds_read2_b32 v[72:73], v5 offset0:181 offset1:189
	ds_read2_b32 v[74:75], v5 offset0:214 offset1:222
	ds_read2_b32 v[78:79], v5 offset0:247 offset1:255
	v_lshl_add_u64 v[30:31], v[76:77], 0, v[2:3]
	v_lshlrev_b32_e32 v2, 1, v8
	global_store_dwordx4 v[30:31], v[26:29], off
	v_lshl_add_u64 v[30:31], v[76:77], 0, v[2:3]
	v_lshlrev_b32_e32 v2, 1, v10
	s_waitcnt lgkmcnt(6)
	v_cvt_pk_bf16_f32 v26, v34, v32
	s_waitcnt lgkmcnt(4)
	v_cvt_pk_bf16_f32 v27, v36, v38
	s_waitcnt lgkmcnt(2)
	v_cvt_pk_bf16_f32 v28, v40, v72
	s_waitcnt lgkmcnt(0)
	v_cvt_pk_bf16_f32 v29, v74, v78
	global_store_dwordx4 v[30:31], v[26:29], off
	v_lshl_add_u64 v[30:31], v[76:77], 0, v[2:3]
	s_nop 0
	v_cvt_pk_bf16_f32 v26, v35, v33
	v_cvt_pk_bf16_f32 v27, v37, v39
	v_cvt_pk_bf16_f32 v28, v41, v73
	v_cvt_pk_bf16_f32 v29, v75, v79
	global_store_dwordx4 v[30:31], v[26:29], off
	s_waitcnt lgkmcnt(0)
	s_branch .LBB0_158

; #define PG8_STAGE(bufoff, gbase, voff) do { _Pragma("unroll") for (int _i = 0; _i < 2; ++_i) \
;         __builtin_amdgcn_global_load_lds((const unsigned*)((const char*)(gbase) + (voff)[_i]), (LAS unsigned*)(lds + (bufoff) + ldsw + _i * 8192), 16, 0, 0); } while (0)
; #define PG8_LDA(dst, b, h) do { _Pragma("unroll") for (int m = 0; m < 4; ++m) _Pragma("unroll") for (int k = 0; k < 2; ++k) dst[m][k] = *(const LAS bf16x8*)(lds + PG8_SA(b, h) + aoff + m * 2048 + k * 1024); } while (0)
; #define PG8_LDB(dst, b, h) do { _Pragma("unroll") for (int n = 0; n < 2; ++n) _Pragma("unroll") for (int k = 0; k < 2; ++k) dst[n][k] = *(const LAS bf16x8*)(lds + PG8_SB(b, h) + boff + n * 2048 + k * 1024); } while (0)
; #define PG8_MMA(ai, bj, At, Bt) do { __builtin_amdgcn_s_setprio(1); _Pragma("unroll") for (int m = 0; m < 4; ++m) _Pragma("unroll") for (int n = 0; n < 2; ++n) _Pragma("unroll") for (int k = 0; k < 2; ++k) \
;         acc[ai][bj][m][n] = __builtin_amdgcn_mfma_f32_16x16x32_bf16(Bt[n][k], At[m][k], acc[ai][bj][m][n], 0, 0, 0); __builtin_amdgcn_s_setprio(0); } while (0)
; #define PG8_WAIT_V(n) asm volatile("s_waitcnt vmcnt(" #n ")" ::: "memory")
; #define PG8_WAIT_L(n) asm volatile("s_waitcnt lgkmcnt(" #n ")" ::: "memory")
; #define PG8_BAR __builtin_amdgcn_s_barrier()
; #define PG8_SCHED __builtin_amdgcn_sched_barrier(0)
; template <int GI>
; __device__ __forceinline__ void gemm_phase(LAS unsigned char* lds, unsigned char* ws, int G, int cblk) {
;     ...
;             PG8_LDB(B0, 0, 0); PG8_LDB(B1, 0, 1); PG8_SCHED; PG8_LDA(At, 0, 0); PG8_STAGE(PG8_SA(1, 1), a1 + hstepA, voffA);
;             PG8_WAIT_V(8); PG8_WAIT_L(0); PG8_BAR; PG8_MMA(0, 0, At, B0); PG8_MMA(0, 1, At, B1); PG8_BAR; PG8_SCHED;
;             PG8_LDA(At, 0, 1); PG8_STAGE(PG8_SB(0, 0), b2, voffB); PG8_STAGE(PG8_SB(0, 1), b2 + hstepB, voffB); PG8_STAGE(PG8_SA(0, 0), a2, voffA);
;             PG8_WAIT_V(8); PG8_WAIT_L(0); PG8_BAR; PG8_MMA(1, 0, At, B0); PG8_MMA(1, 1, At, B1); PG8_BAR; PG8_SCHED;
;     ...
;         for (int a = 0; a < 2; ++a)
; #pragma unroll
;             for (int b = 0; b < 2; ++b)
; #pragma unroll
;                 for (int m = 0; m < 4; ++m)
; #pragma unroll
;                     for (int n = 0; n < 2; ++n) acc[a][b][m][n] = (f32x4){0.f, 0.f, 0.f, 0.f};
.LBB0_399:
	s_add_u32 s46, s46, 0x80080
	s_addc_u32 s47, s47, 0
	s_add_u32 s14, s48, 0x100
	s_addc_u32 s15, s49, 0
	s_mov_b32 s19, -2
	ds_read_b128 v[154:157], v151
	ds_read_b128 v[164:167], v151 offset:1024
	ds_read_b128 v[168:171], v151 offset:2048
	ds_read_b128 v[172:175], v151 offset:3072
	ds_read_b128 v[176:179], v152
	ds_read_b128 v[180:183], v152 offset:1024
	ds_read_b128 v[184:187], v152 offset:2048
	ds_read_b128 v[192:195], v152 offset:3072
	s_add_u32 s34, s46, 0xfff80080
	s_addc_u32 s48, s47, -1
	s_cmp_eq_u32 s19, 28
	s_cselect_b32 s51, s41, s48
	s_cselect_b32 s50, s40, s34
	s_cselect_b32 s49, s43, s15
	s_cselect_b32 s48, s42, s14
	v_lshl_add_u64 v[158:159], s[46:47], 0, v[138:139]
	s_add_i32 m0, s16, 0xc000
	ds_read_b128 v[196:199], v153
	ds_read_b128 v[200:203], v153 offset:1024
	ds_read_b128 v[204:207], v153 offset:2048
	ds_read_b128 v[208:211], v153 offset:3072
	ds_read_b128 v[212:215], v153 offset:4096
	ds_read_b128 v[216:219], v153 offset:5120
	ds_read_b128 v[220:223], v153 offset:6144
	ds_read_b128 v[224:227], v153 offset:7168
	global_load_lds_dwordx4 v[158:159], off
	v_lshl_add_u64 v[158:159], s[46:47], 0, v[140:141]
	s_add_i32 m0, s16, 0xe000
	s_nop 0
	global_load_lds_dwordx4 v[158:159], off
	s_waitcnt vmcnt(8)
	s_waitcnt lgkmcnt(0)
	s_barrier
	s_setprio 1
	s_waitcnt lgkmcnt(0)
	v_mfma_f32_16x16x32_bf16 v[124:127], v[154:157], v[196:199], 0
	v_mfma_f32_16x16x32_bf16 v[120:123], v[168:171], v[196:199], 0
	v_mfma_f32_16x16x32_bf16 v[116:119], v[154:157], v[204:207], 0
	v_mfma_f32_16x16x32_bf16 v[112:115], v[168:171], v[204:207], 0
	v_mfma_f32_16x16x32_bf16 v[100:103], v[154:157], v[212:215], 0
	v_mfma_f32_16x16x32_bf16 v[96:99], v[168:171], v[212:215], 0
	v_mfma_f32_16x16x32_bf16 v[84:87], v[154:157], v[220:223], 0
	v_mfma_f32_16x16x32_bf16 v[80:83], v[168:171], v[220:223], 0
	v_mfma_f32_16x16x32_bf16 v[124:127], v[164:167], v[200:203], v[124:127]
	v_mfma_f32_16x16x32_bf16 v[120:123], v[172:175], v[200:203], v[120:123]
	v_mfma_f32_16x16x32_bf16 v[116:119], v[164:167], v[208:211], v[116:119]
	v_mfma_f32_16x16x32_bf16 v[112:115], v[172:175], v[208:211], v[112:115]
	v_mfma_f32_16x16x32_bf16 v[100:103], v[164:167], v[216:219], v[100:103]
	v_mfma_f32_16x16x32_bf16 v[96:99], v[172:175], v[216:219], v[96:99]
	v_mfma_f32_16x16x32_bf16 v[84:87], v[164:167], v[224:227], v[84:87]
	v_mfma_f32_16x16x32_bf16 v[80:83], v[172:175], v[224:227], v[80:83]
	s_setprio 0
	s_setprio 1
	v_mfma_f32_16x16x32_bf16 v[108:111], v[176:179], v[196:199], 0
	v_mfma_f32_16x16x32_bf16 v[104:107], v[184:187], v[196:199], 0
	v_mfma_f32_16x16x32_bf16 v[92:95], v[176:179], v[204:207], 0
	v_mfma_f32_16x16x32_bf16 v[88:91], v[184:187], v[204:207], 0
	v_mfma_f32_16x16x32_bf16 v[76:79], v[176:179], v[212:215], 0
	v_mfma_f32_16x16x32_bf16 v[72:75], v[184:187], v[212:215], 0
	v_mfma_f32_16x16x32_bf16 v[68:71], v[176:179], v[220:223], 0
	v_mfma_f32_16x16x32_bf16 v[64:67], v[184:187], v[220:223], 0
	v_mfma_f32_16x16x32_bf16 v[108:111], v[180:183], v[200:203], v[108:111]
	v_mfma_f32_16x16x32_bf16 v[104:107], v[192:195], v[200:203], v[104:107]
	v_mfma_f32_16x16x32_bf16 v[92:95], v[180:183], v[208:211], v[92:95]
	v_mfma_f32_16x16x32_bf16 v[88:91], v[192:195], v[208:211], v[88:91]
	v_mfma_f32_16x16x32_bf16 v[76:79], v[180:183], v[216:219], v[76:79]
	v_mfma_f32_16x16x32_bf16 v[72:75], v[192:195], v[216:219], v[72:75]
	v_mfma_f32_16x16x32_bf16 v[68:71], v[180:183], v[224:227], v[68:71]
	v_mfma_f32_16x16x32_bf16 v[64:67], v[192:195], v[224:227], v[64:67]
	s_setprio 0
	s_barrier
	s_add_i32 s34, s33, s0
	v_lshl_add_u64 v[158:159], s[48:49], 0, v[130:131]
	s_mov_b32 m0, s34
	ds_read_b128 v[196:199], v153 offset:16384
	ds_read_b128 v[200:203], v153 offset:17408
	ds_read_b128 v[204:207], v153 offset:18432
	ds_read_b128 v[208:211], v153 offset:19456
	ds_read_b128 v[212:215], v153 offset:20480
	ds_read_b128 v[216:219], v153 offset:21504
	ds_read_b128 v[220:223], v153 offset:22528
	ds_read_b128 v[224:227], v153 offset:23552
	global_load_lds_dwordx4 v[158:159], off
	s_add_i32 m0, s34, 0x2000
	s_add_u32 s54, s48, 0x80000
	v_lshl_add_u64 v[188:189], s[48:49], 0, v[134:135]
	s_addc_u32 s55, s49, 0
	s_add_i32 s34, s35, s0
	global_load_lds_dwordx4 v[188:189], off
	v_lshl_add_u64 v[228:229], s[54:55], 0, v[130:131]
	s_mov_b32 m0, s34
	v_lshl_add_u64 v[230:231], s[50:51], 0, v[132:133]
	global_load_lds_dwordx4 v[228:229], off
	v_lshl_add_u64 v[228:229], s[54:55], 0, v[134:135]
	s_add_i32 m0, s34, 0x2000
	s_nop 0
	global_load_lds_dwordx4 v[228:229], off
	v_lshl_add_u64 v[228:229], s[50:51], 0, v[128:129]
	s_mov_b32 m0, s16
	s_nop 0
	global_load_lds_dwordx4 v[228:229], off
	s_mov_b32 m0, s17
	s_nop 0
	global_load_lds_dwordx4 v[230:231], off
	s_waitcnt vmcnt(8)
	s_waitcnt lgkmcnt(0)
	s_barrier
; #define PG8_STAGE(bufoff, gbase, voff) do { _Pragma("unroll") for (int _i = 0; _i < 2; ++_i) \
;         __builtin_amdgcn_global_load_lds((const unsigned*)((const char*)(gbase) + (voff)[_i]), (LAS unsigned*)(lds + (bufoff) + ldsw + _i * 8192), 16, 0, 0); } while (0)
; #define PG8_LDA(dst, b, h) do { _Pragma("unroll") for (int m = 0; m < 4; ++m) _Pragma("unroll") for (int k = 0; k < 2; ++k) dst[m][k] = *(const LAS bf16x8*)(lds + PG8_SA(b, h) + aoff + m * 2048 + k * 1024); } while (0)
; #define PG8_LDB(dst, b, h) do { _Pragma("unroll") for (int n = 0; n < 2; ++n) _Pragma("unroll") for (int k = 0; k < 2; ++k) dst[n][k] = *(const LAS bf16x8*)(lds + PG8_SB(b, h) + boff + n * 2048 + k * 1024); } while (0)
; #define PG8_MMA(ai, bj, At, Bt) do { __builtin_amdgcn_s_setprio(1); _Pragma("unroll") for (int m = 0; m < 4; ++m) _Pragma("unroll") for (int n = 0; n < 2; ++n) _Pragma("unroll") for (int k = 0; k < 2; ++k) \
;         acc[ai][bj][m][n] = __builtin_amdgcn_mfma_f32_16x16x32_bf16(Bt[n][k], At[m][k], acc[ai][bj][m][n], 0, 0, 0); __builtin_amdgcn_s_setprio(0); } while (0)
; #define PG8_WAIT_V(n) asm volatile("s_waitcnt vmcnt(" #n ")" ::: "memory")
; #define PG8_WAIT_L(n) asm volatile("s_waitcnt lgkmcnt(" #n ")" ::: "memory")
; #define PG8_BAR __builtin_amdgcn_s_barrier()
; #define PG8_SCHED __builtin_amdgcn_sched_barrier(0)
; template <int GI>
; __device__ __forceinline__ void gemm_phase(LAS unsigned char* lds, unsigned char* ws, int G, int cblk) {
;     ...
;             PG8_WAIT_V(8); PG8_WAIT_L(0); PG8_BAR; PG8_MMA(1, 0, At, B0); PG8_MMA(1, 1, At, B1); PG8_BAR; PG8_SCHED;
;             PG8_LDB(B0, 1, 0); PG8_LDB(B1, 1, 1); PG8_SCHED; PG8_LDA(At, 1, 0); PG8_STAGE(PG8_SA(0, 1), a2 + hstepA, voffA);
;             PG8_WAIT_V(8); PG8_WAIT_L(0); PG8_BAR; PG8_MMA(0, 0, At, B0); PG8_MMA(0, 1, At, B1); PG8_BAR; PG8_SCHED;
	s_setprio 1
	s_waitcnt lgkmcnt(0)
	v_mfma_f32_16x16x32_bf16 v[60:63], v[154:157], v[196:199], 0
	v_mfma_f32_16x16x32_bf16 v[56:59], v[168:171], v[196:199], 0
	v_mfma_f32_16x16x32_bf16 v[52:55], v[154:157], v[204:207], 0
	v_mfma_f32_16x16x32_bf16 v[48:51], v[168:171], v[204:207], 0
	v_mfma_f32_16x16x32_bf16 v[36:39], v[154:157], v[212:215], 0
	v_mfma_f32_16x16x32_bf16 v[32:35], v[168:171], v[212:215], 0
	v_mfma_f32_16x16x32_bf16 v[20:23], v[154:157], v[220:223], 0
	v_mfma_f32_16x16x32_bf16 v[16:19], v[168:171], v[220:223], 0
	v_mfma_f32_16x16x32_bf16 v[60:63], v[164:167], v[200:203], v[60:63]
	v_mfma_f32_16x16x32_bf16 v[56:59], v[172:175], v[200:203], v[56:59]
	v_mfma_f32_16x16x32_bf16 v[52:55], v[164:167], v[208:211], v[52:55]
	v_mfma_f32_16x16x32_bf16 v[48:51], v[172:175], v[208:211], v[48:51]
	v_mfma_f32_16x16x32_bf16 v[36:39], v[164:167], v[216:219], v[36:39]
	v_mfma_f32_16x16x32_bf16 v[32:35], v[172:175], v[216:219], v[32:35]
	v_mfma_f32_16x16x32_bf16 v[20:23], v[164:167], v[224:227], v[20:23]
	v_mfma_f32_16x16x32_bf16 v[16:19], v[172:175], v[224:227], v[16:19]
	s_setprio 0
	s_setprio 1
	v_mfma_f32_16x16x32_bf16 v[44:47], v[176:179], v[196:199], 0
	v_mfma_f32_16x16x32_bf16 v[40:43], v[184:187], v[196:199], 0
	v_mfma_f32_16x16x32_bf16 v[28:31], v[176:179], v[204:207], 0
	v_mfma_f32_16x16x32_bf16 v[24:27], v[184:187], v[204:207], 0
	v_mfma_f32_16x16x32_bf16 v[12:15], v[176:179], v[212:215], 0
	v_mfma_f32_16x16x32_bf16 v[8:11], v[184:187], v[212:215], 0
	v_mfma_f32_16x16x32_bf16 v[4:7], v[176:179], v[220:223], 0
	v_mfma_f32_16x16x32_bf16 v[0:3], v[184:187], v[220:223], 0
	v_mfma_f32_16x16x32_bf16 v[44:47], v[180:183], v[200:203], v[44:47]
	v_mfma_f32_16x16x32_bf16 v[40:43], v[192:195], v[200:203], v[40:43]
	v_mfma_f32_16x16x32_bf16 v[28:31], v[180:183], v[208:211], v[28:31]
	v_mfma_f32_16x16x32_bf16 v[24:27], v[192:195], v[208:211], v[24:27]
	v_mfma_f32_16x16x32_bf16 v[12:15], v[180:183], v[216:219], v[12:15]
	v_mfma_f32_16x16x32_bf16 v[8:11], v[192:195], v[216:219], v[8:11]
	v_mfma_f32_16x16x32_bf16 v[4:7], v[180:183], v[224:227], v[4:7]
	v_mfma_f32_16x16x32_bf16 v[0:3], v[192:195], v[224:227], v[0:3]
	s_setprio 0
	s_barrier
	s_add_i32 s34, 0, 0x18000
	v_add_u32_e32 v161, s34, v150
	s_add_i32 s53, 0, 0x1c000
	ds_read_b128 v[154:157], v161
	ds_read_b128 v[164:167], v161 offset:1024
	ds_read_b128 v[168:171], v161 offset:2048
	ds_read_b128 v[172:175], v161 offset:3072
	v_add_u32_e32 v161, s53, v150
	ds_read_b128 v[176:179], v161
	ds_read_b128 v[180:183], v161 offset:1024
	ds_read_b128 v[184:187], v161 offset:2048
	ds_read_b128 v[192:195], v161 offset:3072
	s_add_u32 s50, s50, 0x80000
	s_addc_u32 s51, s51, 0
	s_mov_b32 m0, s22
	v_lshl_add_u64 v[232:233], s[50:51], 0, v[128:129]
	ds_read_b128 v[196:199], v153 offset:32768
	ds_read_b128 v[200:203], v153 offset:33792
	ds_read_b128 v[204:207], v153 offset:34816
	ds_read_b128 v[208:211], v153 offset:35840
	ds_read_b128 v[212:215], v153 offset:36864
	ds_read_b128 v[216:219], v153 offset:37888
	ds_read_b128 v[220:223], v153 offset:38912
	ds_read_b128 v[224:227], v153 offset:39936
	global_load_lds_dwordx4 v[232:233], off
	v_lshl_add_u64 v[232:233], s[50:51], 0, v[132:133]
	s_mov_b32 m0, s23
	s_nop 0
	global_load_lds_dwordx4 v[232:233], off
	s_waitcnt vmcnt(8)
	s_waitcnt lgkmcnt(0)
	s_barrier
	s_setprio 1
	s_waitcnt lgkmcnt(0)
	v_mfma_f32_16x16x32_bf16 v[124:127], v[154:157], v[196:199], v[124:127]
	v_mfma_f32_16x16x32_bf16 v[120:123], v[168:171], v[196:199], v[120:123]
	v_mfma_f32_16x16x32_bf16 v[116:119], v[154:157], v[204:207], v[116:119]
	v_mfma_f32_16x16x32_bf16 v[112:115], v[168:171], v[204:207], v[112:115]
	v_mfma_f32_16x16x32_bf16 v[100:103], v[154:157], v[212:215], v[100:103]
	v_mfma_f32_16x16x32_bf16 v[96:99], v[168:171], v[212:215], v[96:99]
	v_mfma_f32_16x16x32_bf16 v[84:87], v[154:157], v[220:223], v[84:87]
	v_mfma_f32_16x16x32_bf16 v[80:83], v[168:171], v[220:223], v[80:83]
	v_mfma_f32_16x16x32_bf16 v[124:127], v[164:167], v[200:203], v[124:127]
	v_mfma_f32_16x16x32_bf16 v[120:123], v[172:175], v[200:203], v[120:123]
	v_mfma_f32_16x16x32_bf16 v[116:119], v[164:167], v[208:211], v[116:119]
	v_mfma_f32_16x16x32_bf16 v[112:115], v[172:175], v[208:211], v[112:115]
	v_mfma_f32_16x16x32_bf16 v[100:103], v[164:167], v[216:219], v[100:103]
	v_mfma_f32_16x16x32_bf16 v[96:99], v[172:175], v[216:219], v[96:99]
	v_mfma_f32_16x16x32_bf16 v[84:87], v[164:167], v[224:227], v[84:87]
	v_mfma_f32_16x16x32_bf16 v[80:83], v[172:175], v[224:227], v[80:83]
	s_setprio 0
	s_setprio 1
	v_mfma_f32_16x16x32_bf16 v[108:111], v[176:179], v[196:199], v[108:111]
	v_mfma_f32_16x16x32_bf16 v[104:107], v[184:187], v[196:199], v[104:107]
	v_mfma_f32_16x16x32_bf16 v[92:95], v[176:179], v[204:207], v[92:95]
	v_mfma_f32_16x16x32_bf16 v[88:91], v[184:187], v[204:207], v[88:91]
	v_mfma_f32_16x16x32_bf16 v[76:79], v[176:179], v[212:215], v[76:79]
	v_mfma_f32_16x16x32_bf16 v[72:75], v[184:187], v[212:215], v[72:75]
	v_mfma_f32_16x16x32_bf16 v[68:71], v[176:179], v[220:223], v[68:71]
	v_mfma_f32_16x16x32_bf16 v[64:67], v[184:187], v[220:223], v[64:67]
	v_mfma_f32_16x16x32_bf16 v[108:111], v[180:183], v[200:203], v[108:111]
	v_mfma_f32_16x16x32_bf16 v[104:107], v[192:195], v[200:203], v[104:107]
	v_mfma_f32_16x16x32_bf16 v[92:95], v[180:183], v[208:211], v[92:95]
	v_mfma_f32_16x16x32_bf16 v[88:91], v[192:195], v[208:211], v[88:91]
	v_mfma_f32_16x16x32_bf16 v[76:79], v[180:183], v[216:219], v[76:79]
	v_mfma_f32_16x16x32_bf16 v[72:75], v[192:195], v[216:219], v[72:75]
	v_mfma_f32_16x16x32_bf16 v[68:71], v[180:183], v[224:227], v[68:71]
	v_mfma_f32_16x16x32_bf16 v[64:67], v[192:195], v[224:227], v[64:67]
	s_setprio 0
	s_barrier
; #define PG8_STAGE(bufoff, gbase, voff) do { _Pragma("unroll") for (int _i = 0; _i < 2; ++_i) \
;         __builtin_amdgcn_global_load_lds((const unsigned*)((const char*)(gbase) + (voff)[_i]), (LAS unsigned*)(lds + (bufoff) + ldsw + _i * 8192), 16, 0, 0); } while (0)
; #define PG8_LDA(dst, b, h) do { _Pragma("unroll") for (int m = 0; m < 4; ++m) _Pragma("unroll") for (int k = 0; k < 2; ++k) dst[m][k] = *(const LAS bf16x8*)(lds + PG8_SA(b, h) + aoff + m * 2048 + k * 1024); } while (0)
; #define PG8_MMA(ai, bj, At, Bt) do { __builtin_amdgcn_s_setprio(1); _Pragma("unroll") for (int m = 0; m < 4; ++m) _Pragma("unroll") for (int n = 0; n < 2; ++n) _Pragma("unroll") for (int k = 0; k < 2; ++k) \
;         acc[ai][bj][m][n] = __builtin_amdgcn_mfma_f32_16x16x32_bf16(Bt[n][k], At[m][k], acc[ai][bj][m][n], 0, 0, 0); __builtin_amdgcn_s_setprio(0); } while (0)
; #define PG8_WAIT_V(n) asm volatile("s_waitcnt vmcnt(" #n ")" ::: "memory")
; #define PG8_WAIT_L(n) asm volatile("s_waitcnt lgkmcnt(" #n ")" ::: "memory")
; #define PG8_BAR __builtin_amdgcn_s_barrier()
; #define PG8_SCHED __builtin_amdgcn_sched_barrier(0)
; template <int GI>
; __device__ __forceinline__ void gemm_phase(LAS unsigned char* lds, unsigned char* ws, int G, int cblk) {
;     ...
;         for (int t = 0; t < nt; t += 2) {
;             const bool last = (t == nt - 2);
;     ...
;             PG8_LDA(At, 1, 1); PG8_STAGE(PG8_SB(1, 0), b3, voffB); PG8_STAGE(PG8_SB(1, 1), b3 + hstepB, voffB); PG8_STAGE(PG8_SA(1, 0), a3, voffA);
;             PG8_WAIT_V(8); PG8_WAIT_L(0); PG8_BAR; PG8_MMA(1, 0, At, B0); PG8_MMA(1, 1, At, B1); PG8_BAR; PG8_SCHED;
	s_add_i32 s34, s34, s0
	v_lshl_add_u64 v[158:159], v[158:159], 0, s[8:9]
	s_mov_b32 m0, s34
	ds_read_b128 v[196:199], v153 offset:49152
	ds_read_b128 v[200:203], v153 offset:50176
	ds_read_b128 v[204:207], v153 offset:51200
	ds_read_b128 v[208:211], v153 offset:52224
	ds_read_b128 v[212:215], v153 offset:53248
	ds_read_b128 v[216:219], v153 offset:54272
	ds_read_b128 v[220:223], v153 offset:55296
	ds_read_b128 v[224:227], v153 offset:56320
	global_load_lds_dwordx4 v[158:159], off
	s_add_i32 m0, s34, 0x2000
	s_add_u32 s48, s48, 0x80080
	v_lshl_add_u64 v[158:159], v[188:189], 0, s[8:9]
	s_addc_u32 s49, s49, 0
	s_add_i32 s34, s53, s0
	global_load_lds_dwordx4 v[158:159], off
	v_lshl_add_u64 v[158:159], s[48:49], 0, v[130:131]
	s_mov_b32 m0, s34
	s_nop 0
	global_load_lds_dwordx4 v[158:159], off
	v_lshl_add_u64 v[158:159], s[48:49], 0, v[134:135]
	s_add_i32 m0, s34, 0x2000
	s_nop 0
	global_load_lds_dwordx4 v[158:159], off
	v_lshl_add_u64 v[158:159], v[228:229], 0, s[8:9]
	s_mov_b32 m0, s26
	s_nop 0
	global_load_lds_dwordx4 v[158:159], off
	v_lshl_add_u64 v[158:159], v[230:231], 0, s[8:9]
	s_mov_b32 m0, s27
	s_nop 0
	global_load_lds_dwordx4 v[158:159], off
	s_waitcnt vmcnt(8)
	s_waitcnt lgkmcnt(0)
	s_barrier
	s_setprio 1
	s_waitcnt lgkmcnt(0)
	v_mfma_f32_16x16x32_bf16 v[60:63], v[154:157], v[196:199], v[60:63]
	v_mfma_f32_16x16x32_bf16 v[56:59], v[168:171], v[196:199], v[56:59]
	v_mfma_f32_16x16x32_bf16 v[52:55], v[154:157], v[204:207], v[52:55]
	v_mfma_f32_16x16x32_bf16 v[48:51], v[168:171], v[204:207], v[48:51]
	v_mfma_f32_16x16x32_bf16 v[36:39], v[154:157], v[212:215], v[36:39]
	v_mfma_f32_16x16x32_bf16 v[32:35], v[168:171], v[212:215], v[32:35]
	v_mfma_f32_16x16x32_bf16 v[20:23], v[154:157], v[220:223], v[20:23]
	v_mfma_f32_16x16x32_bf16 v[16:19], v[168:171], v[220:223], v[16:19]
	v_mfma_f32_16x16x32_bf16 v[60:63], v[164:167], v[200:203], v[60:63]
	v_mfma_f32_16x16x32_bf16 v[56:59], v[172:175], v[200:203], v[56:59]
	v_mfma_f32_16x16x32_bf16 v[52:55], v[164:167], v[208:211], v[52:55]
	v_mfma_f32_16x16x32_bf16 v[48:51], v[172:175], v[208:211], v[48:51]
	v_mfma_f32_16x16x32_bf16 v[36:39], v[164:167], v[216:219], v[36:39]
	v_mfma_f32_16x16x32_bf16 v[32:35], v[172:175], v[216:219], v[32:35]
	v_mfma_f32_16x16x32_bf16 v[20:23], v[164:167], v[224:227], v[20:23]
	v_mfma_f32_16x16x32_bf16 v[16:19], v[172:175], v[224:227], v[16:19]
	s_setprio 0
	s_setprio 1
	v_mfma_f32_16x16x32_bf16 v[44:47], v[176:179], v[196:199], v[44:47]
	v_mfma_f32_16x16x32_bf16 v[40:43], v[184:187], v[196:199], v[40:43]
	v_mfma_f32_16x16x32_bf16 v[28:31], v[176:179], v[204:207], v[28:31]
	v_mfma_f32_16x16x32_bf16 v[24:27], v[184:187], v[204:207], v[24:27]
	v_mfma_f32_16x16x32_bf16 v[12:15], v[176:179], v[212:215], v[12:15]
	v_mfma_f32_16x16x32_bf16 v[8:11], v[184:187], v[212:215], v[8:11]
	v_mfma_f32_16x16x32_bf16 v[4:7], v[176:179], v[220:223], v[4:7]
	v_mfma_f32_16x16x32_bf16 v[0:3], v[184:187], v[220:223], v[0:3]
	v_mfma_f32_16x16x32_bf16 v[44:47], v[180:183], v[200:203], v[44:47]
	v_mfma_f32_16x16x32_bf16 v[40:43], v[192:195], v[200:203], v[40:43]
	v_mfma_f32_16x16x32_bf16 v[28:31], v[180:183], v[208:211], v[28:31]
	v_mfma_f32_16x16x32_bf16 v[24:27], v[192:195], v[208:211], v[24:27]
	v_mfma_f32_16x16x32_bf16 v[12:15], v[180:183], v[216:219], v[12:15]
	v_mfma_f32_16x16x32_bf16 v[8:11], v[192:195], v[216:219], v[8:11]
	v_mfma_f32_16x16x32_bf16 v[4:7], v[180:183], v[224:227], v[4:7]
	v_mfma_f32_16x16x32_bf16 v[0:3], v[192:195], v[224:227], v[0:3]
	s_setprio 0
	s_barrier
	s_add_i32 s19, s19, 2
	s_add_u32 s46, s46, 0x100
	s_addc_u32 s47, s47, 0
	s_add_u32 s14, s14, 0x100
	s_addc_u32 s15, s15, 0
	s_cmp_gt_u32 s19, 29
	s_cbranch_scc0 .LBB0_400
	s_branch .Lpeel_exit_3

; #define PG8_BAR __builtin_amdgcn_s_barrier()
; template <int GI>
; __device__ __forceinline__ void gemm_phase(LAS unsigned char* lds, unsigned char* ws, int G, int cblk) {
;     ...
;         if (wr == 0) PG8_BAR;
;         epilogue<g.mode>(acc, cur, wr, wc, fr, fq, lds);
.Lpeel_exit_3:
	s_and_b64 vcc, exec, s[12:13]
	s_cbranch_vccz .LBB0_403
	s_barrier

; #define PG8_STAGE(bufoff, gbase, voff) do { _Pragma("unroll") for (int _i = 0; _i < 2; ++_i) \
;         __builtin_amdgcn_global_load_lds((const unsigned*)((const char*)(gbase) + (voff)[_i]), (LAS unsigned*)(lds + (bufoff) + ldsw + _i * 8192), 16, 0, 0); } while (0)
; #define PG8_LDA(dst, b, h) do { _Pragma("unroll") for (int m = 0; m < 4; ++m) _Pragma("unroll") for (int k = 0; k < 2; ++k) dst[m][k] = *(const LAS bf16x8*)(lds + PG8_SA(b, h) + aoff + m * 2048 + k * 1024); } while (0)
; #define PG8_LDB(dst, b, h) do { _Pragma("unroll") for (int n = 0; n < 2; ++n) _Pragma("unroll") for (int k = 0; k < 2; ++k) dst[n][k] = *(const LAS bf16x8*)(lds + PG8_SB(b, h) + boff + n * 2048 + k * 1024); } while (0)
; #define PG8_MMA(ai, bj, At, Bt) do { __builtin_amdgcn_s_setprio(1); _Pragma("unroll") for (int m = 0; m < 4; ++m) _Pragma("unroll") for (int n = 0; n < 2; ++n) _Pragma("unroll") for (int k = 0; k < 2; ++k) \
;         acc[ai][bj][m][n] = __builtin_amdgcn_mfma_f32_16x16x32_bf16(Bt[n][k], At[m][k], acc[ai][bj][m][n], 0, 0, 0); __builtin_amdgcn_s_setprio(0); } while (0)
; #define PG8_WAIT_V(n) asm volatile("s_waitcnt vmcnt(" #n ")" ::: "memory")
; #define PG8_WAIT_L(n) asm volatile("s_waitcnt lgkmcnt(" #n ")" ::: "memory")
; #define PG8_BAR __builtin_amdgcn_s_barrier()
; #define PG8_SCHED __builtin_amdgcn_sched_barrier(0)
; template <int GI>
; __device__ __forceinline__ void gemm_phase(LAS unsigned char* lds, unsigned char* ws, int G, int cblk) {
;     ...
;             PG8_LDB(B0, 0, 0); PG8_LDB(B1, 0, 1); PG8_SCHED; PG8_LDA(At, 0, 0); PG8_STAGE(PG8_SA(1, 1), a1 + hstepA, voffA);
;             PG8_WAIT_V(8); PG8_WAIT_L(0); PG8_BAR; PG8_MMA(0, 0, At, B0); PG8_MMA(0, 1, At, B1); PG8_BAR; PG8_SCHED;
;             PG8_LDA(At, 0, 1); PG8_STAGE(PG8_SB(0, 0), b2, voffB); PG8_STAGE(PG8_SB(0, 1), b2 + hstepB, voffB); PG8_STAGE(PG8_SA(0, 0), a2, voffA);
;             PG8_WAIT_V(8); PG8_WAIT_L(0); PG8_BAR; PG8_MMA(1, 0, At, B0); PG8_MMA(1, 1, At, B1); PG8_BAR; PG8_SCHED;
;     ...
;         for (int a = 0; a < 2; ++a)
; #pragma unroll
;             for (int b = 0; b < 2; ++b)
; #pragma unroll
;                 for (int m = 0; m < 4; ++m)
; #pragma unroll
;                     for (int n = 0; n < 2; ++n) acc[a][b][m][n] = (f32x4){0.f, 0.f, 0.f, 0.f};
.LBB0_415:
	s_add_u32 s50, s50, 0x100080
	s_addc_u32 s51, s51, 0
	s_add_u32 s14, s52, 0x100
	s_addc_u32 s15, s53, 0
	s_mov_b32 s21, -2
	ds_read_b128 v[154:157], v151
	ds_read_b128 v[164:167], v151 offset:1024
	ds_read_b128 v[168:171], v151 offset:2048
	ds_read_b128 v[172:175], v151 offset:3072
	ds_read_b128 v[176:179], v152
	ds_read_b128 v[180:183], v152 offset:1024
	ds_read_b128 v[184:187], v152 offset:2048
	ds_read_b128 v[192:195], v152 offset:3072
	s_add_u32 s34, s50, 0xfff00080
	s_addc_u32 s52, s51, -1
	s_cmp_eq_u32 s21, 4
	s_cselect_b32 s55, s41, s52
	s_cselect_b32 s54, s40, s34
	s_cselect_b32 s53, s43, s15
	s_cselect_b32 s52, s42, s14
	v_lshl_add_u64 v[158:159], s[50:51], 0, v[138:139]
	s_add_i32 m0, s22, 0xc000
	ds_read_b128 v[196:199], v153
	ds_read_b128 v[200:203], v153 offset:1024
	ds_read_b128 v[204:207], v153 offset:2048
	ds_read_b128 v[208:211], v153 offset:3072
	ds_read_b128 v[212:215], v153 offset:4096
	ds_read_b128 v[216:219], v153 offset:5120
	ds_read_b128 v[220:223], v153 offset:6144
	ds_read_b128 v[224:227], v153 offset:7168
	global_load_lds_dwordx4 v[158:159], off
	v_lshl_add_u64 v[158:159], s[50:51], 0, v[140:141]
	s_add_i32 m0, s22, 0xe000
	s_nop 0
	global_load_lds_dwordx4 v[158:159], off
	s_waitcnt vmcnt(8)
	s_waitcnt lgkmcnt(0)
	s_barrier
	s_setprio 1
	s_waitcnt lgkmcnt(0)
	v_mfma_f32_16x16x32_bf16 v[124:127], v[154:157], v[196:199], 0
	v_mfma_f32_16x16x32_bf16 v[120:123], v[168:171], v[196:199], 0
	v_mfma_f32_16x16x32_bf16 v[116:119], v[154:157], v[204:207], 0
	v_mfma_f32_16x16x32_bf16 v[108:111], v[168:171], v[204:207], 0
	v_mfma_f32_16x16x32_bf16 v[100:103], v[154:157], v[212:215], 0
	v_mfma_f32_16x16x32_bf16 v[92:95], v[168:171], v[212:215], 0
	v_mfma_f32_16x16x32_bf16 v[84:87], v[154:157], v[220:223], 0
	v_mfma_f32_16x16x32_bf16 v[76:79], v[168:171], v[220:223], 0
	v_mfma_f32_16x16x32_bf16 v[124:127], v[164:167], v[200:203], v[124:127]
	v_mfma_f32_16x16x32_bf16 v[120:123], v[172:175], v[200:203], v[120:123]
	v_mfma_f32_16x16x32_bf16 v[116:119], v[164:167], v[208:211], v[116:119]
	v_mfma_f32_16x16x32_bf16 v[108:111], v[172:175], v[208:211], v[108:111]
	v_mfma_f32_16x16x32_bf16 v[100:103], v[164:167], v[216:219], v[100:103]
	v_mfma_f32_16x16x32_bf16 v[92:95], v[172:175], v[216:219], v[92:95]
	v_mfma_f32_16x16x32_bf16 v[84:87], v[164:167], v[224:227], v[84:87]
	v_mfma_f32_16x16x32_bf16 v[76:79], v[172:175], v[224:227], v[76:79]
	s_setprio 0
	s_setprio 1
	v_mfma_f32_16x16x32_bf16 v[112:115], v[176:179], v[196:199], 0
	v_mfma_f32_16x16x32_bf16 v[104:107], v[184:187], v[196:199], 0
	v_mfma_f32_16x16x32_bf16 v[96:99], v[176:179], v[204:207], 0
	v_mfma_f32_16x16x32_bf16 v[88:91], v[184:187], v[204:207], 0
	v_mfma_f32_16x16x32_bf16 v[80:83], v[176:179], v[212:215], 0
	v_mfma_f32_16x16x32_bf16 v[72:75], v[184:187], v[212:215], 0
	v_mfma_f32_16x16x32_bf16 v[68:71], v[176:179], v[220:223], 0
	v_mfma_f32_16x16x32_bf16 v[64:67], v[184:187], v[220:223], 0
	v_mfma_f32_16x16x32_bf16 v[112:115], v[180:183], v[200:203], v[112:115]
	v_mfma_f32_16x16x32_bf16 v[104:107], v[192:195], v[200:203], v[104:107]
	v_mfma_f32_16x16x32_bf16 v[96:99], v[180:183], v[208:211], v[96:99]
	v_mfma_f32_16x16x32_bf16 v[88:91], v[192:195], v[208:211], v[88:91]
	v_mfma_f32_16x16x32_bf16 v[80:83], v[180:183], v[216:219], v[80:83]
	v_mfma_f32_16x16x32_bf16 v[72:75], v[192:195], v[216:219], v[72:75]
	v_mfma_f32_16x16x32_bf16 v[68:71], v[180:183], v[224:227], v[68:71]
	v_mfma_f32_16x16x32_bf16 v[64:67], v[192:195], v[224:227], v[64:67]
	s_setprio 0
	s_barrier
	s_add_i32 s34, s39, s0
	v_lshl_add_u64 v[158:159], s[52:53], 0, v[132:133]
	s_mov_b32 m0, s34
	ds_read_b128 v[196:199], v153 offset:16384
	ds_read_b128 v[200:203], v153 offset:17408
	ds_read_b128 v[204:207], v153 offset:18432
	ds_read_b128 v[208:211], v153 offset:19456
	ds_read_b128 v[212:215], v153 offset:20480
	ds_read_b128 v[216:219], v153 offset:21504
	ds_read_b128 v[220:223], v153 offset:22528
	ds_read_b128 v[224:227], v153 offset:23552
	global_load_lds_dwordx4 v[158:159], off
	s_add_i32 m0, s34, 0x2000
	s_add_u32 s58, s52, 0x80000
	v_lshl_add_u64 v[188:189], s[52:53], 0, v[128:129]
	s_addc_u32 s59, s53, 0
	s_add_i32 s34, s56, s0
	global_load_lds_dwordx4 v[188:189], off
	v_lshl_add_u64 v[228:229], s[58:59], 0, v[132:133]
	s_mov_b32 m0, s34
	v_lshl_add_u64 v[230:231], s[54:55], 0, v[130:131]
	global_load_lds_dwordx4 v[228:229], off
	v_lshl_add_u64 v[228:229], s[58:59], 0, v[128:129]
	s_add_i32 m0, s34, 0x2000
	s_nop 0
	global_load_lds_dwordx4 v[228:229], off
	v_lshl_add_u64 v[228:229], s[54:55], 0, v[134:135]
	s_mov_b32 m0, s22
	s_nop 0
	global_load_lds_dwordx4 v[228:229], off
	s_mov_b32 m0, s23
	s_nop 0
	global_load_lds_dwordx4 v[230:231], off
	s_waitcnt vmcnt(8)
	s_waitcnt lgkmcnt(0)
	s_barrier
; #define PG8_STAGE(bufoff, gbase, voff) do { _Pragma("unroll") for (int _i = 0; _i < 2; ++_i) \
;         __builtin_amdgcn_global_load_lds((const unsigned*)((const char*)(gbase) + (voff)[_i]), (LAS unsigned*)(lds + (bufoff) + ldsw + _i * 8192), 16, 0, 0); } while (0)
; #define PG8_LDA(dst, b, h) do { _Pragma("unroll") for (int m = 0; m < 4; ++m) _Pragma("unroll") for (int k = 0; k < 2; ++k) dst[m][k] = *(const LAS bf16x8*)(lds + PG8_SA(b, h) + aoff + m * 2048 + k * 1024); } while (0)
; #define PG8_LDB(dst, b, h) do { _Pragma("unroll") for (int n = 0; n < 2; ++n) _Pragma("unroll") for (int k = 0; k < 2; ++k) dst[n][k] = *(const LAS bf16x8*)(lds + PG8_SB(b, h) + boff + n * 2048 + k * 1024); } while (0)
; #define PG8_MMA(ai, bj, At, Bt) do { __builtin_amdgcn_s_setprio(1); _Pragma("unroll") for (int m = 0; m < 4; ++m) _Pragma("unroll") for (int n = 0; n < 2; ++n) _Pragma("unroll") for (int k = 0; k < 2; ++k) \
;         acc[ai][bj][m][n] = __builtin_amdgcn_mfma_f32_16x16x32_bf16(Bt[n][k], At[m][k], acc[ai][bj][m][n], 0, 0, 0); __builtin_amdgcn_s_setprio(0); } while (0)
; #define PG8_WAIT_V(n) asm volatile("s_waitcnt vmcnt(" #n ")" ::: "memory")
; #define PG8_WAIT_L(n) asm volatile("s_waitcnt lgkmcnt(" #n ")" ::: "memory")
; #define PG8_BAR __builtin_amdgcn_s_barrier()
; #define PG8_SCHED __builtin_amdgcn_sched_barrier(0)
; template <int GI>
; __device__ __forceinline__ void gemm_phase(LAS unsigned char* lds, unsigned char* ws, int G, int cblk) {
;     ...
;             PG8_WAIT_V(8); PG8_WAIT_L(0); PG8_BAR; PG8_MMA(1, 0, At, B0); PG8_MMA(1, 1, At, B1); PG8_BAR; PG8_SCHED;
;             PG8_LDB(B0, 1, 0); PG8_LDB(B1, 1, 1); PG8_SCHED; PG8_LDA(At, 1, 0); PG8_STAGE(PG8_SA(0, 1), a2 + hstepA, voffA);
;             PG8_WAIT_V(8); PG8_WAIT_L(0); PG8_BAR; PG8_MMA(0, 0, At, B0); PG8_MMA(0, 1, At, B1); PG8_BAR; PG8_SCHED;
	s_setprio 1
	s_waitcnt lgkmcnt(0)
	v_mfma_f32_16x16x32_bf16 v[60:63], v[154:157], v[196:199], 0
	v_mfma_f32_16x16x32_bf16 v[56:59], v[168:171], v[196:199], 0
	v_mfma_f32_16x16x32_bf16 v[52:55], v[154:157], v[204:207], 0
	v_mfma_f32_16x16x32_bf16 v[44:47], v[168:171], v[204:207], 0
	v_mfma_f32_16x16x32_bf16 v[36:39], v[154:157], v[212:215], 0
	v_mfma_f32_16x16x32_bf16 v[28:31], v[168:171], v[212:215], 0
	v_mfma_f32_16x16x32_bf16 v[20:23], v[154:157], v[220:223], 0
	v_mfma_f32_16x16x32_bf16 v[12:15], v[168:171], v[220:223], 0
	v_mfma_f32_16x16x32_bf16 v[60:63], v[164:167], v[200:203], v[60:63]
	v_mfma_f32_16x16x32_bf16 v[56:59], v[172:175], v[200:203], v[56:59]
	v_mfma_f32_16x16x32_bf16 v[52:55], v[164:167], v[208:211], v[52:55]
	v_mfma_f32_16x16x32_bf16 v[44:47], v[172:175], v[208:211], v[44:47]
	v_mfma_f32_16x16x32_bf16 v[36:39], v[164:167], v[216:219], v[36:39]
	v_mfma_f32_16x16x32_bf16 v[28:31], v[172:175], v[216:219], v[28:31]
	v_mfma_f32_16x16x32_bf16 v[20:23], v[164:167], v[224:227], v[20:23]
	v_mfma_f32_16x16x32_bf16 v[12:15], v[172:175], v[224:227], v[12:15]
	s_setprio 0
	s_setprio 1
	v_mfma_f32_16x16x32_bf16 v[48:51], v[176:179], v[196:199], 0
	v_mfma_f32_16x16x32_bf16 v[40:43], v[184:187], v[196:199], 0
	v_mfma_f32_16x16x32_bf16 v[32:35], v[176:179], v[204:207], 0
	v_mfma_f32_16x16x32_bf16 v[24:27], v[184:187], v[204:207], 0
	v_mfma_f32_16x16x32_bf16 v[16:19], v[176:179], v[212:215], 0
	v_mfma_f32_16x16x32_bf16 v[8:11], v[184:187], v[212:215], 0
	v_mfma_f32_16x16x32_bf16 v[4:7], v[176:179], v[220:223], 0
	v_mfma_f32_16x16x32_bf16 v[0:3], v[184:187], v[220:223], 0
	v_mfma_f32_16x16x32_bf16 v[48:51], v[180:183], v[200:203], v[48:51]
	v_mfma_f32_16x16x32_bf16 v[40:43], v[192:195], v[200:203], v[40:43]
	v_mfma_f32_16x16x32_bf16 v[32:35], v[180:183], v[208:211], v[32:35]
	v_mfma_f32_16x16x32_bf16 v[24:27], v[192:195], v[208:211], v[24:27]
	v_mfma_f32_16x16x32_bf16 v[16:19], v[180:183], v[216:219], v[16:19]
	v_mfma_f32_16x16x32_bf16 v[8:11], v[192:195], v[216:219], v[8:11]
	v_mfma_f32_16x16x32_bf16 v[4:7], v[180:183], v[224:227], v[4:7]
	v_mfma_f32_16x16x32_bf16 v[0:3], v[192:195], v[224:227], v[0:3]
	s_setprio 0
	s_barrier
	s_add_i32 s34, 0, 0x18000
	v_add_u32_e32 v161, s34, v150
	s_add_i32 s58, 0, 0x1c000
	ds_read_b128 v[154:157], v161
	ds_read_b128 v[164:167], v161 offset:1024
	ds_read_b128 v[168:171], v161 offset:2048
	ds_read_b128 v[172:175], v161 offset:3072
	v_add_u32_e32 v161, s58, v150
	ds_read_b128 v[176:179], v161
	ds_read_b128 v[180:183], v161 offset:1024
	ds_read_b128 v[184:187], v161 offset:2048
	ds_read_b128 v[192:195], v161 offset:3072
	s_add_u32 s54, s54, 0x100000
	s_addc_u32 s55, s55, 0
	s_mov_b32 m0, s24
	v_lshl_add_u64 v[232:233], s[54:55], 0, v[134:135]
	ds_read_b128 v[196:199], v153 offset:32768
	ds_read_b128 v[200:203], v153 offset:33792
	ds_read_b128 v[204:207], v153 offset:34816
	ds_read_b128 v[208:211], v153 offset:35840
	ds_read_b128 v[212:215], v153 offset:36864
	ds_read_b128 v[216:219], v153 offset:37888
	ds_read_b128 v[220:223], v153 offset:38912
	ds_read_b128 v[224:227], v153 offset:39936
	global_load_lds_dwordx4 v[232:233], off
	v_lshl_add_u64 v[232:233], s[54:55], 0, v[130:131]
	s_mov_b32 m0, s25
	s_nop 0
	global_load_lds_dwordx4 v[232:233], off
	s_waitcnt vmcnt(8)
	s_waitcnt lgkmcnt(0)
	s_barrier
	s_setprio 1
	s_waitcnt lgkmcnt(0)
	v_mfma_f32_16x16x32_bf16 v[124:127], v[154:157], v[196:199], v[124:127]
	v_mfma_f32_16x16x32_bf16 v[120:123], v[168:171], v[196:199], v[120:123]
	v_mfma_f32_16x16x32_bf16 v[116:119], v[154:157], v[204:207], v[116:119]
	v_mfma_f32_16x16x32_bf16 v[108:111], v[168:171], v[204:207], v[108:111]
	v_mfma_f32_16x16x32_bf16 v[100:103], v[154:157], v[212:215], v[100:103]
	v_mfma_f32_16x16x32_bf16 v[92:95], v[168:171], v[212:215], v[92:95]
	v_mfma_f32_16x16x32_bf16 v[84:87], v[154:157], v[220:223], v[84:87]
	v_mfma_f32_16x16x32_bf16 v[76:79], v[168:171], v[220:223], v[76:79]
	v_mfma_f32_16x16x32_bf16 v[124:127], v[164:167], v[200:203], v[124:127]
	v_mfma_f32_16x16x32_bf16 v[120:123], v[172:175], v[200:203], v[120:123]
	v_mfma_f32_16x16x32_bf16 v[116:119], v[164:167], v[208:211], v[116:119]
	v_mfma_f32_16x16x32_bf16 v[108:111], v[172:175], v[208:211], v[108:111]
	v_mfma_f32_16x16x32_bf16 v[100:103], v[164:167], v[216:219], v[100:103]
	v_mfma_f32_16x16x32_bf16 v[92:95], v[172:175], v[216:219], v[92:95]
	v_mfma_f32_16x16x32_bf16 v[84:87], v[164:167], v[224:227], v[84:87]
	v_mfma_f32_16x16x32_bf16 v[76:79], v[172:175], v[224:227], v[76:79]
	s_setprio 0
	s_setprio 1
	v_mfma_f32_16x16x32_bf16 v[112:115], v[176:179], v[196:199], v[112:115]
	v_mfma_f32_16x16x32_bf16 v[104:107], v[184:187], v[196:199], v[104:107]
	v_mfma_f32_16x16x32_bf16 v[96:99], v[176:179], v[204:207], v[96:99]
	v_mfma_f32_16x16x32_bf16 v[88:91], v[184:187], v[204:207], v[88:91]
	v_mfma_f32_16x16x32_bf16 v[80:83], v[176:179], v[212:215], v[80:83]
	v_mfma_f32_16x16x32_bf16 v[72:75], v[184:187], v[212:215], v[72:75]
	v_mfma_f32_16x16x32_bf16 v[68:71], v[176:179], v[220:223], v[68:71]
	v_mfma_f32_16x16x32_bf16 v[64:67], v[184:187], v[220:223], v[64:67]
	v_mfma_f32_16x16x32_bf16 v[112:115], v[180:183], v[200:203], v[112:115]
	v_mfma_f32_16x16x32_bf16 v[104:107], v[192:195], v[200:203], v[104:107]
	v_mfma_f32_16x16x32_bf16 v[96:99], v[180:183], v[208:211], v[96:99]
	v_mfma_f32_16x16x32_bf16 v[88:91], v[192:195], v[208:211], v[88:91]
	v_mfma_f32_16x16x32_bf16 v[80:83], v[180:183], v[216:219], v[80:83]
	v_mfma_f32_16x16x32_bf16 v[72:75], v[192:195], v[216:219], v[72:75]
	v_mfma_f32_16x16x32_bf16 v[68:71], v[180:183], v[224:227], v[68:71]
	v_mfma_f32_16x16x32_bf16 v[64:67], v[192:195], v[224:227], v[64:67]
	s_setprio 0
	s_barrier
; #define PG8_STAGE(bufoff, gbase, voff) do { _Pragma("unroll") for (int _i = 0; _i < 2; ++_i) \
;         __builtin_amdgcn_global_load_lds((const unsigned*)((const char*)(gbase) + (voff)[_i]), (LAS unsigned*)(lds + (bufoff) + ldsw + _i * 8192), 16, 0, 0); } while (0)
; #define PG8_LDA(dst, b, h) do { _Pragma("unroll") for (int m = 0; m < 4; ++m) _Pragma("unroll") for (int k = 0; k < 2; ++k) dst[m][k] = *(const LAS bf16x8*)(lds + PG8_SA(b, h) + aoff + m * 2048 + k * 1024); } while (0)
; #define PG8_MMA(ai, bj, At, Bt) do { __builtin_amdgcn_s_setprio(1); _Pragma("unroll") for (int m = 0; m < 4; ++m) _Pragma("unroll") for (int n = 0; n < 2; ++n) _Pragma("unroll") for (int k = 0; k < 2; ++k) \
;         acc[ai][bj][m][n] = __builtin_amdgcn_mfma_f32_16x16x32_bf16(Bt[n][k], At[m][k], acc[ai][bj][m][n], 0, 0, 0); __builtin_amdgcn_s_setprio(0); } while (0)
; #define PG8_WAIT_V(n) asm volatile("s_waitcnt vmcnt(" #n ")" ::: "memory")
; #define PG8_WAIT_L(n) asm volatile("s_waitcnt lgkmcnt(" #n ")" ::: "memory")
; #define PG8_BAR __builtin_amdgcn_s_barrier()
; #define PG8_SCHED __builtin_amdgcn_sched_barrier(0)
; template <int GI>
; __device__ __forceinline__ void gemm_phase(LAS unsigned char* lds, unsigned char* ws, int G, int cblk) {
;     ...
;         for (int t = 0; t < nt; t += 2) {
;             const bool last = (t == nt - 2);
;     ...
;             PG8_LDA(At, 1, 1); PG8_STAGE(PG8_SB(1, 0), b3, voffB); PG8_STAGE(PG8_SB(1, 1), b3 + hstepB, voffB); PG8_STAGE(PG8_SA(1, 0), a3, voffA);
;             PG8_WAIT_V(8); PG8_WAIT_L(0); PG8_BAR; PG8_MMA(1, 0, At, B0); PG8_MMA(1, 1, At, B1); PG8_BAR; PG8_SCHED;
	s_add_i32 s34, s34, s0
	v_lshl_add_u64 v[158:159], v[158:159], 0, s[12:13]
	s_mov_b32 m0, s34
	ds_read_b128 v[196:199], v153 offset:49152
	ds_read_b128 v[200:203], v153 offset:50176
	ds_read_b128 v[204:207], v153 offset:51200
	ds_read_b128 v[208:211], v153 offset:52224
	ds_read_b128 v[212:215], v153 offset:53248
	ds_read_b128 v[216:219], v153 offset:54272
	ds_read_b128 v[220:223], v153 offset:55296
	ds_read_b128 v[224:227], v153 offset:56320
	global_load_lds_dwordx4 v[158:159], off
	s_add_i32 m0, s34, 0x2000
	s_add_u32 s52, s52, 0x80080
	v_lshl_add_u64 v[158:159], v[188:189], 0, s[12:13]
	s_addc_u32 s53, s53, 0
	s_add_i32 s34, s58, s0
	global_load_lds_dwordx4 v[158:159], off
	v_lshl_add_u64 v[158:159], s[52:53], 0, v[132:133]
	s_mov_b32 m0, s34
	s_nop 0
	global_load_lds_dwordx4 v[158:159], off
	v_lshl_add_u64 v[158:159], s[52:53], 0, v[128:129]
	s_add_i32 m0, s34, 0x2000
	s_nop 0
	global_load_lds_dwordx4 v[158:159], off
	v_lshl_add_u64 v[158:159], v[228:229], 0, s[12:13]
	s_mov_b32 m0, s33
	s_nop 0
	global_load_lds_dwordx4 v[158:159], off
	v_lshl_add_u64 v[158:159], v[230:231], 0, s[12:13]
	s_mov_b32 m0, s35
	s_nop 0
	global_load_lds_dwordx4 v[158:159], off
	s_waitcnt vmcnt(8)
	s_waitcnt lgkmcnt(0)
	s_barrier
	s_setprio 1
	s_waitcnt lgkmcnt(0)
	v_mfma_f32_16x16x32_bf16 v[60:63], v[154:157], v[196:199], v[60:63]
	v_mfma_f32_16x16x32_bf16 v[56:59], v[168:171], v[196:199], v[56:59]
	v_mfma_f32_16x16x32_bf16 v[52:55], v[154:157], v[204:207], v[52:55]
	v_mfma_f32_16x16x32_bf16 v[44:47], v[168:171], v[204:207], v[44:47]
	v_mfma_f32_16x16x32_bf16 v[36:39], v[154:157], v[212:215], v[36:39]
	v_mfma_f32_16x16x32_bf16 v[28:31], v[168:171], v[212:215], v[28:31]
	v_mfma_f32_16x16x32_bf16 v[20:23], v[154:157], v[220:223], v[20:23]
	v_mfma_f32_16x16x32_bf16 v[12:15], v[168:171], v[220:223], v[12:15]
	v_mfma_f32_16x16x32_bf16 v[60:63], v[164:167], v[200:203], v[60:63]
	v_mfma_f32_16x16x32_bf16 v[56:59], v[172:175], v[200:203], v[56:59]
	v_mfma_f32_16x16x32_bf16 v[52:55], v[164:167], v[208:211], v[52:55]
	v_mfma_f32_16x16x32_bf16 v[44:47], v[172:175], v[208:211], v[44:47]
	v_mfma_f32_16x16x32_bf16 v[36:39], v[164:167], v[216:219], v[36:39]
	v_mfma_f32_16x16x32_bf16 v[28:31], v[172:175], v[216:219], v[28:31]
	v_mfma_f32_16x16x32_bf16 v[20:23], v[164:167], v[224:227], v[20:23]
	v_mfma_f32_16x16x32_bf16 v[12:15], v[172:175], v[224:227], v[12:15]
	s_setprio 0
	s_setprio 1
	v_mfma_f32_16x16x32_bf16 v[48:51], v[176:179], v[196:199], v[48:51]
	v_mfma_f32_16x16x32_bf16 v[40:43], v[184:187], v[196:199], v[40:43]
	v_mfma_f32_16x16x32_bf16 v[32:35], v[176:179], v[204:207], v[32:35]
	v_mfma_f32_16x16x32_bf16 v[24:27], v[184:187], v[204:207], v[24:27]
	v_mfma_f32_16x16x32_bf16 v[16:19], v[176:179], v[212:215], v[16:19]
	v_mfma_f32_16x16x32_bf16 v[8:11], v[184:187], v[212:215], v[8:11]
	v_mfma_f32_16x16x32_bf16 v[4:7], v[176:179], v[220:223], v[4:7]
	v_mfma_f32_16x16x32_bf16 v[0:3], v[184:187], v[220:223], v[0:3]
	v_mfma_f32_16x16x32_bf16 v[48:51], v[180:183], v[200:203], v[48:51]
	v_mfma_f32_16x16x32_bf16 v[40:43], v[192:195], v[200:203], v[40:43]
	v_mfma_f32_16x16x32_bf16 v[32:35], v[180:183], v[208:211], v[32:35]
	v_mfma_f32_16x16x32_bf16 v[24:27], v[192:195], v[208:211], v[24:27]
	v_mfma_f32_16x16x32_bf16 v[16:19], v[180:183], v[216:219], v[16:19]
	v_mfma_f32_16x16x32_bf16 v[8:11], v[192:195], v[216:219], v[8:11]
	v_mfma_f32_16x16x32_bf16 v[4:7], v[180:183], v[224:227], v[4:7]
	v_mfma_f32_16x16x32_bf16 v[0:3], v[192:195], v[224:227], v[0:3]
	s_setprio 0
	s_barrier
	s_add_i32 s21, s21, 2
	s_add_u32 s50, s50, 0x100
	s_addc_u32 s51, s51, 0
	s_add_u32 s14, s14, 0x100
	s_addc_u32 s15, s15, 0
	s_cmp_gt_u32 s21, 5
	s_cbranch_scc0 .LBB0_416
	s_branch .Lpeel_exit_4

; #define PG8_BAR __builtin_amdgcn_s_barrier()
; template <int GI>
; __device__ __forceinline__ void gemm_phase(LAS unsigned char* lds, unsigned char* ws, int G, int cblk) {
;     ...
;         if (wr == 0) PG8_BAR;
;         epilogue<g.mode>(acc, cur, wr, wc, fr, fq, lds);
.Lpeel_exit_4:
	s_and_b64 vcc, exec, s[18:19]
	s_cbranch_vccz .LBB0_419
	s_barrier

; #define PG8_STAGE(bufoff, gbase, voff) do { _Pragma("unroll") for (int _i = 0; _i < 2; ++_i) \
;         __builtin_amdgcn_global_load_lds((const unsigned*)((const char*)(gbase) + (voff)[_i]), (LAS unsigned*)(lds + (bufoff) + ldsw + _i * 8192), 16, 0, 0); } while (0)
; #define PG8_LDA(dst, b, h) do { _Pragma("unroll") for (int m = 0; m < 4; ++m) _Pragma("unroll") for (int k = 0; k < 2; ++k) dst[m][k] = *(const LAS bf16x8*)(lds + PG8_SA(b, h) + aoff + m * 2048 + k * 1024); } while (0)
; #define PG8_LDB(dst, b, h) do { _Pragma("unroll") for (int n = 0; n < 2; ++n) _Pragma("unroll") for (int k = 0; k < 2; ++k) dst[n][k] = *(const LAS bf16x8*)(lds + PG8_SB(b, h) + boff + n * 2048 + k * 1024); } while (0)
; #define PG8_MMA(ai, bj, At, Bt) do { __builtin_amdgcn_s_setprio(1); _Pragma("unroll") for (int m = 0; m < 4; ++m) _Pragma("unroll") for (int n = 0; n < 2; ++n) _Pragma("unroll") for (int k = 0; k < 2; ++k) \
;         acc[ai][bj][m][n] = __builtin_amdgcn_mfma_f32_16x16x32_bf16(Bt[n][k], At[m][k], acc[ai][bj][m][n], 0, 0, 0); __builtin_amdgcn_s_setprio(0); } while (0)
; #define PG8_WAIT_V(n) asm volatile("s_waitcnt vmcnt(" #n ")" ::: "memory")
; #define PG8_WAIT_L(n) asm volatile("s_waitcnt lgkmcnt(" #n ")" ::: "memory")
; #define PG8_BAR __builtin_amdgcn_s_barrier()
; #define PG8_SCHED __builtin_amdgcn_sched_barrier(0)
; template <int GI>
; __device__ __forceinline__ void gemm_phase(LAS unsigned char* lds, unsigned char* ws, int G, int cblk) {
;     ...
;             PG8_LDB(B0, 0, 0); PG8_LDB(B1, 0, 1); PG8_SCHED; PG8_LDA(At, 0, 0); PG8_STAGE(PG8_SA(1, 1), a1 + hstepA, voffA);
;             PG8_WAIT_V(8); PG8_WAIT_L(0); PG8_BAR; PG8_MMA(0, 0, At, B0); PG8_MMA(0, 1, At, B1); PG8_BAR; PG8_SCHED;
;             PG8_LDA(At, 0, 1); PG8_STAGE(PG8_SB(0, 0), b2, voffB); PG8_STAGE(PG8_SB(0, 1), b2 + hstepB, voffB); PG8_STAGE(PG8_SA(0, 0), a2, voffA);
;             PG8_WAIT_V(8); PG8_WAIT_L(0); PG8_BAR; PG8_MMA(1, 0, At, B0); PG8_MMA(1, 1, At, B1); PG8_BAR; PG8_SCHED;
;     ...
;         for (int a = 0; a < 2; ++a)
; #pragma unroll
;             for (int b = 0; b < 2; ++b)
; #pragma unroll
;                 for (int m = 0; m < 4; ++m)
; #pragma unroll
;                     for (int n = 0; n < 2; ++n) acc[a][b][m][n] = (f32x4){0.f, 0.f, 0.f, 0.f};
.LBB0_431:
	s_add_u32 s46, s46, 0x80080
	s_addc_u32 s47, s47, 0
	s_add_u32 s14, s48, 0x100
	s_addc_u32 s15, s49, 0
	s_mov_b32 s19, -2
	ds_read_b128 v[154:157], v151
	ds_read_b128 v[164:167], v151 offset:1024
	ds_read_b128 v[168:171], v151 offset:2048
	ds_read_b128 v[172:175], v151 offset:3072
	ds_read_b128 v[176:179], v152
	ds_read_b128 v[180:183], v152 offset:1024
	ds_read_b128 v[184:187], v152 offset:2048
	ds_read_b128 v[192:195], v152 offset:3072
	s_add_u32 s34, s46, 0xfff80080
	s_addc_u32 s48, s47, -1
	s_cmp_eq_u32 s19, 4
	s_cselect_b32 s51, s39, s48
	s_cselect_b32 s50, s38, s34
	s_cselect_b32 s49, s41, s15
	s_cselect_b32 s48, s40, s14
	v_lshl_add_u64 v[158:159], s[46:47], 0, v[138:139]
	s_add_i32 m0, s16, 0xc000
	ds_read_b128 v[196:199], v153
	ds_read_b128 v[200:203], v153 offset:1024
	ds_read_b128 v[204:207], v153 offset:2048
	ds_read_b128 v[208:211], v153 offset:3072
	ds_read_b128 v[212:215], v153 offset:4096
	ds_read_b128 v[216:219], v153 offset:5120
	ds_read_b128 v[220:223], v153 offset:6144
	ds_read_b128 v[224:227], v153 offset:7168
	global_load_lds_dwordx4 v[158:159], off
	v_lshl_add_u64 v[158:159], s[46:47], 0, v[140:141]
	s_add_i32 m0, s16, 0xe000
	s_nop 0
	global_load_lds_dwordx4 v[158:159], off
	s_waitcnt vmcnt(8)
	s_waitcnt lgkmcnt(0)
	s_barrier
	s_setprio 1
	s_waitcnt lgkmcnt(0)
	v_mfma_f32_16x16x32_bf16 v[124:127], v[154:157], v[196:199], 0
	v_mfma_f32_16x16x32_bf16 v[120:123], v[168:171], v[196:199], 0
	v_mfma_f32_16x16x32_bf16 v[116:119], v[154:157], v[204:207], 0
	v_mfma_f32_16x16x32_bf16 v[112:115], v[168:171], v[204:207], 0
	v_mfma_f32_16x16x32_bf16 v[100:103], v[154:157], v[212:215], 0
	v_mfma_f32_16x16x32_bf16 v[96:99], v[168:171], v[212:215], 0
	v_mfma_f32_16x16x32_bf16 v[84:87], v[154:157], v[220:223], 0
	v_mfma_f32_16x16x32_bf16 v[80:83], v[168:171], v[220:223], 0
	v_mfma_f32_16x16x32_bf16 v[124:127], v[164:167], v[200:203], v[124:127]
	v_mfma_f32_16x16x32_bf16 v[120:123], v[172:175], v[200:203], v[120:123]
	v_mfma_f32_16x16x32_bf16 v[116:119], v[164:167], v[208:211], v[116:119]
	v_mfma_f32_16x16x32_bf16 v[112:115], v[172:175], v[208:211], v[112:115]
	v_mfma_f32_16x16x32_bf16 v[100:103], v[164:167], v[216:219], v[100:103]
	v_mfma_f32_16x16x32_bf16 v[96:99], v[172:175], v[216:219], v[96:99]
	v_mfma_f32_16x16x32_bf16 v[84:87], v[164:167], v[224:227], v[84:87]
	v_mfma_f32_16x16x32_bf16 v[80:83], v[172:175], v[224:227], v[80:83]
	s_setprio 0
	s_setprio 1
	v_mfma_f32_16x16x32_bf16 v[108:111], v[176:179], v[196:199], 0
	v_mfma_f32_16x16x32_bf16 v[104:107], v[184:187], v[196:199], 0
	v_mfma_f32_16x16x32_bf16 v[92:95], v[176:179], v[204:207], 0
	v_mfma_f32_16x16x32_bf16 v[88:91], v[184:187], v[204:207], 0
	v_mfma_f32_16x16x32_bf16 v[76:79], v[176:179], v[212:215], 0
	v_mfma_f32_16x16x32_bf16 v[72:75], v[184:187], v[212:215], 0
	v_mfma_f32_16x16x32_bf16 v[68:71], v[176:179], v[220:223], 0
	v_mfma_f32_16x16x32_bf16 v[64:67], v[184:187], v[220:223], 0
	v_mfma_f32_16x16x32_bf16 v[108:111], v[180:183], v[200:203], v[108:111]
	v_mfma_f32_16x16x32_bf16 v[104:107], v[192:195], v[200:203], v[104:107]
	v_mfma_f32_16x16x32_bf16 v[92:95], v[180:183], v[208:211], v[92:95]
	v_mfma_f32_16x16x32_bf16 v[88:91], v[192:195], v[208:211], v[88:91]
	v_mfma_f32_16x16x32_bf16 v[76:79], v[180:183], v[216:219], v[76:79]
	v_mfma_f32_16x16x32_bf16 v[72:75], v[192:195], v[216:219], v[72:75]
	v_mfma_f32_16x16x32_bf16 v[68:71], v[180:183], v[224:227], v[68:71]
	v_mfma_f32_16x16x32_bf16 v[64:67], v[192:195], v[224:227], v[64:67]
	s_setprio 0
	s_barrier
	s_add_i32 s34, s33, s0
	v_lshl_add_u64 v[158:159], s[48:49], 0, v[132:133]
	s_mov_b32 m0, s34
	ds_read_b128 v[196:199], v153 offset:16384
	ds_read_b128 v[200:203], v153 offset:17408
	ds_read_b128 v[204:207], v153 offset:18432
	ds_read_b128 v[208:211], v153 offset:19456
	ds_read_b128 v[212:215], v153 offset:20480
	ds_read_b128 v[216:219], v153 offset:21504
	ds_read_b128 v[220:223], v153 offset:22528
	ds_read_b128 v[224:227], v153 offset:23552
	global_load_lds_dwordx4 v[158:159], off
	s_add_i32 m0, s34, 0x2000
	s_add_u32 s54, s48, 0x100000
	v_lshl_add_u64 v[188:189], s[48:49], 0, v[128:129]
	s_addc_u32 s55, s49, 0
	s_add_i32 s34, s35, s0
	global_load_lds_dwordx4 v[188:189], off
	v_lshl_add_u64 v[228:229], s[54:55], 0, v[132:133]
	s_mov_b32 m0, s34
	v_lshl_add_u64 v[230:231], s[50:51], 0, v[130:131]
	global_load_lds_dwordx4 v[228:229], off
	v_lshl_add_u64 v[228:229], s[54:55], 0, v[128:129]
	s_add_i32 m0, s34, 0x2000
	s_nop 0
	global_load_lds_dwordx4 v[228:229], off
	v_lshl_add_u64 v[228:229], s[50:51], 0, v[134:135]
	s_mov_b32 m0, s16
	s_nop 0
	global_load_lds_dwordx4 v[228:229], off
	s_mov_b32 m0, s17
	s_nop 0
	global_load_lds_dwordx4 v[230:231], off
	s_waitcnt vmcnt(8)
	s_waitcnt lgkmcnt(0)
	s_barrier
; #define PG8_STAGE(bufoff, gbase, voff) do { _Pragma("unroll") for (int _i = 0; _i < 2; ++_i) \
;         __builtin_amdgcn_global_load_lds((const unsigned*)((const char*)(gbase) + (voff)[_i]), (LAS unsigned*)(lds + (bufoff) + ldsw + _i * 8192), 16, 0, 0); } while (0)
; #define PG8_LDA(dst, b, h) do { _Pragma("unroll") for (int m = 0; m < 4; ++m) _Pragma("unroll") for (int k = 0; k < 2; ++k) dst[m][k] = *(const LAS bf16x8*)(lds + PG8_SA(b, h) + aoff + m * 2048 + k * 1024); } while (0)
; #define PG8_LDB(dst, b, h) do { _Pragma("unroll") for (int n = 0; n < 2; ++n) _Pragma("unroll") for (int k = 0; k < 2; ++k) dst[n][k] = *(const LAS bf16x8*)(lds + PG8_SB(b, h) + boff + n * 2048 + k * 1024); } while (0)
; #define PG8_MMA(ai, bj, At, Bt) do { __builtin_amdgcn_s_setprio(1); _Pragma("unroll") for (int m = 0; m < 4; ++m) _Pragma("unroll") for (int n = 0; n < 2; ++n) _Pragma("unroll") for (int k = 0; k < 2; ++k) \
;         acc[ai][bj][m][n] = __builtin_amdgcn_mfma_f32_16x16x32_bf16(Bt[n][k], At[m][k], acc[ai][bj][m][n], 0, 0, 0); __builtin_amdgcn_s_setprio(0); } while (0)
; #define PG8_WAIT_V(n) asm volatile("s_waitcnt vmcnt(" #n ")" ::: "memory")
; #define PG8_WAIT_L(n) asm volatile("s_waitcnt lgkmcnt(" #n ")" ::: "memory")
; #define PG8_BAR __builtin_amdgcn_s_barrier()
; #define PG8_SCHED __builtin_amdgcn_sched_barrier(0)
; template <int GI>
; __device__ __forceinline__ void gemm_phase(LAS unsigned char* lds, unsigned char* ws, int G, int cblk) {
;     ...
;             PG8_WAIT_V(8); PG8_WAIT_L(0); PG8_BAR; PG8_MMA(1, 0, At, B0); PG8_MMA(1, 1, At, B1); PG8_BAR; PG8_SCHED;
;             PG8_LDB(B0, 1, 0); PG8_LDB(B1, 1, 1); PG8_SCHED; PG8_LDA(At, 1, 0); PG8_STAGE(PG8_SA(0, 1), a2 + hstepA, voffA);
;             PG8_WAIT_V(8); PG8_WAIT_L(0); PG8_BAR; PG8_MMA(0, 0, At, B0); PG8_MMA(0, 1, At, B1); PG8_BAR; PG8_SCHED;
	s_setprio 1
	s_waitcnt lgkmcnt(0)
	v_mfma_f32_16x16x32_bf16 v[60:63], v[154:157], v[196:199], 0
	v_mfma_f32_16x16x32_bf16 v[56:59], v[168:171], v[196:199], 0
	v_mfma_f32_16x16x32_bf16 v[52:55], v[154:157], v[204:207], 0
	v_mfma_f32_16x16x32_bf16 v[48:51], v[168:171], v[204:207], 0
	v_mfma_f32_16x16x32_bf16 v[36:39], v[154:157], v[212:215], 0
	v_mfma_f32_16x16x32_bf16 v[32:35], v[168:171], v[212:215], 0
	v_mfma_f32_16x16x32_bf16 v[20:23], v[154:157], v[220:223], 0
	v_mfma_f32_16x16x32_bf16 v[16:19], v[168:171], v[220:223], 0
	v_mfma_f32_16x16x32_bf16 v[60:63], v[164:167], v[200:203], v[60:63]
	v_mfma_f32_16x16x32_bf16 v[56:59], v[172:175], v[200:203], v[56:59]
	v_mfma_f32_16x16x32_bf16 v[52:55], v[164:167], v[208:211], v[52:55]
	v_mfma_f32_16x16x32_bf16 v[48:51], v[172:175], v[208:211], v[48:51]
	v_mfma_f32_16x16x32_bf16 v[36:39], v[164:167], v[216:219], v[36:39]
	v_mfma_f32_16x16x32_bf16 v[32:35], v[172:175], v[216:219], v[32:35]
	v_mfma_f32_16x16x32_bf16 v[20:23], v[164:167], v[224:227], v[20:23]
	v_mfma_f32_16x16x32_bf16 v[16:19], v[172:175], v[224:227], v[16:19]
	s_setprio 0
	s_setprio 1
	v_mfma_f32_16x16x32_bf16 v[44:47], v[176:179], v[196:199], 0
	v_mfma_f32_16x16x32_bf16 v[40:43], v[184:187], v[196:199], 0
	v_mfma_f32_16x16x32_bf16 v[28:31], v[176:179], v[204:207], 0
	v_mfma_f32_16x16x32_bf16 v[24:27], v[184:187], v[204:207], 0
	v_mfma_f32_16x16x32_bf16 v[12:15], v[176:179], v[212:215], 0
	v_mfma_f32_16x16x32_bf16 v[8:11], v[184:187], v[212:215], 0
	v_mfma_f32_16x16x32_bf16 v[4:7], v[176:179], v[220:223], 0
	v_mfma_f32_16x16x32_bf16 v[0:3], v[184:187], v[220:223], 0
	v_mfma_f32_16x16x32_bf16 v[44:47], v[180:183], v[200:203], v[44:47]
	v_mfma_f32_16x16x32_bf16 v[40:43], v[192:195], v[200:203], v[40:43]
	v_mfma_f32_16x16x32_bf16 v[28:31], v[180:183], v[208:211], v[28:31]
	v_mfma_f32_16x16x32_bf16 v[24:27], v[192:195], v[208:211], v[24:27]
	v_mfma_f32_16x16x32_bf16 v[12:15], v[180:183], v[216:219], v[12:15]
	v_mfma_f32_16x16x32_bf16 v[8:11], v[192:195], v[216:219], v[8:11]
	v_mfma_f32_16x16x32_bf16 v[4:7], v[180:183], v[224:227], v[4:7]
	v_mfma_f32_16x16x32_bf16 v[0:3], v[192:195], v[224:227], v[0:3]
	s_setprio 0
	s_barrier
	s_add_i32 s34, 0, 0x18000
	v_add_u32_e32 v161, s34, v150
	s_add_i32 s53, 0, 0x1c000
	ds_read_b128 v[154:157], v161
	ds_read_b128 v[164:167], v161 offset:1024
	ds_read_b128 v[168:171], v161 offset:2048
	ds_read_b128 v[172:175], v161 offset:3072
	v_add_u32_e32 v161, s53, v150
	ds_read_b128 v[176:179], v161
	ds_read_b128 v[180:183], v161 offset:1024
	ds_read_b128 v[184:187], v161 offset:2048
	ds_read_b128 v[192:195], v161 offset:3072
	s_add_u32 s50, s50, 0x80000
	s_addc_u32 s51, s51, 0
	s_mov_b32 m0, s22
	v_lshl_add_u64 v[232:233], s[50:51], 0, v[134:135]
	ds_read_b128 v[196:199], v153 offset:32768
	ds_read_b128 v[200:203], v153 offset:33792
	ds_read_b128 v[204:207], v153 offset:34816
	ds_read_b128 v[208:211], v153 offset:35840
	ds_read_b128 v[212:215], v153 offset:36864
	ds_read_b128 v[216:219], v153 offset:37888
	ds_read_b128 v[220:223], v153 offset:38912
	ds_read_b128 v[224:227], v153 offset:39936
	global_load_lds_dwordx4 v[232:233], off
	v_lshl_add_u64 v[232:233], s[50:51], 0, v[130:131]
	s_mov_b32 m0, s23
	s_nop 0
	global_load_lds_dwordx4 v[232:233], off
	s_waitcnt vmcnt(8)
	s_waitcnt lgkmcnt(0)
	s_barrier
	s_setprio 1
	s_waitcnt lgkmcnt(0)
	v_mfma_f32_16x16x32_bf16 v[124:127], v[154:157], v[196:199], v[124:127]
	v_mfma_f32_16x16x32_bf16 v[120:123], v[168:171], v[196:199], v[120:123]
	v_mfma_f32_16x16x32_bf16 v[116:119], v[154:157], v[204:207], v[116:119]
	v_mfma_f32_16x16x32_bf16 v[112:115], v[168:171], v[204:207], v[112:115]
	v_mfma_f32_16x16x32_bf16 v[100:103], v[154:157], v[212:215], v[100:103]
	v_mfma_f32_16x16x32_bf16 v[96:99], v[168:171], v[212:215], v[96:99]
	v_mfma_f32_16x16x32_bf16 v[84:87], v[154:157], v[220:223], v[84:87]
	v_mfma_f32_16x16x32_bf16 v[80:83], v[168:171], v[220:223], v[80:83]
	v_mfma_f32_16x16x32_bf16 v[124:127], v[164:167], v[200:203], v[124:127]
	v_mfma_f32_16x16x32_bf16 v[120:123], v[172:175], v[200:203], v[120:123]
	v_mfma_f32_16x16x32_bf16 v[116:119], v[164:167], v[208:211], v[116:119]
	v_mfma_f32_16x16x32_bf16 v[112:115], v[172:175], v[208:211], v[112:115]
	v_mfma_f32_16x16x32_bf16 v[100:103], v[164:167], v[216:219], v[100:103]
	v_mfma_f32_16x16x32_bf16 v[96:99], v[172:175], v[216:219], v[96:99]
	v_mfma_f32_16x16x32_bf16 v[84:87], v[164:167], v[224:227], v[84:87]
	v_mfma_f32_16x16x32_bf16 v[80:83], v[172:175], v[224:227], v[80:83]
	s_setprio 0
	s_setprio 1
	v_mfma_f32_16x16x32_bf16 v[108:111], v[176:179], v[196:199], v[108:111]
	v_mfma_f32_16x16x32_bf16 v[104:107], v[184:187], v[196:199], v[104:107]
	v_mfma_f32_16x16x32_bf16 v[92:95], v[176:179], v[204:207], v[92:95]
	v_mfma_f32_16x16x32_bf16 v[88:91], v[184:187], v[204:207], v[88:91]
	v_mfma_f32_16x16x32_bf16 v[76:79], v[176:179], v[212:215], v[76:79]
	v_mfma_f32_16x16x32_bf16 v[72:75], v[184:187], v[212:215], v[72:75]
	v_mfma_f32_16x16x32_bf16 v[68:71], v[176:179], v[220:223], v[68:71]
	v_mfma_f32_16x16x32_bf16 v[64:67], v[184:187], v[220:223], v[64:67]
	v_mfma_f32_16x16x32_bf16 v[108:111], v[180:183], v[200:203], v[108:111]
	v_mfma_f32_16x16x32_bf16 v[104:107], v[192:195], v[200:203], v[104:107]
	v_mfma_f32_16x16x32_bf16 v[92:95], v[180:183], v[208:211], v[92:95]
	v_mfma_f32_16x16x32_bf16 v[88:91], v[192:195], v[208:211], v[88:91]
	v_mfma_f32_16x16x32_bf16 v[76:79], v[180:183], v[216:219], v[76:79]
	v_mfma_f32_16x16x32_bf16 v[72:75], v[192:195], v[216:219], v[72:75]
	v_mfma_f32_16x16x32_bf16 v[68:71], v[180:183], v[224:227], v[68:71]
	v_mfma_f32_16x16x32_bf16 v[64:67], v[192:195], v[224:227], v[64:67]
	s_setprio 0
	s_barrier
; #define PG8_STAGE(bufoff, gbase, voff) do { _Pragma("unroll") for (int _i = 0; _i < 2; ++_i) \
;         __builtin_amdgcn_global_load_lds((const unsigned*)((const char*)(gbase) + (voff)[_i]), (LAS unsigned*)(lds + (bufoff) + ldsw + _i * 8192), 16, 0, 0); } while (0)
; #define PG8_LDA(dst, b, h) do { _Pragma("unroll") for (int m = 0; m < 4; ++m) _Pragma("unroll") for (int k = 0; k < 2; ++k) dst[m][k] = *(const LAS bf16x8*)(lds + PG8_SA(b, h) + aoff + m * 2048 + k * 1024); } while (0)
; #define PG8_MMA(ai, bj, At, Bt) do { __builtin_amdgcn_s_setprio(1); _Pragma("unroll") for (int m = 0; m < 4; ++m) _Pragma("unroll") for (int n = 0; n < 2; ++n) _Pragma("unroll") for (int k = 0; k < 2; ++k) \
;         acc[ai][bj][m][n] = __builtin_amdgcn_mfma_f32_16x16x32_bf16(Bt[n][k], At[m][k], acc[ai][bj][m][n], 0, 0, 0); __builtin_amdgcn_s_setprio(0); } while (0)
; #define PG8_WAIT_V(n) asm volatile("s_waitcnt vmcnt(" #n ")" ::: "memory")
; #define PG8_WAIT_L(n) asm volatile("s_waitcnt lgkmcnt(" #n ")" ::: "memory")
; #define PG8_BAR __builtin_amdgcn_s_barrier()
; #define PG8_SCHED __builtin_amdgcn_sched_barrier(0)
; template <int GI>
; __device__ __forceinline__ void gemm_phase(LAS unsigned char* lds, unsigned char* ws, int G, int cblk) {
;     ...
;         for (int t = 0; t < nt; t += 2) {
;             const bool last = (t == nt - 2);
;     ...
;             PG8_LDA(At, 1, 1); PG8_STAGE(PG8_SB(1, 0), b3, voffB); PG8_STAGE(PG8_SB(1, 1), b3 + hstepB, voffB); PG8_STAGE(PG8_SA(1, 0), a3, voffA);
;             PG8_WAIT_V(8); PG8_WAIT_L(0); PG8_BAR; PG8_MMA(1, 0, At, B0); PG8_MMA(1, 1, At, B1); PG8_BAR; PG8_SCHED;
	s_add_i32 s34, s34, s0
	v_lshl_add_u64 v[158:159], v[158:159], 0, s[8:9]
	s_mov_b32 m0, s34
	ds_read_b128 v[196:199], v153 offset:49152
	ds_read_b128 v[200:203], v153 offset:50176
	ds_read_b128 v[204:207], v153 offset:51200
	ds_read_b128 v[208:211], v153 offset:52224
	ds_read_b128 v[212:215], v153 offset:53248
	ds_read_b128 v[216:219], v153 offset:54272
	ds_read_b128 v[220:223], v153 offset:55296
	ds_read_b128 v[224:227], v153 offset:56320
	global_load_lds_dwordx4 v[158:159], off
	s_add_i32 m0, s34, 0x2000
	s_add_u32 s48, s48, 0x100080
	v_lshl_add_u64 v[158:159], v[188:189], 0, s[8:9]
	s_addc_u32 s49, s49, 0
	s_add_i32 s34, s53, s0
	global_load_lds_dwordx4 v[158:159], off
	v_lshl_add_u64 v[158:159], s[48:49], 0, v[132:133]
	s_mov_b32 m0, s34
	s_nop 0
	global_load_lds_dwordx4 v[158:159], off
	v_lshl_add_u64 v[158:159], s[48:49], 0, v[128:129]
	s_add_i32 m0, s34, 0x2000
	s_nop 0
	global_load_lds_dwordx4 v[158:159], off
	v_lshl_add_u64 v[158:159], v[228:229], 0, s[8:9]
	s_mov_b32 m0, s26
	s_nop 0
	global_load_lds_dwordx4 v[158:159], off
	v_lshl_add_u64 v[158:159], v[230:231], 0, s[8:9]
	s_mov_b32 m0, s27
	s_nop 0
	global_load_lds_dwordx4 v[158:159], off
	s_waitcnt vmcnt(8)
	s_waitcnt lgkmcnt(0)
	s_barrier
	s_setprio 1
	s_waitcnt lgkmcnt(0)
	v_mfma_f32_16x16x32_bf16 v[60:63], v[154:157], v[196:199], v[60:63]
	v_mfma_f32_16x16x32_bf16 v[56:59], v[168:171], v[196:199], v[56:59]
	v_mfma_f32_16x16x32_bf16 v[52:55], v[154:157], v[204:207], v[52:55]
	v_mfma_f32_16x16x32_bf16 v[48:51], v[168:171], v[204:207], v[48:51]
	v_mfma_f32_16x16x32_bf16 v[36:39], v[154:157], v[212:215], v[36:39]
	v_mfma_f32_16x16x32_bf16 v[32:35], v[168:171], v[212:215], v[32:35]
	v_mfma_f32_16x16x32_bf16 v[20:23], v[154:157], v[220:223], v[20:23]
	v_mfma_f32_16x16x32_bf16 v[16:19], v[168:171], v[220:223], v[16:19]
	v_mfma_f32_16x16x32_bf16 v[60:63], v[164:167], v[200:203], v[60:63]
	v_mfma_f32_16x16x32_bf16 v[56:59], v[172:175], v[200:203], v[56:59]
	v_mfma_f32_16x16x32_bf16 v[52:55], v[164:167], v[208:211], v[52:55]
	v_mfma_f32_16x16x32_bf16 v[48:51], v[172:175], v[208:211], v[48:51]
	v_mfma_f32_16x16x32_bf16 v[36:39], v[164:167], v[216:219], v[36:39]
	v_mfma_f32_16x16x32_bf16 v[32:35], v[172:175], v[216:219], v[32:35]
	v_mfma_f32_16x16x32_bf16 v[20:23], v[164:167], v[224:227], v[20:23]
	v_mfma_f32_16x16x32_bf16 v[16:19], v[172:175], v[224:227], v[16:19]
	s_setprio 0
	s_setprio 1
	v_mfma_f32_16x16x32_bf16 v[44:47], v[176:179], v[196:199], v[44:47]
	v_mfma_f32_16x16x32_bf16 v[40:43], v[184:187], v[196:199], v[40:43]
	v_mfma_f32_16x16x32_bf16 v[28:31], v[176:179], v[204:207], v[28:31]
	v_mfma_f32_16x16x32_bf16 v[24:27], v[184:187], v[204:207], v[24:27]
	v_mfma_f32_16x16x32_bf16 v[12:15], v[176:179], v[212:215], v[12:15]
	v_mfma_f32_16x16x32_bf16 v[8:11], v[184:187], v[212:215], v[8:11]
	v_mfma_f32_16x16x32_bf16 v[4:7], v[176:179], v[220:223], v[4:7]
	v_mfma_f32_16x16x32_bf16 v[0:3], v[184:187], v[220:223], v[0:3]
	v_mfma_f32_16x16x32_bf16 v[44:47], v[180:183], v[200:203], v[44:47]
	v_mfma_f32_16x16x32_bf16 v[40:43], v[192:195], v[200:203], v[40:43]
	v_mfma_f32_16x16x32_bf16 v[28:31], v[180:183], v[208:211], v[28:31]
	v_mfma_f32_16x16x32_bf16 v[24:27], v[192:195], v[208:211], v[24:27]
	v_mfma_f32_16x16x32_bf16 v[12:15], v[180:183], v[216:219], v[12:15]
	v_mfma_f32_16x16x32_bf16 v[8:11], v[192:195], v[216:219], v[8:11]
	v_mfma_f32_16x16x32_bf16 v[4:7], v[180:183], v[224:227], v[4:7]
	v_mfma_f32_16x16x32_bf16 v[0:3], v[192:195], v[224:227], v[0:3]
	s_setprio 0
	s_barrier
	s_add_i32 s19, s19, 2
	s_add_u32 s46, s46, 0x100
	s_addc_u32 s47, s47, 0
	s_add_u32 s14, s14, 0x100
	s_addc_u32 s15, s15, 0
	s_cmp_gt_u32 s19, 5
	s_cbranch_scc0 .LBB0_432
	s_branch .Lpeel_exit_5

; #define PG8_STAGE(bufoff, gbase, voff) do { _Pragma("unroll") for (int _i = 0; _i < 2; ++_i) \
;         __builtin_amdgcn_global_load_lds((const unsigned*)((const char*)(gbase) + (voff)[_i]), (LAS unsigned*)(lds + (bufoff) + ldsw + _i * 8192), 16, 0, 0); } while (0)
; #define PG8_LDA(dst, b, h) do { _Pragma("unroll") for (int m = 0; m < 4; ++m) _Pragma("unroll") for (int k = 0; k < 2; ++k) dst[m][k] = *(const LAS bf16x8*)(lds + PG8_SA(b, h) + aoff + m * 2048 + k * 1024); } while (0)
; #define PG8_LDB(dst, b, h) do { _Pragma("unroll") for (int n = 0; n < 2; ++n) _Pragma("unroll") for (int k = 0; k < 2; ++k) dst[n][k] = *(const LAS bf16x8*)(lds + PG8_SB(b, h) + boff + n * 2048 + k * 1024); } while (0)
; #define PG8_MMA(ai, bj, At, Bt) do { __builtin_amdgcn_s_setprio(1); _Pragma("unroll") for (int m = 0; m < 4; ++m) _Pragma("unroll") for (int n = 0; n < 2; ++n) _Pragma("unroll") for (int k = 0; k < 2; ++k) \
;         acc[ai][bj][m][n] = __builtin_amdgcn_mfma_f32_16x16x32_bf16(Bt[n][k], At[m][k], acc[ai][bj][m][n], 0, 0, 0); __builtin_amdgcn_s_setprio(0); } while (0)
; #define PG8_WAIT_V(n) asm volatile("s_waitcnt vmcnt(" #n ")" ::: "memory")
; #define PG8_WAIT_L(n) asm volatile("s_waitcnt lgkmcnt(" #n ")" ::: "memory")
; #define PG8_BAR __builtin_amdgcn_s_barrier()
; #define PG8_SCHED __builtin_amdgcn_sched_barrier(0)
; template <int GI>
; __device__ __forceinline__ void gemm_phase(LAS unsigned char* lds, unsigned char* ws, int G, int cblk) {
;     ...
;             PG8_LDB(B0, 0, 0); PG8_LDB(B1, 0, 1); PG8_SCHED; PG8_LDA(At, 0, 0); PG8_STAGE(PG8_SA(1, 1), a1 + hstepA, voffA);
;             PG8_WAIT_V(8); PG8_WAIT_L(0); PG8_BAR; PG8_MMA(0, 0, At, B0); PG8_MMA(0, 1, At, B1); PG8_BAR; PG8_SCHED;
;             PG8_LDA(At, 0, 1); PG8_STAGE(PG8_SB(0, 0), b2, voffB); PG8_STAGE(PG8_SB(0, 1), b2 + hstepB, voffB); PG8_STAGE(PG8_SA(0, 0), a2, voffA);
;             PG8_WAIT_V(8); PG8_WAIT_L(0); PG8_BAR; PG8_MMA(1, 0, At, B0); PG8_MMA(1, 1, At, B1); PG8_BAR; PG8_SCHED;
;     ...
;         for (int a = 0; a < 2; ++a)
; #pragma unroll
;             for (int b = 0; b < 2; ++b)
; #pragma unroll
;                 for (int m = 0; m < 4; ++m)
; #pragma unroll
;                     for (int n = 0; n < 2; ++n) acc[a][b][m][n] = (f32x4){0.f, 0.f, 0.f, 0.f};
.LBB0_564:
	s_add_u32 s48, s48, 0x80080
	s_addc_u32 s49, s49, 0
	s_add_u32 s0, s50, 0x100
	s_addc_u32 s1, s51, 0
	s_mov_b32 s16, -2
	ds_read_b128 v[152:155], v167
	ds_read_b128 v[156:159], v167 offset:1024
	ds_read_b128 v[172:175], v167 offset:2048
	ds_read_b128 v[176:179], v167 offset:3072
	ds_read_b128 v[180:183], v168
	ds_read_b128 v[184:187], v168 offset:1024
	ds_read_b128 v[192:195], v168 offset:2048
	ds_read_b128 v[196:199], v168 offset:3072
	s_add_u32 s17, s48, 0xfff80080
	s_addc_u32 s33, s49, -1
	s_cmp_eq_u32 s16, 28
	s_cselect_b32 s53, s41, s33
	s_cselect_b32 s52, s40, s17
	s_cselect_b32 s51, s43, s1
	s_cselect_b32 s50, s42, s0
	v_lshl_add_u64 v[164:165], s[48:49], 0, v[148:149]
	s_add_i32 m0, s23, 0xc000
	ds_read_b128 v[200:203], v169
	ds_read_b128 v[204:207], v169 offset:1024
	ds_read_b128 v[208:211], v169 offset:2048
	ds_read_b128 v[212:215], v169 offset:3072
	ds_read_b128 v[216:219], v169 offset:4096
	ds_read_b128 v[220:223], v169 offset:5120
	ds_read_b128 v[224:227], v169 offset:6144
	ds_read_b128 v[228:231], v169 offset:7168
	global_load_lds_dwordx4 v[164:165], off
	v_lshl_add_u64 v[164:165], s[48:49], 0, v[150:151]
	s_add_i32 m0, s23, 0xe000
	s_nop 0
	global_load_lds_dwordx4 v[164:165], off
	s_waitcnt vmcnt(8)
	s_waitcnt lgkmcnt(0)
	s_barrier
	s_setprio 1
	s_waitcnt lgkmcnt(0)
	v_mfma_f32_16x16x32_bf16 v[124:127], v[152:155], v[200:203], 0
	v_mfma_f32_16x16x32_bf16 v[120:123], v[172:175], v[200:203], 0
	v_mfma_f32_16x16x32_bf16 v[108:111], v[152:155], v[208:211], 0
	v_mfma_f32_16x16x32_bf16 v[104:107], v[172:175], v[208:211], 0
	v_mfma_f32_16x16x32_bf16 v[92:95], v[152:155], v[216:219], 0
	v_mfma_f32_16x16x32_bf16 v[88:91], v[172:175], v[216:219], 0
	v_mfma_f32_16x16x32_bf16 v[76:79], v[152:155], v[224:227], 0
	v_mfma_f32_16x16x32_bf16 v[72:75], v[172:175], v[224:227], 0
	v_mfma_f32_16x16x32_bf16 v[124:127], v[156:159], v[204:207], v[124:127]
	v_mfma_f32_16x16x32_bf16 v[120:123], v[176:179], v[204:207], v[120:123]
	v_mfma_f32_16x16x32_bf16 v[108:111], v[156:159], v[212:215], v[108:111]
	v_mfma_f32_16x16x32_bf16 v[104:107], v[176:179], v[212:215], v[104:107]
	v_mfma_f32_16x16x32_bf16 v[92:95], v[156:159], v[220:223], v[92:95]
	v_mfma_f32_16x16x32_bf16 v[88:91], v[176:179], v[220:223], v[88:91]
	v_mfma_f32_16x16x32_bf16 v[76:79], v[156:159], v[228:231], v[76:79]
	v_mfma_f32_16x16x32_bf16 v[72:75], v[176:179], v[228:231], v[72:75]
	s_setprio 0
	s_setprio 1
	v_mfma_f32_16x16x32_bf16 v[116:119], v[180:183], v[200:203], 0
	v_mfma_f32_16x16x32_bf16 v[112:115], v[192:195], v[200:203], 0
	v_mfma_f32_16x16x32_bf16 v[100:103], v[180:183], v[208:211], 0
	v_mfma_f32_16x16x32_bf16 v[96:99], v[192:195], v[208:211], 0
	v_mfma_f32_16x16x32_bf16 v[84:87], v[180:183], v[216:219], 0
	v_mfma_f32_16x16x32_bf16 v[80:83], v[192:195], v[216:219], 0
	v_mfma_f32_16x16x32_bf16 v[68:71], v[180:183], v[224:227], 0
	v_mfma_f32_16x16x32_bf16 v[64:67], v[192:195], v[224:227], 0
	v_mfma_f32_16x16x32_bf16 v[116:119], v[184:187], v[204:207], v[116:119]
	v_mfma_f32_16x16x32_bf16 v[112:115], v[196:199], v[204:207], v[112:115]
	v_mfma_f32_16x16x32_bf16 v[100:103], v[184:187], v[212:215], v[100:103]
	v_mfma_f32_16x16x32_bf16 v[96:99], v[196:199], v[212:215], v[96:99]
	v_mfma_f32_16x16x32_bf16 v[84:87], v[184:187], v[220:223], v[84:87]
	v_mfma_f32_16x16x32_bf16 v[80:83], v[196:199], v[220:223], v[80:83]
	v_mfma_f32_16x16x32_bf16 v[68:71], v[184:187], v[228:231], v[68:71]
	v_mfma_f32_16x16x32_bf16 v[64:67], v[196:199], v[228:231], v[64:67]
	s_setprio 0
	s_barrier
	s_add_i32 s17, s60, s22
	v_lshl_add_u64 v[164:165], s[50:51], 0, v[132:133]
	s_mov_b32 m0, s17
	ds_read_b128 v[200:203], v169 offset:16384
	ds_read_b128 v[204:207], v169 offset:17408
	ds_read_b128 v[208:211], v169 offset:18432
	ds_read_b128 v[212:215], v169 offset:19456
	ds_read_b128 v[216:219], v169 offset:20480
	ds_read_b128 v[220:223], v169 offset:21504
	ds_read_b128 v[224:227], v169 offset:22528
	ds_read_b128 v[228:231], v169 offset:23552
	global_load_lds_dwordx4 v[164:165], off
	s_add_i32 m0, s17, 0x2000
	s_add_u32 s64, s50, 0x80000
	v_lshl_add_u64 v[188:189], s[50:51], 0, v[136:137]
	s_addc_u32 s65, s51, 0
	s_add_i32 s17, s61, s22
	global_load_lds_dwordx4 v[188:189], off
	v_lshl_add_u64 v[232:233], s[64:65], 0, v[132:133]
	s_mov_b32 m0, s17
	v_lshl_add_u64 v[234:235], s[52:53], 0, v[134:135]
	global_load_lds_dwordx4 v[232:233], off
	v_lshl_add_u64 v[232:233], s[64:65], 0, v[136:137]
	s_add_i32 m0, s17, 0x2000
	s_nop 0
	global_load_lds_dwordx4 v[232:233], off
	v_lshl_add_u64 v[232:233], s[52:53], 0, v[130:131]
	s_mov_b32 m0, s23
	s_nop 0
	global_load_lds_dwordx4 v[232:233], off
	s_mov_b32 m0, s24
	s_nop 0
	global_load_lds_dwordx4 v[234:235], off
	s_waitcnt vmcnt(8)
	s_waitcnt lgkmcnt(0)
	s_barrier
; #define PG8_STAGE(bufoff, gbase, voff) do { _Pragma("unroll") for (int _i = 0; _i < 2; ++_i) \
;         __builtin_amdgcn_global_load_lds((const unsigned*)((const char*)(gbase) + (voff)[_i]), (LAS unsigned*)(lds + (bufoff) + ldsw + _i * 8192), 16, 0, 0); } while (0)
; #define PG8_LDA(dst, b, h) do { _Pragma("unroll") for (int m = 0; m < 4; ++m) _Pragma("unroll") for (int k = 0; k < 2; ++k) dst[m][k] = *(const LAS bf16x8*)(lds + PG8_SA(b, h) + aoff + m * 2048 + k * 1024); } while (0)
; #define PG8_LDB(dst, b, h) do { _Pragma("unroll") for (int n = 0; n < 2; ++n) _Pragma("unroll") for (int k = 0; k < 2; ++k) dst[n][k] = *(const LAS bf16x8*)(lds + PG8_SB(b, h) + boff + n * 2048 + k * 1024); } while (0)
; #define PG8_MMA(ai, bj, At, Bt) do { __builtin_amdgcn_s_setprio(1); _Pragma("unroll") for (int m = 0; m < 4; ++m) _Pragma("unroll") for (int n = 0; n < 2; ++n) _Pragma("unroll") for (int k = 0; k < 2; ++k) \
;         acc[ai][bj][m][n] = __builtin_amdgcn_mfma_f32_16x16x32_bf16(Bt[n][k], At[m][k], acc[ai][bj][m][n], 0, 0, 0); __builtin_amdgcn_s_setprio(0); } while (0)
; #define PG8_WAIT_V(n) asm volatile("s_waitcnt vmcnt(" #n ")" ::: "memory")
; #define PG8_WAIT_L(n) asm volatile("s_waitcnt lgkmcnt(" #n ")" ::: "memory")
; #define PG8_BAR __builtin_amdgcn_s_barrier()
; #define PG8_SCHED __builtin_amdgcn_sched_barrier(0)
; template <int GI>
; __device__ __forceinline__ void gemm_phase(LAS unsigned char* lds, unsigned char* ws, int G, int cblk) {
;     ...
;             PG8_WAIT_V(8); PG8_WAIT_L(0); PG8_BAR; PG8_MMA(1, 0, At, B0); PG8_MMA(1, 1, At, B1); PG8_BAR; PG8_SCHED;
;             PG8_LDB(B0, 1, 0); PG8_LDB(B1, 1, 1); PG8_SCHED; PG8_LDA(At, 1, 0); PG8_STAGE(PG8_SA(0, 1), a2 + hstepA, voffA);
;             PG8_WAIT_V(8); PG8_WAIT_L(0); PG8_BAR; PG8_MMA(0, 0, At, B0); PG8_MMA(0, 1, At, B1); PG8_BAR; PG8_SCHED;
	s_setprio 1
	s_waitcnt lgkmcnt(0)
	v_mfma_f32_16x16x32_bf16 v[60:63], v[152:155], v[200:203], 0
	v_mfma_f32_16x16x32_bf16 v[56:59], v[172:175], v[200:203], 0
	v_mfma_f32_16x16x32_bf16 v[44:47], v[152:155], v[208:211], 0
	v_mfma_f32_16x16x32_bf16 v[40:43], v[172:175], v[208:211], 0
	v_mfma_f32_16x16x32_bf16 v[28:31], v[152:155], v[216:219], 0
	v_mfma_f32_16x16x32_bf16 v[24:27], v[172:175], v[216:219], 0
	v_mfma_f32_16x16x32_bf16 v[12:15], v[152:155], v[224:227], 0
	v_mfma_f32_16x16x32_bf16 v[8:11], v[172:175], v[224:227], 0
	v_mfma_f32_16x16x32_bf16 v[60:63], v[156:159], v[204:207], v[60:63]
	v_mfma_f32_16x16x32_bf16 v[56:59], v[176:179], v[204:207], v[56:59]
	v_mfma_f32_16x16x32_bf16 v[44:47], v[156:159], v[212:215], v[44:47]
	v_mfma_f32_16x16x32_bf16 v[40:43], v[176:179], v[212:215], v[40:43]
	v_mfma_f32_16x16x32_bf16 v[28:31], v[156:159], v[220:223], v[28:31]
	v_mfma_f32_16x16x32_bf16 v[24:27], v[176:179], v[220:223], v[24:27]
	v_mfma_f32_16x16x32_bf16 v[12:15], v[156:159], v[228:231], v[12:15]
	v_mfma_f32_16x16x32_bf16 v[8:11], v[176:179], v[228:231], v[8:11]
	s_setprio 0
	s_setprio 1
	v_mfma_f32_16x16x32_bf16 v[52:55], v[180:183], v[200:203], 0
	v_mfma_f32_16x16x32_bf16 v[48:51], v[192:195], v[200:203], 0
	v_mfma_f32_16x16x32_bf16 v[36:39], v[180:183], v[208:211], 0
	v_mfma_f32_16x16x32_bf16 v[32:35], v[192:195], v[208:211], 0
	v_mfma_f32_16x16x32_bf16 v[20:23], v[180:183], v[216:219], 0
	v_mfma_f32_16x16x32_bf16 v[16:19], v[192:195], v[216:219], 0
	v_mfma_f32_16x16x32_bf16 v[4:7], v[180:183], v[224:227], 0
	v_mfma_f32_16x16x32_bf16 v[0:3], v[192:195], v[224:227], 0
	v_mfma_f32_16x16x32_bf16 v[52:55], v[184:187], v[204:207], v[52:55]
	v_mfma_f32_16x16x32_bf16 v[48:51], v[196:199], v[204:207], v[48:51]
	v_mfma_f32_16x16x32_bf16 v[36:39], v[184:187], v[212:215], v[36:39]
	v_mfma_f32_16x16x32_bf16 v[32:35], v[196:199], v[212:215], v[32:35]
	v_mfma_f32_16x16x32_bf16 v[20:23], v[184:187], v[220:223], v[20:23]
	v_mfma_f32_16x16x32_bf16 v[16:19], v[196:199], v[220:223], v[16:19]
	v_mfma_f32_16x16x32_bf16 v[4:7], v[184:187], v[228:231], v[4:7]
	v_mfma_f32_16x16x32_bf16 v[0:3], v[196:199], v[228:231], v[0:3]
	s_setprio 0
	s_barrier
	s_add_i32 s17, 0, 0x18000
	s_add_i32 s33, 0, 0x1c000
	v_add_u32_e32 v176, s17, v161
	v_add_u32_e32 v191, s33, v161
	ds_read_b128 v[152:155], v176
	ds_read_b128 v[156:159], v176 offset:1024
	ds_read_b128 v[172:175], v176 offset:2048
	ds_read_b128 v[176:179], v176 offset:3072
	ds_read_b128 v[180:183], v191
	ds_read_b128 v[184:187], v191 offset:1024
	ds_read_b128 v[192:195], v191 offset:2048
	ds_read_b128 v[196:199], v191 offset:3072
	s_add_u32 s52, s52, 0x80000
	s_addc_u32 s53, s53, 0
	s_mov_b32 m0, s25
	v_lshl_add_u64 v[236:237], s[52:53], 0, v[130:131]
	ds_read_b128 v[200:203], v169 offset:32768
	ds_read_b128 v[204:207], v169 offset:33792
	ds_read_b128 v[208:211], v169 offset:34816
	ds_read_b128 v[212:215], v169 offset:35840
	ds_read_b128 v[216:219], v169 offset:36864
	ds_read_b128 v[220:223], v169 offset:37888
	ds_read_b128 v[224:227], v169 offset:38912
	ds_read_b128 v[228:231], v169 offset:39936
	global_load_lds_dwordx4 v[236:237], off
	v_lshl_add_u64 v[236:237], s[52:53], 0, v[134:135]
	s_mov_b32 m0, s26
	s_nop 0
	global_load_lds_dwordx4 v[236:237], off
	s_waitcnt vmcnt(8)
	s_waitcnt lgkmcnt(0)
	s_barrier
	s_setprio 1
	s_waitcnt lgkmcnt(0)
	v_mfma_f32_16x16x32_bf16 v[124:127], v[152:155], v[200:203], v[124:127]
	v_mfma_f32_16x16x32_bf16 v[120:123], v[172:175], v[200:203], v[120:123]
	v_mfma_f32_16x16x32_bf16 v[108:111], v[152:155], v[208:211], v[108:111]
	v_mfma_f32_16x16x32_bf16 v[104:107], v[172:175], v[208:211], v[104:107]
	v_mfma_f32_16x16x32_bf16 v[92:95], v[152:155], v[216:219], v[92:95]
	v_mfma_f32_16x16x32_bf16 v[88:91], v[172:175], v[216:219], v[88:91]
	v_mfma_f32_16x16x32_bf16 v[76:79], v[152:155], v[224:227], v[76:79]
	v_mfma_f32_16x16x32_bf16 v[72:75], v[172:175], v[224:227], v[72:75]
	v_mfma_f32_16x16x32_bf16 v[124:127], v[156:159], v[204:207], v[124:127]
	v_mfma_f32_16x16x32_bf16 v[120:123], v[176:179], v[204:207], v[120:123]
	v_mfma_f32_16x16x32_bf16 v[108:111], v[156:159], v[212:215], v[108:111]
	v_mfma_f32_16x16x32_bf16 v[104:107], v[176:179], v[212:215], v[104:107]
	v_mfma_f32_16x16x32_bf16 v[92:95], v[156:159], v[220:223], v[92:95]
	v_mfma_f32_16x16x32_bf16 v[88:91], v[176:179], v[220:223], v[88:91]
	v_mfma_f32_16x16x32_bf16 v[76:79], v[156:159], v[228:231], v[76:79]
	v_mfma_f32_16x16x32_bf16 v[72:75], v[176:179], v[228:231], v[72:75]
	s_setprio 0
	s_setprio 1
	v_mfma_f32_16x16x32_bf16 v[116:119], v[180:183], v[200:203], v[116:119]
	v_mfma_f32_16x16x32_bf16 v[112:115], v[192:195], v[200:203], v[112:115]
	v_mfma_f32_16x16x32_bf16 v[100:103], v[180:183], v[208:211], v[100:103]
	v_mfma_f32_16x16x32_bf16 v[96:99], v[192:195], v[208:211], v[96:99]
	v_mfma_f32_16x16x32_bf16 v[84:87], v[180:183], v[216:219], v[84:87]
	v_mfma_f32_16x16x32_bf16 v[80:83], v[192:195], v[216:219], v[80:83]
	v_mfma_f32_16x16x32_bf16 v[68:71], v[180:183], v[224:227], v[68:71]
	v_mfma_f32_16x16x32_bf16 v[64:67], v[192:195], v[224:227], v[64:67]
	v_mfma_f32_16x16x32_bf16 v[116:119], v[184:187], v[204:207], v[116:119]
	v_mfma_f32_16x16x32_bf16 v[112:115], v[196:199], v[204:207], v[112:115]
	v_mfma_f32_16x16x32_bf16 v[100:103], v[184:187], v[212:215], v[100:103]
	v_mfma_f32_16x16x32_bf16 v[96:99], v[196:199], v[212:215], v[96:99]
	v_mfma_f32_16x16x32_bf16 v[84:87], v[184:187], v[220:223], v[84:87]
	v_mfma_f32_16x16x32_bf16 v[80:83], v[196:199], v[220:223], v[80:83]
	v_mfma_f32_16x16x32_bf16 v[68:71], v[184:187], v[228:231], v[68:71]
	v_mfma_f32_16x16x32_bf16 v[64:67], v[196:199], v[228:231], v[64:67]
	s_setprio 0
	s_barrier
; #define PG8_STAGE(bufoff, gbase, voff) do { _Pragma("unroll") for (int _i = 0; _i < 2; ++_i) \
;         __builtin_amdgcn_global_load_lds((const unsigned*)((const char*)(gbase) + (voff)[_i]), (LAS unsigned*)(lds + (bufoff) + ldsw + _i * 8192), 16, 0, 0); } while (0)
; #define PG8_LDA(dst, b, h) do { _Pragma("unroll") for (int m = 0; m < 4; ++m) _Pragma("unroll") for (int k = 0; k < 2; ++k) dst[m][k] = *(const LAS bf16x8*)(lds + PG8_SA(b, h) + aoff + m * 2048 + k * 1024); } while (0)
; #define PG8_MMA(ai, bj, At, Bt) do { __builtin_amdgcn_s_setprio(1); _Pragma("unroll") for (int m = 0; m < 4; ++m) _Pragma("unroll") for (int n = 0; n < 2; ++n) _Pragma("unroll") for (int k = 0; k < 2; ++k) \
;         acc[ai][bj][m][n] = __builtin_amdgcn_mfma_f32_16x16x32_bf16(Bt[n][k], At[m][k], acc[ai][bj][m][n], 0, 0, 0); __builtin_amdgcn_s_setprio(0); } while (0)
; #define PG8_WAIT_V(n) asm volatile("s_waitcnt vmcnt(" #n ")" ::: "memory")
; #define PG8_WAIT_L(n) asm volatile("s_waitcnt lgkmcnt(" #n ")" ::: "memory")
; #define PG8_BAR __builtin_amdgcn_s_barrier()
; #define PG8_SCHED __builtin_amdgcn_sched_barrier(0)
; template <int GI>
; __device__ __forceinline__ void gemm_phase(LAS unsigned char* lds, unsigned char* ws, int G, int cblk) {
;     ...
;         for (int t = 0; t < nt; t += 2) {
;             const bool last = (t == nt - 2);
;     ...
;             PG8_LDA(At, 1, 1); PG8_STAGE(PG8_SB(1, 0), b3, voffB); PG8_STAGE(PG8_SB(1, 1), b3 + hstepB, voffB); PG8_STAGE(PG8_SA(1, 0), a3, voffA);
;             PG8_WAIT_V(8); PG8_WAIT_L(0); PG8_BAR; PG8_MMA(1, 0, At, B0); PG8_MMA(1, 1, At, B1); PG8_BAR; PG8_SCHED;
	s_add_i32 s17, s17, s22
	v_lshl_add_u64 v[164:165], v[164:165], 0, s[18:19]
	s_mov_b32 m0, s17
	ds_read_b128 v[200:203], v169 offset:49152
	ds_read_b128 v[204:207], v169 offset:50176
	ds_read_b128 v[208:211], v169 offset:51200
	ds_read_b128 v[212:215], v169 offset:52224
	ds_read_b128 v[216:219], v169 offset:53248
	ds_read_b128 v[220:223], v169 offset:54272
	ds_read_b128 v[224:227], v169 offset:55296
	ds_read_b128 v[228:231], v169 offset:56320
	global_load_lds_dwordx4 v[164:165], off
	s_add_i32 m0, s17, 0x2000
	s_add_u32 s50, s50, 0x80080
	v_lshl_add_u64 v[164:165], v[188:189], 0, s[18:19]
	s_addc_u32 s51, s51, 0
	s_add_i32 s17, s33, s22
	global_load_lds_dwordx4 v[164:165], off
	v_lshl_add_u64 v[164:165], s[50:51], 0, v[132:133]
	s_mov_b32 m0, s17
	s_nop 0
	global_load_lds_dwordx4 v[164:165], off
	v_lshl_add_u64 v[164:165], s[50:51], 0, v[136:137]
	s_add_i32 m0, s17, 0x2000
	s_nop 0
	global_load_lds_dwordx4 v[164:165], off
	v_lshl_add_u64 v[164:165], v[232:233], 0, s[18:19]
	s_mov_b32 m0, s35
	s_nop 0
	global_load_lds_dwordx4 v[164:165], off
	v_lshl_add_u64 v[164:165], v[234:235], 0, s[18:19]
	s_mov_b32 m0, s55
	s_nop 0
	global_load_lds_dwordx4 v[164:165], off
	s_waitcnt vmcnt(8)
	s_waitcnt lgkmcnt(0)
	s_barrier
	s_setprio 1
	s_waitcnt lgkmcnt(0)
	v_mfma_f32_16x16x32_bf16 v[60:63], v[152:155], v[200:203], v[60:63]
	v_mfma_f32_16x16x32_bf16 v[56:59], v[172:175], v[200:203], v[56:59]
	v_mfma_f32_16x16x32_bf16 v[44:47], v[152:155], v[208:211], v[44:47]
	v_mfma_f32_16x16x32_bf16 v[40:43], v[172:175], v[208:211], v[40:43]
	v_mfma_f32_16x16x32_bf16 v[28:31], v[152:155], v[216:219], v[28:31]
	v_mfma_f32_16x16x32_bf16 v[24:27], v[172:175], v[216:219], v[24:27]
	v_mfma_f32_16x16x32_bf16 v[12:15], v[152:155], v[224:227], v[12:15]
	v_mfma_f32_16x16x32_bf16 v[8:11], v[172:175], v[224:227], v[8:11]
	v_mfma_f32_16x16x32_bf16 v[60:63], v[156:159], v[204:207], v[60:63]
	v_mfma_f32_16x16x32_bf16 v[56:59], v[176:179], v[204:207], v[56:59]
	v_mfma_f32_16x16x32_bf16 v[44:47], v[156:159], v[212:215], v[44:47]
	v_mfma_f32_16x16x32_bf16 v[40:43], v[176:179], v[212:215], v[40:43]
	v_mfma_f32_16x16x32_bf16 v[28:31], v[156:159], v[220:223], v[28:31]
	v_mfma_f32_16x16x32_bf16 v[24:27], v[176:179], v[220:223], v[24:27]
	v_mfma_f32_16x16x32_bf16 v[12:15], v[156:159], v[228:231], v[12:15]
	v_mfma_f32_16x16x32_bf16 v[8:11], v[176:179], v[228:231], v[8:11]
	s_setprio 0
	s_setprio 1
	v_mfma_f32_16x16x32_bf16 v[52:55], v[180:183], v[200:203], v[52:55]
	v_mfma_f32_16x16x32_bf16 v[48:51], v[192:195], v[200:203], v[48:51]
	v_mfma_f32_16x16x32_bf16 v[36:39], v[180:183], v[208:211], v[36:39]
	v_mfma_f32_16x16x32_bf16 v[32:35], v[192:195], v[208:211], v[32:35]
	v_mfma_f32_16x16x32_bf16 v[20:23], v[180:183], v[216:219], v[20:23]
	v_mfma_f32_16x16x32_bf16 v[16:19], v[192:195], v[216:219], v[16:19]
	v_mfma_f32_16x16x32_bf16 v[4:7], v[180:183], v[224:227], v[4:7]
	v_mfma_f32_16x16x32_bf16 v[0:3], v[192:195], v[224:227], v[0:3]
	v_mfma_f32_16x16x32_bf16 v[52:55], v[184:187], v[204:207], v[52:55]
	v_mfma_f32_16x16x32_bf16 v[48:51], v[196:199], v[204:207], v[48:51]
	v_mfma_f32_16x16x32_bf16 v[36:39], v[184:187], v[212:215], v[36:39]
	v_mfma_f32_16x16x32_bf16 v[32:35], v[196:199], v[212:215], v[32:35]
	v_mfma_f32_16x16x32_bf16 v[20:23], v[184:187], v[220:223], v[20:23]
	v_mfma_f32_16x16x32_bf16 v[16:19], v[196:199], v[220:223], v[16:19]
	v_mfma_f32_16x16x32_bf16 v[4:7], v[184:187], v[228:231], v[4:7]
	v_mfma_f32_16x16x32_bf16 v[0:3], v[196:199], v[228:231], v[0:3]
	s_setprio 0
	s_barrier
	s_add_i32 s16, s16, 2
	s_add_u32 s48, s48, 0x100
	s_addc_u32 s49, s49, 0
	s_add_u32 s0, s0, 0x100
	s_addc_u32 s1, s1, 0
	s_cmp_gt_u32 s16, 29
	s_cbranch_scc0 .LBB0_565
	s_branch .Lpeel_exit_6

; #define PG8_BAR __builtin_amdgcn_s_barrier()
; template <int GI>
; __device__ __forceinline__ void gemm_phase(LAS unsigned char* lds, unsigned char* ws, int G, int cblk) {
;     ...
;         if (wr == 0) PG8_BAR;
;         epilogue<g.mode>(acc, cur, wr, wc, fr, fq, lds);
.Lpeel_exit_6:
	s_and_b64 vcc, exec, s[20:21]
	s_cbranch_vccz .LBB0_568
	s_barrier

; #define PG8_STAGE(bufoff, gbase, voff) do { _Pragma("unroll") for (int _i = 0; _i < 2; ++_i) \
;         __builtin_amdgcn_global_load_lds((const unsigned*)((const char*)(gbase) + (voff)[_i]), (LAS unsigned*)(lds + (bufoff) + ldsw + _i * 8192), 16, 0, 0); } while (0)
; #define PG8_LDA(dst, b, h) do { _Pragma("unroll") for (int m = 0; m < 4; ++m) _Pragma("unroll") for (int k = 0; k < 2; ++k) dst[m][k] = *(const LAS bf16x8*)(lds + PG8_SA(b, h) + aoff + m * 2048 + k * 1024); } while (0)
; #define PG8_LDB(dst, b, h) do { _Pragma("unroll") for (int n = 0; n < 2; ++n) _Pragma("unroll") for (int k = 0; k < 2; ++k) dst[n][k] = *(const LAS bf16x8*)(lds + PG8_SB(b, h) + boff + n * 2048 + k * 1024); } while (0)
; #define PG8_MMA(ai, bj, At, Bt) do { __builtin_amdgcn_s_setprio(1); _Pragma("unroll") for (int m = 0; m < 4; ++m) _Pragma("unroll") for (int n = 0; n < 2; ++n) _Pragma("unroll") for (int k = 0; k < 2; ++k) \
;         acc[ai][bj][m][n] = __builtin_amdgcn_mfma_f32_16x16x32_bf16(Bt[n][k], At[m][k], acc[ai][bj][m][n], 0, 0, 0); __builtin_amdgcn_s_setprio(0); } while (0)
; #define PG8_WAIT_V(n) asm volatile("s_waitcnt vmcnt(" #n ")" ::: "memory")
; #define PG8_WAIT_L(n) asm volatile("s_waitcnt lgkmcnt(" #n ")" ::: "memory")
; #define PG8_BAR __builtin_amdgcn_s_barrier()
; #define PG8_SCHED __builtin_amdgcn_sched_barrier(0)
; template <int GI>
; __device__ __forceinline__ void gemm_phase(LAS unsigned char* lds, unsigned char* ws, int G, int cblk) {
;     ...
;             PG8_LDB(B0, 0, 0); PG8_LDB(B1, 0, 1); PG8_SCHED; PG8_LDA(At, 0, 0); PG8_STAGE(PG8_SA(1, 1), a1 + hstepA, voffA);
;             PG8_WAIT_V(8); PG8_WAIT_L(0); PG8_BAR; PG8_MMA(0, 0, At, B0); PG8_MMA(0, 1, At, B1); PG8_BAR; PG8_SCHED;
;             PG8_LDA(At, 0, 1); PG8_STAGE(PG8_SB(0, 0), b2, voffB); PG8_STAGE(PG8_SB(0, 1), b2 + hstepB, voffB); PG8_STAGE(PG8_SA(0, 0), a2, voffA);
;             PG8_WAIT_V(8); PG8_WAIT_L(0); PG8_BAR; PG8_MMA(1, 0, At, B0); PG8_MMA(1, 1, At, B1); PG8_BAR; PG8_SCHED;
;     ...
;         for (int a = 0; a < 2; ++a)
; #pragma unroll
;             for (int b = 0; b < 2; ++b)
; #pragma unroll
;                 for (int m = 0; m < 4; ++m)
; #pragma unroll
;                     for (int n = 0; n < 2; ++n) acc[a][b][m][n] = (f32x4){0.f, 0.f, 0.f, 0.f};
.LBB0_696:
	s_add_u32 s44, s44, 0x40080
	s_addc_u32 s45, s45, 0
	s_add_u32 s16, s46, 0x100
	s_addc_u32 s17, s47, 0
	s_mov_b32 s19, -2
	ds_read_b128 v[156:159], v153
	ds_read_b128 v[164:167], v153 offset:1024
	ds_read_b128 v[168:171], v153 offset:2048
	ds_read_b128 v[172:175], v153 offset:3072
	ds_read_b128 v[176:179], v154
	ds_read_b128 v[180:183], v154 offset:1024
	ds_read_b128 v[184:187], v154 offset:2048
	ds_read_b128 v[192:195], v154 offset:3072
	s_add_u32 s34, s44, 0xfffc0080
	s_addc_u32 s46, s45, -1
	s_cmp_eq_u32 s19, 12
	s_cselect_b32 s49, s39, s46
	s_cselect_b32 s48, s38, s34
	s_cselect_b32 s47, s41, s17
	s_cselect_b32 s46, s40, s16
	v_lshl_add_u64 v[188:189], s[44:45], 0, v[140:141]
	s_add_i32 m0, s25, 0xc000
	ds_read_b128 v[196:199], v155
	ds_read_b128 v[200:203], v155 offset:1024
	ds_read_b128 v[204:207], v155 offset:2048
	ds_read_b128 v[208:211], v155 offset:3072
	ds_read_b128 v[212:215], v155 offset:4096
	ds_read_b128 v[216:219], v155 offset:5120
	ds_read_b128 v[220:223], v155 offset:6144
	ds_read_b128 v[224:227], v155 offset:7168
	global_load_lds_dwordx4 v[188:189], off
	v_lshl_add_u64 v[188:189], s[44:45], 0, v[142:143]
	s_add_i32 m0, s25, 0xe000
	s_nop 0
	global_load_lds_dwordx4 v[188:189], off
	s_waitcnt vmcnt(8)
	s_waitcnt lgkmcnt(0)
	s_barrier
	s_setprio 1
	s_waitcnt lgkmcnt(0)
	v_mfma_f32_16x16x32_bf16 v[124:127], v[156:159], v[196:199], 0
	v_mfma_f32_16x16x32_bf16 v[120:123], v[168:171], v[196:199], 0
	v_mfma_f32_16x16x32_bf16 v[116:119], v[156:159], v[204:207], 0
	v_mfma_f32_16x16x32_bf16 v[112:115], v[168:171], v[204:207], 0
	v_mfma_f32_16x16x32_bf16 v[100:103], v[156:159], v[212:215], 0
	v_mfma_f32_16x16x32_bf16 v[96:99], v[168:171], v[212:215], 0
	v_mfma_f32_16x16x32_bf16 v[84:87], v[156:159], v[220:223], 0
	v_mfma_f32_16x16x32_bf16 v[80:83], v[168:171], v[220:223], 0
	v_mfma_f32_16x16x32_bf16 v[124:127], v[164:167], v[200:203], v[124:127]
	v_mfma_f32_16x16x32_bf16 v[120:123], v[172:175], v[200:203], v[120:123]
	v_mfma_f32_16x16x32_bf16 v[116:119], v[164:167], v[208:211], v[116:119]
	v_mfma_f32_16x16x32_bf16 v[112:115], v[172:175], v[208:211], v[112:115]
	v_mfma_f32_16x16x32_bf16 v[100:103], v[164:167], v[216:219], v[100:103]
	v_mfma_f32_16x16x32_bf16 v[96:99], v[172:175], v[216:219], v[96:99]
	v_mfma_f32_16x16x32_bf16 v[84:87], v[164:167], v[224:227], v[84:87]
	v_mfma_f32_16x16x32_bf16 v[80:83], v[172:175], v[224:227], v[80:83]
	s_setprio 0
	s_setprio 1
	v_mfma_f32_16x16x32_bf16 v[108:111], v[176:179], v[196:199], 0
	v_mfma_f32_16x16x32_bf16 v[104:107], v[184:187], v[196:199], 0
	v_mfma_f32_16x16x32_bf16 v[92:95], v[176:179], v[204:207], 0
	v_mfma_f32_16x16x32_bf16 v[88:91], v[184:187], v[204:207], 0
	v_mfma_f32_16x16x32_bf16 v[76:79], v[176:179], v[212:215], 0
	v_mfma_f32_16x16x32_bf16 v[72:75], v[184:187], v[212:215], 0
	v_mfma_f32_16x16x32_bf16 v[68:71], v[176:179], v[220:223], 0
	v_mfma_f32_16x16x32_bf16 v[64:67], v[184:187], v[220:223], 0
	v_mfma_f32_16x16x32_bf16 v[108:111], v[180:183], v[200:203], v[108:111]
	v_mfma_f32_16x16x32_bf16 v[104:107], v[192:195], v[200:203], v[104:107]
	v_mfma_f32_16x16x32_bf16 v[92:95], v[180:183], v[208:211], v[92:95]
	v_mfma_f32_16x16x32_bf16 v[88:91], v[192:195], v[208:211], v[88:91]
	v_mfma_f32_16x16x32_bf16 v[76:79], v[180:183], v[216:219], v[76:79]
	v_mfma_f32_16x16x32_bf16 v[72:75], v[192:195], v[216:219], v[72:75]
	v_mfma_f32_16x16x32_bf16 v[68:71], v[180:183], v[224:227], v[68:71]
	v_mfma_f32_16x16x32_bf16 v[64:67], v[192:195], v[224:227], v[64:67]
	s_setprio 0
	s_barrier
	s_add_i32 s34, s53, s0
	v_lshl_add_u64 v[188:189], s[46:47], 0, v[132:133]
	s_mov_b32 m0, s34
	ds_read_b128 v[196:199], v155 offset:16384
	ds_read_b128 v[200:203], v155 offset:17408
	ds_read_b128 v[204:207], v155 offset:18432
	ds_read_b128 v[208:211], v155 offset:19456
	ds_read_b128 v[212:215], v155 offset:20480
	ds_read_b128 v[216:219], v155 offset:21504
	ds_read_b128 v[220:223], v155 offset:22528
	ds_read_b128 v[224:227], v155 offset:23552
	global_load_lds_dwordx4 v[188:189], off
	s_add_i32 m0, s34, 0x2000
	s_add_u32 s58, s46, 0x40000
	v_lshl_add_u64 v[228:229], s[46:47], 0, v[136:137]
	s_addc_u32 s59, s47, 0
	s_add_i32 s34, s55, s0
	global_load_lds_dwordx4 v[228:229], off
	v_lshl_add_u64 v[230:231], s[58:59], 0, v[132:133]
	s_mov_b32 m0, s34
	v_lshl_add_u64 v[232:233], s[48:49], 0, v[134:135]
	global_load_lds_dwordx4 v[230:231], off
	v_lshl_add_u64 v[230:231], s[58:59], 0, v[136:137]
	s_add_i32 m0, s34, 0x2000
	s_nop 0
	global_load_lds_dwordx4 v[230:231], off
	v_lshl_add_u64 v[230:231], s[48:49], 0, v[130:131]
	s_mov_b32 m0, s25
	s_nop 0
	global_load_lds_dwordx4 v[230:231], off
	s_mov_b32 m0, s26
	s_nop 0
	global_load_lds_dwordx4 v[232:233], off
	s_waitcnt vmcnt(8)
	s_waitcnt lgkmcnt(0)
	s_barrier
; #define PG8_STAGE(bufoff, gbase, voff) do { _Pragma("unroll") for (int _i = 0; _i < 2; ++_i) \
;         __builtin_amdgcn_global_load_lds((const unsigned*)((const char*)(gbase) + (voff)[_i]), (LAS unsigned*)(lds + (bufoff) + ldsw + _i * 8192), 16, 0, 0); } while (0)
; #define PG8_LDA(dst, b, h) do { _Pragma("unroll") for (int m = 0; m < 4; ++m) _Pragma("unroll") for (int k = 0; k < 2; ++k) dst[m][k] = *(const LAS bf16x8*)(lds + PG8_SA(b, h) + aoff + m * 2048 + k * 1024); } while (0)
; #define PG8_LDB(dst, b, h) do { _Pragma("unroll") for (int n = 0; n < 2; ++n) _Pragma("unroll") for (int k = 0; k < 2; ++k) dst[n][k] = *(const LAS bf16x8*)(lds + PG8_SB(b, h) + boff + n * 2048 + k * 1024); } while (0)
; #define PG8_MMA(ai, bj, At, Bt) do { __builtin_amdgcn_s_setprio(1); _Pragma("unroll") for (int m = 0; m < 4; ++m) _Pragma("unroll") for (int n = 0; n < 2; ++n) _Pragma("unroll") for (int k = 0; k < 2; ++k) \
;         acc[ai][bj][m][n] = __builtin_amdgcn_mfma_f32_16x16x32_bf16(Bt[n][k], At[m][k], acc[ai][bj][m][n], 0, 0, 0); __builtin_amdgcn_s_setprio(0); } while (0)
; #define PG8_WAIT_V(n) asm volatile("s_waitcnt vmcnt(" #n ")" ::: "memory")
; #define PG8_WAIT_L(n) asm volatile("s_waitcnt lgkmcnt(" #n ")" ::: "memory")
; #define PG8_BAR __builtin_amdgcn_s_barrier()
; #define PG8_SCHED __builtin_amdgcn_sched_barrier(0)
; template <int GI>
; __device__ __forceinline__ void gemm_phase(LAS unsigned char* lds, unsigned char* ws, int G, int cblk) {
;     ...
;             PG8_WAIT_V(8); PG8_WAIT_L(0); PG8_BAR; PG8_MMA(1, 0, At, B0); PG8_MMA(1, 1, At, B1); PG8_BAR; PG8_SCHED;
;             PG8_LDB(B0, 1, 0); PG8_LDB(B1, 1, 1); PG8_SCHED; PG8_LDA(At, 1, 0); PG8_STAGE(PG8_SA(0, 1), a2 + hstepA, voffA);
;             PG8_WAIT_V(8); PG8_WAIT_L(0); PG8_BAR; PG8_MMA(0, 0, At, B0); PG8_MMA(0, 1, At, B1); PG8_BAR; PG8_SCHED;
	s_setprio 1
	s_waitcnt lgkmcnt(0)
	v_mfma_f32_16x16x32_bf16 v[60:63], v[156:159], v[196:199], 0
	v_mfma_f32_16x16x32_bf16 v[56:59], v[168:171], v[196:199], 0
	v_mfma_f32_16x16x32_bf16 v[52:55], v[156:159], v[204:207], 0
	v_mfma_f32_16x16x32_bf16 v[48:51], v[168:171], v[204:207], 0
	v_mfma_f32_16x16x32_bf16 v[36:39], v[156:159], v[212:215], 0
	v_mfma_f32_16x16x32_bf16 v[32:35], v[168:171], v[212:215], 0
	v_mfma_f32_16x16x32_bf16 v[20:23], v[156:159], v[220:223], 0
	v_mfma_f32_16x16x32_bf16 v[16:19], v[168:171], v[220:223], 0
	v_mfma_f32_16x16x32_bf16 v[60:63], v[164:167], v[200:203], v[60:63]
	v_mfma_f32_16x16x32_bf16 v[56:59], v[172:175], v[200:203], v[56:59]
	v_mfma_f32_16x16x32_bf16 v[52:55], v[164:167], v[208:211], v[52:55]
	v_mfma_f32_16x16x32_bf16 v[48:51], v[172:175], v[208:211], v[48:51]
	v_mfma_f32_16x16x32_bf16 v[36:39], v[164:167], v[216:219], v[36:39]
	v_mfma_f32_16x16x32_bf16 v[32:35], v[172:175], v[216:219], v[32:35]
	v_mfma_f32_16x16x32_bf16 v[20:23], v[164:167], v[224:227], v[20:23]
	v_mfma_f32_16x16x32_bf16 v[16:19], v[172:175], v[224:227], v[16:19]
	s_setprio 0
	s_setprio 1
	v_mfma_f32_16x16x32_bf16 v[44:47], v[176:179], v[196:199], 0
	v_mfma_f32_16x16x32_bf16 v[40:43], v[184:187], v[196:199], 0
	v_mfma_f32_16x16x32_bf16 v[28:31], v[176:179], v[204:207], 0
	v_mfma_f32_16x16x32_bf16 v[24:27], v[184:187], v[204:207], 0
	v_mfma_f32_16x16x32_bf16 v[12:15], v[176:179], v[212:215], 0
	v_mfma_f32_16x16x32_bf16 v[8:11], v[184:187], v[212:215], 0
	v_mfma_f32_16x16x32_bf16 v[4:7], v[176:179], v[220:223], 0
	v_mfma_f32_16x16x32_bf16 v[0:3], v[184:187], v[220:223], 0
	v_mfma_f32_16x16x32_bf16 v[44:47], v[180:183], v[200:203], v[44:47]
	v_mfma_f32_16x16x32_bf16 v[40:43], v[192:195], v[200:203], v[40:43]
	v_mfma_f32_16x16x32_bf16 v[28:31], v[180:183], v[208:211], v[28:31]
	v_mfma_f32_16x16x32_bf16 v[24:27], v[192:195], v[208:211], v[24:27]
	v_mfma_f32_16x16x32_bf16 v[12:15], v[180:183], v[216:219], v[12:15]
	v_mfma_f32_16x16x32_bf16 v[8:11], v[192:195], v[216:219], v[8:11]
	v_mfma_f32_16x16x32_bf16 v[4:7], v[180:183], v[224:227], v[4:7]
	v_mfma_f32_16x16x32_bf16 v[0:3], v[192:195], v[224:227], v[0:3]
	s_setprio 0
	s_barrier
	s_add_i32 s34, 0, 0x18000
	v_add_u32_e32 v161, s34, v152
	s_add_i32 s57, 0, 0x1c000
	ds_read_b128 v[156:159], v161
	ds_read_b128 v[164:167], v161 offset:1024
	ds_read_b128 v[168:171], v161 offset:2048
	ds_read_b128 v[172:175], v161 offset:3072
	v_add_u32_e32 v161, s57, v152
	ds_read_b128 v[176:179], v161
	ds_read_b128 v[180:183], v161 offset:1024
	ds_read_b128 v[184:187], v161 offset:2048
	ds_read_b128 v[192:195], v161 offset:3072
	s_add_u32 s48, s48, 0x40000
	s_addc_u32 s49, s49, 0
	s_mov_b32 m0, s27
	v_lshl_add_u64 v[234:235], s[48:49], 0, v[130:131]
	ds_read_b128 v[196:199], v155 offset:32768
	ds_read_b128 v[200:203], v155 offset:33792
	ds_read_b128 v[204:207], v155 offset:34816
	ds_read_b128 v[208:211], v155 offset:35840
	ds_read_b128 v[212:215], v155 offset:36864
	ds_read_b128 v[216:219], v155 offset:37888
	ds_read_b128 v[220:223], v155 offset:38912
	ds_read_b128 v[224:227], v155 offset:39936
	global_load_lds_dwordx4 v[234:235], off
	v_lshl_add_u64 v[234:235], s[48:49], 0, v[134:135]
	s_mov_b32 m0, s33
	s_nop 0
	global_load_lds_dwordx4 v[234:235], off
	s_waitcnt vmcnt(8)
	s_waitcnt lgkmcnt(0)
	s_barrier
	s_setprio 1
	s_waitcnt lgkmcnt(0)
	v_mfma_f32_16x16x32_bf16 v[124:127], v[156:159], v[196:199], v[124:127]
	v_mfma_f32_16x16x32_bf16 v[120:123], v[168:171], v[196:199], v[120:123]
	v_mfma_f32_16x16x32_bf16 v[116:119], v[156:159], v[204:207], v[116:119]
	v_mfma_f32_16x16x32_bf16 v[112:115], v[168:171], v[204:207], v[112:115]
	v_mfma_f32_16x16x32_bf16 v[100:103], v[156:159], v[212:215], v[100:103]
	v_mfma_f32_16x16x32_bf16 v[96:99], v[168:171], v[212:215], v[96:99]
	v_mfma_f32_16x16x32_bf16 v[84:87], v[156:159], v[220:223], v[84:87]
	v_mfma_f32_16x16x32_bf16 v[80:83], v[168:171], v[220:223], v[80:83]
	v_mfma_f32_16x16x32_bf16 v[124:127], v[164:167], v[200:203], v[124:127]
	v_mfma_f32_16x16x32_bf16 v[120:123], v[172:175], v[200:203], v[120:123]
	v_mfma_f32_16x16x32_bf16 v[116:119], v[164:167], v[208:211], v[116:119]
	v_mfma_f32_16x16x32_bf16 v[112:115], v[172:175], v[208:211], v[112:115]
	v_mfma_f32_16x16x32_bf16 v[100:103], v[164:167], v[216:219], v[100:103]
	v_mfma_f32_16x16x32_bf16 v[96:99], v[172:175], v[216:219], v[96:99]
	v_mfma_f32_16x16x32_bf16 v[84:87], v[164:167], v[224:227], v[84:87]
	v_mfma_f32_16x16x32_bf16 v[80:83], v[172:175], v[224:227], v[80:83]
	s_setprio 0
	s_setprio 1
	v_mfma_f32_16x16x32_bf16 v[108:111], v[176:179], v[196:199], v[108:111]
	v_mfma_f32_16x16x32_bf16 v[104:107], v[184:187], v[196:199], v[104:107]
	v_mfma_f32_16x16x32_bf16 v[92:95], v[176:179], v[204:207], v[92:95]
	v_mfma_f32_16x16x32_bf16 v[88:91], v[184:187], v[204:207], v[88:91]
	v_mfma_f32_16x16x32_bf16 v[76:79], v[176:179], v[212:215], v[76:79]
	v_mfma_f32_16x16x32_bf16 v[72:75], v[184:187], v[212:215], v[72:75]
	v_mfma_f32_16x16x32_bf16 v[68:71], v[176:179], v[220:223], v[68:71]
	v_mfma_f32_16x16x32_bf16 v[64:67], v[184:187], v[220:223], v[64:67]
	v_mfma_f32_16x16x32_bf16 v[108:111], v[180:183], v[200:203], v[108:111]
	v_mfma_f32_16x16x32_bf16 v[104:107], v[192:195], v[200:203], v[104:107]
	v_mfma_f32_16x16x32_bf16 v[92:95], v[180:183], v[208:211], v[92:95]
	v_mfma_f32_16x16x32_bf16 v[88:91], v[192:195], v[208:211], v[88:91]
	v_mfma_f32_16x16x32_bf16 v[76:79], v[180:183], v[216:219], v[76:79]
	v_mfma_f32_16x16x32_bf16 v[72:75], v[192:195], v[216:219], v[72:75]
	v_mfma_f32_16x16x32_bf16 v[68:71], v[180:183], v[224:227], v[68:71]
	v_mfma_f32_16x16x32_bf16 v[64:67], v[192:195], v[224:227], v[64:67]
	s_setprio 0
	s_barrier
; #define PG8_STAGE(bufoff, gbase, voff) do { _Pragma("unroll") for (int _i = 0; _i < 2; ++_i) \
;         __builtin_amdgcn_global_load_lds((const unsigned*)((const char*)(gbase) + (voff)[_i]), (LAS unsigned*)(lds + (bufoff) + ldsw + _i * 8192), 16, 0, 0); } while (0)
; #define PG8_LDA(dst, b, h) do { _Pragma("unroll") for (int m = 0; m < 4; ++m) _Pragma("unroll") for (int k = 0; k < 2; ++k) dst[m][k] = *(const LAS bf16x8*)(lds + PG8_SA(b, h) + aoff + m * 2048 + k * 1024); } while (0)
; #define PG8_MMA(ai, bj, At, Bt) do { __builtin_amdgcn_s_setprio(1); _Pragma("unroll") for (int m = 0; m < 4; ++m) _Pragma("unroll") for (int n = 0; n < 2; ++n) _Pragma("unroll") for (int k = 0; k < 2; ++k) \
;         acc[ai][bj][m][n] = __builtin_amdgcn_mfma_f32_16x16x32_bf16(Bt[n][k], At[m][k], acc[ai][bj][m][n], 0, 0, 0); __builtin_amdgcn_s_setprio(0); } while (0)
; #define PG8_WAIT_V(n) asm volatile("s_waitcnt vmcnt(" #n ")" ::: "memory")
; #define PG8_WAIT_L(n) asm volatile("s_waitcnt lgkmcnt(" #n ")" ::: "memory")
; #define PG8_BAR __builtin_amdgcn_s_barrier()
; #define PG8_SCHED __builtin_amdgcn_sched_barrier(0)
; template <int GI>
; __device__ __forceinline__ void gemm_phase(LAS unsigned char* lds, unsigned char* ws, int G, int cblk) {
;     ...
;         for (int t = 0; t < nt; t += 2) {
;             const bool last = (t == nt - 2);
;     ...
;             PG8_LDA(At, 1, 1); PG8_STAGE(PG8_SB(1, 0), b3, voffB); PG8_STAGE(PG8_SB(1, 1), b3 + hstepB, voffB); PG8_STAGE(PG8_SA(1, 0), a3, voffA);
;             PG8_WAIT_V(8); PG8_WAIT_L(0); PG8_BAR; PG8_MMA(1, 0, At, B0); PG8_MMA(1, 1, At, B1); PG8_BAR; PG8_SCHED;
	s_add_i32 s34, s34, s0
	v_lshl_add_u64 v[188:189], v[188:189], 0, s[12:13]
	s_mov_b32 m0, s34
	ds_read_b128 v[196:199], v155 offset:49152
	ds_read_b128 v[200:203], v155 offset:50176
	ds_read_b128 v[204:207], v155 offset:51200
	ds_read_b128 v[208:211], v155 offset:52224
	ds_read_b128 v[212:215], v155 offset:53248
	ds_read_b128 v[216:219], v155 offset:54272
	ds_read_b128 v[220:223], v155 offset:55296
	ds_read_b128 v[224:227], v155 offset:56320
	global_load_lds_dwordx4 v[188:189], off
	s_add_i32 m0, s34, 0x2000
	s_add_u32 s46, s46, 0x40080
	v_lshl_add_u64 v[188:189], v[228:229], 0, s[12:13]
	s_addc_u32 s47, s47, 0
	s_add_i32 s34, s57, s0
	global_load_lds_dwordx4 v[188:189], off
	v_lshl_add_u64 v[188:189], s[46:47], 0, v[132:133]
	s_mov_b32 m0, s34
	s_nop 0
	global_load_lds_dwordx4 v[188:189], off
	v_lshl_add_u64 v[188:189], s[46:47], 0, v[136:137]
	s_add_i32 m0, s34, 0x2000
	s_nop 0
	global_load_lds_dwordx4 v[188:189], off
	v_lshl_add_u64 v[188:189], v[230:231], 0, s[12:13]
	s_mov_b32 m0, s51
	s_nop 0
	global_load_lds_dwordx4 v[188:189], off
	v_lshl_add_u64 v[188:189], v[232:233], 0, s[12:13]
	s_mov_b32 m0, s52
	s_nop 0
	global_load_lds_dwordx4 v[188:189], off
	s_waitcnt vmcnt(8)
	s_waitcnt lgkmcnt(0)
	s_barrier
	s_setprio 1
	s_waitcnt lgkmcnt(0)
	v_mfma_f32_16x16x32_bf16 v[60:63], v[156:159], v[196:199], v[60:63]
	v_mfma_f32_16x16x32_bf16 v[56:59], v[168:171], v[196:199], v[56:59]
	v_mfma_f32_16x16x32_bf16 v[52:55], v[156:159], v[204:207], v[52:55]
	v_mfma_f32_16x16x32_bf16 v[48:51], v[168:171], v[204:207], v[48:51]
	v_mfma_f32_16x16x32_bf16 v[36:39], v[156:159], v[212:215], v[36:39]
	v_mfma_f32_16x16x32_bf16 v[32:35], v[168:171], v[212:215], v[32:35]
	v_mfma_f32_16x16x32_bf16 v[20:23], v[156:159], v[220:223], v[20:23]
	v_mfma_f32_16x16x32_bf16 v[16:19], v[168:171], v[220:223], v[16:19]
	v_mfma_f32_16x16x32_bf16 v[60:63], v[164:167], v[200:203], v[60:63]
	v_mfma_f32_16x16x32_bf16 v[56:59], v[172:175], v[200:203], v[56:59]
	v_mfma_f32_16x16x32_bf16 v[52:55], v[164:167], v[208:211], v[52:55]
	v_mfma_f32_16x16x32_bf16 v[48:51], v[172:175], v[208:211], v[48:51]
	v_mfma_f32_16x16x32_bf16 v[36:39], v[164:167], v[216:219], v[36:39]
	v_mfma_f32_16x16x32_bf16 v[32:35], v[172:175], v[216:219], v[32:35]
	v_mfma_f32_16x16x32_bf16 v[20:23], v[164:167], v[224:227], v[20:23]
	v_mfma_f32_16x16x32_bf16 v[16:19], v[172:175], v[224:227], v[16:19]
	s_setprio 0
	s_setprio 1
	v_mfma_f32_16x16x32_bf16 v[44:47], v[176:179], v[196:199], v[44:47]
	v_mfma_f32_16x16x32_bf16 v[40:43], v[184:187], v[196:199], v[40:43]
	v_mfma_f32_16x16x32_bf16 v[28:31], v[176:179], v[204:207], v[28:31]
	v_mfma_f32_16x16x32_bf16 v[24:27], v[184:187], v[204:207], v[24:27]
	v_mfma_f32_16x16x32_bf16 v[12:15], v[176:179], v[212:215], v[12:15]
	v_mfma_f32_16x16x32_bf16 v[8:11], v[184:187], v[212:215], v[8:11]
	v_mfma_f32_16x16x32_bf16 v[4:7], v[176:179], v[220:223], v[4:7]
	v_mfma_f32_16x16x32_bf16 v[0:3], v[184:187], v[220:223], v[0:3]
	v_mfma_f32_16x16x32_bf16 v[44:47], v[180:183], v[200:203], v[44:47]
	v_mfma_f32_16x16x32_bf16 v[40:43], v[192:195], v[200:203], v[40:43]
	v_mfma_f32_16x16x32_bf16 v[28:31], v[180:183], v[208:211], v[28:31]
	v_mfma_f32_16x16x32_bf16 v[24:27], v[192:195], v[208:211], v[24:27]
	v_mfma_f32_16x16x32_bf16 v[12:15], v[180:183], v[216:219], v[12:15]
	v_mfma_f32_16x16x32_bf16 v[8:11], v[192:195], v[216:219], v[8:11]
	v_mfma_f32_16x16x32_bf16 v[4:7], v[180:183], v[224:227], v[4:7]
	v_mfma_f32_16x16x32_bf16 v[0:3], v[192:195], v[224:227], v[0:3]
	s_setprio 0
	s_barrier
	s_add_i32 s19, s19, 2
	s_add_u32 s44, s44, 0x100
	s_addc_u32 s45, s45, 0
	s_add_u32 s16, s16, 0x100
	s_addc_u32 s17, s17, 0
	s_cmp_gt_u32 s19, 13
	s_cbranch_scc0 .LBB0_697
	s_branch .Lpeel_exit_7

; #define PG8_BAR __builtin_amdgcn_s_barrier()
; template <int GI>
; __device__ __forceinline__ void gemm_phase(LAS unsigned char* lds, unsigned char* ws, int G, int cblk) {
;     ...
;         if (wr == 0) PG8_BAR;
;         epilogue<g.mode>(acc, cur, wr, wc, fr, fq, lds);
.Lpeel_exit_7:
	s_and_b64 vcc, exec, s[14:15]
	s_cbranch_vccz .LBB0_700
	s_barrier

; #define PG8_STAGE(bufoff, gbase, voff) do { _Pragma("unroll") for (int _i = 0; _i < 2; ++_i) \
;         __builtin_amdgcn_global_load_lds((const unsigned*)((const char*)(gbase) + (voff)[_i]), (LAS unsigned*)(lds + (bufoff) + ldsw + _i * 8192), 16, 0, 0); } while (0)
; #define PG8_LDA(dst, b, h) do { _Pragma("unroll") for (int m = 0; m < 4; ++m) _Pragma("unroll") for (int k = 0; k < 2; ++k) dst[m][k] = *(const LAS bf16x8*)(lds + PG8_SA(b, h) + aoff + m * 2048 + k * 1024); } while (0)
; #define PG8_LDB(dst, b, h) do { _Pragma("unroll") for (int n = 0; n < 2; ++n) _Pragma("unroll") for (int k = 0; k < 2; ++k) dst[n][k] = *(const LAS bf16x8*)(lds + PG8_SB(b, h) + boff + n * 2048 + k * 1024); } while (0)
; #define PG8_MMA(ai, bj, At, Bt) do { __builtin_amdgcn_s_setprio(1); _Pragma("unroll") for (int m = 0; m < 4; ++m) _Pragma("unroll") for (int n = 0; n < 2; ++n) _Pragma("unroll") for (int k = 0; k < 2; ++k) \
;         acc[ai][bj][m][n] = __builtin_amdgcn_mfma_f32_16x16x32_bf16(Bt[n][k], At[m][k], acc[ai][bj][m][n], 0, 0, 0); __builtin_amdgcn_s_setprio(0); } while (0)
; #define PG8_WAIT_V(n) asm volatile("s_waitcnt vmcnt(" #n ")" ::: "memory")
; #define PG8_WAIT_L(n) asm volatile("s_waitcnt lgkmcnt(" #n ")" ::: "memory")
; #define PG8_BAR __builtin_amdgcn_s_barrier()
; #define PG8_SCHED __builtin_amdgcn_sched_barrier(0)
; template <int GI>
; __device__ __forceinline__ void gemm_phase(LAS unsigned char* lds, unsigned char* ws, int G, int cblk) {
;     ...
;             PG8_LDB(B0, 0, 0); PG8_LDB(B1, 0, 1); PG8_SCHED; PG8_LDA(At, 0, 0); PG8_STAGE(PG8_SA(1, 1), a1 + hstepA, voffA);
;             PG8_WAIT_V(8); PG8_WAIT_L(0); PG8_BAR; PG8_MMA(0, 0, At, B0); PG8_MMA(0, 1, At, B1); PG8_BAR; PG8_SCHED;
;             PG8_LDA(At, 0, 1); PG8_STAGE(PG8_SB(0, 0), b2, voffB); PG8_STAGE(PG8_SB(0, 1), b2 + hstepB, voffB); PG8_STAGE(PG8_SA(0, 0), a2, voffA);
;             PG8_WAIT_V(8); PG8_WAIT_L(0); PG8_BAR; PG8_MMA(1, 0, At, B0); PG8_MMA(1, 1, At, B1); PG8_BAR; PG8_SCHED;
;     ...
;         for (int a = 0; a < 2; ++a)
; #pragma unroll
;             for (int b = 0; b < 2; ++b)
; #pragma unroll
;                 for (int m = 0; m < 4; ++m)
; #pragma unroll
;                     for (int n = 0; n < 2; ++n) acc[a][b][m][n] = (f32x4){0.f, 0.f, 0.f, 0.f};
.LBB0_819:
	s_add_u32 s40, s40, 0x80080
	s_addc_u32 s41, s41, 0
	s_add_u32 s0, s42, 0x100
	s_addc_u32 s1, s43, 0
	s_mov_b32 s17, -2
	ds_read_b128 v[156:159], v153
	ds_read_b128 v[164:167], v153 offset:1024
	ds_read_b128 v[168:171], v153 offset:2048
	ds_read_b128 v[172:175], v153 offset:3072
	ds_read_b128 v[176:179], v154
	ds_read_b128 v[180:183], v154 offset:1024
	ds_read_b128 v[184:187], v154 offset:2048
	ds_read_b128 v[192:195], v154 offset:3072
	s_add_u32 s24, s40, 0xfff80080
	s_addc_u32 s25, s41, -1
	s_cmp_eq_u32 s17, 28
	s_cselect_b32 s45, s19, s25
	s_cselect_b32 s44, s18, s24
	s_cselect_b32 s43, s21, s1
	s_cselect_b32 s42, s20, s0
	v_lshl_add_u64 v[188:189], s[40:41], 0, v[140:141]
	s_add_i32 m0, s49, 0xc000
	ds_read_b128 v[196:199], v155
	ds_read_b128 v[200:203], v155 offset:1024
	ds_read_b128 v[204:207], v155 offset:2048
	ds_read_b128 v[208:211], v155 offset:3072
	ds_read_b128 v[212:215], v155 offset:4096
	ds_read_b128 v[216:219], v155 offset:5120
	ds_read_b128 v[220:223], v155 offset:6144
	ds_read_b128 v[224:227], v155 offset:7168
	global_load_lds_dwordx4 v[188:189], off
	v_lshl_add_u64 v[188:189], s[40:41], 0, v[142:143]
	s_add_i32 m0, s49, 0xe000
	s_nop 0
	global_load_lds_dwordx4 v[188:189], off
	s_waitcnt vmcnt(8)
	s_waitcnt lgkmcnt(0)
	s_barrier
	s_setprio 1
	s_waitcnt lgkmcnt(0)
	v_mfma_f32_16x16x32_bf16 v[124:127], v[156:159], v[196:199], 0
	v_mfma_f32_16x16x32_bf16 v[120:123], v[168:171], v[196:199], 0
	v_mfma_f32_16x16x32_bf16 v[108:111], v[156:159], v[204:207], 0
	v_mfma_f32_16x16x32_bf16 v[104:107], v[168:171], v[204:207], 0
	v_mfma_f32_16x16x32_bf16 v[92:95], v[156:159], v[212:215], 0
	v_mfma_f32_16x16x32_bf16 v[88:91], v[168:171], v[212:215], 0
	v_mfma_f32_16x16x32_bf16 v[76:79], v[156:159], v[220:223], 0
	v_mfma_f32_16x16x32_bf16 v[72:75], v[168:171], v[220:223], 0
	v_mfma_f32_16x16x32_bf16 v[124:127], v[164:167], v[200:203], v[124:127]
	v_mfma_f32_16x16x32_bf16 v[120:123], v[172:175], v[200:203], v[120:123]
	v_mfma_f32_16x16x32_bf16 v[108:111], v[164:167], v[208:211], v[108:111]
	v_mfma_f32_16x16x32_bf16 v[104:107], v[172:175], v[208:211], v[104:107]
	v_mfma_f32_16x16x32_bf16 v[92:95], v[164:167], v[216:219], v[92:95]
	v_mfma_f32_16x16x32_bf16 v[88:91], v[172:175], v[216:219], v[88:91]
	v_mfma_f32_16x16x32_bf16 v[76:79], v[164:167], v[224:227], v[76:79]
	v_mfma_f32_16x16x32_bf16 v[72:75], v[172:175], v[224:227], v[72:75]
	s_setprio 0
	s_setprio 1
	v_mfma_f32_16x16x32_bf16 v[116:119], v[176:179], v[196:199], 0
	v_mfma_f32_16x16x32_bf16 v[112:115], v[184:187], v[196:199], 0
	v_mfma_f32_16x16x32_bf16 v[100:103], v[176:179], v[204:207], 0
	v_mfma_f32_16x16x32_bf16 v[96:99], v[184:187], v[204:207], 0
	v_mfma_f32_16x16x32_bf16 v[84:87], v[176:179], v[212:215], 0
	v_mfma_f32_16x16x32_bf16 v[80:83], v[184:187], v[212:215], 0
	v_mfma_f32_16x16x32_bf16 v[68:71], v[176:179], v[220:223], 0
	v_mfma_f32_16x16x32_bf16 v[64:67], v[184:187], v[220:223], 0
	v_mfma_f32_16x16x32_bf16 v[116:119], v[180:183], v[200:203], v[116:119]
	v_mfma_f32_16x16x32_bf16 v[112:115], v[192:195], v[200:203], v[112:115]
	v_mfma_f32_16x16x32_bf16 v[100:103], v[180:183], v[208:211], v[100:103]
	v_mfma_f32_16x16x32_bf16 v[96:99], v[192:195], v[208:211], v[96:99]
	v_mfma_f32_16x16x32_bf16 v[84:87], v[180:183], v[216:219], v[84:87]
	v_mfma_f32_16x16x32_bf16 v[80:83], v[192:195], v[216:219], v[80:83]
	v_mfma_f32_16x16x32_bf16 v[68:71], v[180:183], v[224:227], v[68:71]
	v_mfma_f32_16x16x32_bf16 v[64:67], v[192:195], v[224:227], v[64:67]
	s_setprio 0
	s_barrier
	s_add_i32 s24, s56, s26
	v_lshl_add_u64 v[188:189], s[42:43], 0, v[134:135]
	s_mov_b32 m0, s24
	ds_read_b128 v[196:199], v155 offset:16384
	ds_read_b128 v[200:203], v155 offset:17408
	ds_read_b128 v[204:207], v155 offset:18432
	ds_read_b128 v[208:211], v155 offset:19456
	ds_read_b128 v[212:215], v155 offset:20480
	ds_read_b128 v[216:219], v155 offset:21504
	ds_read_b128 v[220:223], v155 offset:22528
	ds_read_b128 v[224:227], v155 offset:23552
	global_load_lds_dwordx4 v[188:189], off
	s_add_i32 m0, s24, 0x2000
	s_add_u32 s24, s42, 0x80000
	v_lshl_add_u64 v[228:229], s[42:43], 0, v[130:131]
	s_addc_u32 s25, s43, 0
	s_add_i32 s33, s57, s26
	global_load_lds_dwordx4 v[228:229], off
	v_lshl_add_u64 v[230:231], s[24:25], 0, v[134:135]
	s_mov_b32 m0, s33
	v_lshl_add_u64 v[232:233], s[44:45], 0, v[132:133]
	global_load_lds_dwordx4 v[230:231], off
	v_lshl_add_u64 v[230:231], s[24:25], 0, v[130:131]
	s_add_i32 m0, s33, 0x2000
	s_nop 0
	global_load_lds_dwordx4 v[230:231], off
	v_lshl_add_u64 v[230:231], s[44:45], 0, v[136:137]
	s_mov_b32 m0, s49
	s_nop 0
	global_load_lds_dwordx4 v[230:231], off
	s_mov_b32 m0, s50
	s_nop 0
	global_load_lds_dwordx4 v[232:233], off
	s_waitcnt vmcnt(8)
	s_waitcnt lgkmcnt(0)
	s_barrier
; #define PG8_STAGE(bufoff, gbase, voff) do { _Pragma("unroll") for (int _i = 0; _i < 2; ++_i) \
;         __builtin_amdgcn_global_load_lds((const unsigned*)((const char*)(gbase) + (voff)[_i]), (LAS unsigned*)(lds + (bufoff) + ldsw + _i * 8192), 16, 0, 0); } while (0)
; #define PG8_LDA(dst, b, h) do { _Pragma("unroll") for (int m = 0; m < 4; ++m) _Pragma("unroll") for (int k = 0; k < 2; ++k) dst[m][k] = *(const LAS bf16x8*)(lds + PG8_SA(b, h) + aoff + m * 2048 + k * 1024); } while (0)
; #define PG8_LDB(dst, b, h) do { _Pragma("unroll") for (int n = 0; n < 2; ++n) _Pragma("unroll") for (int k = 0; k < 2; ++k) dst[n][k] = *(const LAS bf16x8*)(lds + PG8_SB(b, h) + boff + n * 2048 + k * 1024); } while (0)
; #define PG8_MMA(ai, bj, At, Bt) do { __builtin_amdgcn_s_setprio(1); _Pragma("unroll") for (int m = 0; m < 4; ++m) _Pragma("unroll") for (int n = 0; n < 2; ++n) _Pragma("unroll") for (int k = 0; k < 2; ++k) \
;         acc[ai][bj][m][n] = __builtin_amdgcn_mfma_f32_16x16x32_bf16(Bt[n][k], At[m][k], acc[ai][bj][m][n], 0, 0, 0); __builtin_amdgcn_s_setprio(0); } while (0)
; #define PG8_WAIT_V(n) asm volatile("s_waitcnt vmcnt(" #n ")" ::: "memory")
; #define PG8_WAIT_L(n) asm volatile("s_waitcnt lgkmcnt(" #n ")" ::: "memory")
; #define PG8_BAR __builtin_amdgcn_s_barrier()
; #define PG8_SCHED __builtin_amdgcn_sched_barrier(0)
; template <int GI>
; __device__ __forceinline__ void gemm_phase(LAS unsigned char* lds, unsigned char* ws, int G, int cblk) {
;     ...
;             PG8_WAIT_V(8); PG8_WAIT_L(0); PG8_BAR; PG8_MMA(1, 0, At, B0); PG8_MMA(1, 1, At, B1); PG8_BAR; PG8_SCHED;
;             PG8_LDB(B0, 1, 0); PG8_LDB(B1, 1, 1); PG8_SCHED; PG8_LDA(At, 1, 0); PG8_STAGE(PG8_SA(0, 1), a2 + hstepA, voffA);
;             PG8_WAIT_V(8); PG8_WAIT_L(0); PG8_BAR; PG8_MMA(0, 0, At, B0); PG8_MMA(0, 1, At, B1); PG8_BAR; PG8_SCHED;
	s_setprio 1
	s_waitcnt lgkmcnt(0)
	v_mfma_f32_16x16x32_bf16 v[60:63], v[156:159], v[196:199], 0
	v_mfma_f32_16x16x32_bf16 v[56:59], v[168:171], v[196:199], 0
	v_mfma_f32_16x16x32_bf16 v[44:47], v[156:159], v[204:207], 0
	v_mfma_f32_16x16x32_bf16 v[40:43], v[168:171], v[204:207], 0
	v_mfma_f32_16x16x32_bf16 v[28:31], v[156:159], v[212:215], 0
	v_mfma_f32_16x16x32_bf16 v[24:27], v[168:171], v[212:215], 0
	v_mfma_f32_16x16x32_bf16 v[12:15], v[156:159], v[220:223], 0
	v_mfma_f32_16x16x32_bf16 v[8:11], v[168:171], v[220:223], 0
	v_mfma_f32_16x16x32_bf16 v[60:63], v[164:167], v[200:203], v[60:63]
	v_mfma_f32_16x16x32_bf16 v[56:59], v[172:175], v[200:203], v[56:59]
	v_mfma_f32_16x16x32_bf16 v[44:47], v[164:167], v[208:211], v[44:47]
	v_mfma_f32_16x16x32_bf16 v[40:43], v[172:175], v[208:211], v[40:43]
	v_mfma_f32_16x16x32_bf16 v[28:31], v[164:167], v[216:219], v[28:31]
	v_mfma_f32_16x16x32_bf16 v[24:27], v[172:175], v[216:219], v[24:27]
	v_mfma_f32_16x16x32_bf16 v[12:15], v[164:167], v[224:227], v[12:15]
	v_mfma_f32_16x16x32_bf16 v[8:11], v[172:175], v[224:227], v[8:11]
	s_setprio 0
	s_setprio 1
	v_mfma_f32_16x16x32_bf16 v[52:55], v[176:179], v[196:199], 0
	v_mfma_f32_16x16x32_bf16 v[48:51], v[184:187], v[196:199], 0
	v_mfma_f32_16x16x32_bf16 v[36:39], v[176:179], v[204:207], 0
	v_mfma_f32_16x16x32_bf16 v[32:35], v[184:187], v[204:207], 0
	v_mfma_f32_16x16x32_bf16 v[20:23], v[176:179], v[212:215], 0
	v_mfma_f32_16x16x32_bf16 v[16:19], v[184:187], v[212:215], 0
	v_mfma_f32_16x16x32_bf16 v[4:7], v[176:179], v[220:223], 0
	v_mfma_f32_16x16x32_bf16 v[0:3], v[184:187], v[220:223], 0
	v_mfma_f32_16x16x32_bf16 v[52:55], v[180:183], v[200:203], v[52:55]
	v_mfma_f32_16x16x32_bf16 v[48:51], v[192:195], v[200:203], v[48:51]
	v_mfma_f32_16x16x32_bf16 v[36:39], v[180:183], v[208:211], v[36:39]
	v_mfma_f32_16x16x32_bf16 v[32:35], v[192:195], v[208:211], v[32:35]
	v_mfma_f32_16x16x32_bf16 v[20:23], v[180:183], v[216:219], v[20:23]
	v_mfma_f32_16x16x32_bf16 v[16:19], v[192:195], v[216:219], v[16:19]
	v_mfma_f32_16x16x32_bf16 v[4:7], v[180:183], v[224:227], v[4:7]
	v_mfma_f32_16x16x32_bf16 v[0:3], v[192:195], v[224:227], v[0:3]
	s_setprio 0
	s_barrier
	s_add_i32 s33, 0, 0x18000
	v_add_u32_e32 v161, s33, v152
	s_add_i32 s34, 0, 0x1c000
	ds_read_b128 v[156:159], v161
	ds_read_b128 v[164:167], v161 offset:1024
	ds_read_b128 v[168:171], v161 offset:2048
	ds_read_b128 v[172:175], v161 offset:3072
	v_add_u32_e32 v161, s34, v152
	ds_read_b128 v[176:179], v161
	ds_read_b128 v[180:183], v161 offset:1024
	ds_read_b128 v[184:187], v161 offset:2048
	ds_read_b128 v[192:195], v161 offset:3072
	s_add_u32 s24, s44, 0x80000
	s_addc_u32 s25, s45, 0
	s_mov_b32 m0, s51
	v_lshl_add_u64 v[234:235], s[24:25], 0, v[136:137]
	ds_read_b128 v[196:199], v155 offset:32768
	ds_read_b128 v[200:203], v155 offset:33792
	ds_read_b128 v[204:207], v155 offset:34816
	ds_read_b128 v[208:211], v155 offset:35840
	ds_read_b128 v[212:215], v155 offset:36864
	ds_read_b128 v[216:219], v155 offset:37888
	ds_read_b128 v[220:223], v155 offset:38912
	ds_read_b128 v[224:227], v155 offset:39936
	global_load_lds_dwordx4 v[234:235], off
	v_lshl_add_u64 v[234:235], s[24:25], 0, v[132:133]
	s_mov_b32 m0, s52
	s_nop 0
	global_load_lds_dwordx4 v[234:235], off
	s_waitcnt vmcnt(8)
	s_waitcnt lgkmcnt(0)
	s_barrier
	s_setprio 1
	s_waitcnt lgkmcnt(0)
	v_mfma_f32_16x16x32_bf16 v[124:127], v[156:159], v[196:199], v[124:127]
	v_mfma_f32_16x16x32_bf16 v[120:123], v[168:171], v[196:199], v[120:123]
	v_mfma_f32_16x16x32_bf16 v[108:111], v[156:159], v[204:207], v[108:111]
	v_mfma_f32_16x16x32_bf16 v[104:107], v[168:171], v[204:207], v[104:107]
	v_mfma_f32_16x16x32_bf16 v[92:95], v[156:159], v[212:215], v[92:95]
	v_mfma_f32_16x16x32_bf16 v[88:91], v[168:171], v[212:215], v[88:91]
	v_mfma_f32_16x16x32_bf16 v[76:79], v[156:159], v[220:223], v[76:79]
	v_mfma_f32_16x16x32_bf16 v[72:75], v[168:171], v[220:223], v[72:75]
	v_mfma_f32_16x16x32_bf16 v[124:127], v[164:167], v[200:203], v[124:127]
	v_mfma_f32_16x16x32_bf16 v[120:123], v[172:175], v[200:203], v[120:123]
	v_mfma_f32_16x16x32_bf16 v[108:111], v[164:167], v[208:211], v[108:111]
	v_mfma_f32_16x16x32_bf16 v[104:107], v[172:175], v[208:211], v[104:107]
	v_mfma_f32_16x16x32_bf16 v[92:95], v[164:167], v[216:219], v[92:95]
	v_mfma_f32_16x16x32_bf16 v[88:91], v[172:175], v[216:219], v[88:91]
	v_mfma_f32_16x16x32_bf16 v[76:79], v[164:167], v[224:227], v[76:79]
	v_mfma_f32_16x16x32_bf16 v[72:75], v[172:175], v[224:227], v[72:75]
	s_setprio 0
	s_setprio 1
	v_mfma_f32_16x16x32_bf16 v[116:119], v[176:179], v[196:199], v[116:119]
	v_mfma_f32_16x16x32_bf16 v[112:115], v[184:187], v[196:199], v[112:115]
	v_mfma_f32_16x16x32_bf16 v[100:103], v[176:179], v[204:207], v[100:103]
	v_mfma_f32_16x16x32_bf16 v[96:99], v[184:187], v[204:207], v[96:99]
	v_mfma_f32_16x16x32_bf16 v[84:87], v[176:179], v[212:215], v[84:87]
	v_mfma_f32_16x16x32_bf16 v[80:83], v[184:187], v[212:215], v[80:83]
	v_mfma_f32_16x16x32_bf16 v[68:71], v[176:179], v[220:223], v[68:71]
	v_mfma_f32_16x16x32_bf16 v[64:67], v[184:187], v[220:223], v[64:67]
	v_mfma_f32_16x16x32_bf16 v[116:119], v[180:183], v[200:203], v[116:119]
	v_mfma_f32_16x16x32_bf16 v[112:115], v[192:195], v[200:203], v[112:115]
	v_mfma_f32_16x16x32_bf16 v[100:103], v[180:183], v[208:211], v[100:103]
	v_mfma_f32_16x16x32_bf16 v[96:99], v[192:195], v[208:211], v[96:99]
	v_mfma_f32_16x16x32_bf16 v[84:87], v[180:183], v[216:219], v[84:87]
	v_mfma_f32_16x16x32_bf16 v[80:83], v[192:195], v[216:219], v[80:83]
	v_mfma_f32_16x16x32_bf16 v[68:71], v[180:183], v[224:227], v[68:71]
	v_mfma_f32_16x16x32_bf16 v[64:67], v[192:195], v[224:227], v[64:67]
	s_setprio 0
	s_barrier
; #define PG8_STAGE(bufoff, gbase, voff) do { _Pragma("unroll") for (int _i = 0; _i < 2; ++_i) \
;         __builtin_amdgcn_global_load_lds((const unsigned*)((const char*)(gbase) + (voff)[_i]), (LAS unsigned*)(lds + (bufoff) + ldsw + _i * 8192), 16, 0, 0); } while (0)
; #define PG8_LDA(dst, b, h) do { _Pragma("unroll") for (int m = 0; m < 4; ++m) _Pragma("unroll") for (int k = 0; k < 2; ++k) dst[m][k] = *(const LAS bf16x8*)(lds + PG8_SA(b, h) + aoff + m * 2048 + k * 1024); } while (0)
; #define PG8_MMA(ai, bj, At, Bt) do { __builtin_amdgcn_s_setprio(1); _Pragma("unroll") for (int m = 0; m < 4; ++m) _Pragma("unroll") for (int n = 0; n < 2; ++n) _Pragma("unroll") for (int k = 0; k < 2; ++k) \
;         acc[ai][bj][m][n] = __builtin_amdgcn_mfma_f32_16x16x32_bf16(Bt[n][k], At[m][k], acc[ai][bj][m][n], 0, 0, 0); __builtin_amdgcn_s_setprio(0); } while (0)
; #define PG8_WAIT_V(n) asm volatile("s_waitcnt vmcnt(" #n ")" ::: "memory")
; #define PG8_WAIT_L(n) asm volatile("s_waitcnt lgkmcnt(" #n ")" ::: "memory")
; #define PG8_BAR __builtin_amdgcn_s_barrier()
; #define PG8_SCHED __builtin_amdgcn_sched_barrier(0)
; template <int GI>
; __device__ __forceinline__ void gemm_phase(LAS unsigned char* lds, unsigned char* ws, int G, int cblk) {
;     ...
;         for (int t = 0; t < nt; t += 2) {
;             const bool last = (t == nt - 2);
;     ...
;             PG8_LDA(At, 1, 1); PG8_STAGE(PG8_SB(1, 0), b3, voffB); PG8_STAGE(PG8_SB(1, 1), b3 + hstepB, voffB); PG8_STAGE(PG8_SA(1, 0), a3, voffA);
;             PG8_WAIT_V(8); PG8_WAIT_L(0); PG8_BAR; PG8_MMA(1, 0, At, B0); PG8_MMA(1, 1, At, B1); PG8_BAR; PG8_SCHED;
	s_add_i32 s24, s33, s26
	v_lshl_add_u64 v[188:189], v[188:189], 0, s[12:13]
	s_mov_b32 m0, s24
	ds_read_b128 v[196:199], v155 offset:49152
	ds_read_b128 v[200:203], v155 offset:50176
	ds_read_b128 v[204:207], v155 offset:51200
	ds_read_b128 v[208:211], v155 offset:52224
	ds_read_b128 v[212:215], v155 offset:53248
	ds_read_b128 v[216:219], v155 offset:54272
	ds_read_b128 v[220:223], v155 offset:55296
	ds_read_b128 v[224:227], v155 offset:56320
	global_load_lds_dwordx4 v[188:189], off
	s_add_i32 m0, s24, 0x2000
	s_add_u32 s24, s42, 0x80080
	v_lshl_add_u64 v[188:189], v[228:229], 0, s[12:13]
	s_addc_u32 s25, s43, 0
	s_add_i32 s33, s34, s26
	global_load_lds_dwordx4 v[188:189], off
	v_lshl_add_u64 v[188:189], s[24:25], 0, v[134:135]
	s_mov_b32 m0, s33
	s_nop 0
	global_load_lds_dwordx4 v[188:189], off
	v_lshl_add_u64 v[188:189], s[24:25], 0, v[130:131]
	s_add_i32 m0, s33, 0x2000
	s_nop 0
	global_load_lds_dwordx4 v[188:189], off
	v_lshl_add_u64 v[188:189], v[230:231], 0, s[12:13]
	s_mov_b32 m0, s53
	s_nop 0
	global_load_lds_dwordx4 v[188:189], off
	v_lshl_add_u64 v[188:189], v[232:233], 0, s[12:13]
	s_mov_b32 m0, s55
	s_nop 0
	global_load_lds_dwordx4 v[188:189], off
	s_waitcnt vmcnt(8)
	s_waitcnt lgkmcnt(0)
	s_barrier
	s_setprio 1
	s_waitcnt lgkmcnt(0)
	v_mfma_f32_16x16x32_bf16 v[60:63], v[156:159], v[196:199], v[60:63]
	v_mfma_f32_16x16x32_bf16 v[56:59], v[168:171], v[196:199], v[56:59]
	v_mfma_f32_16x16x32_bf16 v[44:47], v[156:159], v[204:207], v[44:47]
	v_mfma_f32_16x16x32_bf16 v[40:43], v[168:171], v[204:207], v[40:43]
	v_mfma_f32_16x16x32_bf16 v[28:31], v[156:159], v[212:215], v[28:31]
	v_mfma_f32_16x16x32_bf16 v[24:27], v[168:171], v[212:215], v[24:27]
	v_mfma_f32_16x16x32_bf16 v[12:15], v[156:159], v[220:223], v[12:15]
	v_mfma_f32_16x16x32_bf16 v[8:11], v[168:171], v[220:223], v[8:11]
	v_mfma_f32_16x16x32_bf16 v[60:63], v[164:167], v[200:203], v[60:63]
	v_mfma_f32_16x16x32_bf16 v[56:59], v[172:175], v[200:203], v[56:59]
	v_mfma_f32_16x16x32_bf16 v[44:47], v[164:167], v[208:211], v[44:47]
	v_mfma_f32_16x16x32_bf16 v[40:43], v[172:175], v[208:211], v[40:43]
	v_mfma_f32_16x16x32_bf16 v[28:31], v[164:167], v[216:219], v[28:31]
	v_mfma_f32_16x16x32_bf16 v[24:27], v[172:175], v[216:219], v[24:27]
	v_mfma_f32_16x16x32_bf16 v[12:15], v[164:167], v[224:227], v[12:15]
	v_mfma_f32_16x16x32_bf16 v[8:11], v[172:175], v[224:227], v[8:11]
	s_setprio 0
	s_setprio 1
	v_mfma_f32_16x16x32_bf16 v[52:55], v[176:179], v[196:199], v[52:55]
	v_mfma_f32_16x16x32_bf16 v[48:51], v[184:187], v[196:199], v[48:51]
	v_mfma_f32_16x16x32_bf16 v[36:39], v[176:179], v[204:207], v[36:39]
	v_mfma_f32_16x16x32_bf16 v[32:35], v[184:187], v[204:207], v[32:35]
	v_mfma_f32_16x16x32_bf16 v[20:23], v[176:179], v[212:215], v[20:23]
	v_mfma_f32_16x16x32_bf16 v[16:19], v[184:187], v[212:215], v[16:19]
	v_mfma_f32_16x16x32_bf16 v[4:7], v[176:179], v[220:223], v[4:7]
	v_mfma_f32_16x16x32_bf16 v[0:3], v[184:187], v[220:223], v[0:3]
	v_mfma_f32_16x16x32_bf16 v[52:55], v[180:183], v[200:203], v[52:55]
	v_mfma_f32_16x16x32_bf16 v[48:51], v[192:195], v[200:203], v[48:51]
	v_mfma_f32_16x16x32_bf16 v[36:39], v[180:183], v[208:211], v[36:39]
	v_mfma_f32_16x16x32_bf16 v[32:35], v[192:195], v[208:211], v[32:35]
	v_mfma_f32_16x16x32_bf16 v[20:23], v[180:183], v[216:219], v[20:23]
	v_mfma_f32_16x16x32_bf16 v[16:19], v[192:195], v[216:219], v[16:19]
	v_mfma_f32_16x16x32_bf16 v[4:7], v[180:183], v[224:227], v[4:7]
	v_mfma_f32_16x16x32_bf16 v[0:3], v[192:195], v[224:227], v[0:3]
	s_setprio 0
	s_barrier
	s_add_i32 s17, s17, 2
	s_add_u32 s40, s40, 0x100
	s_addc_u32 s41, s41, 0
	s_add_u32 s0, s0, 0x100
	s_addc_u32 s1, s1, 0
	s_cmp_gt_u32 s17, 29
	s_cbranch_scc0 .LBB0_820
	s_branch .Lpeel_exit_8

; #define PG8_STAGE(bufoff, gbase, voff) do { _Pragma("unroll") for (int _i = 0; _i < 2; ++_i) \
;         __builtin_amdgcn_global_load_lds((const unsigned*)((const char*)(gbase) + (voff)[_i]), (LAS unsigned*)(lds + (bufoff) + ldsw + _i * 8192), 16, 0, 0); } while (0)
; #define PG8_LDA(dst, b, h) do { _Pragma("unroll") for (int m = 0; m < 4; ++m) _Pragma("unroll") for (int k = 0; k < 2; ++k) dst[m][k] = *(const LAS bf16x8*)(lds + PG8_SA(b, h) + aoff + m * 2048 + k * 1024); } while (0)
; #define PG8_LDB(dst, b, h) do { _Pragma("unroll") for (int n = 0; n < 2; ++n) _Pragma("unroll") for (int k = 0; k < 2; ++k) dst[n][k] = *(const LAS bf16x8*)(lds + PG8_SB(b, h) + boff + n * 2048 + k * 1024); } while (0)
; #define PG8_MMA(ai, bj, At, Bt) do { __builtin_amdgcn_s_setprio(1); _Pragma("unroll") for (int m = 0; m < 4; ++m) _Pragma("unroll") for (int n = 0; n < 2; ++n) _Pragma("unroll") for (int k = 0; k < 2; ++k) \
;         acc[ai][bj][m][n] = __builtin_amdgcn_mfma_f32_16x16x32_bf16(Bt[n][k], At[m][k], acc[ai][bj][m][n], 0, 0, 0); __builtin_amdgcn_s_setprio(0); } while (0)
; #define PG8_WAIT_V(n) asm volatile("s_waitcnt vmcnt(" #n ")" ::: "memory")
; #define PG8_WAIT_L(n) asm volatile("s_waitcnt lgkmcnt(" #n ")" ::: "memory")
; #define PG8_BAR __builtin_amdgcn_s_barrier()
; #define PG8_SCHED __builtin_amdgcn_sched_barrier(0)
; template <int GI>
; __device__ __forceinline__ void gemm_phase(LAS unsigned char* lds, unsigned char* ws, int G, int cblk) {
;     ...
;             PG8_LDB(B0, 0, 0); PG8_LDB(B1, 0, 1); PG8_SCHED; PG8_LDA(At, 0, 0); PG8_STAGE(PG8_SA(1, 1), a1 + hstepA, voffA);
;             PG8_WAIT_V(8); PG8_WAIT_L(0); PG8_BAR; PG8_MMA(0, 0, At, B0); PG8_MMA(0, 1, At, B1); PG8_BAR; PG8_SCHED;
;             PG8_LDA(At, 0, 1); PG8_STAGE(PG8_SB(0, 0), b2, voffB); PG8_STAGE(PG8_SB(0, 1), b2 + hstepB, voffB); PG8_STAGE(PG8_SA(0, 0), a2, voffA);
;             PG8_WAIT_V(8); PG8_WAIT_L(0); PG8_BAR; PG8_MMA(1, 0, At, B0); PG8_MMA(1, 1, At, B1); PG8_BAR; PG8_SCHED;
;     ...
;         for (int a = 0; a < 2; ++a)
; #pragma unroll
;             for (int b = 0; b < 2; ++b)
; #pragma unroll
;                 for (int m = 0; m < 4; ++m)
; #pragma unroll
;                     for (int n = 0; n < 2; ++n) acc[a][b][m][n] = (f32x4){0.f, 0.f, 0.f, 0.f};
.LBB0_895:
	s_add_u32 s15, s40, 0x100
	s_addc_u32 s53, s41, 0
	s_mov_b32 s54, -2
	ds_read_b128 v[156:159], v153
	ds_read_b128 v[164:167], v153 offset:1024
	ds_read_b128 v[168:171], v153 offset:2048
	ds_read_b128 v[172:175], v153 offset:3072
	ds_read_b128 v[176:179], v154
	ds_read_b128 v[180:183], v154 offset:1024
	ds_read_b128 v[184:187], v154 offset:2048
	ds_read_b128 v[192:195], v154 offset:3072
	s_add_u32 s40, s38, 0x100
	s_addc_u32 s41, s39, 0
	s_cmpk_eq_i32 s54, 0x54
	s_cselect_b32 s45, s21, s41
	s_cselect_b32 s44, s20, s40
	s_cselect_b32 s43, s23, s53
	s_cselect_b32 s42, s22, s15
	v_lshl_add_u64 v[188:189], s[38:39], 0, v[140:141]
	s_add_i32 m0, s24, 0xc000
	ds_read_b128 v[196:199], v155
	ds_read_b128 v[200:203], v155 offset:1024
	ds_read_b128 v[204:207], v155 offset:2048
	ds_read_b128 v[208:211], v155 offset:3072
	ds_read_b128 v[212:215], v155 offset:4096
	ds_read_b128 v[216:219], v155 offset:5120
	ds_read_b128 v[220:223], v155 offset:6144
	ds_read_b128 v[224:227], v155 offset:7168
	global_load_lds_dwordx4 v[188:189], off
	v_lshl_add_u64 v[188:189], s[38:39], 0, v[142:143]
	s_add_i32 m0, s24, 0xe000
	s_nop 0
	global_load_lds_dwordx4 v[188:189], off
	s_waitcnt vmcnt(8)
	s_waitcnt lgkmcnt(0)
	s_barrier
	s_setprio 1
	s_waitcnt lgkmcnt(0)
	v_mfma_f32_16x16x32_bf16 v[124:127], v[156:159], v[196:199], 0
	v_mfma_f32_16x16x32_bf16 v[120:123], v[168:171], v[196:199], 0
	v_mfma_f32_16x16x32_bf16 v[116:119], v[156:159], v[204:207], 0
	v_mfma_f32_16x16x32_bf16 v[112:115], v[168:171], v[204:207], 0
	v_mfma_f32_16x16x32_bf16 v[100:103], v[156:159], v[212:215], 0
	v_mfma_f32_16x16x32_bf16 v[96:99], v[168:171], v[212:215], 0
	v_mfma_f32_16x16x32_bf16 v[84:87], v[156:159], v[220:223], 0
	v_mfma_f32_16x16x32_bf16 v[80:83], v[168:171], v[220:223], 0
	v_mfma_f32_16x16x32_bf16 v[124:127], v[164:167], v[200:203], v[124:127]
	v_mfma_f32_16x16x32_bf16 v[120:123], v[172:175], v[200:203], v[120:123]
	v_mfma_f32_16x16x32_bf16 v[116:119], v[164:167], v[208:211], v[116:119]
	v_mfma_f32_16x16x32_bf16 v[112:115], v[172:175], v[208:211], v[112:115]
	v_mfma_f32_16x16x32_bf16 v[100:103], v[164:167], v[216:219], v[100:103]
	v_mfma_f32_16x16x32_bf16 v[96:99], v[172:175], v[216:219], v[96:99]
	v_mfma_f32_16x16x32_bf16 v[84:87], v[164:167], v[224:227], v[84:87]
	v_mfma_f32_16x16x32_bf16 v[80:83], v[172:175], v[224:227], v[80:83]
	s_setprio 0
	s_setprio 1
	v_mfma_f32_16x16x32_bf16 v[108:111], v[176:179], v[196:199], 0
	v_mfma_f32_16x16x32_bf16 v[104:107], v[184:187], v[196:199], 0
	v_mfma_f32_16x16x32_bf16 v[92:95], v[176:179], v[204:207], 0
	v_mfma_f32_16x16x32_bf16 v[88:91], v[184:187], v[204:207], 0
	v_mfma_f32_16x16x32_bf16 v[76:79], v[176:179], v[212:215], 0
	v_mfma_f32_16x16x32_bf16 v[72:75], v[184:187], v[212:215], 0
	v_mfma_f32_16x16x32_bf16 v[68:71], v[176:179], v[220:223], 0
	v_mfma_f32_16x16x32_bf16 v[64:67], v[184:187], v[220:223], 0
	v_mfma_f32_16x16x32_bf16 v[108:111], v[180:183], v[200:203], v[108:111]
	v_mfma_f32_16x16x32_bf16 v[104:107], v[192:195], v[200:203], v[104:107]
	v_mfma_f32_16x16x32_bf16 v[92:95], v[180:183], v[208:211], v[92:95]
	v_mfma_f32_16x16x32_bf16 v[88:91], v[192:195], v[208:211], v[88:91]
	v_mfma_f32_16x16x32_bf16 v[76:79], v[180:183], v[216:219], v[76:79]
	v_mfma_f32_16x16x32_bf16 v[72:75], v[192:195], v[216:219], v[72:75]
	v_mfma_f32_16x16x32_bf16 v[68:71], v[180:183], v[224:227], v[68:71]
	v_mfma_f32_16x16x32_bf16 v[64:67], v[192:195], v[224:227], v[64:67]
	s_setprio 0
	s_barrier
	s_add_i32 s34, s50, s0
	v_lshl_add_u64 v[188:189], s[42:43], 0, v[132:133]
	s_mov_b32 m0, s34
	ds_read_b128 v[196:199], v155 offset:16384
	ds_read_b128 v[200:203], v155 offset:17408
	ds_read_b128 v[204:207], v155 offset:18432
	ds_read_b128 v[208:211], v155 offset:19456
	ds_read_b128 v[212:215], v155 offset:20480
	ds_read_b128 v[216:219], v155 offset:21504
	ds_read_b128 v[220:223], v155 offset:22528
	ds_read_b128 v[224:227], v155 offset:23552
	global_load_lds_dwordx4 v[188:189], off
	s_add_i32 m0, s34, 0x2000
	s_add_u32 s38, s42, 0x160000
	v_lshl_add_u64 v[228:229], s[42:43], 0, v[136:137]
	s_addc_u32 s39, s43, 0
	s_add_i32 s34, s51, s0
	global_load_lds_dwordx4 v[228:229], off
	v_lshl_add_u64 v[230:231], s[38:39], 0, v[132:133]
	s_mov_b32 m0, s34
	v_lshl_add_u64 v[232:233], s[44:45], 0, v[134:135]
	global_load_lds_dwordx4 v[230:231], off
	v_lshl_add_u64 v[230:231], s[38:39], 0, v[136:137]
	s_add_i32 m0, s34, 0x2000
	s_nop 0
	global_load_lds_dwordx4 v[230:231], off
	v_lshl_add_u64 v[230:231], s[44:45], 0, v[130:131]
	s_mov_b32 m0, s24
	s_nop 0
	global_load_lds_dwordx4 v[230:231], off
	s_mov_b32 m0, s25
	s_nop 0
	global_load_lds_dwordx4 v[232:233], off
	s_waitcnt vmcnt(8)
	s_waitcnt lgkmcnt(0)
	s_barrier
; #define PG8_STAGE(bufoff, gbase, voff) do { _Pragma("unroll") for (int _i = 0; _i < 2; ++_i) \
;         __builtin_amdgcn_global_load_lds((const unsigned*)((const char*)(gbase) + (voff)[_i]), (LAS unsigned*)(lds + (bufoff) + ldsw + _i * 8192), 16, 0, 0); } while (0)
; #define PG8_LDA(dst, b, h) do { _Pragma("unroll") for (int m = 0; m < 4; ++m) _Pragma("unroll") for (int k = 0; k < 2; ++k) dst[m][k] = *(const LAS bf16x8*)(lds + PG8_SA(b, h) + aoff + m * 2048 + k * 1024); } while (0)
; #define PG8_LDB(dst, b, h) do { _Pragma("unroll") for (int n = 0; n < 2; ++n) _Pragma("unroll") for (int k = 0; k < 2; ++k) dst[n][k] = *(const LAS bf16x8*)(lds + PG8_SB(b, h) + boff + n * 2048 + k * 1024); } while (0)
; #define PG8_MMA(ai, bj, At, Bt) do { __builtin_amdgcn_s_setprio(1); _Pragma("unroll") for (int m = 0; m < 4; ++m) _Pragma("unroll") for (int n = 0; n < 2; ++n) _Pragma("unroll") for (int k = 0; k < 2; ++k) \
;         acc[ai][bj][m][n] = __builtin_amdgcn_mfma_f32_16x16x32_bf16(Bt[n][k], At[m][k], acc[ai][bj][m][n], 0, 0, 0); __builtin_amdgcn_s_setprio(0); } while (0)
; #define PG8_WAIT_V(n) asm volatile("s_waitcnt vmcnt(" #n ")" ::: "memory")
; #define PG8_WAIT_L(n) asm volatile("s_waitcnt lgkmcnt(" #n ")" ::: "memory")
; #define PG8_BAR __builtin_amdgcn_s_barrier()
; #define PG8_SCHED __builtin_amdgcn_sched_barrier(0)
; template <int GI>
; __device__ __forceinline__ void gemm_phase(LAS unsigned char* lds, unsigned char* ws, int G, int cblk) {
;     ...
;             PG8_WAIT_V(8); PG8_WAIT_L(0); PG8_BAR; PG8_MMA(1, 0, At, B0); PG8_MMA(1, 1, At, B1); PG8_BAR; PG8_SCHED;
;             PG8_LDB(B0, 1, 0); PG8_LDB(B1, 1, 1); PG8_SCHED; PG8_LDA(At, 1, 0); PG8_STAGE(PG8_SA(0, 1), a2 + hstepA, voffA);
;             PG8_WAIT_V(8); PG8_WAIT_L(0); PG8_BAR; PG8_MMA(0, 0, At, B0); PG8_MMA(0, 1, At, B1); PG8_BAR; PG8_SCHED;
	s_setprio 1
	s_waitcnt lgkmcnt(0)
	v_mfma_f32_16x16x32_bf16 v[60:63], v[156:159], v[196:199], 0
	v_mfma_f32_16x16x32_bf16 v[56:59], v[168:171], v[196:199], 0
	v_mfma_f32_16x16x32_bf16 v[52:55], v[156:159], v[204:207], 0
	v_mfma_f32_16x16x32_bf16 v[48:51], v[168:171], v[204:207], 0
	v_mfma_f32_16x16x32_bf16 v[36:39], v[156:159], v[212:215], 0
	v_mfma_f32_16x16x32_bf16 v[32:35], v[168:171], v[212:215], 0
	v_mfma_f32_16x16x32_bf16 v[20:23], v[156:159], v[220:223], 0
	v_mfma_f32_16x16x32_bf16 v[16:19], v[168:171], v[220:223], 0
	v_mfma_f32_16x16x32_bf16 v[60:63], v[164:167], v[200:203], v[60:63]
	v_mfma_f32_16x16x32_bf16 v[56:59], v[172:175], v[200:203], v[56:59]
	v_mfma_f32_16x16x32_bf16 v[52:55], v[164:167], v[208:211], v[52:55]
	v_mfma_f32_16x16x32_bf16 v[48:51], v[172:175], v[208:211], v[48:51]
	v_mfma_f32_16x16x32_bf16 v[36:39], v[164:167], v[216:219], v[36:39]
	v_mfma_f32_16x16x32_bf16 v[32:35], v[172:175], v[216:219], v[32:35]
	v_mfma_f32_16x16x32_bf16 v[20:23], v[164:167], v[224:227], v[20:23]
	v_mfma_f32_16x16x32_bf16 v[16:19], v[172:175], v[224:227], v[16:19]
	s_setprio 0
	s_setprio 1
	v_mfma_f32_16x16x32_bf16 v[44:47], v[176:179], v[196:199], 0
	v_mfma_f32_16x16x32_bf16 v[40:43], v[184:187], v[196:199], 0
	v_mfma_f32_16x16x32_bf16 v[28:31], v[176:179], v[204:207], 0
	v_mfma_f32_16x16x32_bf16 v[24:27], v[184:187], v[204:207], 0
	v_mfma_f32_16x16x32_bf16 v[12:15], v[176:179], v[212:215], 0
	v_mfma_f32_16x16x32_bf16 v[8:11], v[184:187], v[212:215], 0
	v_mfma_f32_16x16x32_bf16 v[4:7], v[176:179], v[220:223], 0
	v_mfma_f32_16x16x32_bf16 v[0:3], v[184:187], v[220:223], 0
	v_mfma_f32_16x16x32_bf16 v[44:47], v[180:183], v[200:203], v[44:47]
	v_mfma_f32_16x16x32_bf16 v[40:43], v[192:195], v[200:203], v[40:43]
	v_mfma_f32_16x16x32_bf16 v[28:31], v[180:183], v[208:211], v[28:31]
	v_mfma_f32_16x16x32_bf16 v[24:27], v[192:195], v[208:211], v[24:27]
	v_mfma_f32_16x16x32_bf16 v[12:15], v[180:183], v[216:219], v[12:15]
	v_mfma_f32_16x16x32_bf16 v[8:11], v[192:195], v[216:219], v[8:11]
	v_mfma_f32_16x16x32_bf16 v[4:7], v[180:183], v[224:227], v[4:7]
	v_mfma_f32_16x16x32_bf16 v[0:3], v[192:195], v[224:227], v[0:3]
	s_setprio 0
	s_barrier
	s_add_i32 s34, 0, 0x18000
	v_add_u32_e32 v161, s34, v152
	s_add_i32 s55, 0, 0x1c000
	ds_read_b128 v[156:159], v161
	ds_read_b128 v[164:167], v161 offset:1024
	ds_read_b128 v[168:171], v161 offset:2048
	ds_read_b128 v[172:175], v161 offset:3072
	v_add_u32_e32 v161, s55, v152
	ds_read_b128 v[176:179], v161
	ds_read_b128 v[180:183], v161 offset:1024
	ds_read_b128 v[184:187], v161 offset:2048
	ds_read_b128 v[192:195], v161 offset:3072
	s_add_u32 s38, s44, 0x160000
	s_addc_u32 s39, s45, 0
	s_mov_b32 m0, s26
	v_lshl_add_u64 v[234:235], s[38:39], 0, v[130:131]
	ds_read_b128 v[196:199], v155 offset:32768
	ds_read_b128 v[200:203], v155 offset:33792
	ds_read_b128 v[204:207], v155 offset:34816
	ds_read_b128 v[208:211], v155 offset:35840
	ds_read_b128 v[212:215], v155 offset:36864
	ds_read_b128 v[216:219], v155 offset:37888
	ds_read_b128 v[220:223], v155 offset:38912
	ds_read_b128 v[224:227], v155 offset:39936
	global_load_lds_dwordx4 v[234:235], off
	v_lshl_add_u64 v[234:235], s[38:39], 0, v[134:135]
	s_mov_b32 m0, s27
	s_nop 0
	global_load_lds_dwordx4 v[234:235], off
	s_waitcnt vmcnt(8)
	s_waitcnt lgkmcnt(0)
	s_barrier
	s_setprio 1
	s_waitcnt lgkmcnt(0)
	v_mfma_f32_16x16x32_bf16 v[124:127], v[156:159], v[196:199], v[124:127]
	v_mfma_f32_16x16x32_bf16 v[120:123], v[168:171], v[196:199], v[120:123]
	v_mfma_f32_16x16x32_bf16 v[116:119], v[156:159], v[204:207], v[116:119]
	v_mfma_f32_16x16x32_bf16 v[112:115], v[168:171], v[204:207], v[112:115]
	v_mfma_f32_16x16x32_bf16 v[100:103], v[156:159], v[212:215], v[100:103]
	v_mfma_f32_16x16x32_bf16 v[96:99], v[168:171], v[212:215], v[96:99]
	v_mfma_f32_16x16x32_bf16 v[84:87], v[156:159], v[220:223], v[84:87]
	v_mfma_f32_16x16x32_bf16 v[80:83], v[168:171], v[220:223], v[80:83]
	v_mfma_f32_16x16x32_bf16 v[124:127], v[164:167], v[200:203], v[124:127]
	v_mfma_f32_16x16x32_bf16 v[120:123], v[172:175], v[200:203], v[120:123]
	v_mfma_f32_16x16x32_bf16 v[116:119], v[164:167], v[208:211], v[116:119]
	v_mfma_f32_16x16x32_bf16 v[112:115], v[172:175], v[208:211], v[112:115]
	v_mfma_f32_16x16x32_bf16 v[100:103], v[164:167], v[216:219], v[100:103]
	v_mfma_f32_16x16x32_bf16 v[96:99], v[172:175], v[216:219], v[96:99]
	v_mfma_f32_16x16x32_bf16 v[84:87], v[164:167], v[224:227], v[84:87]
	v_mfma_f32_16x16x32_bf16 v[80:83], v[172:175], v[224:227], v[80:83]
	s_setprio 0
	s_setprio 1
	v_mfma_f32_16x16x32_bf16 v[108:111], v[176:179], v[196:199], v[108:111]
	v_mfma_f32_16x16x32_bf16 v[104:107], v[184:187], v[196:199], v[104:107]
	v_mfma_f32_16x16x32_bf16 v[92:95], v[176:179], v[204:207], v[92:95]
	v_mfma_f32_16x16x32_bf16 v[88:91], v[184:187], v[204:207], v[88:91]
	v_mfma_f32_16x16x32_bf16 v[76:79], v[176:179], v[212:215], v[76:79]
	v_mfma_f32_16x16x32_bf16 v[72:75], v[184:187], v[212:215], v[72:75]
	v_mfma_f32_16x16x32_bf16 v[68:71], v[176:179], v[220:223], v[68:71]
	v_mfma_f32_16x16x32_bf16 v[64:67], v[184:187], v[220:223], v[64:67]
	v_mfma_f32_16x16x32_bf16 v[108:111], v[180:183], v[200:203], v[108:111]
	v_mfma_f32_16x16x32_bf16 v[104:107], v[192:195], v[200:203], v[104:107]
	v_mfma_f32_16x16x32_bf16 v[92:95], v[180:183], v[208:211], v[92:95]
	v_mfma_f32_16x16x32_bf16 v[88:91], v[192:195], v[208:211], v[88:91]
	v_mfma_f32_16x16x32_bf16 v[76:79], v[180:183], v[216:219], v[76:79]
	v_mfma_f32_16x16x32_bf16 v[72:75], v[192:195], v[216:219], v[72:75]
	v_mfma_f32_16x16x32_bf16 v[68:71], v[180:183], v[224:227], v[68:71]
	v_mfma_f32_16x16x32_bf16 v[64:67], v[192:195], v[224:227], v[64:67]
	s_setprio 0
	s_barrier
; #define PG8_STAGE(bufoff, gbase, voff) do { _Pragma("unroll") for (int _i = 0; _i < 2; ++_i) \
;         __builtin_amdgcn_global_load_lds((const unsigned*)((const char*)(gbase) + (voff)[_i]), (LAS unsigned*)(lds + (bufoff) + ldsw + _i * 8192), 16, 0, 0); } while (0)
; #define PG8_LDA(dst, b, h) do { _Pragma("unroll") for (int m = 0; m < 4; ++m) _Pragma("unroll") for (int k = 0; k < 2; ++k) dst[m][k] = *(const LAS bf16x8*)(lds + PG8_SA(b, h) + aoff + m * 2048 + k * 1024); } while (0)
; #define PG8_MMA(ai, bj, At, Bt) do { __builtin_amdgcn_s_setprio(1); _Pragma("unroll") for (int m = 0; m < 4; ++m) _Pragma("unroll") for (int n = 0; n < 2; ++n) _Pragma("unroll") for (int k = 0; k < 2; ++k) \
;         acc[ai][bj][m][n] = __builtin_amdgcn_mfma_f32_16x16x32_bf16(Bt[n][k], At[m][k], acc[ai][bj][m][n], 0, 0, 0); __builtin_amdgcn_s_setprio(0); } while (0)
; #define PG8_WAIT_V(n) asm volatile("s_waitcnt vmcnt(" #n ")" ::: "memory")
; #define PG8_WAIT_L(n) asm volatile("s_waitcnt lgkmcnt(" #n ")" ::: "memory")
; #define PG8_BAR __builtin_amdgcn_s_barrier()
; #define PG8_SCHED __builtin_amdgcn_sched_barrier(0)
; template <int GI>
; __device__ __forceinline__ void gemm_phase(LAS unsigned char* lds, unsigned char* ws, int G, int cblk) {
;     ...
;         for (int t = 0; t < nt; t += 2) {
;             const bool last = (t == nt - 2);
;     ...
;             PG8_LDA(At, 1, 1); PG8_STAGE(PG8_SB(1, 0), b3, voffB); PG8_STAGE(PG8_SB(1, 1), b3 + hstepB, voffB); PG8_STAGE(PG8_SA(1, 0), a3, voffA);
;             PG8_WAIT_V(8); PG8_WAIT_L(0); PG8_BAR; PG8_MMA(1, 0, At, B0); PG8_MMA(1, 1, At, B1); PG8_BAR; PG8_SCHED;
	s_add_i32 s34, s34, s0
	v_lshl_add_u64 v[188:189], v[188:189], 0, s[10:11]
	s_mov_b32 m0, s34
	ds_read_b128 v[196:199], v155 offset:49152
	ds_read_b128 v[200:203], v155 offset:50176
	ds_read_b128 v[204:207], v155 offset:51200
	ds_read_b128 v[208:211], v155 offset:52224
	ds_read_b128 v[212:215], v155 offset:53248
	ds_read_b128 v[216:219], v155 offset:54272
	ds_read_b128 v[220:223], v155 offset:55296
	ds_read_b128 v[224:227], v155 offset:56320
	global_load_lds_dwordx4 v[188:189], off
	s_add_i32 m0, s34, 0x2000
	s_add_u32 s38, s42, 0x160080
	v_lshl_add_u64 v[188:189], v[228:229], 0, s[10:11]
	s_addc_u32 s39, s43, 0
	s_add_i32 s34, s55, s0
	global_load_lds_dwordx4 v[188:189], off
	v_lshl_add_u64 v[188:189], s[38:39], 0, v[132:133]
	s_mov_b32 m0, s34
	s_nop 0
	global_load_lds_dwordx4 v[188:189], off
	v_lshl_add_u64 v[188:189], s[38:39], 0, v[136:137]
	s_add_i32 m0, s34, 0x2000
	s_nop 0
	global_load_lds_dwordx4 v[188:189], off
	v_lshl_add_u64 v[188:189], v[230:231], 0, s[10:11]
	s_mov_b32 m0, s48
	s_nop 0
	global_load_lds_dwordx4 v[188:189], off
	v_lshl_add_u64 v[188:189], v[232:233], 0, s[10:11]
	s_mov_b32 m0, s49
	s_nop 0
	global_load_lds_dwordx4 v[188:189], off
	s_waitcnt vmcnt(8)
	s_waitcnt lgkmcnt(0)
	s_barrier
	s_setprio 1
	s_waitcnt lgkmcnt(0)
	v_mfma_f32_16x16x32_bf16 v[60:63], v[156:159], v[196:199], v[60:63]
	v_mfma_f32_16x16x32_bf16 v[56:59], v[168:171], v[196:199], v[56:59]
	v_mfma_f32_16x16x32_bf16 v[52:55], v[156:159], v[204:207], v[52:55]
	v_mfma_f32_16x16x32_bf16 v[48:51], v[168:171], v[204:207], v[48:51]
	v_mfma_f32_16x16x32_bf16 v[36:39], v[156:159], v[212:215], v[36:39]
	v_mfma_f32_16x16x32_bf16 v[32:35], v[168:171], v[212:215], v[32:35]
	v_mfma_f32_16x16x32_bf16 v[20:23], v[156:159], v[220:223], v[20:23]
	v_mfma_f32_16x16x32_bf16 v[16:19], v[168:171], v[220:223], v[16:19]
	v_mfma_f32_16x16x32_bf16 v[60:63], v[164:167], v[200:203], v[60:63]
	v_mfma_f32_16x16x32_bf16 v[56:59], v[172:175], v[200:203], v[56:59]
	v_mfma_f32_16x16x32_bf16 v[52:55], v[164:167], v[208:211], v[52:55]
	v_mfma_f32_16x16x32_bf16 v[48:51], v[172:175], v[208:211], v[48:51]
	v_mfma_f32_16x16x32_bf16 v[36:39], v[164:167], v[216:219], v[36:39]
	v_mfma_f32_16x16x32_bf16 v[32:35], v[172:175], v[216:219], v[32:35]
	v_mfma_f32_16x16x32_bf16 v[20:23], v[164:167], v[224:227], v[20:23]
	v_mfma_f32_16x16x32_bf16 v[16:19], v[172:175], v[224:227], v[16:19]
	s_setprio 0
	s_setprio 1
	v_mfma_f32_16x16x32_bf16 v[44:47], v[176:179], v[196:199], v[44:47]
	v_mfma_f32_16x16x32_bf16 v[40:43], v[184:187], v[196:199], v[40:43]
	v_mfma_f32_16x16x32_bf16 v[28:31], v[176:179], v[204:207], v[28:31]
	v_mfma_f32_16x16x32_bf16 v[24:27], v[184:187], v[204:207], v[24:27]
	v_mfma_f32_16x16x32_bf16 v[12:15], v[176:179], v[212:215], v[12:15]
	v_mfma_f32_16x16x32_bf16 v[8:11], v[184:187], v[212:215], v[8:11]
	v_mfma_f32_16x16x32_bf16 v[4:7], v[176:179], v[220:223], v[4:7]
	v_mfma_f32_16x16x32_bf16 v[0:3], v[184:187], v[220:223], v[0:3]
	v_mfma_f32_16x16x32_bf16 v[44:47], v[180:183], v[200:203], v[44:47]
	v_mfma_f32_16x16x32_bf16 v[40:43], v[192:195], v[200:203], v[40:43]
	v_mfma_f32_16x16x32_bf16 v[28:31], v[180:183], v[208:211], v[28:31]
	v_mfma_f32_16x16x32_bf16 v[24:27], v[192:195], v[208:211], v[24:27]
	v_mfma_f32_16x16x32_bf16 v[12:15], v[180:183], v[216:219], v[12:15]
	v_mfma_f32_16x16x32_bf16 v[8:11], v[192:195], v[216:219], v[8:11]
	v_mfma_f32_16x16x32_bf16 v[4:7], v[180:183], v[224:227], v[4:7]
	v_mfma_f32_16x16x32_bf16 v[0:3], v[192:195], v[224:227], v[0:3]
	s_setprio 0
	s_barrier
	s_add_i32 s54, s54, 2
	s_add_u32 s15, s15, 0x100
	s_addc_u32 s53, s53, 0
	s_cmpk_gt_u32 s54, 0x55
	s_mov_b64 s[38:39], s[40:41]
	s_cbranch_scc0 .LBB0_896
	s_branch .Lpeel_exit_9
